# rotate-by-i fold extended across workgroup barriers (231 sites)
# speedup vs baseline: 1.0131x; 1.0058x over previous
.LBB0_271:
	global_load_dword v40, v35, s[18:19]
	v_lshl_add_u64 v[44:45], s[18:19], 0, v[34:35]
	global_load_dword v42, v[44:45], off
	s_waitcnt vmcnt(9)
	v_cvt_f32_f16_e32 v62, v6
	v_cvt_f32_f16_sdwa v44, v6 dst_sel:DWORD dst_unused:UNUSED_PAD src0_sel:WORD_1
	v_cvt_f32_f16_e32 v45, v7
	v_cvt_f32_f16_e32 v47, v8
	v_cvt_f32_f16_sdwa v48, v8 dst_sel:DWORD dst_unused:UNUSED_PAD src0_sel:WORD_1
	v_cvt_f32_f16_e32 v49, v9
	v_cvt_f32_f16_sdwa v8, v9 dst_sel:DWORD dst_unused:UNUSED_PAD src0_sel:WORD_1
	s_waitcnt vmcnt(8)
	v_cvt_f32_f16_e32 v9, v30
	s_waitcnt vmcnt(7)
	v_cvt_f32_f16_sdwa v52, v26 dst_sel:DWORD dst_unused:UNUSED_PAD src0_sel:WORD_1
	v_cvt_f32_f16_e32 v53, v27
	v_cvt_f32_f16_sdwa v46, v7 dst_sel:DWORD dst_unused:UNUSED_PAD src0_sel:WORD_1
	v_cvt_f32_f16_sdwa v50, v30 dst_sel:DWORD dst_unused:UNUSED_PAD src0_sel:WORD_1
	v_cvt_f32_f16_e32 v51, v31
	v_cvt_f32_f16_sdwa v30, v31 dst_sel:DWORD dst_unused:UNUSED_PAD src0_sel:WORD_1
	v_cvt_f32_f16_e32 v31, v32
	v_cvt_f32_f16_sdwa v7, v33 dst_sel:DWORD dst_unused:UNUSED_PAD src0_sel:WORD_1
	v_cvt_f32_f16_sdwa v32, v32 dst_sel:DWORD dst_unused:UNUSED_PAD src0_sel:WORD_1
	v_cvt_f32_f16_e32 v33, v33
	v_cvt_f32_f16_sdwa v26, v27 dst_sel:DWORD dst_unused:UNUSED_PAD src0_sel:WORD_1
	v_cvt_f32_f16_e32 v27, v28
	v_cvt_f32_f16_sdwa v54, v28 dst_sel:DWORD dst_unused:UNUSED_PAD src0_sel:WORD_1
	v_cvt_f32_f16_e32 v55, v29
	s_waitcnt vmcnt(6)
	v_cvt_f32_f16_e32 v28, v18
	v_cvt_f32_f16_sdwa v56, v18 dst_sel:DWORD dst_unused:UNUSED_PAD src0_sel:WORD_1
	v_cvt_f32_f16_e32 v57, v19
	v_cvt_f32_f16_sdwa v18, v19 dst_sel:DWORD dst_unused:UNUSED_PAD src0_sel:WORD_1
	v_cvt_f32_f16_e32 v19, v20
	v_cvt_f32_f16_sdwa v58, v20 dst_sel:DWORD dst_unused:UNUSED_PAD src0_sel:WORD_1
	v_cvt_f32_f16_e32 v59, v21
	v_cvt_f32_f16_sdwa v29, v29 dst_sel:DWORD dst_unused:UNUSED_PAD src0_sel:WORD_1
	v_cvt_f32_f16_sdwa v21, v21 dst_sel:DWORD dst_unused:UNUSED_PAD src0_sel:WORD_1
	v_cvt_f32_f16_e32 v20, v120
	s_waitcnt vmcnt(5)
	v_cvt_f32_f16_e32 v63, v22
	v_mul_f32_e32 v62, 0x3b800000, v62
	v_pk_mul_f32 v[44:45], v[44:45], s[38:39] op_sel_hi:[1,0]
	v_pk_mul_f32 v[8:9], v[8:9], s[38:39] op_sel_hi:[1,0]
	v_pk_mul_f32 v[52:53], v[52:53], s[38:39] op_sel_hi:[1,0]
	v_pk_mul_f32 v[46:47], v[46:47], s[38:39] op_sel_hi:[1,0]
	v_pk_mul_f32 v[48:49], v[48:49], s[38:39] op_sel_hi:[1,0]
	v_pk_mul_f32 v[50:51], v[50:51], s[38:39] op_sel_hi:[1,0]
	v_pk_mul_f32 v[30:31], v[30:31], s[38:39] op_sel_hi:[1,0]
	v_mul_f32_e32 v7, 0x3b800000, v7
	v_pk_mul_f32 v[32:33], v[32:33], s[38:39] op_sel_hi:[1,0]
	v_pk_mul_f32 v[26:27], v[26:27], s[38:39] op_sel_hi:[1,0]
	v_pk_mul_f32 v[54:55], v[54:55], s[38:39] op_sel_hi:[1,0]
	v_pk_mul_f32 v[56:57], v[56:57], s[38:39] op_sel_hi:[1,0]
	v_pk_mul_f32 v[18:19], v[18:19], s[38:39] op_sel_hi:[1,0]
	v_pk_mul_f32 v[58:59], v[58:59], s[38:39] op_sel_hi:[1,0]
	ds_write2_b32 v135, v44, v45 offset0:1 offset1:2
	ds_write2_b32 v135, v46, v47 offset0:3 offset1:4
	ds_write2_b32 v135, v48, v49 offset0:5 offset1:6
	ds_write2_b32 v135, v8, v9 offset0:7 offset1:8
	ds_write2_b32 v135, v50, v51 offset0:9 offset1:10
	ds_write2_b32 v135, v30, v31 offset0:11 offset1:12
	ds_write2_b32 v135, v32, v33 offset0:13 offset1:14
	v_pk_mov_b32 v[8:9], v[52:53], v[52:53] op_sel:[1,0]
	v_pk_mul_f32 v[28:29], v[28:29], s[38:39] op_sel_hi:[1,0]
	v_pk_mul_f32 v[20:21], v[20:21], s[38:39] op_sel_hi:[1,0]
	v_mul_f32_e32 v63, 0x3b800000, v63
	v_pk_mov_b32 v[26:27], v[26:27], v[26:27] op_sel:[1,0]
	v_pk_mov_b32 v[30:31], v[54:55], v[54:55] op_sel:[1,0]
	v_pk_mov_b32 v[32:33], v[56:57], v[56:57] op_sel:[1,0]
	v_pk_mov_b32 v[18:19], v[18:19], v[18:19] op_sel:[1,0]
	v_pk_mov_b32 v[44:45], v[58:59], v[58:59] op_sel:[1,0]
	ds_write_b64 v136, v[8:9]
	ds_write_b64 v137, v[26:27]
	ds_write_b64 v138, v[30:31]
	ds_write_b64 v139, v[28:29]
	ds_write_b64 v140, v[32:33]
	ds_write_b64 v141, v[18:19]
	ds_write_b64 v142, v[44:45]
	ds_write_b64 v143, v[20:21]
	v_cvt_f32_f16_e32 v9, v25
	s_waitcnt vmcnt(4)
	v_cvt_f32_f16_sdwa v18, v14 dst_sel:DWORD dst_unused:UNUSED_PAD src0_sel:WORD_1
	v_cvt_f32_f16_e32 v19, v15
	v_cvt_f32_f16_sdwa v60, v22 dst_sel:DWORD dst_unused:UNUSED_PAD src0_sel:WORD_1
	v_cvt_f32_f16_e32 v61, v23
	s_mov_b32 s10, s69
	s_mov_b32 s71, s64
	s_mov_b32 s78, s67
	v_pk_mul_f32 v[60:61], v[60:61], s[38:39] op_sel_hi:[1,0]
	s_mov_b32 s73, s50
	s_mov_b32 s76, s63
	s_waitcnt vmcnt(1)
	v_fma_mix_f32 v6, v6, s38, v40 op_sel_hi:[1,0,0]
	s_nop 0
	v_cndmask_b32_e64 v6, v62, v6, s[6:7]
	s_waitcnt vmcnt(0)
	v_fma_mix_f32 v8, v22, s38, v42 op_sel_hi:[1,0,0]
	ds_write2_b32 v135, v6, v7 offset1:15
	v_cvt_f32_f16_sdwa v6, v23 dst_sel:DWORD dst_unused:UNUSED_PAD src0_sel:WORD_1
	v_cvt_f32_f16_e32 v7, v24
	v_cndmask_b32_e64 v20, v63, v8, s[8:9]
	v_cvt_f32_f16_sdwa v8, v24 dst_sel:DWORD dst_unused:UNUSED_PAD src0_sel:WORD_1
	ds_write2_b32 v144, v60, v61 offset0:1 offset1:2
	v_pk_mul_f32 v[6:7], v[6:7], s[38:39] op_sel_hi:[1,0]
	ds_write2_b32 v144, v6, v7 offset0:3 offset1:4
	v_pk_mul_f32 v[6:7], v[8:9], s[38:39] op_sel_hi:[1,0]
	v_cvt_f32_f16_sdwa v8, v25 dst_sel:DWORD dst_unused:UNUSED_PAD src0_sel:WORD_1
	v_cvt_f32_f16_e32 v9, v14
	ds_write2_b32 v144, v6, v7 offset0:5 offset1:6
	v_cvt_f32_f16_sdwa v14, v17 dst_sel:DWORD dst_unused:UNUSED_PAD src0_sel:WORD_1
	v_pk_mul_f32 v[6:7], v[8:9], s[38:39] op_sel_hi:[1,0]
	ds_write2_b32 v144, v6, v7 offset0:7 offset1:8
	v_pk_mul_f32 v[6:7], v[18:19], s[38:39] op_sel_hi:[1,0]
	ds_write2_b32 v144, v6, v7 offset0:9 offset1:10
	v_cvt_f32_f16_sdwa v6, v15 dst_sel:DWORD dst_unused:UNUSED_PAD src0_sel:WORD_1
	v_cvt_f32_f16_e32 v7, v16
	v_cvt_f32_f16_sdwa v8, v16 dst_sel:DWORD dst_unused:UNUSED_PAD src0_sel:WORD_1
	v_cvt_f32_f16_e32 v9, v17
	v_mul_f32_e32 v14, 0x3b800000, v14
	v_pk_mul_f32 v[6:7], v[6:7], s[38:39] op_sel_hi:[1,0]
	ds_write2_b32 v144, v6, v7 offset0:11 offset1:12
	v_pk_mul_f32 v[6:7], v[8:9], s[38:39] op_sel_hi:[1,0]
	ds_write2_b32 v144, v6, v7 offset0:13 offset1:14
	v_cvt_f32_f16_sdwa v6, v10 dst_sel:DWORD dst_unused:UNUSED_PAD src0_sel:WORD_1
	v_cvt_f32_f16_e32 v7, v11
	v_cvt_f32_f16_sdwa v8, v11 dst_sel:DWORD dst_unused:UNUSED_PAD src0_sel:WORD_1
	v_cvt_f32_f16_e32 v9, v12
	ds_write2_b32 v144, v20, v14 offset1:15
	v_pk_mul_f32 v[6:7], v[6:7], s[38:39] op_sel_hi:[1,0]
	s_nop 0
	v_pk_mov_b32 v[6:7], v[6:7], v[6:7] op_sel:[1,0]
	ds_write_b64 v145, v[6:7]
	v_pk_mul_f32 v[6:7], v[8:9], s[38:39] op_sel_hi:[1,0]
	v_cvt_f32_f16_sdwa v8, v12 dst_sel:DWORD dst_unused:UNUSED_PAD src0_sel:WORD_1
	v_cvt_f32_f16_e32 v9, v13
	v_pk_mov_b32 v[6:7], v[6:7], v[6:7] op_sel:[1,0]
	ds_write_b64 v147, v[6:7]
	v_cvt_f32_f16_sdwa v7, v13 dst_sel:DWORD dst_unused:UNUSED_PAD src0_sel:WORD_1
	v_pk_mul_f32 v[8:9], v[8:9], s[38:39] op_sel_hi:[1,0]
	v_cvt_f32_f16_e32 v6, v2
	v_pk_mov_b32 v[8:9], v[8:9], v[8:9] op_sel:[1,0]
	ds_write_b64 v148, v[8:9]
	v_cvt_f32_f16_sdwa v8, v2 dst_sel:DWORD dst_unused:UNUSED_PAD src0_sel:WORD_1
	v_cvt_f32_f16_e32 v9, v3
	v_cvt_f32_f16_sdwa v2, v3 dst_sel:DWORD dst_unused:UNUSED_PAD src0_sel:WORD_1
	v_cvt_f32_f16_e32 v3, v4
	v_pk_mul_f32 v[6:7], v[6:7], s[38:39] op_sel_hi:[1,0]
	ds_write_b64 v149, v[6:7]
	v_pk_mul_f32 v[6:7], v[8:9], s[38:39] op_sel_hi:[1,0]
	v_pk_mul_f32 v[2:3], v[2:3], s[38:39] op_sel_hi:[1,0]
	v_pk_mov_b32 v[6:7], v[6:7], v[6:7] op_sel:[1,0]
	ds_write_b64 v150, v[6:7]
	v_pk_mov_b32 v[2:3], v[2:3], v[2:3] op_sel:[1,0]
	v_cvt_f32_f16_sdwa v6, v4 dst_sel:DWORD dst_unused:UNUSED_PAD src0_sel:WORD_1
	v_cvt_f32_f16_e32 v7, v5
	ds_write_b64 v151, v[2:3]
	v_cvt_f32_f16_sdwa v3, v5 dst_sel:DWORD dst_unused:UNUSED_PAD src0_sel:WORD_1
	v_cvt_f32_f16_e32 v2, v43
	v_pk_mul_f32 v[4:5], v[6:7], s[38:39] op_sel_hi:[1,0]
	v_pk_mul_f32 v[2:3], v[2:3], s[38:39] op_sel_hi:[1,0]
	v_pk_mov_b32 v[4:5], v[4:5], v[4:5] op_sel:[1,0]
	ds_write_b64 v152, v[4:5]
	ds_write_b64 v153, v[2:3]
	v_mov_b32_e32 v2, v1
	s_waitcnt lgkmcnt(0)
	s_barrier
	s_nop 0
	v_and_b32_e32 v3, 0x1ff, v2
	v_lshlrev_b32_e32 v2, 5, v2
	v_and_or_b32 v2, v2, s3, v3
	v_cvt_f32_u32_e32 v4, v3
	v_ashrrev_i32_e32 v3, 5, v2
	v_lshlrev_b32_e32 v5, 3, v2
	v_lshlrev_b32_e32 v3, 3, v3
	v_add3_u32 v40, 0, v5, v3
	v_add_u32_e32 v155, 0x10800, v40
	ds_read_b64 v[156:157], v40
	ds_read_b64 v[158:159], v40 offset:4224
	ds_read_b64 v[160:161], v40 offset:8448
	ds_read_b64 v[162:163], v40 offset:12672
	ds_read_b64 v[164:165], v40 offset:16896
	ds_read_b64 v[166:167], v40 offset:21120
	ds_read_b64 v[168:169], v40 offset:25344
	ds_read_b64 v[170:171], v40 offset:29568
	ds_read_b64 v[172:173], v40 offset:33792
	ds_read_b64 v[174:175], v40 offset:38016
	ds_read_b64 v[176:177], v40 offset:42240
	ds_read_b64 v[178:179], v40 offset:46464
	ds_read_b64 v[180:181], v40 offset:50688
	ds_read_b64 v[182:183], v40 offset:54912
	ds_read_b64 v[184:185], v40 offset:59136
	ds_read_b64 v[186:187], v40 offset:63360
	v_add_u32_e32 v201, 0x11880, v40
	v_add_u32_e32 v224, 0x12900, v40
	v_add_u32_e32 v225, 0x13980, v40
	ds_read_b64 v[188:189], v155
	ds_read_b64 v[190:191], v201
	ds_read_b64 v[192:193], v224
	ds_read_b64 v[194:195], v225
	v_add_u32_e32 v226, 0x14a00, v40
	s_waitcnt lgkmcnt(3)
	v_pk_add_f32 v[222:223], v[156:157], v[188:189]
	v_pk_add_f32 v[156:157], v[156:157], v[188:189] neg_lo:[0,1] neg_hi:[0,1]
	s_waitcnt lgkmcnt(2)
	v_pk_add_f32 v[188:189], v[158:159], v[190:191]
	v_pk_add_f32 v[158:159], v[158:159], v[190:191] neg_lo:[0,1] neg_hi:[0,1]
	v_add_u32_e32 v227, 0x15a80, v40
	v_pk_mul_f32 v[190:191], v[158:159], s[46:47]
	v_add_u32_e32 v228, 0x16b00, v40
	v_pk_fma_f32 v[158:159], v[158:159], s[42:43], v[190:191] op_sel:[0,0,1] op_sel_hi:[1,0,0]
	s_waitcnt lgkmcnt(1)
	v_pk_add_f32 v[190:191], v[160:161], v[192:193]
	v_pk_add_f32 v[160:161], v[160:161], v[192:193] neg_lo:[0,1] neg_hi:[0,1]
	v_add_u32_e32 v229, 0x17b80, v40
	v_pk_mul_f32 v[192:193], v[160:161], s[62:63]
	ds_read_b64 v[196:197], v226
	ds_read_b64 v[198:199], v227
	ds_read_b64 v[202:203], v228
	ds_read_b64 v[204:205], v229
	v_pk_fma_f32 v[160:161], v[160:161], s[50:51], v[192:193] op_sel:[0,0,1] op_sel_hi:[1,0,0]
	s_waitcnt lgkmcnt(4)
	v_pk_add_f32 v[192:193], v[162:163], v[194:195]
	v_pk_add_f32 v[162:163], v[162:163], v[194:195] neg_lo:[0,1] neg_hi:[0,1]
	v_add_u32_e32 v230, 0x18c00, v40
	v_pk_mul_f32 v[194:195], v[162:163], s[66:67]
	v_add_u32_e32 v231, 0x19c80, v40
	v_pk_fma_f32 v[162:163], v[162:163], s[64:65], v[194:195] op_sel:[0,0,1] op_sel_hi:[1,0,0]
	s_waitcnt lgkmcnt(3)
	v_pk_add_f32 v[194:195], v[164:165], v[196:197]
	v_pk_add_f32 v[164:165], v[164:165], v[196:197] neg_lo:[0,1] neg_hi:[0,1]
	v_add_u32_e32 v232, 0x1ad00, v40
	v_pk_mul_f32 v[196:197], v[164:165], s[68:69]
	v_add_u32_e32 v233, 0x1bd80, v40
	v_pk_fma_f32 v[164:165], v[164:165], s[10:11], v[196:197] op_sel:[0,0,1] op_sel_hi:[1,0,0]
	s_waitcnt lgkmcnt(2)
	v_pk_add_f32 v[196:197], v[166:167], v[198:199]
	v_pk_add_f32 v[166:167], v[166:167], v[198:199] neg_lo:[0,1] neg_hi:[0,1]
	ds_read_b64 v[206:207], v230
	ds_read_b64 v[208:209], v231
	ds_read_b64 v[210:211], v232
	ds_read_b64 v[212:213], v233
	v_pk_mul_f32 v[198:199], v[166:167], s[70:71]
	v_add_u32_e32 v234, 0x1ce00, v40
	v_pk_fma_f32 v[166:167], v[166:167], s[78:79], v[198:199] op_sel:[0,0,1] op_sel_hi:[1,0,0]
	s_waitcnt lgkmcnt(5)
	v_pk_add_f32 v[198:199], v[168:169], v[202:203]
	v_pk_add_f32 v[168:169], v[168:169], v[202:203] neg_lo:[0,1] neg_hi:[0,1]
	v_add_u32_e32 v235, 0x1de80, v40
	v_pk_mul_f32 v[202:203], v[168:169], s[72:73]
	v_add_u32_e32 v236, 0x1ef00, v40
	v_pk_fma_f32 v[168:169], v[168:169], s[76:77], v[202:203] op_sel:[0,0,1] op_sel_hi:[1,0,0]
	s_waitcnt lgkmcnt(4)
	v_pk_add_f32 v[202:203], v[170:171], v[204:205]
	v_pk_add_f32 v[170:171], v[170:171], v[204:205] neg_lo:[0,1] neg_hi:[0,1]
	v_add_u32_e32 v237, 0x1ff80, v40
	v_pk_mul_f32 v[204:205], v[170:171], s[40:41]
	ds_read_b64 v[214:215], v234
	ds_read_b64 v[216:217], v235
	ds_read_b64 v[218:219], v236
	ds_read_b64 v[220:221], v237
	v_pk_fma_f32 v[170:171], v[170:171], s[44:45], v[204:205] op_sel:[0,0,1] op_sel_hi:[1,0,0]
	s_waitcnt lgkmcnt(7)
	v_pk_add_f32 v[204:205], v[172:173], v[206:207]
	v_pk_add_f32 v[206:207], v[172:173], v[206:207] neg_lo:[0,1] neg_hi:[0,1]
	v_mul_f32_e32 v4, 0x38800000, v4
	s_waitcnt lgkmcnt(6)
	v_pk_add_f32 v[172:173], v[174:175], v[208:209]
	v_pk_add_f32 v[174:175], v[174:175], v[208:209] neg_lo:[0,1] neg_hi:[0,1]
	v_sin_f32_e32 v2, v4
	v_pk_mul_f32 v[208:209], v[174:175], s[40:41]
	v_cos_f32_e32 v4, v4
	v_pk_fma_f32 v[174:175], v[174:175], s[44:45], v[208:209] op_sel:[0,0,1] op_sel_hi:[1,0,0] neg_lo:[1,0,0] neg_hi:[1,0,0]
	s_waitcnt lgkmcnt(5)
	v_pk_add_f32 v[208:209], v[176:177], v[210:211]
	v_pk_add_f32 v[176:177], v[176:177], v[210:211] neg_lo:[0,1] neg_hi:[0,1]
	v_xor_b32_e32 v5, 0x80000000, v2
	v_pk_mul_f32 v[210:211], v[176:177], s[72:73]
	v_mov_b32_e32 v3, v5
	v_pk_fma_f32 v[176:177], v[176:177], s[76:77], v[210:211] op_sel:[0,0,1] op_sel_hi:[1,0,0] neg_lo:[1,0,0] neg_hi:[1,0,0]
	s_waitcnt lgkmcnt(4)
	v_pk_add_f32 v[210:211], v[178:179], v[212:213]
	v_pk_add_f32 v[178:179], v[178:179], v[212:213] neg_lo:[0,1] neg_hi:[0,1]
	v_pk_mul_f32 v[6:7], v[4:5], v[2:3] op_sel:[1,0] op_sel_hi:[0,1]
	v_pk_mul_f32 v[212:213], v[178:179], s[70:71]
	v_pk_fma_f32 v[6:7], v[4:5], v[4:5], v[6:7] op_sel_hi:[1,0,1]
	v_pk_fma_f32 v[178:179], v[178:179], s[78:79], v[212:213] op_sel:[0,0,1] op_sel_hi:[1,0,0] neg_lo:[1,0,0] neg_hi:[1,0,0]
	s_waitcnt lgkmcnt(3)
	v_pk_add_f32 v[212:213], v[180:181], v[214:215]
	v_pk_add_f32 v[180:181], v[180:181], v[214:215] neg_lo:[0,1] neg_hi:[0,1]
	v_xor_b32_e32 v12, 0x80000000, v7
	v_pk_mul_f32 v[214:215], v[180:181], s[68:69]
	v_mov_b32_e32 v13, v7
	v_pk_fma_f32 v[180:181], v[180:181], s[10:11], v[214:215] op_sel:[0,0,1] op_sel_hi:[1,0,0] neg_lo:[1,0,0] neg_hi:[1,0,0]
	s_waitcnt lgkmcnt(2)
	v_pk_add_f32 v[214:215], v[182:183], v[216:217]
	v_pk_add_f32 v[182:183], v[182:183], v[216:217] neg_lo:[0,1] neg_hi:[0,1]
	v_pk_mul_f32 v[10:11], v[6:7], v[12:13] op_sel:[1,0] op_sel_hi:[0,1]
	v_pk_mul_f32 v[216:217], v[182:183], s[66:67]
	v_pk_fma_f32 v[10:11], v[6:7], v[6:7], v[10:11] op_sel_hi:[1,0,1]
	v_pk_fma_f32 v[182:183], v[182:183], s[64:65], v[216:217] op_sel:[0,0,1] op_sel_hi:[1,0,0] neg_lo:[1,0,0] neg_hi:[1,0,0]
	s_waitcnt lgkmcnt(1)
	v_pk_add_f32 v[216:217], v[184:185], v[218:219]
	v_pk_add_f32 v[184:185], v[184:185], v[218:219] neg_lo:[0,1] neg_hi:[0,1]
	v_xor_b32_e32 v14, 0x80000000, v11
	v_pk_mul_f32 v[218:219], v[184:185], s[62:63]
	v_mov_b32_e32 v15, v11
	v_pk_fma_f32 v[184:185], v[184:185], s[50:51], v[218:219] op_sel:[0,0,1] op_sel_hi:[1,0,0] neg_lo:[1,0,0] neg_hi:[1,0,0]
	s_waitcnt lgkmcnt(0)
	v_pk_add_f32 v[218:219], v[186:187], v[220:221]
	v_pk_add_f32 v[186:187], v[186:187], v[220:221] neg_lo:[0,1] neg_hi:[0,1]
	v_pk_mul_f32 v[26:27], v[10:11], v[14:15] op_sel:[1,0] op_sel_hi:[0,1]
	v_pk_mul_f32 v[220:221], v[186:187], s[46:47]
	v_pk_fma_f32 v[26:27], v[10:11], v[10:11], v[26:27] op_sel_hi:[1,0,1]
	v_pk_fma_f32 v[186:187], v[186:187], s[42:43], v[220:221] op_sel:[0,0,1] op_sel_hi:[1,0,0] neg_lo:[1,0,0] neg_hi:[1,0,0]
	v_pk_add_f32 v[220:221], v[222:223], v[204:205]
	v_pk_add_f32 v[204:205], v[222:223], v[204:205] neg_lo:[0,1] neg_hi:[0,1]
	v_pk_add_f32 v[222:223], v[188:189], v[172:173]
	v_pk_add_f32 v[172:173], v[188:189], v[172:173] neg_lo:[0,1] neg_hi:[0,1]
	v_pk_mul_f32 v[50:51], v[14:15], v[26:27] op_sel:[0,1] op_sel_hi:[1,0]
	v_pk_mul_f32 v[188:189], v[172:173], s[62:63]
	v_pk_fma_f32 v[50:51], v[10:11], v[26:27], v[50:51] op_sel_hi:[0,1,1]
	v_pk_fma_f32 v[172:173], v[172:173], s[50:51], v[188:189] op_sel:[0,0,1] op_sel_hi:[1,0,0]
	v_pk_add_f32 v[188:189], v[190:191], v[208:209]
	v_pk_add_f32 v[190:191], v[190:191], v[208:209] neg_lo:[0,1] neg_hi:[0,1]
	v_pk_mul_f32 v[66:67], v[14:15], v[50:51] op_sel:[0,1] op_sel_hi:[1,0]
	v_pk_mul_f32 v[208:209], v[190:191], s[68:69]
	v_pk_fma_f32 v[66:67], v[10:11], v[50:51], v[66:67] op_sel_hi:[0,1,1]
	v_pk_fma_f32 v[190:191], v[190:191], s[10:11], v[208:209] op_sel:[0,0,1] op_sel_hi:[1,0,0]
	v_pk_add_f32 v[208:209], v[192:193], v[210:211]
	v_pk_add_f32 v[192:193], v[192:193], v[210:211] neg_lo:[0,1] neg_hi:[0,1]
	v_pk_mul_f32 v[82:83], v[14:15], v[66:67] op_sel:[0,1] op_sel_hi:[1,0]
	v_pk_mul_f32 v[210:211], v[192:193], s[72:73]
	v_pk_fma_f32 v[82:83], v[10:11], v[66:67], v[82:83] op_sel_hi:[0,1,1]
	v_pk_fma_f32 v[192:193], v[192:193], s[76:77], v[210:211] op_sel:[0,0,1] op_sel_hi:[1,0,0]
	v_pk_add_f32 v[210:211], v[194:195], v[212:213]
	v_pk_add_f32 v[212:213], v[194:195], v[212:213] neg_lo:[0,1] neg_hi:[0,1]
	v_pk_mul_f32 v[98:99], v[14:15], v[82:83] op_sel:[0,1] op_sel_hi:[1,0]
	v_pk_add_f32 v[194:195], v[196:197], v[214:215]
	v_pk_add_f32 v[196:197], v[196:197], v[214:215] neg_lo:[0,1] neg_hi:[0,1]
	v_pk_fma_f32 v[98:99], v[10:11], v[82:83], v[98:99] op_sel_hi:[0,1,1]
	v_pk_mul_f32 v[214:215], v[196:197], s[72:73]
	v_pk_mul_f32 v[114:115], v[14:15], v[98:99] op_sel:[0,1] op_sel_hi:[1,0]
	v_pk_fma_f32 v[196:197], v[196:197], s[76:77], v[214:215] op_sel:[0,0,1] op_sel_hi:[1,0,0] neg_lo:[1,0,0] neg_hi:[1,0,0]
	v_pk_add_f32 v[214:215], v[198:199], v[216:217]
	v_pk_add_f32 v[198:199], v[198:199], v[216:217] neg_lo:[0,1] neg_hi:[0,1]
	v_pk_mul_f32 v[8:9], v[2:3], v[6:7] op_sel:[0,1] op_sel_hi:[1,0]
	v_pk_mul_f32 v[216:217], v[198:199], s[68:69]
	v_pk_fma_f32 v[114:115], v[10:11], v[98:99], v[114:115] op_sel_hi:[0,1,1]
	v_pk_fma_f32 v[198:199], v[198:199], s[10:11], v[216:217] op_sel:[0,0,1] op_sel_hi:[1,0,0] neg_lo:[1,0,0] neg_hi:[1,0,0]
	v_pk_add_f32 v[216:217], v[202:203], v[218:219]
	v_pk_add_f32 v[202:203], v[202:203], v[218:219] neg_lo:[0,1] neg_hi:[0,1]
	v_pk_fma_f32 v[8:9], v[4:5], v[6:7], v[8:9] op_sel_hi:[0,1,1]
	v_pk_mul_f32 v[218:219], v[202:203], s[62:63]
	v_pk_mul_f32 v[16:17], v[2:3], v[10:11] op_sel:[0,1] op_sel_hi:[1,0]
	v_pk_fma_f32 v[202:203], v[202:203], s[50:51], v[218:219] op_sel:[0,0,1] op_sel_hi:[1,0,0] neg_lo:[1,0,0] neg_hi:[1,0,0]
	v_pk_add_f32 v[218:219], v[156:157], v[206:207] op_sel:[0,1] op_sel_hi:[1,0] neg_hi:[0,1]
	v_pk_add_f32 v[156:157], v[156:157], v[206:207] op_sel:[0,1] op_sel_hi:[1,0] neg_lo:[0,1]
	v_pk_add_f32 v[206:207], v[158:159], v[174:175]
	v_pk_add_f32 v[158:159], v[158:159], v[174:175] neg_lo:[0,1] neg_hi:[0,1]
	v_pk_mul_f32 v[30:31], v[2:3], v[26:27] op_sel:[0,1] op_sel_hi:[1,0]
	v_pk_mul_f32 v[174:175], v[158:159], s[62:63]
	v_pk_mul_f32 v[54:55], v[2:3], v[50:51] op_sel:[0,1] op_sel_hi:[1,0]
	v_pk_fma_f32 v[158:159], v[158:159], s[50:51], v[174:175] op_sel:[0,0,1] op_sel_hi:[1,0,0]
	v_pk_add_f32 v[174:175], v[160:161], v[176:177]
	v_pk_add_f32 v[160:161], v[160:161], v[176:177] neg_lo:[0,1] neg_hi:[0,1]
	v_pk_mul_f32 v[70:71], v[2:3], v[66:67] op_sel:[0,1] op_sel_hi:[1,0]
	v_pk_mul_f32 v[176:177], v[160:161], s[68:69]
	v_pk_mul_f32 v[86:87], v[2:3], v[82:83] op_sel:[0,1] op_sel_hi:[1,0]
	v_pk_fma_f32 v[160:161], v[160:161], s[10:11], v[176:177] op_sel:[0,0,1] op_sel_hi:[1,0,0]
	v_pk_add_f32 v[176:177], v[162:163], v[178:179]
	v_pk_add_f32 v[162:163], v[162:163], v[178:179] neg_lo:[0,1] neg_hi:[0,1]
	v_pk_mul_f32 v[102:103], v[2:3], v[98:99] op_sel:[0,1] op_sel_hi:[1,0]
	v_pk_mul_f32 v[178:179], v[162:163], s[72:73]
	v_pk_mul_f32 v[118:119], v[2:3], v[114:115] op_sel:[0,1] op_sel_hi:[1,0]
	v_pk_fma_f32 v[162:163], v[162:163], s[76:77], v[178:179] op_sel:[0,0,1] op_sel_hi:[1,0,0]
	v_pk_add_f32 v[178:179], v[164:165], v[180:181]
	v_pk_add_f32 v[180:181], v[164:165], v[180:181] neg_lo:[0,1] neg_hi:[0,1]
	v_xor_b32_e32 v20, 0x80000000, v9
	v_pk_add_f32 v[164:165], v[166:167], v[182:183]
	v_pk_add_f32 v[166:167], v[166:167], v[182:183] neg_lo:[0,1] neg_hi:[0,1]
	v_mov_b32_e32 v21, v9
	v_pk_mul_f32 v[182:183], v[166:167], s[72:73]
	v_pk_fma_f32 v[16:17], v[4:5], v[10:11], v[16:17] op_sel_hi:[0,1,1]
	v_pk_fma_f32 v[166:167], v[166:167], s[76:77], v[182:183] op_sel:[0,0,1] op_sel_hi:[1,0,0] neg_lo:[1,0,0] neg_hi:[1,0,0]
	v_pk_add_f32 v[182:183], v[168:169], v[184:185]
	v_pk_add_f32 v[168:169], v[168:169], v[184:185] neg_lo:[0,1] neg_hi:[0,1]
	v_pk_mul_f32 v[18:19], v[12:13], v[10:11] op_sel:[0,1] op_sel_hi:[1,0]
	v_pk_mul_f32 v[184:185], v[168:169], s[68:69]
	v_pk_fma_f32 v[30:31], v[4:5], v[26:27], v[30:31] op_sel_hi:[0,1,1]
	v_pk_fma_f32 v[168:169], v[168:169], s[10:11], v[184:185] op_sel:[0,0,1] op_sel_hi:[1,0,0] neg_lo:[1,0,0] neg_hi:[1,0,0]
	v_pk_add_f32 v[184:185], v[170:171], v[186:187]
	v_pk_add_f32 v[170:171], v[170:171], v[186:187] neg_lo:[0,1] neg_hi:[0,1]
	v_pk_mul_f32 v[42:43], v[12:13], v[26:27] op_sel:[0,1] op_sel_hi:[1,0]
	v_pk_mul_f32 v[186:187], v[170:171], s[62:63]
	v_pk_fma_f32 v[54:55], v[4:5], v[50:51], v[54:55] op_sel_hi:[0,1,1]
	v_pk_fma_f32 v[170:171], v[170:171], s[50:51], v[186:187] op_sel:[0,0,1] op_sel_hi:[1,0,0] neg_lo:[1,0,0] neg_hi:[1,0,0]
	v_pk_add_f32 v[186:187], v[220:221], v[210:211]
	v_pk_add_f32 v[210:211], v[220:221], v[210:211] neg_lo:[0,1] neg_hi:[0,1]
	v_pk_add_f32 v[220:221], v[222:223], v[194:195]
	v_pk_add_f32 v[194:195], v[222:223], v[194:195] neg_lo:[0,1] neg_hi:[0,1]
	v_pk_mul_f32 v[58:59], v[12:13], v[50:51] op_sel:[0,1] op_sel_hi:[1,0]
	v_pk_mul_f32 v[222:223], v[194:195], s[68:69]
	v_pk_fma_f32 v[70:71], v[4:5], v[66:67], v[70:71] op_sel_hi:[0,1,1]
	v_pk_fma_f32 v[194:195], v[194:195], s[10:11], v[222:223] op_sel:[0,0,1] op_sel_hi:[1,0,0]
	v_pk_add_f32 v[222:223], v[188:189], v[214:215]
	v_pk_add_f32 v[214:215], v[188:189], v[214:215] neg_lo:[0,1] neg_hi:[0,1]
	v_pk_mul_f32 v[74:75], v[12:13], v[66:67] op_sel:[0,1] op_sel_hi:[1,0]
	v_pk_add_f32 v[188:189], v[208:209], v[216:217]
	v_pk_add_f32 v[208:209], v[208:209], v[216:217] neg_lo:[0,1] neg_hi:[0,1]
	v_pk_fma_f32 v[86:87], v[4:5], v[82:83], v[86:87] op_sel_hi:[0,1,1]
	v_pk_mul_f32 v[216:217], v[208:209], s[68:69]
	v_pk_mul_f32 v[90:91], v[12:13], v[82:83] op_sel:[0,1] op_sel_hi:[1,0]
	v_pk_fma_f32 v[208:209], v[208:209], s[10:11], v[216:217] op_sel:[0,0,1] op_sel_hi:[1,0,0] neg_lo:[1,0,0] neg_hi:[1,0,0]
	v_pk_add_f32 v[216:217], v[204:205], v[212:213] op_sel:[0,1] op_sel_hi:[1,0] neg_hi:[0,1]
	v_pk_add_f32 v[204:205], v[204:205], v[212:213] op_sel:[0,1] op_sel_hi:[1,0] neg_lo:[0,1]
	v_pk_add_f32 v[212:213], v[172:173], v[196:197]
	v_pk_add_f32 v[172:173], v[172:173], v[196:197] neg_lo:[0,1] neg_hi:[0,1]
	v_pk_fma_f32 v[102:103], v[4:5], v[98:99], v[102:103] op_sel_hi:[0,1,1]
	v_pk_mul_f32 v[196:197], v[172:173], s[68:69]
	v_pk_mul_f32 v[106:107], v[12:13], v[98:99] op_sel:[0,1] op_sel_hi:[1,0]
	v_pk_fma_f32 v[172:173], v[172:173], s[10:11], v[196:197] op_sel:[0,0,1] op_sel_hi:[1,0,0]
	v_pk_add_f32 v[196:197], v[190:191], v[198:199]
	v_pk_add_f32 v[198:199], v[190:191], v[198:199] neg_lo:[0,1] neg_hi:[0,1]
	v_pk_fma_f32 v[118:119], v[4:5], v[114:115], v[118:119] op_sel_hi:[0,1,1]
	v_pk_add_f32 v[190:191], v[192:193], v[202:203]
	v_pk_add_f32 v[192:193], v[192:193], v[202:203] neg_lo:[0,1] neg_hi:[0,1]
	v_pk_mul_f32 v[122:123], v[12:13], v[114:115] op_sel:[0,1] op_sel_hi:[1,0]
	v_pk_mul_f32 v[202:203], v[192:193], s[68:69]
	v_pk_fma_f32 v[18:19], v[6:7], v[10:11], v[18:19] op_sel_hi:[0,1,1]
	v_pk_fma_f32 v[192:193], v[192:193], s[10:11], v[202:203] op_sel:[0,0,1] op_sel_hi:[1,0,0] neg_lo:[1,0,0] neg_hi:[1,0,0]
	v_pk_add_f32 v[202:203], v[218:219], v[178:179]
	v_pk_add_f32 v[178:179], v[218:219], v[178:179] neg_lo:[0,1] neg_hi:[0,1]
	v_pk_add_f32 v[218:219], v[206:207], v[164:165]
	v_pk_add_f32 v[164:165], v[206:207], v[164:165] neg_lo:[0,1] neg_hi:[0,1]
	v_pk_mul_f32 v[22:23], v[10:11], v[20:21] op_sel:[1,0] op_sel_hi:[0,1]
	v_pk_mul_f32 v[206:207], v[164:165], s[68:69]
	v_pk_fma_f32 v[42:43], v[6:7], v[26:27], v[42:43] op_sel_hi:[0,1,1]
	v_pk_fma_f32 v[164:165], v[164:165], s[10:11], v[206:207] op_sel:[0,0,1] op_sel_hi:[1,0,0]
	v_pk_add_f32 v[206:207], v[174:175], v[182:183]
	v_pk_add_f32 v[182:183], v[174:175], v[182:183] neg_lo:[0,1] neg_hi:[0,1]
	v_pk_mul_f32 v[46:47], v[20:21], v[26:27] op_sel:[0,1] op_sel_hi:[1,0]
	v_pk_add_f32 v[174:175], v[176:177], v[184:185]
	v_pk_add_f32 v[176:177], v[176:177], v[184:185] neg_lo:[0,1] neg_hi:[0,1]
	v_pk_fma_f32 v[58:59], v[6:7], v[50:51], v[58:59] op_sel_hi:[0,1,1]
	v_pk_mul_f32 v[184:185], v[176:177], s[68:69]
	v_pk_mul_f32 v[62:63], v[20:21], v[50:51] op_sel:[0,1] op_sel_hi:[1,0]
	v_pk_fma_f32 v[176:177], v[176:177], s[10:11], v[184:185] op_sel:[0,0,1] op_sel_hi:[1,0,0] neg_lo:[1,0,0] neg_hi:[1,0,0]
	v_pk_add_f32 v[184:185], v[156:157], v[180:181] op_sel:[0,1] op_sel_hi:[1,0] neg_hi:[0,1]
	v_pk_add_f32 v[156:157], v[156:157], v[180:181] op_sel:[0,1] op_sel_hi:[1,0] neg_lo:[0,1]
	v_pk_add_f32 v[180:181], v[158:159], v[166:167]
	v_pk_add_f32 v[158:159], v[158:159], v[166:167] neg_lo:[0,1] neg_hi:[0,1]
	v_pk_fma_f32 v[74:75], v[6:7], v[66:67], v[74:75] op_sel_hi:[0,1,1]
	v_pk_mul_f32 v[166:167], v[158:159], s[68:69]
	v_pk_mul_f32 v[78:79], v[20:21], v[66:67] op_sel:[0,1] op_sel_hi:[1,0]
	v_pk_fma_f32 v[158:159], v[158:159], s[10:11], v[166:167] op_sel:[0,0,1] op_sel_hi:[1,0,0]
	v_pk_add_f32 v[166:167], v[160:161], v[168:169]
	v_pk_add_f32 v[168:169], v[160:161], v[168:169] neg_lo:[0,1] neg_hi:[0,1]
	v_pk_fma_f32 v[90:91], v[6:7], v[82:83], v[90:91] op_sel_hi:[0,1,1]
	v_pk_add_f32 v[160:161], v[162:163], v[170:171]
	v_pk_add_f32 v[162:163], v[162:163], v[170:171] neg_lo:[0,1] neg_hi:[0,1]
	v_pk_mul_f32 v[94:95], v[20:21], v[82:83] op_sel:[0,1] op_sel_hi:[1,0]
	v_pk_mul_f32 v[170:171], v[162:163], s[68:69]
	v_pk_fma_f32 v[106:107], v[6:7], v[98:99], v[106:107] op_sel_hi:[0,1,1]
	v_pk_fma_f32 v[162:163], v[162:163], s[10:11], v[170:171] op_sel:[0,0,1] op_sel_hi:[1,0,0] neg_lo:[1,0,0] neg_hi:[1,0,0]
	v_pk_add_f32 v[170:171], v[186:187], v[222:223]
	v_pk_add_f32 v[186:187], v[186:187], v[222:223] neg_lo:[0,1] neg_hi:[0,1]
	v_pk_add_f32 v[222:223], v[220:221], v[188:189]
	v_pk_add_f32 v[220:221], v[220:221], v[188:189] neg_lo:[0,1] neg_hi:[0,1]
	v_pk_mul_f32 v[110:111], v[20:21], v[98:99] op_sel:[0,1] op_sel_hi:[1,0]
	v_pk_add_f32 v[188:189], v[210:211], v[214:215] op_sel:[0,1] op_sel_hi:[1,0] neg_hi:[0,1]
	v_pk_add_f32 v[210:211], v[210:211], v[214:215] op_sel:[0,1] op_sel_hi:[1,0] neg_lo:[0,1]
	v_pk_add_f32 v[214:215], v[194:195], v[208:209]
	v_pk_add_f32 v[208:209], v[194:195], v[208:209] neg_lo:[0,1] neg_hi:[0,1]
	v_pk_fma_f32 v[122:123], v[6:7], v[114:115], v[122:123] op_sel_hi:[0,1,1]
	v_pk_add_f32 v[194:195], v[216:217], v[196:197]
	v_pk_add_f32 v[196:197], v[216:217], v[196:197] neg_lo:[0,1] neg_hi:[0,1]
	v_pk_add_f32 v[216:217], v[212:213], v[190:191]
	v_pk_add_f32 v[212:213], v[212:213], v[190:191] neg_lo:[0,1] neg_hi:[0,1]
	v_pk_mul_f32 v[126:127], v[20:21], v[114:115] op_sel:[0,1] op_sel_hi:[1,0]
	v_pk_add_f32 v[190:191], v[204:205], v[198:199] op_sel:[0,1] op_sel_hi:[1,0] neg_hi:[0,1]
	v_pk_add_f32 v[198:199], v[204:205], v[198:199] op_sel:[0,1] op_sel_hi:[1,0] neg_lo:[0,1]
	v_pk_add_f32 v[204:205], v[172:173], v[192:193]
	v_pk_add_f32 v[192:193], v[172:173], v[192:193] neg_lo:[0,1] neg_hi:[0,1]
	v_xor_b32_e32 v24, 0x80000000, v17
	v_pk_add_f32 v[172:173], v[202:203], v[206:207]
	v_pk_add_f32 v[202:203], v[202:203], v[206:207] neg_lo:[0,1] neg_hi:[0,1]
	v_pk_add_f32 v[206:207], v[218:219], v[174:175]
	v_pk_add_f32 v[218:219], v[218:219], v[174:175] neg_lo:[0,1] neg_hi:[0,1]
	v_xor_b32_e32 v28, 0x80000000, v19
	v_pk_add_f32 v[174:175], v[178:179], v[182:183] op_sel:[0,1] op_sel_hi:[1,0] neg_hi:[0,1]
	v_pk_add_f32 v[178:179], v[178:179], v[182:183] op_sel:[0,1] op_sel_hi:[1,0] neg_lo:[0,1]
	v_pk_add_f32 v[182:183], v[164:165], v[176:177]
	v_pk_add_f32 v[176:177], v[164:165], v[176:177] neg_lo:[0,1] neg_hi:[0,1]
	v_pk_fma_f32 v[22:23], v[10:11], v[8:9], v[22:23] op_sel_hi:[1,0,1]
	v_pk_add_f32 v[164:165], v[184:185], v[166:167]
	v_pk_add_f32 v[166:167], v[184:185], v[166:167] neg_lo:[0,1] neg_hi:[0,1]
	v_pk_add_f32 v[184:185], v[180:181], v[160:161]
	v_pk_add_f32 v[180:181], v[180:181], v[160:161] neg_lo:[0,1] neg_hi:[0,1]
	v_pk_fma_f32 v[46:47], v[8:9], v[26:27], v[46:47] op_sel_hi:[0,1,1]
	v_pk_add_f32 v[160:161], v[156:157], v[168:169] op_sel:[0,1] op_sel_hi:[1,0] neg_hi:[0,1]
	v_pk_add_f32 v[156:157], v[156:157], v[168:169] op_sel:[0,1] op_sel_hi:[1,0] neg_lo:[0,1]
	v_pk_add_f32 v[168:169], v[158:159], v[162:163]
	v_pk_add_f32 v[162:163], v[158:159], v[162:163] neg_lo:[0,1] neg_hi:[0,1]
	v_pk_fma_f32 v[62:63], v[8:9], v[50:51], v[62:63] op_sel_hi:[0,1,1]
	v_pk_add_f32 v[158:159], v[170:171], v[222:223]
	v_pk_add_f32 v[170:171], v[170:171], v[222:223] neg_lo:[0,1] neg_hi:[0,1]
	v_pk_add_f32 v[222:223], v[186:187], v[220:221] op_sel:[0,1] op_sel_hi:[1,0] neg_hi:[0,1]
	v_pk_add_f32 v[186:187], v[186:187], v[220:221] op_sel:[0,1] op_sel_hi:[1,0] neg_lo:[0,1]
	v_pk_add_f32 v[220:221], v[188:189], v[214:215]
	v_pk_add_f32 v[188:189], v[188:189], v[214:215] neg_lo:[0,1] neg_hi:[0,1]
	v_pk_add_f32 v[214:215], v[210:211], v[208:209] op_sel:[0,1] op_sel_hi:[1,0] neg_hi:[0,1]
	v_pk_add_f32 v[208:209], v[210:211], v[208:209] op_sel:[0,1] op_sel_hi:[1,0] neg_lo:[0,1]
	v_pk_add_f32 v[210:211], v[194:195], v[216:217]
	v_pk_add_f32 v[194:195], v[194:195], v[216:217] neg_lo:[0,1] neg_hi:[0,1]
	v_pk_add_f32 v[216:217], v[196:197], v[212:213] op_sel:[0,1] op_sel_hi:[1,0] neg_hi:[0,1]
	v_pk_add_f32 v[196:197], v[196:197], v[212:213] op_sel:[0,1] op_sel_hi:[1,0] neg_lo:[0,1]
	v_pk_add_f32 v[212:213], v[190:191], v[204:205]
	v_pk_add_f32 v[190:191], v[190:191], v[204:205] neg_lo:[0,1] neg_hi:[0,1]
	v_pk_add_f32 v[204:205], v[198:199], v[192:193] op_sel:[0,1] op_sel_hi:[1,0] neg_hi:[0,1]
	v_pk_add_f32 v[192:193], v[198:199], v[192:193] op_sel:[0,1] op_sel_hi:[1,0] neg_lo:[0,1]
	v_pk_add_f32 v[198:199], v[172:173], v[206:207]
	v_pk_add_f32 v[172:173], v[172:173], v[206:207] neg_lo:[0,1] neg_hi:[0,1]
	v_pk_mul_f32 v[2:3], v[2:3], v[198:199] op_sel:[0,1] op_sel_hi:[1,0]
	v_pk_add_f32 v[206:207], v[202:203], v[218:219] op_sel:[0,1] op_sel_hi:[1,0] neg_hi:[0,1]
	v_pk_add_f32 v[202:203], v[202:203], v[218:219] op_sel:[0,1] op_sel_hi:[1,0] neg_lo:[0,1]
	v_pk_add_f32 v[218:219], v[174:175], v[182:183]
	v_pk_add_f32 v[174:175], v[174:175], v[182:183] neg_lo:[0,1] neg_hi:[0,1]
	v_pk_add_f32 v[182:183], v[178:179], v[176:177] op_sel:[0,1] op_sel_hi:[1,0] neg_hi:[0,1]
	v_pk_add_f32 v[176:177], v[178:179], v[176:177] op_sel:[0,1] op_sel_hi:[1,0] neg_lo:[0,1]
	v_pk_add_f32 v[178:179], v[164:165], v[184:185]
	v_pk_fma_f32 v[2:3], v[4:5], v[198:199], v[2:3] op_sel_hi:[0,1,1]
	v_pk_mul_f32 v[4:5], v[12:13], v[210:211] op_sel:[0,1] op_sel_hi:[1,0]
	v_pk_fma_f32 v[78:79], v[8:9], v[66:67], v[78:79] op_sel_hi:[0,1,1]
	v_pk_fma_f32 v[4:5], v[6:7], v[210:211], v[4:5] op_sel_hi:[0,1,1]
	v_pk_mul_f32 v[6:7], v[20:21], v[178:179] op_sel:[0,1] op_sel_hi:[1,0]
	v_pk_fma_f32 v[94:95], v[8:9], v[82:83], v[94:95] op_sel_hi:[0,1,1]
	v_pk_fma_f32 v[110:111], v[8:9], v[98:99], v[110:111] op_sel_hi:[0,1,1]
	v_pk_fma_f32 v[126:127], v[8:9], v[114:115], v[126:127] op_sel_hi:[0,1,1]
	v_mov_b32_e32 v25, v17
	v_mov_b32_e32 v29, v19
	v_pk_fma_f32 v[6:7], v[8:9], v[178:179], v[6:7] op_sel_hi:[0,1,1]
	v_pk_mul_f32 v[8:9], v[14:15], v[220:221] op_sel:[0,1] op_sel_hi:[1,0]
	v_xor_b32_e32 v32, 0x80000000, v23
	v_xor_b32_e32 v44, 0x80000000, v27
	v_xor_b32_e32 v48, 0x80000000, v31
	v_xor_b32_e32 v52, 0x80000000, v43
	v_mov_b32_e32 v33, v23
	v_mov_b32_e32 v45, v27
	v_mov_b32_e32 v49, v31
	v_mov_b32_e32 v53, v43
	v_pk_add_f32 v[164:165], v[164:165], v[184:185] neg_lo:[0,1] neg_hi:[0,1]
	v_pk_add_f32 v[184:185], v[166:167], v[180:181] op_sel:[0,1] op_sel_hi:[1,0] neg_hi:[0,1]
	v_pk_add_f32 v[166:167], v[166:167], v[180:181] op_sel:[0,1] op_sel_hi:[1,0] neg_lo:[0,1]
	v_pk_add_f32 v[180:181], v[160:161], v[168:169]
	v_pk_fma_f32 v[8:9], v[10:11], v[220:221], v[8:9] op_sel_hi:[0,1,1]
	v_pk_mul_f32 v[10:11], v[24:25], v[218:219] op_sel:[0,1] op_sel_hi:[1,0]
	v_pk_mul_f32 v[12:13], v[28:29], v[212:213] op_sel:[0,1] op_sel_hi:[1,0]
	v_xor_b32_e32 v56, 0x80000000, v47
	v_xor_b32_e32 v60, 0x80000000, v51
	v_xor_b32_e32 v64, 0x80000000, v55
	v_xor_b32_e32 v68, 0x80000000, v59
	v_xor_b32_e32 v72, 0x80000000, v63
	v_xor_b32_e32 v76, 0x80000000, v67
	v_xor_b32_e32 v80, 0x80000000, v71
	v_mov_b32_e32 v57, v47
	v_mov_b32_e32 v61, v51
	v_mov_b32_e32 v65, v55
	v_mov_b32_e32 v69, v59
	v_mov_b32_e32 v73, v63
	v_mov_b32_e32 v77, v67
	v_mov_b32_e32 v81, v71
	v_pk_add_f32 v[160:161], v[160:161], v[168:169] neg_lo:[0,1] neg_hi:[0,1]
	v_pk_add_f32 v[168:169], v[156:157], v[162:163] op_sel:[0,1] op_sel_hi:[1,0] neg_hi:[0,1]
	v_pk_fma_f32 v[10:11], v[16:17], v[218:219], v[10:11] op_sel_hi:[0,1,1]
	v_pk_fma_f32 v[12:13], v[18:19], v[212:213], v[12:13] op_sel_hi:[0,1,1]
	v_pk_mul_f32 v[14:15], v[32:33], v[180:181] op_sel:[0,1] op_sel_hi:[1,0]
	v_pk_mul_f32 v[16:17], v[44:45], v[222:223] op_sel:[0,1] op_sel_hi:[1,0]
	v_pk_mul_f32 v[18:19], v[48:49], v[206:207] op_sel:[0,1] op_sel_hi:[1,0]
	v_pk_mul_f32 v[20:21], v[52:53], v[216:217] op_sel:[0,1] op_sel_hi:[1,0]
	v_xor_b32_e32 v84, 0x80000000, v75
	v_xor_b32_e32 v88, 0x80000000, v79
	v_xor_b32_e32 v92, 0x80000000, v83
	v_xor_b32_e32 v96, 0x80000000, v87
	v_xor_b32_e32 v100, 0x80000000, v91
	v_xor_b32_e32 v104, 0x80000000, v95
	v_xor_b32_e32 v108, 0x80000000, v99
	v_xor_b32_e32 v112, 0x80000000, v103
	v_xor_b32_e32 v116, 0x80000000, v107
	v_xor_b32_e32 v120, 0x80000000, v111
	v_xor_b32_e32 v124, 0x80000000, v115
	v_xor_b32_e32 v128, 0x80000000, v119
	v_xor_b32_e32 v130, 0x80000000, v123
	v_xor_b32_e32 v132, 0x80000000, v127
	v_mov_b32_e32 v85, v75
	v_mov_b32_e32 v89, v79
	v_mov_b32_e32 v93, v83
	v_mov_b32_e32 v97, v87
	v_mov_b32_e32 v101, v91
	v_mov_b32_e32 v105, v95
	v_mov_b32_e32 v109, v99
	v_mov_b32_e32 v113, v103
	v_mov_b32_e32 v117, v107
	v_mov_b32_e32 v121, v111
	v_mov_b32_e32 v125, v115
	v_mov_b32_e32 v129, v119
	v_mov_b32_e32 v131, v123
	v_mov_b32_e32 v133, v127
	v_pk_add_f32 v[156:157], v[156:157], v[162:163] op_sel:[0,1] op_sel_hi:[1,0] neg_lo:[0,1]
	v_pk_fma_f32 v[14:15], v[22:23], v[180:181], v[14:15] op_sel_hi:[0,1,1]
	v_pk_fma_f32 v[16:17], v[26:27], v[222:223], v[16:17] op_sel_hi:[0,1,1]
	v_pk_fma_f32 v[18:19], v[30:31], v[206:207], v[18:19] op_sel_hi:[0,1,1]
	v_pk_fma_f32 v[20:21], v[42:43], v[216:217], v[20:21] op_sel_hi:[0,1,1]
	v_pk_mul_f32 v[22:23], v[56:57], v[184:185] op_sel:[0,1] op_sel_hi:[1,0]
	v_pk_mul_f32 v[24:25], v[60:61], v[214:215] op_sel:[0,1] op_sel_hi:[1,0]
	v_pk_mul_f32 v[26:27], v[64:65], v[182:183] op_sel:[0,1] op_sel_hi:[1,0]
	v_pk_mul_f32 v[28:29], v[68:69], v[204:205] op_sel:[0,1] op_sel_hi:[1,0]
	v_pk_mul_f32 v[30:31], v[72:73], v[168:169] op_sel:[0,1] op_sel_hi:[1,0]
	v_pk_mul_f32 v[32:33], v[76:77], v[170:171] op_sel:[0,1] op_sel_hi:[1,0]
	v_pk_mul_f32 v[42:43], v[80:81], v[172:173] op_sel:[0,1] op_sel_hi:[1,0]
	v_pk_fma_f32 v[22:23], v[46:47], v[184:185], v[22:23] op_sel_hi:[0,1,1]
	v_pk_fma_f32 v[24:25], v[50:51], v[214:215], v[24:25] op_sel_hi:[0,1,1]
	v_pk_fma_f32 v[26:27], v[54:55], v[182:183], v[26:27] op_sel_hi:[0,1,1]
	v_pk_fma_f32 v[28:29], v[58:59], v[204:205], v[28:29] op_sel_hi:[0,1,1]
	v_pk_fma_f32 v[30:31], v[62:63], v[168:169], v[30:31] op_sel_hi:[0,1,1]
	v_pk_fma_f32 v[32:33], v[66:67], v[170:171], v[32:33] op_sel_hi:[0,1,1]
	v_pk_fma_f32 v[42:43], v[70:71], v[172:173], v[42:43] op_sel_hi:[0,1,1]
	v_pk_mul_f32 v[44:45], v[84:85], v[194:195] op_sel:[0,1] op_sel_hi:[1,0]
	v_pk_mul_f32 v[46:47], v[88:89], v[164:165] op_sel:[0,1] op_sel_hi:[1,0]
	v_pk_mul_f32 v[48:49], v[92:93], v[188:189] op_sel:[0,1] op_sel_hi:[1,0]
	v_pk_mul_f32 v[50:51], v[96:97], v[174:175] op_sel:[0,1] op_sel_hi:[1,0]
	v_pk_mul_f32 v[52:53], v[100:101], v[190:191] op_sel:[0,1] op_sel_hi:[1,0]
	v_pk_mul_f32 v[54:55], v[104:105], v[160:161] op_sel:[0,1] op_sel_hi:[1,0]
	v_pk_mul_f32 v[56:57], v[108:109], v[186:187] op_sel:[0,1] op_sel_hi:[1,0]
	v_pk_mul_f32 v[58:59], v[112:113], v[202:203] op_sel:[0,1] op_sel_hi:[1,0]
	v_pk_mul_f32 v[60:61], v[116:117], v[196:197] op_sel:[0,1] op_sel_hi:[1,0]
	v_pk_mul_f32 v[62:63], v[120:121], v[166:167] op_sel:[0,1] op_sel_hi:[1,0]
	v_pk_mul_f32 v[64:65], v[124:125], v[208:209] op_sel:[0,1] op_sel_hi:[1,0]
	v_pk_mul_f32 v[66:67], v[128:129], v[176:177] op_sel:[0,1] op_sel_hi:[1,0]
	v_pk_mul_f32 v[68:69], v[130:131], v[192:193] op_sel:[0,1] op_sel_hi:[1,0]
	v_pk_mul_f32 v[70:71], v[132:133], v[156:157] op_sel:[0,1] op_sel_hi:[1,0]
	v_pk_fma_f32 v[44:45], v[74:75], v[194:195], v[44:45] op_sel_hi:[0,1,1]
	v_pk_fma_f32 v[46:47], v[78:79], v[164:165], v[46:47] op_sel_hi:[0,1,1]
	v_pk_fma_f32 v[48:49], v[82:83], v[188:189], v[48:49] op_sel_hi:[0,1,1]
	v_pk_fma_f32 v[50:51], v[86:87], v[174:175], v[50:51] op_sel_hi:[0,1,1]
	v_pk_fma_f32 v[52:53], v[90:91], v[190:191], v[52:53] op_sel_hi:[0,1,1]
	v_pk_fma_f32 v[54:55], v[94:95], v[160:161], v[54:55] op_sel_hi:[0,1,1]
	v_pk_fma_f32 v[56:57], v[98:99], v[186:187], v[56:57] op_sel_hi:[0,1,1]
	v_pk_fma_f32 v[58:59], v[102:103], v[202:203], v[58:59] op_sel_hi:[0,1,1]
	v_pk_fma_f32 v[60:61], v[106:107], v[196:197], v[60:61] op_sel_hi:[0,1,1]
	v_pk_fma_f32 v[62:63], v[110:111], v[166:167], v[62:63] op_sel_hi:[0,1,1]
	v_pk_fma_f32 v[64:65], v[114:115], v[208:209], v[64:65] op_sel_hi:[0,1,1]
	v_pk_fma_f32 v[66:67], v[118:119], v[176:177], v[66:67] op_sel_hi:[0,1,1]
	v_pk_fma_f32 v[68:69], v[122:123], v[192:193], v[68:69] op_sel_hi:[0,1,1]
	v_pk_fma_f32 v[70:71], v[126:127], v[156:157], v[70:71] op_sel_hi:[0,1,1]
	ds_write_b64 v40, v[158:159]
	ds_write_b64 v40, v[32:33] offset:4224
	ds_write_b64 v40, v[16:17] offset:8448
	ds_write_b64 v40, v[56:57] offset:12672
	ds_write_b64 v40, v[8:9] offset:16896
	ds_write_b64 v40, v[48:49] offset:21120
	ds_write_b64 v40, v[24:25] offset:25344
	ds_write_b64 v40, v[64:65] offset:29568
	ds_write_b64 v40, v[4:5] offset:33792
	ds_write_b64 v40, v[44:45] offset:38016
	ds_write_b64 v40, v[20:21] offset:42240
	ds_write_b64 v40, v[60:61] offset:46464
	ds_write_b64 v40, v[12:13] offset:50688
	ds_write_b64 v40, v[52:53] offset:54912
	ds_write_b64 v40, v[28:29] offset:59136
	ds_write_b64 v40, v[68:69] offset:63360
	ds_write_b64 v155, v[2:3]
	ds_write_b64 v201, v[42:43]
	ds_write_b64 v224, v[18:19]
	ds_write_b64 v225, v[58:59]
	ds_write_b64 v226, v[10:11]
	ds_write_b64 v227, v[50:51]
	ds_write_b64 v228, v[26:27]
	ds_write_b64 v229, v[66:67]
	ds_write_b64 v230, v[6:7]
	ds_write_b64 v231, v[46:47]
	ds_write_b64 v232, v[22:23]
	ds_write_b64 v233, v[62:63]
	ds_write_b64 v234, v[14:15]
	ds_write_b64 v235, v[54:55]
	ds_write_b64 v236, v[30:31]
	ds_write_b64 v237, v[70:71]
	v_mov_b32_e32 v2, v1
	s_waitcnt lgkmcnt(0)
	s_barrier
	s_nop 0
	v_and_b32_e32 v3, 15, v2
	v_lshlrev_b32_e32 v2, 5, v2
	v_and_b32_e32 v4, 0xfffffe00, v2
	v_lshl_add_u32 v5, v4, 3, 0
	v_lshlrev_b32_e32 v6, 3, v3
	v_ashrrev_i32_e32 v7, 2, v4
	v_add3_u32 v40, v5, v6, v7
	v_add_u32_e32 v155, 0x800, v40
	ds_read2_b64 v[156:159], v40 offset1:16
	ds_read2_b64 v[160:163], v40 offset0:33 offset1:49
	ds_read2_b64 v[164:167], v40 offset0:66 offset1:82
	ds_read2_b64 v[168:171], v40 offset0:99 offset1:115
	ds_read2_b64 v[172:175], v40 offset0:132 offset1:148
	ds_read2_b64 v[176:179], v40 offset0:165 offset1:181
	ds_read2_b64 v[180:183], v40 offset0:198 offset1:214
	ds_read2_b64 v[184:187], v40 offset0:231 offset1:247
	ds_read2_b64 v[188:191], v155 offset0:8 offset1:24
	ds_read2_b64 v[192:195], v155 offset0:41 offset1:57
	ds_read2_b64 v[196:199], v155 offset0:74 offset1:90
	ds_read2_b64 v[202:205], v155 offset0:107 offset1:123
	ds_read2_b64 v[206:209], v155 offset0:140 offset1:156
	ds_read2_b64 v[210:213], v155 offset0:173 offset1:189
	ds_read2_b64 v[214:217], v155 offset0:206 offset1:222
	ds_read2_b64 v[218:221], v155 offset0:239 offset1:255
	s_waitcnt lgkmcnt(7)
	v_pk_add_f32 v[222:223], v[156:157], v[188:189]
	v_pk_add_f32 v[156:157], v[156:157], v[188:189] neg_lo:[0,1] neg_hi:[0,1]
	v_pk_add_f32 v[188:189], v[158:159], v[190:191]
	v_pk_add_f32 v[158:159], v[158:159], v[190:191] neg_lo:[0,1] neg_hi:[0,1]
	v_cvt_f32_ubyte0_e32 v2, v3
	v_pk_mul_f32 v[190:191], v[158:159], s[46:47]
	v_mul_f32_e32 v3, 0x3b000000, v2
	v_pk_fma_f32 v[158:159], v[158:159], s[42:43], v[190:191] op_sel:[0,0,1] op_sel_hi:[1,0,0]
	s_waitcnt lgkmcnt(6)
	v_pk_add_f32 v[190:191], v[160:161], v[192:193]
	v_pk_add_f32 v[160:161], v[160:161], v[192:193] neg_lo:[0,1] neg_hi:[0,1]
	v_sin_f32_e32 v2, v3
	v_pk_mul_f32 v[192:193], v[160:161], s[62:63]
	v_cos_f32_e32 v4, v3
	v_pk_fma_f32 v[160:161], v[160:161], s[50:51], v[192:193] op_sel:[0,0,1] op_sel_hi:[1,0,0]
	v_pk_add_f32 v[192:193], v[162:163], v[194:195]
	v_pk_add_f32 v[162:163], v[162:163], v[194:195] neg_lo:[0,1] neg_hi:[0,1]
	v_xor_b32_e32 v5, 0x80000000, v2
	v_pk_mul_f32 v[194:195], v[162:163], s[66:67]
	v_mov_b32_e32 v3, v5
	v_pk_fma_f32 v[162:163], v[162:163], s[64:65], v[194:195] op_sel:[0,0,1] op_sel_hi:[1,0,0]
	s_waitcnt lgkmcnt(5)
	v_pk_add_f32 v[194:195], v[164:165], v[196:197]
	v_pk_add_f32 v[164:165], v[164:165], v[196:197] neg_lo:[0,1] neg_hi:[0,1]
	v_pk_mul_f32 v[6:7], v[4:5], v[2:3] op_sel:[1,0] op_sel_hi:[0,1]
	v_pk_mul_f32 v[196:197], v[164:165], s[68:69]
	v_pk_fma_f32 v[6:7], v[4:5], v[4:5], v[6:7] op_sel_hi:[1,0,1]
	v_pk_fma_f32 v[164:165], v[164:165], s[10:11], v[196:197] op_sel:[0,0,1] op_sel_hi:[1,0,0]
	v_pk_add_f32 v[196:197], v[166:167], v[198:199]
	v_pk_add_f32 v[166:167], v[166:167], v[198:199] neg_lo:[0,1] neg_hi:[0,1]
	v_xor_b32_e32 v12, 0x80000000, v7
	v_pk_mul_f32 v[198:199], v[166:167], s[70:71]
	v_mov_b32_e32 v13, v7
	v_pk_fma_f32 v[166:167], v[166:167], s[78:79], v[198:199] op_sel:[0,0,1] op_sel_hi:[1,0,0]
	s_waitcnt lgkmcnt(4)
	v_pk_add_f32 v[198:199], v[168:169], v[202:203]
	v_pk_add_f32 v[168:169], v[168:169], v[202:203] neg_lo:[0,1] neg_hi:[0,1]
	v_pk_mul_f32 v[10:11], v[6:7], v[12:13] op_sel:[1,0] op_sel_hi:[0,1]
	v_pk_mul_f32 v[202:203], v[168:169], s[72:73]
	v_pk_fma_f32 v[10:11], v[6:7], v[6:7], v[10:11] op_sel_hi:[1,0,1]
	v_pk_fma_f32 v[168:169], v[168:169], s[76:77], v[202:203] op_sel:[0,0,1] op_sel_hi:[1,0,0]
	v_pk_add_f32 v[202:203], v[170:171], v[204:205]
	v_pk_add_f32 v[170:171], v[170:171], v[204:205] neg_lo:[0,1] neg_hi:[0,1]
	v_xor_b32_e32 v14, 0x80000000, v11
	v_pk_mul_f32 v[204:205], v[170:171], s[40:41]
	v_mov_b32_e32 v15, v11
	v_pk_fma_f32 v[170:171], v[170:171], s[44:45], v[204:205] op_sel:[0,0,1] op_sel_hi:[1,0,0]
	s_waitcnt lgkmcnt(3)
	v_pk_add_f32 v[204:205], v[172:173], v[206:207]
	v_pk_add_f32 v[206:207], v[172:173], v[206:207] neg_lo:[0,1] neg_hi:[0,1]
	v_pk_mul_f32 v[26:27], v[10:11], v[14:15] op_sel:[1,0] op_sel_hi:[0,1]
	v_pk_add_f32 v[172:173], v[174:175], v[208:209]
	v_pk_add_f32 v[174:175], v[174:175], v[208:209] neg_lo:[0,1] neg_hi:[0,1]
	v_pk_fma_f32 v[26:27], v[10:11], v[10:11], v[26:27] op_sel_hi:[1,0,1]
	v_pk_mul_f32 v[208:209], v[174:175], s[40:41]
	v_pk_mul_f32 v[50:51], v[14:15], v[26:27] op_sel:[0,1] op_sel_hi:[1,0]
	v_pk_fma_f32 v[174:175], v[174:175], s[44:45], v[208:209] op_sel:[0,0,1] op_sel_hi:[1,0,0] neg_lo:[1,0,0] neg_hi:[1,0,0]
	s_waitcnt lgkmcnt(2)
	v_pk_add_f32 v[208:209], v[176:177], v[210:211]
	v_pk_add_f32 v[176:177], v[176:177], v[210:211] neg_lo:[0,1] neg_hi:[0,1]
	v_pk_fma_f32 v[50:51], v[10:11], v[26:27], v[50:51] op_sel_hi:[0,1,1]
	v_pk_mul_f32 v[210:211], v[176:177], s[72:73]
	v_pk_mul_f32 v[66:67], v[14:15], v[50:51] op_sel:[0,1] op_sel_hi:[1,0]
	v_pk_fma_f32 v[176:177], v[176:177], s[76:77], v[210:211] op_sel:[0,0,1] op_sel_hi:[1,0,0] neg_lo:[1,0,0] neg_hi:[1,0,0]
	v_pk_add_f32 v[210:211], v[178:179], v[212:213]
	v_pk_add_f32 v[178:179], v[178:179], v[212:213] neg_lo:[0,1] neg_hi:[0,1]
	v_pk_fma_f32 v[66:67], v[10:11], v[50:51], v[66:67] op_sel_hi:[0,1,1]
	v_pk_mul_f32 v[212:213], v[178:179], s[70:71]
	v_pk_mul_f32 v[82:83], v[14:15], v[66:67] op_sel:[0,1] op_sel_hi:[1,0]
	v_pk_fma_f32 v[178:179], v[178:179], s[78:79], v[212:213] op_sel:[0,0,1] op_sel_hi:[1,0,0] neg_lo:[1,0,0] neg_hi:[1,0,0]
	s_waitcnt lgkmcnt(1)
	v_pk_add_f32 v[212:213], v[180:181], v[214:215]
	v_pk_add_f32 v[180:181], v[180:181], v[214:215] neg_lo:[0,1] neg_hi:[0,1]
	v_pk_fma_f32 v[82:83], v[10:11], v[66:67], v[82:83] op_sel_hi:[0,1,1]
	v_pk_mul_f32 v[214:215], v[180:181], s[68:69]
	v_pk_mul_f32 v[98:99], v[14:15], v[82:83] op_sel:[0,1] op_sel_hi:[1,0]
	v_pk_fma_f32 v[180:181], v[180:181], s[10:11], v[214:215] op_sel:[0,0,1] op_sel_hi:[1,0,0] neg_lo:[1,0,0] neg_hi:[1,0,0]
	v_pk_add_f32 v[214:215], v[182:183], v[216:217]
	v_pk_add_f32 v[182:183], v[182:183], v[216:217] neg_lo:[0,1] neg_hi:[0,1]
	v_pk_fma_f32 v[98:99], v[10:11], v[82:83], v[98:99] op_sel_hi:[0,1,1]
	v_pk_mul_f32 v[216:217], v[182:183], s[66:67]
	v_pk_mul_f32 v[114:115], v[14:15], v[98:99] op_sel:[0,1] op_sel_hi:[1,0]
	v_pk_fma_f32 v[182:183], v[182:183], s[64:65], v[216:217] op_sel:[0,0,1] op_sel_hi:[1,0,0] neg_lo:[1,0,0] neg_hi:[1,0,0]
	s_waitcnt lgkmcnt(0)
	v_pk_add_f32 v[216:217], v[184:185], v[218:219]
	v_pk_add_f32 v[184:185], v[184:185], v[218:219] neg_lo:[0,1] neg_hi:[0,1]
	v_pk_mul_f32 v[8:9], v[2:3], v[6:7] op_sel:[0,1] op_sel_hi:[1,0]
	v_pk_mul_f32 v[218:219], v[184:185], s[62:63]
	v_pk_fma_f32 v[114:115], v[10:11], v[98:99], v[114:115] op_sel_hi:[0,1,1]
	v_pk_fma_f32 v[184:185], v[184:185], s[50:51], v[218:219] op_sel:[0,0,1] op_sel_hi:[1,0,0] neg_lo:[1,0,0] neg_hi:[1,0,0]
	v_pk_add_f32 v[218:219], v[186:187], v[220:221]
	v_pk_add_f32 v[186:187], v[186:187], v[220:221] neg_lo:[0,1] neg_hi:[0,1]
	v_pk_fma_f32 v[8:9], v[4:5], v[6:7], v[8:9] op_sel_hi:[0,1,1]
	v_pk_mul_f32 v[220:221], v[186:187], s[46:47]
	v_pk_mul_f32 v[16:17], v[2:3], v[10:11] op_sel:[0,1] op_sel_hi:[1,0]
	v_pk_fma_f32 v[186:187], v[186:187], s[42:43], v[220:221] op_sel:[0,0,1] op_sel_hi:[1,0,0] neg_lo:[1,0,0] neg_hi:[1,0,0]
	v_pk_add_f32 v[220:221], v[222:223], v[204:205]
	v_pk_add_f32 v[204:205], v[222:223], v[204:205] neg_lo:[0,1] neg_hi:[0,1]
	v_pk_add_f32 v[222:223], v[188:189], v[172:173]
	v_pk_add_f32 v[172:173], v[188:189], v[172:173] neg_lo:[0,1] neg_hi:[0,1]
	v_pk_mul_f32 v[30:31], v[2:3], v[26:27] op_sel:[0,1] op_sel_hi:[1,0]
	v_pk_mul_f32 v[188:189], v[172:173], s[62:63]
	v_pk_mul_f32 v[54:55], v[2:3], v[50:51] op_sel:[0,1] op_sel_hi:[1,0]
	v_pk_fma_f32 v[172:173], v[172:173], s[50:51], v[188:189] op_sel:[0,0,1] op_sel_hi:[1,0,0]
	v_pk_add_f32 v[188:189], v[190:191], v[208:209]
	v_pk_add_f32 v[190:191], v[190:191], v[208:209] neg_lo:[0,1] neg_hi:[0,1]
	v_pk_mul_f32 v[70:71], v[2:3], v[66:67] op_sel:[0,1] op_sel_hi:[1,0]
	v_pk_mul_f32 v[208:209], v[190:191], s[68:69]
	v_pk_mul_f32 v[86:87], v[2:3], v[82:83] op_sel:[0,1] op_sel_hi:[1,0]
	v_pk_fma_f32 v[190:191], v[190:191], s[10:11], v[208:209] op_sel:[0,0,1] op_sel_hi:[1,0,0]
	v_pk_add_f32 v[208:209], v[192:193], v[210:211]
	v_pk_add_f32 v[192:193], v[192:193], v[210:211] neg_lo:[0,1] neg_hi:[0,1]
	v_pk_mul_f32 v[102:103], v[2:3], v[98:99] op_sel:[0,1] op_sel_hi:[1,0]
	v_pk_mul_f32 v[210:211], v[192:193], s[72:73]
	v_pk_mul_f32 v[118:119], v[2:3], v[114:115] op_sel:[0,1] op_sel_hi:[1,0]
	v_pk_fma_f32 v[192:193], v[192:193], s[76:77], v[210:211] op_sel:[0,0,1] op_sel_hi:[1,0,0]
	v_pk_add_f32 v[210:211], v[194:195], v[212:213]
	v_pk_add_f32 v[212:213], v[194:195], v[212:213] neg_lo:[0,1] neg_hi:[0,1]
	v_xor_b32_e32 v20, 0x80000000, v9
	v_pk_add_f32 v[194:195], v[196:197], v[214:215]
	v_pk_add_f32 v[196:197], v[196:197], v[214:215] neg_lo:[0,1] neg_hi:[0,1]
	v_mov_b32_e32 v21, v9
	v_pk_mul_f32 v[214:215], v[196:197], s[72:73]
	v_pk_fma_f32 v[16:17], v[4:5], v[10:11], v[16:17] op_sel_hi:[0,1,1]
	v_pk_fma_f32 v[196:197], v[196:197], s[76:77], v[214:215] op_sel:[0,0,1] op_sel_hi:[1,0,0] neg_lo:[1,0,0] neg_hi:[1,0,0]
	v_pk_add_f32 v[214:215], v[198:199], v[216:217]
	v_pk_add_f32 v[198:199], v[198:199], v[216:217] neg_lo:[0,1] neg_hi:[0,1]
	v_pk_mul_f32 v[18:19], v[12:13], v[10:11] op_sel:[0,1] op_sel_hi:[1,0]
	v_pk_mul_f32 v[216:217], v[198:199], s[68:69]
	v_pk_fma_f32 v[30:31], v[4:5], v[26:27], v[30:31] op_sel_hi:[0,1,1]
	v_pk_fma_f32 v[198:199], v[198:199], s[10:11], v[216:217] op_sel:[0,0,1] op_sel_hi:[1,0,0] neg_lo:[1,0,0] neg_hi:[1,0,0]
	v_pk_add_f32 v[216:217], v[202:203], v[218:219]
	v_pk_add_f32 v[202:203], v[202:203], v[218:219] neg_lo:[0,1] neg_hi:[0,1]
	v_pk_mul_f32 v[42:43], v[12:13], v[26:27] op_sel:[0,1] op_sel_hi:[1,0]
	v_pk_mul_f32 v[218:219], v[202:203], s[62:63]
	v_pk_fma_f32 v[54:55], v[4:5], v[50:51], v[54:55] op_sel_hi:[0,1,1]
	v_pk_fma_f32 v[202:203], v[202:203], s[50:51], v[218:219] op_sel:[0,0,1] op_sel_hi:[1,0,0] neg_lo:[1,0,0] neg_hi:[1,0,0]
	v_pk_add_f32 v[218:219], v[156:157], v[206:207] op_sel:[0,1] op_sel_hi:[1,0] neg_hi:[0,1]
	v_pk_add_f32 v[156:157], v[156:157], v[206:207] op_sel:[0,1] op_sel_hi:[1,0] neg_lo:[0,1]
	v_pk_add_f32 v[206:207], v[158:159], v[174:175]
	v_pk_add_f32 v[158:159], v[158:159], v[174:175] neg_lo:[0,1] neg_hi:[0,1]
	v_pk_mul_f32 v[58:59], v[12:13], v[50:51] op_sel:[0,1] op_sel_hi:[1,0]
	v_pk_mul_f32 v[174:175], v[158:159], s[62:63]
	v_pk_fma_f32 v[70:71], v[4:5], v[66:67], v[70:71] op_sel_hi:[0,1,1]
	v_pk_fma_f32 v[158:159], v[158:159], s[50:51], v[174:175] op_sel:[0,0,1] op_sel_hi:[1,0,0]
	v_pk_add_f32 v[174:175], v[160:161], v[176:177]
	v_pk_add_f32 v[160:161], v[160:161], v[176:177] neg_lo:[0,1] neg_hi:[0,1]
	v_pk_mul_f32 v[74:75], v[12:13], v[66:67] op_sel:[0,1] op_sel_hi:[1,0]
	v_pk_mul_f32 v[176:177], v[160:161], s[68:69]
	v_pk_fma_f32 v[86:87], v[4:5], v[82:83], v[86:87] op_sel_hi:[0,1,1]
	v_pk_fma_f32 v[160:161], v[160:161], s[10:11], v[176:177] op_sel:[0,0,1] op_sel_hi:[1,0,0]
	v_pk_add_f32 v[176:177], v[162:163], v[178:179]
	v_pk_add_f32 v[162:163], v[162:163], v[178:179] neg_lo:[0,1] neg_hi:[0,1]
	v_pk_mul_f32 v[90:91], v[12:13], v[82:83] op_sel:[0,1] op_sel_hi:[1,0]
	v_pk_mul_f32 v[178:179], v[162:163], s[72:73]
	v_pk_fma_f32 v[102:103], v[4:5], v[98:99], v[102:103] op_sel_hi:[0,1,1]
	v_pk_fma_f32 v[162:163], v[162:163], s[76:77], v[178:179] op_sel:[0,0,1] op_sel_hi:[1,0,0]
	v_pk_add_f32 v[178:179], v[164:165], v[180:181]
	v_pk_add_f32 v[180:181], v[164:165], v[180:181] neg_lo:[0,1] neg_hi:[0,1]
	v_pk_mul_f32 v[106:107], v[12:13], v[98:99] op_sel:[0,1] op_sel_hi:[1,0]
	v_pk_add_f32 v[164:165], v[166:167], v[182:183]
	v_pk_add_f32 v[166:167], v[166:167], v[182:183] neg_lo:[0,1] neg_hi:[0,1]
	v_pk_fma_f32 v[118:119], v[4:5], v[114:115], v[118:119] op_sel_hi:[0,1,1]
	v_pk_mul_f32 v[182:183], v[166:167], s[72:73]
	v_pk_mul_f32 v[122:123], v[12:13], v[114:115] op_sel:[0,1] op_sel_hi:[1,0]
	v_pk_fma_f32 v[166:167], v[166:167], s[76:77], v[182:183] op_sel:[0,0,1] op_sel_hi:[1,0,0] neg_lo:[1,0,0] neg_hi:[1,0,0]
	v_pk_add_f32 v[182:183], v[168:169], v[184:185]
	v_pk_add_f32 v[168:169], v[168:169], v[184:185] neg_lo:[0,1] neg_hi:[0,1]
	v_pk_fma_f32 v[18:19], v[6:7], v[10:11], v[18:19] op_sel_hi:[0,1,1]
	v_pk_mul_f32 v[184:185], v[168:169], s[68:69]
	v_pk_mul_f32 v[22:23], v[10:11], v[20:21] op_sel:[1,0] op_sel_hi:[0,1]
	v_pk_fma_f32 v[168:169], v[168:169], s[10:11], v[184:185] op_sel:[0,0,1] op_sel_hi:[1,0,0] neg_lo:[1,0,0] neg_hi:[1,0,0]
	v_pk_add_f32 v[184:185], v[170:171], v[186:187]
	v_pk_add_f32 v[170:171], v[170:171], v[186:187] neg_lo:[0,1] neg_hi:[0,1]
	v_pk_fma_f32 v[42:43], v[6:7], v[26:27], v[42:43] op_sel_hi:[0,1,1]
	v_pk_mul_f32 v[186:187], v[170:171], s[62:63]
	v_pk_mul_f32 v[46:47], v[20:21], v[26:27] op_sel:[0,1] op_sel_hi:[1,0]
	v_pk_fma_f32 v[170:171], v[170:171], s[50:51], v[186:187] op_sel:[0,0,1] op_sel_hi:[1,0,0] neg_lo:[1,0,0] neg_hi:[1,0,0]
	v_pk_add_f32 v[186:187], v[220:221], v[210:211]
	v_pk_add_f32 v[210:211], v[220:221], v[210:211] neg_lo:[0,1] neg_hi:[0,1]
	v_pk_add_f32 v[220:221], v[222:223], v[194:195]
	v_pk_add_f32 v[194:195], v[222:223], v[194:195] neg_lo:[0,1] neg_hi:[0,1]
	v_pk_fma_f32 v[58:59], v[6:7], v[50:51], v[58:59] op_sel_hi:[0,1,1]
	v_pk_mul_f32 v[222:223], v[194:195], s[68:69]
	v_pk_mul_f32 v[62:63], v[20:21], v[50:51] op_sel:[0,1] op_sel_hi:[1,0]
	v_pk_fma_f32 v[194:195], v[194:195], s[10:11], v[222:223] op_sel:[0,0,1] op_sel_hi:[1,0,0]
	v_pk_add_f32 v[222:223], v[188:189], v[214:215]
	v_pk_add_f32 v[214:215], v[188:189], v[214:215] neg_lo:[0,1] neg_hi:[0,1]
	v_pk_fma_f32 v[74:75], v[6:7], v[66:67], v[74:75] op_sel_hi:[0,1,1]
	v_pk_add_f32 v[188:189], v[208:209], v[216:217]
	v_pk_add_f32 v[208:209], v[208:209], v[216:217] neg_lo:[0,1] neg_hi:[0,1]
	v_pk_mul_f32 v[78:79], v[20:21], v[66:67] op_sel:[0,1] op_sel_hi:[1,0]
	v_pk_mul_f32 v[216:217], v[208:209], s[68:69]
	v_pk_fma_f32 v[90:91], v[6:7], v[82:83], v[90:91] op_sel_hi:[0,1,1]
	v_pk_fma_f32 v[208:209], v[208:209], s[10:11], v[216:217] op_sel:[0,0,1] op_sel_hi:[1,0,0] neg_lo:[1,0,0] neg_hi:[1,0,0]
	v_pk_add_f32 v[216:217], v[204:205], v[212:213] op_sel:[0,1] op_sel_hi:[1,0] neg_hi:[0,1]
	v_pk_add_f32 v[204:205], v[204:205], v[212:213] op_sel:[0,1] op_sel_hi:[1,0] neg_lo:[0,1]
	v_pk_add_f32 v[212:213], v[172:173], v[196:197]
	v_pk_add_f32 v[172:173], v[172:173], v[196:197] neg_lo:[0,1] neg_hi:[0,1]
	v_pk_mul_f32 v[94:95], v[20:21], v[82:83] op_sel:[0,1] op_sel_hi:[1,0]
	v_pk_mul_f32 v[196:197], v[172:173], s[68:69]
	v_pk_fma_f32 v[106:107], v[6:7], v[98:99], v[106:107] op_sel_hi:[0,1,1]
	v_pk_fma_f32 v[172:173], v[172:173], s[10:11], v[196:197] op_sel:[0,0,1] op_sel_hi:[1,0,0]
	v_pk_add_f32 v[196:197], v[190:191], v[198:199]
	v_pk_add_f32 v[198:199], v[190:191], v[198:199] neg_lo:[0,1] neg_hi:[0,1]
	v_pk_mul_f32 v[110:111], v[20:21], v[98:99] op_sel:[0,1] op_sel_hi:[1,0]
	v_pk_add_f32 v[190:191], v[192:193], v[202:203]
	v_pk_add_f32 v[192:193], v[192:193], v[202:203] neg_lo:[0,1] neg_hi:[0,1]
	v_pk_fma_f32 v[122:123], v[6:7], v[114:115], v[122:123] op_sel_hi:[0,1,1]
	v_pk_mul_f32 v[202:203], v[192:193], s[68:69]
	v_pk_mul_f32 v[126:127], v[20:21], v[114:115] op_sel:[0,1] op_sel_hi:[1,0]
	v_pk_fma_f32 v[192:193], v[192:193], s[10:11], v[202:203] op_sel:[0,0,1] op_sel_hi:[1,0,0] neg_lo:[1,0,0] neg_hi:[1,0,0]
	v_pk_add_f32 v[202:203], v[218:219], v[178:179]
	v_pk_add_f32 v[178:179], v[218:219], v[178:179] neg_lo:[0,1] neg_hi:[0,1]
	v_pk_add_f32 v[218:219], v[206:207], v[164:165]
	v_pk_add_f32 v[164:165], v[206:207], v[164:165] neg_lo:[0,1] neg_hi:[0,1]
	v_xor_b32_e32 v24, 0x80000000, v17
	v_pk_mul_f32 v[206:207], v[164:165], s[68:69]
	v_xor_b32_e32 v28, 0x80000000, v19
	v_pk_fma_f32 v[164:165], v[164:165], s[10:11], v[206:207] op_sel:[0,0,1] op_sel_hi:[1,0,0]
	v_pk_add_f32 v[206:207], v[174:175], v[182:183]
	v_pk_add_f32 v[182:183], v[174:175], v[182:183] neg_lo:[0,1] neg_hi:[0,1]
	v_pk_fma_f32 v[22:23], v[10:11], v[8:9], v[22:23] op_sel_hi:[1,0,1]
	v_pk_add_f32 v[174:175], v[176:177], v[184:185]
	v_pk_add_f32 v[176:177], v[176:177], v[184:185] neg_lo:[0,1] neg_hi:[0,1]
	v_pk_fma_f32 v[46:47], v[8:9], v[26:27], v[46:47] op_sel_hi:[0,1,1]
	v_pk_mul_f32 v[184:185], v[176:177], s[68:69]
	v_pk_fma_f32 v[62:63], v[8:9], v[50:51], v[62:63] op_sel_hi:[0,1,1]
	v_pk_fma_f32 v[176:177], v[176:177], s[10:11], v[184:185] op_sel:[0,0,1] op_sel_hi:[1,0,0] neg_lo:[1,0,0] neg_hi:[1,0,0]
	v_pk_add_f32 v[184:185], v[156:157], v[180:181] op_sel:[0,1] op_sel_hi:[1,0] neg_hi:[0,1]
	v_pk_add_f32 v[156:157], v[156:157], v[180:181] op_sel:[0,1] op_sel_hi:[1,0] neg_lo:[0,1]
	v_pk_add_f32 v[180:181], v[158:159], v[166:167]
	v_pk_add_f32 v[158:159], v[158:159], v[166:167] neg_lo:[0,1] neg_hi:[0,1]
	v_pk_fma_f32 v[78:79], v[8:9], v[66:67], v[78:79] op_sel_hi:[0,1,1]
	v_pk_mul_f32 v[166:167], v[158:159], s[68:69]
	v_pk_fma_f32 v[94:95], v[8:9], v[82:83], v[94:95] op_sel_hi:[0,1,1]
	v_pk_fma_f32 v[158:159], v[158:159], s[10:11], v[166:167] op_sel:[0,0,1] op_sel_hi:[1,0,0]
	v_pk_add_f32 v[166:167], v[160:161], v[168:169]
	v_pk_add_f32 v[168:169], v[160:161], v[168:169] neg_lo:[0,1] neg_hi:[0,1]
	v_pk_fma_f32 v[110:111], v[8:9], v[98:99], v[110:111] op_sel_hi:[0,1,1]
	v_pk_add_f32 v[160:161], v[162:163], v[170:171]
	v_pk_add_f32 v[162:163], v[162:163], v[170:171] neg_lo:[0,1] neg_hi:[0,1]
	v_pk_fma_f32 v[126:127], v[8:9], v[114:115], v[126:127] op_sel_hi:[0,1,1]
	v_pk_mul_f32 v[170:171], v[162:163], s[68:69]
	v_mov_b32_e32 v25, v17
	v_pk_fma_f32 v[162:163], v[162:163], s[10:11], v[170:171] op_sel:[0,0,1] op_sel_hi:[1,0,0] neg_lo:[1,0,0] neg_hi:[1,0,0]
	v_pk_add_f32 v[170:171], v[186:187], v[222:223]
	v_pk_add_f32 v[186:187], v[186:187], v[222:223] neg_lo:[0,1] neg_hi:[0,1]
	v_pk_add_f32 v[222:223], v[220:221], v[188:189]
	v_pk_add_f32 v[220:221], v[220:221], v[188:189] neg_lo:[0,1] neg_hi:[0,1]
	s_mov_b32 s10, s60
	s_nop 0
	s_nop 0
	v_pk_add_f32 v[188:189], v[210:211], v[214:215] op_sel:[0,1] op_sel_hi:[1,0] neg_hi:[0,1]
	v_pk_add_f32 v[210:211], v[210:211], v[214:215] op_sel:[0,1] op_sel_hi:[1,0] neg_lo:[0,1]
	v_pk_add_f32 v[214:215], v[194:195], v[208:209]
	v_pk_add_f32 v[208:209], v[194:195], v[208:209] neg_lo:[0,1] neg_hi:[0,1]
	s_add_i32 s60, s60, s28
	s_nop 0
	s_nop 0
	v_pk_add_f32 v[194:195], v[216:217], v[196:197]
	v_pk_add_f32 v[196:197], v[216:217], v[196:197] neg_lo:[0,1] neg_hi:[0,1]
	v_pk_add_f32 v[216:217], v[212:213], v[190:191]
	v_pk_add_f32 v[212:213], v[212:213], v[190:191] neg_lo:[0,1] neg_hi:[0,1]
	s_cmpk_gt_i32 s60, 0x7ff
	s_nop 0
	s_nop 0
	v_pk_add_f32 v[190:191], v[204:205], v[198:199] op_sel:[0,1] op_sel_hi:[1,0] neg_hi:[0,1]
	v_pk_add_f32 v[198:199], v[204:205], v[198:199] op_sel:[0,1] op_sel_hi:[1,0] neg_lo:[0,1]
	v_pk_add_f32 v[204:205], v[172:173], v[192:193]
	v_pk_add_f32 v[192:193], v[172:173], v[192:193] neg_lo:[0,1] neg_hi:[0,1]
	s_cselect_b64 s[76:77], -1, 0
	s_nop 0
	s_nop 0
	v_pk_add_f32 v[172:173], v[202:203], v[206:207]
	v_pk_add_f32 v[202:203], v[202:203], v[206:207] neg_lo:[0,1] neg_hi:[0,1]
	v_pk_add_f32 v[206:207], v[218:219], v[174:175]
	v_pk_add_f32 v[218:219], v[218:219], v[174:175] neg_lo:[0,1] neg_hi:[0,1]
	s_cmpk_lt_i32 s60, 0x800
	s_nop 0
	s_nop 0
	v_pk_add_f32 v[174:175], v[178:179], v[182:183] op_sel:[0,1] op_sel_hi:[1,0] neg_hi:[0,1]
	v_pk_add_f32 v[178:179], v[178:179], v[182:183] op_sel:[0,1] op_sel_hi:[1,0] neg_lo:[0,1]
	v_pk_add_f32 v[182:183], v[164:165], v[176:177]
	v_pk_add_f32 v[176:177], v[164:165], v[176:177] neg_lo:[0,1] neg_hi:[0,1]
	s_cselect_b32 s45, s60, s10
	s_nop 0
	s_nop 0
	v_pk_add_f32 v[164:165], v[184:185], v[166:167]
	v_pk_add_f32 v[166:167], v[184:185], v[166:167] neg_lo:[0,1] neg_hi:[0,1]
	v_pk_add_f32 v[184:185], v[180:181], v[160:161]
	v_pk_add_f32 v[180:181], v[180:181], v[160:161] neg_lo:[0,1] neg_hi:[0,1]
	s_lshl_b32 s11, s45, 1
	s_nop 0
	s_nop 0
	v_pk_add_f32 v[160:161], v[156:157], v[168:169] op_sel:[0,1] op_sel_hi:[1,0] neg_hi:[0,1]
	v_pk_add_f32 v[156:157], v[156:157], v[168:169] op_sel:[0,1] op_sel_hi:[1,0] neg_lo:[0,1]
	v_pk_add_f32 v[168:169], v[158:159], v[162:163]
	v_pk_add_f32 v[158:159], v[158:159], v[162:163] neg_lo:[0,1] neg_hi:[0,1]
	v_mov_b32_e32 v29, v19
	v_xor_b32_e32 v163, 0x80000000, v158
	v_mov_b32_e32 v162, v159
	v_pk_add_f32 v[158:159], v[170:171], v[222:223]
	v_pk_add_f32 v[170:171], v[170:171], v[222:223] neg_lo:[0,1] neg_hi:[0,1]
	v_pk_add_f32 v[222:223], v[186:187], v[220:221] op_sel:[0,1] op_sel_hi:[1,0] neg_hi:[0,1]
	v_pk_add_f32 v[186:187], v[186:187], v[220:221] op_sel:[0,1] op_sel_hi:[1,0] neg_lo:[0,1]
	v_pk_add_f32 v[220:221], v[188:189], v[214:215]
	v_pk_add_f32 v[188:189], v[188:189], v[214:215] neg_lo:[0,1] neg_hi:[0,1]
	v_pk_add_f32 v[214:215], v[210:211], v[208:209] op_sel:[0,1] op_sel_hi:[1,0] neg_hi:[0,1]
	v_pk_add_f32 v[208:209], v[210:211], v[208:209] op_sel:[0,1] op_sel_hi:[1,0] neg_lo:[0,1]
	v_pk_add_f32 v[210:211], v[194:195], v[216:217]
	v_pk_add_f32 v[194:195], v[194:195], v[216:217] neg_lo:[0,1] neg_hi:[0,1]
	v_pk_add_f32 v[216:217], v[196:197], v[212:213] op_sel:[0,1] op_sel_hi:[1,0] neg_hi:[0,1]
	v_pk_add_f32 v[196:197], v[196:197], v[212:213] op_sel:[0,1] op_sel_hi:[1,0] neg_lo:[0,1]
	v_pk_add_f32 v[212:213], v[190:191], v[204:205]
	v_pk_add_f32 v[190:191], v[190:191], v[204:205] neg_lo:[0,1] neg_hi:[0,1]
	v_pk_add_f32 v[204:205], v[198:199], v[192:193] op_sel:[0,1] op_sel_hi:[1,0] neg_hi:[0,1]
	v_pk_add_f32 v[192:193], v[198:199], v[192:193] op_sel:[0,1] op_sel_hi:[1,0] neg_lo:[0,1]
	v_pk_add_f32 v[198:199], v[172:173], v[206:207]
	v_pk_add_f32 v[172:173], v[172:173], v[206:207] neg_lo:[0,1] neg_hi:[0,1]
	v_pk_mul_f32 v[2:3], v[2:3], v[198:199] op_sel:[0,1] op_sel_hi:[1,0]
	v_pk_add_f32 v[206:207], v[202:203], v[218:219] op_sel:[0,1] op_sel_hi:[1,0] neg_hi:[0,1]
	v_pk_add_f32 v[202:203], v[202:203], v[218:219] op_sel:[0,1] op_sel_hi:[1,0] neg_lo:[0,1]
	v_pk_add_f32 v[218:219], v[174:175], v[182:183]
	v_pk_add_f32 v[174:175], v[174:175], v[182:183] neg_lo:[0,1] neg_hi:[0,1]
	v_pk_add_f32 v[182:183], v[178:179], v[176:177] op_sel:[0,1] op_sel_hi:[1,0] neg_hi:[0,1]
	v_pk_add_f32 v[176:177], v[178:179], v[176:177] op_sel:[0,1] op_sel_hi:[1,0] neg_lo:[0,1]
	v_pk_add_f32 v[178:179], v[164:165], v[184:185]
	v_pk_fma_f32 v[2:3], v[4:5], v[198:199], v[2:3] op_sel_hi:[0,1,1]
	v_pk_mul_f32 v[4:5], v[12:13], v[210:211] op_sel:[0,1] op_sel_hi:[1,0]
	s_and_b32 s10, s45, 0x3ff
	v_pk_fma_f32 v[4:5], v[6:7], v[210:211], v[4:5] op_sel_hi:[0,1,1]
	v_pk_mul_f32 v[6:7], v[20:21], v[178:179] op_sel:[0,1] op_sel_hi:[1,0]
	s_and_b32 s11, s11, 0xfffff800
	v_pk_fma_f32 v[6:7], v[8:9], v[178:179], v[6:7] op_sel_hi:[0,1,1]
	v_pk_mul_f32 v[8:9], v[14:15], v[220:221] op_sel:[0,1] op_sel_hi:[1,0]
	v_xor_b32_e32 v32, 0x80000000, v23
	v_xor_b32_e32 v44, 0x80000000, v27
	v_xor_b32_e32 v48, 0x80000000, v31
	v_xor_b32_e32 v52, 0x80000000, v43
	v_mov_b32_e32 v33, v23
	v_mov_b32_e32 v45, v27
	v_mov_b32_e32 v49, v31
	v_mov_b32_e32 v53, v43
	v_pk_add_f32 v[164:165], v[164:165], v[184:185] neg_lo:[0,1] neg_hi:[0,1]
	v_pk_add_f32 v[184:185], v[166:167], v[180:181] op_sel:[0,1] op_sel_hi:[1,0] neg_hi:[0,1]
	v_pk_add_f32 v[166:167], v[166:167], v[180:181] op_sel:[0,1] op_sel_hi:[1,0] neg_lo:[0,1]
	v_pk_add_f32 v[180:181], v[160:161], v[168:169]
	v_pk_fma_f32 v[8:9], v[10:11], v[220:221], v[8:9] op_sel_hi:[0,1,1]
	v_pk_mul_f32 v[10:11], v[24:25], v[218:219] op_sel:[0,1] op_sel_hi:[1,0]
	v_pk_mul_f32 v[12:13], v[28:29], v[212:213] op_sel:[0,1] op_sel_hi:[1,0]
	s_or_b32 s10, s11, s10
	v_xor_b32_e32 v56, 0x80000000, v47
	v_xor_b32_e32 v60, 0x80000000, v51
	v_xor_b32_e32 v64, 0x80000000, v55
	v_xor_b32_e32 v68, 0x80000000, v59
	v_xor_b32_e32 v72, 0x80000000, v63
	v_xor_b32_e32 v76, 0x80000000, v67
	v_xor_b32_e32 v80, 0x80000000, v71
	v_mov_b32_e32 v57, v47
	v_mov_b32_e32 v61, v51
	v_mov_b32_e32 v65, v55
	v_mov_b32_e32 v69, v59
	v_mov_b32_e32 v73, v63
	v_mov_b32_e32 v77, v67
	v_mov_b32_e32 v81, v71
	v_pk_add_f32 v[160:161], v[160:161], v[168:169] neg_lo:[0,1] neg_hi:[0,1]
	v_pk_add_f32 v[168:169], v[156:157], v[162:163]
	v_pk_fma_f32 v[10:11], v[16:17], v[218:219], v[10:11] op_sel_hi:[0,1,1]
	v_pk_fma_f32 v[12:13], v[18:19], v[212:213], v[12:13] op_sel_hi:[0,1,1]
	v_pk_mul_f32 v[14:15], v[32:33], v[180:181] op_sel:[0,1] op_sel_hi:[1,0]
	v_pk_mul_f32 v[16:17], v[44:45], v[222:223] op_sel:[0,1] op_sel_hi:[1,0]
	v_pk_mul_f32 v[18:19], v[48:49], v[206:207] op_sel:[0,1] op_sel_hi:[1,0]
	v_pk_mul_f32 v[20:21], v[52:53], v[216:217] op_sel:[0,1] op_sel_hi:[1,0]
	s_ashr_i32 s11, s10, 31
	v_xor_b32_e32 v84, 0x80000000, v75
	v_xor_b32_e32 v88, 0x80000000, v79
	v_xor_b32_e32 v92, 0x80000000, v83
	v_xor_b32_e32 v96, 0x80000000, v87
	v_xor_b32_e32 v100, 0x80000000, v91
	v_xor_b32_e32 v104, 0x80000000, v95
	v_xor_b32_e32 v108, 0x80000000, v99
	v_xor_b32_e32 v112, 0x80000000, v103
	v_xor_b32_e32 v116, 0x80000000, v107
	v_xor_b32_e32 v120, 0x80000000, v111
	v_xor_b32_e32 v124, 0x80000000, v115
	v_xor_b32_e32 v128, 0x80000000, v119
	v_xor_b32_e32 v130, 0x80000000, v123
	v_xor_b32_e32 v132, 0x80000000, v127
	v_mov_b32_e32 v85, v75
	v_mov_b32_e32 v89, v79
	v_mov_b32_e32 v93, v83
	v_mov_b32_e32 v97, v87
	v_mov_b32_e32 v101, v91
	v_mov_b32_e32 v105, v95
	v_mov_b32_e32 v109, v99
	v_mov_b32_e32 v113, v103
	v_mov_b32_e32 v117, v107
	v_mov_b32_e32 v121, v111
	v_mov_b32_e32 v125, v115
	v_mov_b32_e32 v129, v119
	v_mov_b32_e32 v131, v123
	v_mov_b32_e32 v133, v127
	v_pk_add_f32 v[156:157], v[156:157], v[162:163] neg_lo:[0,1] neg_hi:[0,1]
	v_pk_fma_f32 v[14:15], v[22:23], v[180:181], v[14:15] op_sel_hi:[0,1,1]
	v_pk_fma_f32 v[16:17], v[26:27], v[222:223], v[16:17] op_sel_hi:[0,1,1]
	v_pk_fma_f32 v[18:19], v[30:31], v[206:207], v[18:19] op_sel_hi:[0,1,1]
	v_pk_fma_f32 v[20:21], v[42:43], v[216:217], v[20:21] op_sel_hi:[0,1,1]
	v_pk_mul_f32 v[22:23], v[56:57], v[184:185] op_sel:[0,1] op_sel_hi:[1,0]
	v_pk_mul_f32 v[24:25], v[60:61], v[214:215] op_sel:[0,1] op_sel_hi:[1,0]
	v_pk_mul_f32 v[26:27], v[64:65], v[182:183] op_sel:[0,1] op_sel_hi:[1,0]
	v_pk_mul_f32 v[28:29], v[68:69], v[204:205] op_sel:[0,1] op_sel_hi:[1,0]
	v_pk_mul_f32 v[30:31], v[72:73], v[168:169] op_sel:[0,1] op_sel_hi:[1,0]
	v_pk_mul_f32 v[32:33], v[76:77], v[170:171] op_sel:[0,1] op_sel_hi:[1,0]
	v_pk_mul_f32 v[42:43], v[80:81], v[172:173] op_sel:[0,1] op_sel_hi:[1,0]
	s_lshl_b64 s[78:79], s[10:11], 15
	s_bitset1_b32 s10, 10
	v_pk_fma_f32 v[22:23], v[46:47], v[184:185], v[22:23] op_sel_hi:[0,1,1]
	v_pk_fma_f32 v[24:25], v[50:51], v[214:215], v[24:25] op_sel_hi:[0,1,1]
	v_pk_fma_f32 v[26:27], v[54:55], v[182:183], v[26:27] op_sel_hi:[0,1,1]
	v_pk_fma_f32 v[28:29], v[58:59], v[204:205], v[28:29] op_sel_hi:[0,1,1]
	v_pk_fma_f32 v[30:31], v[62:63], v[168:169], v[30:31] op_sel_hi:[0,1,1]
	v_pk_fma_f32 v[32:33], v[66:67], v[170:171], v[32:33] op_sel_hi:[0,1,1]
	v_pk_fma_f32 v[42:43], v[70:71], v[172:173], v[42:43] op_sel_hi:[0,1,1]
	v_pk_mul_f32 v[44:45], v[84:85], v[194:195] op_sel:[0,1] op_sel_hi:[1,0]
	v_pk_mul_f32 v[46:47], v[88:89], v[164:165] op_sel:[0,1] op_sel_hi:[1,0]
	v_pk_mul_f32 v[48:49], v[92:93], v[188:189] op_sel:[0,1] op_sel_hi:[1,0]
	v_pk_mul_f32 v[50:51], v[96:97], v[174:175] op_sel:[0,1] op_sel_hi:[1,0]
	v_pk_mul_f32 v[52:53], v[100:101], v[190:191] op_sel:[0,1] op_sel_hi:[1,0]
	v_pk_mul_f32 v[54:55], v[104:105], v[160:161] op_sel:[0,1] op_sel_hi:[1,0]
	v_pk_mul_f32 v[56:57], v[108:109], v[186:187] op_sel:[0,1] op_sel_hi:[1,0]
	v_pk_mul_f32 v[58:59], v[112:113], v[202:203] op_sel:[0,1] op_sel_hi:[1,0]
	v_pk_mul_f32 v[60:61], v[116:117], v[196:197] op_sel:[0,1] op_sel_hi:[1,0]
	v_pk_mul_f32 v[62:63], v[120:121], v[166:167] op_sel:[0,1] op_sel_hi:[1,0]
	v_pk_mul_f32 v[64:65], v[124:125], v[208:209] op_sel:[0,1] op_sel_hi:[1,0]
	v_pk_mul_f32 v[66:67], v[128:129], v[176:177] op_sel:[0,1] op_sel_hi:[1,0]
	v_pk_mul_f32 v[68:69], v[130:131], v[192:193] op_sel:[0,1] op_sel_hi:[1,0]
	v_pk_mul_f32 v[70:71], v[132:133], v[156:157] op_sel:[0,1] op_sel_hi:[1,0]
	s_ashr_i32 s11, s10, 31
	v_pk_fma_f32 v[44:45], v[74:75], v[194:195], v[44:45] op_sel_hi:[0,1,1]
	v_pk_fma_f32 v[46:47], v[78:79], v[164:165], v[46:47] op_sel_hi:[0,1,1]
	v_pk_fma_f32 v[48:49], v[82:83], v[188:189], v[48:49] op_sel_hi:[0,1,1]
	v_pk_fma_f32 v[50:51], v[86:87], v[174:175], v[50:51] op_sel_hi:[0,1,1]
	v_pk_fma_f32 v[52:53], v[90:91], v[190:191], v[52:53] op_sel_hi:[0,1,1]
	v_pk_fma_f32 v[54:55], v[94:95], v[160:161], v[54:55] op_sel_hi:[0,1,1]
	v_pk_fma_f32 v[56:57], v[98:99], v[186:187], v[56:57] op_sel_hi:[0,1,1]
	v_pk_fma_f32 v[58:59], v[102:103], v[202:203], v[58:59] op_sel_hi:[0,1,1]
	v_pk_fma_f32 v[60:61], v[106:107], v[196:197], v[60:61] op_sel_hi:[0,1,1]
	v_pk_fma_f32 v[62:63], v[110:111], v[166:167], v[62:63] op_sel_hi:[0,1,1]
	v_pk_fma_f32 v[64:65], v[114:115], v[208:209], v[64:65] op_sel_hi:[0,1,1]
	v_pk_fma_f32 v[66:67], v[118:119], v[176:177], v[66:67] op_sel_hi:[0,1,1]
	v_pk_fma_f32 v[68:69], v[122:123], v[192:193], v[68:69] op_sel_hi:[0,1,1]
	v_pk_fma_f32 v[70:71], v[126:127], v[156:157], v[70:71] op_sel_hi:[0,1,1]
	ds_write2_b64 v40, v[158:159], v[32:33] offset1:16
	ds_write2_b64 v40, v[16:17], v[56:57] offset0:33 offset1:49
	ds_write2_b64 v40, v[8:9], v[48:49] offset0:66 offset1:82
	ds_write2_b64 v40, v[24:25], v[64:65] offset0:99 offset1:115
	ds_write2_b64 v40, v[4:5], v[44:45] offset0:132 offset1:148
	ds_write2_b64 v40, v[20:21], v[60:61] offset0:165 offset1:181
	ds_write2_b64 v40, v[12:13], v[52:53] offset0:198 offset1:214
	ds_write2_b64 v40, v[28:29], v[68:69] offset0:231 offset1:247
	ds_write2_b64 v155, v[2:3], v[42:43] offset0:8 offset1:24
	ds_write2_b64 v155, v[18:19], v[58:59] offset0:41 offset1:57
	ds_write2_b64 v155, v[10:11], v[50:51] offset0:74 offset1:90
	ds_write2_b64 v155, v[26:27], v[66:67] offset0:107 offset1:123
	ds_write2_b64 v155, v[6:7], v[46:47] offset0:140 offset1:156
	ds_write2_b64 v155, v[22:23], v[62:63] offset0:173 offset1:189
	ds_write2_b64 v155, v[14:15], v[54:55] offset0:206 offset1:222
	ds_write2_b64 v155, v[30:31], v[70:71] offset0:239 offset1:255
	s_lshl_b64 s[10:11], s[10:11], 15
	v_lshl_add_u64 v[2:3], v[36:37], 0, s[78:79]
	s_waitcnt lgkmcnt(0)
	s_barrier
	global_load_dwordx4 v[6:9], v[2:3], off nt
	global_load_dwordx4 v[30:33], v[2:3], off offset:16 nt
	v_lshl_add_u64 v[2:3], v[36:37], 0, s[10:11]
	global_load_dwordx4 v[26:29], v[2:3], off nt
	global_load_dwordx4 v[18:21], v[2:3], off offset:16 nt
	v_mov_b32_e32 v120, 0
	s_and_saveexec_b64 s[10:11], s[0:1]
	s_cbranch_execz .LBB0_273
	global_load_ushort v120, v[2:3], off offset:32

.LBB0_499:
	v_mov_b32_e32 v2, v210
	s_mov_b32 s43, s8
	v_and_b32_e32 v3, 0x1ff, v2
	v_lshlrev_b32_e32 v2, 5, v2
	v_and_or_b32 v2, v2, s94, v3
	v_ashrrev_i32_e32 v4, 5, v2
	v_lshlrev_b32_e32 v2, 3, v2
	v_lshlrev_b32_e32 v4, 3, v4
	v_add3_u32 v18, 0, v2, v4
	ds_read_b64 v[128:129], v18
	ds_read_b64 v[134:135], v18 offset:4224
	ds_read_b64 v[136:137], v18 offset:8448
	ds_read_b64 v[138:139], v18 offset:12672
	ds_read_b64 v[140:141], v18 offset:16896
	ds_read_b64 v[142:143], v18 offset:21120
	ds_read_b64 v[132:133], v18 offset:25344
	ds_read_b64 v[130:131], v18 offset:29568
	ds_read_b64 v[144:145], v18 offset:33792
	ds_read_b64 v[148:149], v18 offset:38016
	ds_read_b64 v[150:151], v18 offset:42240
	ds_read_b64 v[152:153], v18 offset:46464
	s_waitcnt lgkmcnt(10)
	v_pk_mul_f32 v[162:163], v[134:135], s[10:11]
	s_mov_b32 s74, s11
	v_pk_fma_f32 v[162:163], v[134:135], s[8:9], v[162:163] op_sel:[0,0,1] op_sel_hi:[1,0,0]
	s_waitcnt lgkmcnt(2)
	v_pk_mul_f32 v[178:179], v[148:149], s[42:43]
	v_pk_add_f32 v[194:195], v[134:135], v[148:149]
	v_pk_add_f32 v[134:135], v[134:135], v[148:149] neg_lo:[0,1] neg_hi:[0,1]
	v_pk_mul_f32 v[164:165], v[136:137], s[18:19]
	s_mov_b32 s41, s16
	v_pk_fma_f32 v[178:179], v[148:149], s[74:75], v[178:179] op_sel:[0,0,1] op_sel_hi:[1,0,0] neg_lo:[1,0,0] neg_hi:[1,0,0]
	v_pk_mul_f32 v[148:149], v[134:135], s[18:19]
	v_pk_fma_f32 v[164:165], v[136:137], s[16:17], v[164:165] op_sel:[0,0,1] op_sel_hi:[1,0,0]
	s_mov_b32 s80, s19
	s_waitcnt lgkmcnt(1)
	v_pk_mul_f32 v[180:181], v[150:151], s[40:41]
	v_pk_fma_f32 v[134:135], v[134:135], s[16:17], v[148:149] op_sel:[0,0,1] op_sel_hi:[1,0,0]
	v_pk_add_f32 v[148:149], v[136:137], v[150:151]
	v_pk_add_f32 v[136:137], v[136:137], v[150:151] neg_lo:[0,1] neg_hi:[0,1]
	v_pk_mul_f32 v[166:167], v[138:139], s[26:27]
	s_mov_b32 s78, s37
	s_mov_b32 s39, s24
	v_pk_fma_f32 v[180:181], v[150:151], s[80:81], v[180:181] op_sel:[0,0,1] op_sel_hi:[1,0,0] neg_lo:[1,0,0] neg_hi:[1,0,0]
	v_pk_mul_f32 v[150:151], v[136:137], s[36:37]
	ds_read_b64 v[154:155], v18 offset:50688
	ds_read_b64 v[156:157], v18 offset:54912
	ds_read_b64 v[158:159], v18 offset:59136
	ds_read_b64 v[160:161], v18 offset:63360
	v_pk_fma_f32 v[166:167], v[138:139], s[24:25], v[166:167] op_sel:[0,0,1] op_sel_hi:[1,0,0]
	s_mov_b32 s0, s27
	s_waitcnt lgkmcnt(4)
	v_pk_mul_f32 v[182:183], v[152:153], s[38:39]
	v_pk_fma_f32 v[136:137], v[136:137], s[78:79], v[150:151] op_sel:[0,0,1] op_sel_hi:[1,0,0]
	v_pk_add_f32 v[150:151], v[138:139], v[152:153]
	v_pk_add_f32 v[138:139], v[138:139], v[152:153] neg_lo:[0,1] neg_hi:[0,1]
	v_pk_mul_f32 v[168:169], v[140:141], s[36:37]
	v_pk_fma_f32 v[182:183], v[152:153], s[0:1], v[182:183] op_sel:[0,0,1] op_sel_hi:[1,0,0] neg_lo:[1,0,0] neg_hi:[1,0,0]
	v_pk_mul_f32 v[152:153], v[138:139], s[40:41]
	v_pk_fma_f32 v[168:169], v[140:141], s[78:79], v[168:169] op_sel:[0,0,1] op_sel_hi:[1,0,0]
	v_pk_mul_f32 v[170:171], v[142:143], s[38:39]
	s_waitcnt lgkmcnt(3)
	v_pk_mul_f32 v[184:185], v[154:155], s[36:37]
	v_pk_fma_f32 v[138:139], v[138:139], s[80:81], v[152:153] op_sel:[0,0,1] op_sel_hi:[1,0,0]
	v_pk_add_f32 v[152:153], v[140:141], v[154:155]
	v_pk_add_f32 v[140:141], v[140:141], v[154:155] neg_lo:[0,1] neg_hi:[0,1]
	v_pk_fma_f32 v[170:171], v[142:143], s[0:1], v[170:171] op_sel:[0,0,1] op_sel_hi:[1,0,0]
	v_pk_fma_f32 v[184:185], v[154:155], s[78:79], v[184:185] op_sel:[0,0,1] op_sel_hi:[1,0,0] neg_lo:[1,0,0] neg_hi:[1,0,0]
	s_waitcnt lgkmcnt(2)
	v_pk_mul_f32 v[186:187], v[156:157], s[26:27]
	v_xor_b32_e32 v155, 0x80000000, v140
	v_mov_b32_e32 v154, v141
	v_pk_add_f32 v[140:141], v[142:143], v[156:157]
	v_pk_add_f32 v[142:143], v[142:143], v[156:157] neg_lo:[0,1] neg_hi:[0,1]
	v_pk_mul_f32 v[172:173], v[132:133], s[40:41]
	v_pk_fma_f32 v[186:187], v[156:157], s[24:25], v[186:187] op_sel:[0,0,1] op_sel_hi:[1,0,0] neg_lo:[1,0,0] neg_hi:[1,0,0]
	v_pk_mul_f32 v[156:157], v[142:143], s[40:41]
	v_pk_fma_f32 v[172:173], v[132:133], s[80:81], v[172:173] op_sel:[0,0,1] op_sel_hi:[1,0,0]
	s_waitcnt lgkmcnt(1)
	v_pk_mul_f32 v[188:189], v[158:159], s[18:19]
	v_pk_fma_f32 v[142:143], v[142:143], s[80:81], v[156:157] op_sel:[0,0,1] op_sel_hi:[1,0,0] neg_lo:[1,0,0] neg_hi:[1,0,0]
	v_pk_add_f32 v[156:157], v[132:133], v[158:159]
	v_pk_add_f32 v[132:133], v[132:133], v[158:159] neg_lo:[0,1] neg_hi:[0,1]
	v_pk_mul_f32 v[174:175], v[130:131], s[42:43]
	v_pk_fma_f32 v[188:189], v[158:159], s[16:17], v[188:189] op_sel:[0,0,1] op_sel_hi:[1,0,0] neg_lo:[1,0,0] neg_hi:[1,0,0]
	v_pk_mul_f32 v[158:159], v[132:133], s[36:37]
	v_pk_fma_f32 v[174:175], v[130:131], s[74:75], v[174:175] op_sel:[0,0,1] op_sel_hi:[1,0,0]
	s_waitcnt lgkmcnt(0)
	v_pk_mul_f32 v[190:191], v[160:161], s[10:11]
	v_pk_fma_f32 v[132:133], v[132:133], s[78:79], v[158:159] op_sel:[0,0,1] op_sel_hi:[1,0,0] neg_lo:[1,0,0] neg_hi:[1,0,0]
	v_pk_add_f32 v[158:159], v[130:131], v[160:161]
	v_pk_add_f32 v[130:131], v[130:131], v[160:161] neg_lo:[0,1] neg_hi:[0,1]
	v_xor_b32_e32 v177, 0x80000000, v144
	v_mov_b32_e32 v176, v145
	v_pk_fma_f32 v[190:191], v[160:161], s[8:9], v[190:191] op_sel:[0,0,1] op_sel_hi:[1,0,0] neg_lo:[1,0,0] neg_hi:[1,0,0]
	v_pk_mul_f32 v[160:161], v[130:131], s[18:19]
	v_pk_add_f32 v[192:193], v[128:129], v[144:145]
	v_pk_add_f32 v[144:145], v[128:129], v[144:145] neg_lo:[0,1] neg_hi:[0,1]
	v_pk_fma_f32 v[130:131], v[130:131], s[16:17], v[160:161] op_sel:[0,0,1] op_sel_hi:[1,0,0] neg_lo:[1,0,0] neg_hi:[1,0,0]
	v_pk_add_f32 v[160:161], v[128:129], v[176:177]
	v_pk_add_f32 v[128:129], v[128:129], v[176:177] neg_lo:[0,1] neg_hi:[0,1]
	v_pk_add_f32 v[176:177], v[162:163], v[178:179]
	v_pk_add_f32 v[162:163], v[162:163], v[178:179] neg_lo:[0,1] neg_hi:[0,1]
	v_cvt_f32_u32_e32 v2, v3
	v_pk_mul_f32 v[178:179], v[162:163], s[18:19]
	s_add_i32 s76, s72, s48
	v_pk_fma_f32 v[162:163], v[162:163], s[16:17], v[178:179] op_sel:[0,0,1] op_sel_hi:[1,0,0]
	v_pk_add_f32 v[178:179], v[164:165], v[180:181]
	v_pk_add_f32 v[164:165], v[164:165], v[180:181] neg_lo:[0,1] neg_hi:[0,1]
	v_mul_f32_e32 v2, 0x38800000, v2
	v_pk_mul_f32 v[180:181], v[164:165], s[36:37]
	v_sin_f32_e32 v34, v2
	v_pk_fma_f32 v[164:165], v[164:165], s[78:79], v[180:181] op_sel:[0,0,1] op_sel_hi:[1,0,0]
	v_pk_add_f32 v[180:181], v[166:167], v[182:183]
	v_pk_add_f32 v[166:167], v[166:167], v[182:183] neg_lo:[0,1] neg_hi:[0,1]
	v_cos_f32_e32 v30, v2
	v_pk_mul_f32 v[182:183], v[166:167], s[40:41]
	v_xor_b32_e32 v31, 0x80000000, v34
	v_pk_fma_f32 v[166:167], v[166:167], s[80:81], v[182:183] op_sel:[0,0,1] op_sel_hi:[1,0,0]
	v_pk_add_f32 v[182:183], v[168:169], v[184:185]
	v_pk_add_f32 v[184:185], v[168:169], v[184:185] neg_lo:[0,1] neg_hi:[0,1]
	v_mov_b32_e32 v35, v31
	v_pk_add_f32 v[168:169], v[170:171], v[186:187]
	v_pk_add_f32 v[170:171], v[170:171], v[186:187] neg_lo:[0,1] neg_hi:[0,1]
	v_pk_mul_f32 v[2:3], v[30:31], v[34:35] op_sel:[1,0] op_sel_hi:[0,1]
	v_pk_mul_f32 v[186:187], v[170:171], s[40:41]
	v_pk_fma_f32 v[44:45], v[30:31], v[30:31], v[2:3] op_sel_hi:[1,0,1]
	v_pk_fma_f32 v[170:171], v[170:171], s[80:81], v[186:187] op_sel:[0,0,1] op_sel_hi:[1,0,0] neg_lo:[1,0,0] neg_hi:[1,0,0]
	v_pk_add_f32 v[186:187], v[172:173], v[188:189]
	v_pk_add_f32 v[172:173], v[172:173], v[188:189] neg_lo:[0,1] neg_hi:[0,1]
	v_pk_mul_f32 v[2:3], v[34:35], v[44:45] op_sel:[0,1] op_sel_hi:[1,0]
	v_pk_mul_f32 v[188:189], v[172:173], s[36:37]
	v_xor_b32_e32 v54, 0x80000000, v45
	v_pk_fma_f32 v[172:173], v[172:173], s[78:79], v[188:189] op_sel:[0,0,1] op_sel_hi:[1,0,0] neg_lo:[1,0,0] neg_hi:[1,0,0]
	v_pk_add_f32 v[188:189], v[174:175], v[190:191]
	v_pk_add_f32 v[174:175], v[174:175], v[190:191] neg_lo:[0,1] neg_hi:[0,1]
	v_mov_b32_e32 v55, v45
	v_pk_mul_f32 v[190:191], v[174:175], s[18:19]
	v_pk_fma_f32 v[46:47], v[30:31], v[44:45], v[2:3] op_sel_hi:[0,1,1]
	v_pk_fma_f32 v[174:175], v[174:175], s[16:17], v[190:191] op_sel:[0,0,1] op_sel_hi:[1,0,0] neg_lo:[1,0,0] neg_hi:[1,0,0]
	v_pk_add_f32 v[190:191], v[192:193], v[152:153]
	v_pk_add_f32 v[152:153], v[192:193], v[152:153] neg_lo:[0,1] neg_hi:[0,1]
	v_pk_add_f32 v[192:193], v[194:195], v[140:141]
	v_pk_add_f32 v[140:141], v[194:195], v[140:141] neg_lo:[0,1] neg_hi:[0,1]
	v_pk_mul_f32 v[2:3], v[44:45], v[54:55] op_sel:[1,0] op_sel_hi:[0,1]
	v_pk_mul_f32 v[194:195], v[140:141], s[36:37]
	v_pk_fma_f32 v[52:53], v[44:45], v[44:45], v[2:3] op_sel_hi:[1,0,1]
	v_pk_fma_f32 v[140:141], v[140:141], s[78:79], v[194:195] op_sel:[0,0,1] op_sel_hi:[1,0,0]
	v_pk_add_f32 v[194:195], v[148:149], v[156:157]
	v_pk_add_f32 v[156:157], v[148:149], v[156:157] neg_lo:[0,1] neg_hi:[0,1]
	v_xor_b32_e32 v58, 0x80000000, v53
	v_pk_add_f32 v[148:149], v[150:151], v[158:159]
	v_pk_add_f32 v[150:151], v[150:151], v[158:159] neg_lo:[0,1] neg_hi:[0,1]
	v_mov_b32_e32 v59, v53
	v_pk_mul_f32 v[158:159], v[150:151], s[36:37]
	v_pk_mul_f32 v[2:3], v[52:53], v[58:59] op_sel:[1,0] op_sel_hi:[0,1]
	v_pk_fma_f32 v[150:151], v[150:151], s[78:79], v[158:159] op_sel:[0,0,1] op_sel_hi:[1,0,0] neg_lo:[1,0,0] neg_hi:[1,0,0]
	v_pk_add_f32 v[158:159], v[144:145], v[154:155]
	v_pk_add_f32 v[144:145], v[144:145], v[154:155] neg_lo:[0,1] neg_hi:[0,1]
	v_pk_add_f32 v[154:155], v[134:135], v[142:143]
	v_pk_add_f32 v[134:135], v[134:135], v[142:143] neg_lo:[0,1] neg_hi:[0,1]
	v_pk_fma_f32 v[48:49], v[52:53], v[52:53], v[2:3] op_sel_hi:[1,0,1]
	v_pk_mul_f32 v[142:143], v[134:135], s[36:37]
	v_pk_mul_f32 v[2:3], v[58:59], v[48:49] op_sel:[0,1] op_sel_hi:[1,0]
	v_pk_fma_f32 v[134:135], v[134:135], s[78:79], v[142:143] op_sel:[0,0,1] op_sel_hi:[1,0,0]
	v_pk_add_f32 v[142:143], v[136:137], v[132:133]
	v_pk_add_f32 v[136:137], v[136:137], v[132:133] neg_lo:[0,1] neg_hi:[0,1]
	v_pk_fma_f32 v[36:37], v[52:53], v[48:49], v[2:3] op_sel_hi:[0,1,1]
	v_pk_add_f32 v[132:133], v[138:139], v[130:131]
	v_pk_add_f32 v[130:131], v[138:139], v[130:131] neg_lo:[0,1] neg_hi:[0,1]
	v_pk_mul_f32 v[2:3], v[58:59], v[36:37] op_sel:[0,1] op_sel_hi:[1,0]
	v_pk_mul_f32 v[138:139], v[130:131], s[36:37]
	v_pk_fma_f32 v[26:27], v[52:53], v[36:37], v[2:3] op_sel_hi:[0,1,1]
	v_pk_fma_f32 v[130:131], v[130:131], s[78:79], v[138:139] op_sel:[0,0,1] op_sel_hi:[1,0,0] neg_lo:[1,0,0] neg_hi:[1,0,0]
	v_pk_add_f32 v[138:139], v[160:161], v[182:183]
	v_pk_add_f32 v[160:161], v[160:161], v[182:183] neg_lo:[0,1] neg_hi:[0,1]
	v_pk_add_f32 v[182:183], v[176:177], v[168:169]
	v_pk_add_f32 v[168:169], v[176:177], v[168:169] neg_lo:[0,1] neg_hi:[0,1]
	v_pk_mul_f32 v[2:3], v[58:59], v[26:27] op_sel:[0,1] op_sel_hi:[1,0]
	v_pk_mul_f32 v[176:177], v[168:169], s[36:37]
	v_pk_fma_f32 v[20:21], v[52:53], v[26:27], v[2:3] op_sel_hi:[0,1,1]
	v_pk_fma_f32 v[168:169], v[168:169], s[78:79], v[176:177] op_sel:[0,0,1] op_sel_hi:[1,0,0]
	v_pk_add_f32 v[176:177], v[178:179], v[186:187]
	v_pk_add_f32 v[186:187], v[178:179], v[186:187] neg_lo:[0,1] neg_hi:[0,1]
	v_pk_mul_f32 v[2:3], v[58:59], v[20:21] op_sel:[0,1] op_sel_hi:[1,0]
	v_pk_add_f32 v[178:179], v[180:181], v[188:189]
	v_pk_add_f32 v[180:181], v[180:181], v[188:189] neg_lo:[0,1] neg_hi:[0,1]
	v_pk_fma_f32 v[10:11], v[52:53], v[20:21], v[2:3] op_sel_hi:[0,1,1]
	v_pk_mul_f32 v[188:189], v[180:181], s[36:37]
	v_pk_mul_f32 v[2:3], v[58:59], v[10:11] op_sel:[0,1] op_sel_hi:[1,0]
	v_pk_fma_f32 v[180:181], v[180:181], s[78:79], v[188:189] op_sel:[0,0,1] op_sel_hi:[1,0,0] neg_lo:[1,0,0] neg_hi:[1,0,0]
	v_pk_add_f32 v[188:189], v[128:129], v[184:185] op_sel:[0,1] op_sel_hi:[1,0] neg_hi:[0,1]
	v_pk_add_f32 v[128:129], v[128:129], v[184:185] op_sel:[0,1] op_sel_hi:[1,0] neg_lo:[0,1]
	v_pk_add_f32 v[184:185], v[162:163], v[170:171]
	v_pk_add_f32 v[162:163], v[162:163], v[170:171] neg_lo:[0,1] neg_hi:[0,1]
	v_pk_fma_f32 v[4:5], v[52:53], v[10:11], v[2:3] op_sel_hi:[0,1,1]
	v_pk_mul_f32 v[170:171], v[162:163], s[36:37]
	v_pk_mul_f32 v[8:9], v[54:55], v[4:5] op_sel:[0,1] op_sel_hi:[1,0]
	v_pk_fma_f32 v[162:163], v[162:163], s[78:79], v[170:171] op_sel:[0,0,1] op_sel_hi:[1,0,0]
	v_pk_add_f32 v[170:171], v[164:165], v[172:173]
	v_pk_add_f32 v[172:173], v[164:165], v[172:173] neg_lo:[0,1] neg_hi:[0,1]
	v_pk_mul_f32 v[14:15], v[34:35], v[4:5] op_sel:[0,1] op_sel_hi:[1,0]
	v_pk_add_f32 v[164:165], v[166:167], v[174:175]
	v_pk_add_f32 v[166:167], v[166:167], v[174:175] neg_lo:[0,1] neg_hi:[0,1]
	v_pk_mul_f32 v[32:33], v[54:55], v[10:11] op_sel:[0,1] op_sel_hi:[1,0]
	v_pk_mul_f32 v[174:175], v[166:167], s[36:37]
	v_pk_mul_f32 v[40:41], v[34:35], v[10:11] op_sel:[0,1] op_sel_hi:[1,0]
	v_pk_fma_f32 v[166:167], v[166:167], s[78:79], v[174:175] op_sel:[0,0,1] op_sel_hi:[1,0,0] neg_lo:[1,0,0] neg_hi:[1,0,0]
	v_pk_add_f32 v[174:175], v[190:191], v[194:195]
	v_pk_add_f32 v[190:191], v[190:191], v[194:195] neg_lo:[0,1] neg_hi:[0,1]
	v_pk_add_f32 v[194:195], v[192:193], v[148:149]
	v_pk_add_f32 v[192:193], v[192:193], v[148:149] neg_lo:[0,1] neg_hi:[0,1]
	v_pk_mul_f32 v[62:63], v[54:55], v[20:21] op_sel:[0,1] op_sel_hi:[1,0]
	v_pk_add_f32 v[148:149], v[152:153], v[156:157] op_sel:[0,1] op_sel_hi:[1,0] neg_hi:[0,1]
	v_pk_add_f32 v[152:153], v[152:153], v[156:157] op_sel:[0,1] op_sel_hi:[1,0] neg_lo:[0,1]
	v_pk_add_f32 v[156:157], v[140:141], v[150:151]
	v_pk_add_f32 v[150:151], v[140:141], v[150:151] neg_lo:[0,1] neg_hi:[0,1]
	v_pk_mul_f32 v[66:67], v[34:35], v[20:21] op_sel:[0,1] op_sel_hi:[1,0]
	v_pk_add_f32 v[140:141], v[158:159], v[142:143]
	v_pk_add_f32 v[142:143], v[158:159], v[142:143] neg_lo:[0,1] neg_hi:[0,1]
	v_pk_add_f32 v[158:159], v[154:155], v[132:133]
	v_pk_add_f32 v[154:155], v[154:155], v[132:133] neg_lo:[0,1] neg_hi:[0,1]
	v_pk_mul_f32 v[78:79], v[54:55], v[26:27] op_sel:[0,1] op_sel_hi:[1,0]
	v_pk_add_f32 v[132:133], v[144:145], v[136:137] op_sel:[0,1] op_sel_hi:[1,0] neg_hi:[0,1]
	v_pk_add_f32 v[136:137], v[144:145], v[136:137] op_sel:[0,1] op_sel_hi:[1,0] neg_lo:[0,1]
	v_pk_add_f32 v[144:145], v[134:135], v[130:131]
	v_pk_add_f32 v[134:135], v[134:135], v[130:131] neg_lo:[0,1] neg_hi:[0,1]
	v_pk_mul_f32 v[82:83], v[34:35], v[26:27] op_sel:[0,1] op_sel_hi:[1,0]
	v_pk_add_f32 v[130:131], v[138:139], v[176:177]
	v_pk_add_f32 v[138:139], v[138:139], v[176:177] neg_lo:[0,1] neg_hi:[0,1]
	v_pk_add_f32 v[176:177], v[182:183], v[178:179]
	v_pk_add_f32 v[182:183], v[182:183], v[178:179] neg_lo:[0,1] neg_hi:[0,1]
	v_pk_mul_f32 v[92:93], v[54:55], v[36:37] op_sel:[0,1] op_sel_hi:[1,0]
	v_pk_add_f32 v[178:179], v[160:161], v[186:187] op_sel:[0,1] op_sel_hi:[1,0] neg_hi:[0,1]
	v_pk_add_f32 v[160:161], v[160:161], v[186:187] op_sel:[0,1] op_sel_hi:[1,0] neg_lo:[0,1]
	v_pk_add_f32 v[186:187], v[168:169], v[180:181]
	v_pk_add_f32 v[180:181], v[168:169], v[180:181] neg_lo:[0,1] neg_hi:[0,1]
	v_pk_mul_f32 v[96:97], v[34:35], v[36:37] op_sel:[0,1] op_sel_hi:[1,0]
	v_pk_add_f32 v[168:169], v[188:189], v[170:171]
	v_pk_add_f32 v[170:171], v[188:189], v[170:171] neg_lo:[0,1] neg_hi:[0,1]
	v_pk_add_f32 v[188:189], v[184:185], v[164:165]
	v_pk_add_f32 v[184:185], v[184:185], v[164:165] neg_lo:[0,1] neg_hi:[0,1]
	v_pk_mul_f32 v[106:107], v[54:55], v[48:49] op_sel:[0,1] op_sel_hi:[1,0]
	v_pk_add_f32 v[164:165], v[128:129], v[172:173] op_sel:[0,1] op_sel_hi:[1,0] neg_hi:[0,1]
	v_pk_add_f32 v[128:129], v[128:129], v[172:173] op_sel:[0,1] op_sel_hi:[1,0] neg_lo:[0,1]
	v_pk_add_f32 v[172:173], v[162:163], v[166:167]
	v_pk_add_f32 v[166:167], v[162:163], v[166:167] neg_lo:[0,1] neg_hi:[0,1]
	v_pk_mul_f32 v[110:111], v[34:35], v[48:49] op_sel:[0,1] op_sel_hi:[1,0]
	v_pk_add_f32 v[162:163], v[174:175], v[194:195]
	v_pk_add_f32 v[174:175], v[174:175], v[194:195] neg_lo:[0,1] neg_hi:[0,1]
	v_pk_add_f32 v[194:195], v[190:191], v[192:193] op_sel:[0,1] op_sel_hi:[1,0] neg_hi:[0,1]
	v_pk_add_f32 v[190:191], v[190:191], v[192:193] op_sel:[0,1] op_sel_hi:[1,0] neg_lo:[0,1]
	v_pk_add_f32 v[192:193], v[148:149], v[156:157]
	v_pk_add_f32 v[148:149], v[148:149], v[156:157] neg_lo:[0,1] neg_hi:[0,1]
	v_pk_add_f32 v[156:157], v[152:153], v[150:151] op_sel:[0,1] op_sel_hi:[1,0] neg_hi:[0,1]
	v_pk_add_f32 v[150:151], v[152:153], v[150:151] op_sel:[0,1] op_sel_hi:[1,0] neg_lo:[0,1]
	v_pk_add_f32 v[152:153], v[140:141], v[158:159]
	v_pk_add_f32 v[140:141], v[140:141], v[158:159] neg_lo:[0,1] neg_hi:[0,1]
	v_pk_add_f32 v[158:159], v[142:143], v[154:155] op_sel:[0,1] op_sel_hi:[1,0] neg_hi:[0,1]
	v_pk_add_f32 v[142:143], v[142:143], v[154:155] op_sel:[0,1] op_sel_hi:[1,0] neg_lo:[0,1]
	v_pk_add_f32 v[154:155], v[132:133], v[144:145]
	v_pk_add_f32 v[132:133], v[132:133], v[144:145] neg_lo:[0,1] neg_hi:[0,1]
	v_pk_add_f32 v[144:145], v[136:137], v[134:135] op_sel:[0,1] op_sel_hi:[1,0] neg_hi:[0,1]
	v_pk_add_f32 v[134:135], v[136:137], v[134:135] op_sel:[0,1] op_sel_hi:[1,0] neg_lo:[0,1]
	v_pk_add_f32 v[136:137], v[130:131], v[176:177]
	v_pk_mul_f32 v[120:121], v[54:55], v[52:53] op_sel:[0,1] op_sel_hi:[1,0]
	v_pk_mul_f32 v[124:125], v[34:35], v[52:53] op_sel:[0,1] op_sel_hi:[1,0]
	v_pk_mul_f32 v[34:35], v[34:35], v[136:137] op_sel:[0,1] op_sel_hi:[1,0]
	v_xor_b32_e32 v72, 0x80000000, v47
	v_mov_b32_e32 v73, v47
	v_pk_fma_f32 v[8:9], v[44:45], v[4:5], v[8:9] op_sel_hi:[0,1,1]
	v_pk_fma_f32 v[14:15], v[30:31], v[4:5], v[14:15] op_sel_hi:[0,1,1]
	v_xor_b32_e32 v22, 0x80000000, v5
	v_pk_fma_f32 v[32:33], v[44:45], v[10:11], v[32:33] op_sel_hi:[0,1,1]
	v_pk_fma_f32 v[40:41], v[30:31], v[10:11], v[40:41] op_sel_hi:[0,1,1]
	v_pk_fma_f32 v[62:63], v[44:45], v[20:21], v[62:63] op_sel_hi:[0,1,1]
	v_pk_fma_f32 v[66:67], v[30:31], v[20:21], v[66:67] op_sel_hi:[0,1,1]
	v_pk_fma_f32 v[78:79], v[44:45], v[26:27], v[78:79] op_sel_hi:[0,1,1]
	v_pk_fma_f32 v[82:83], v[30:31], v[26:27], v[82:83] op_sel_hi:[0,1,1]
	v_pk_fma_f32 v[92:93], v[44:45], v[36:37], v[92:93] op_sel_hi:[0,1,1]
	v_pk_fma_f32 v[96:97], v[30:31], v[36:37], v[96:97] op_sel_hi:[0,1,1]
	v_pk_fma_f32 v[106:107], v[44:45], v[48:49], v[106:107] op_sel_hi:[0,1,1]
	v_pk_fma_f32 v[110:111], v[30:31], v[48:49], v[110:111] op_sel_hi:[0,1,1]
	v_pk_fma_f32 v[120:121], v[44:45], v[52:53], v[120:121] op_sel_hi:[0,1,1]
	v_pk_fma_f32 v[124:125], v[30:31], v[52:53], v[124:125] op_sel_hi:[0,1,1]
	v_mov_b32_e32 v23, v5
	v_pk_add_f32 v[130:131], v[130:131], v[176:177] neg_lo:[0,1] neg_hi:[0,1]
	v_pk_add_f32 v[176:177], v[138:139], v[182:183] op_sel:[0,1] op_sel_hi:[1,0] neg_hi:[0,1]
	v_pk_add_f32 v[138:139], v[138:139], v[182:183] op_sel:[0,1] op_sel_hi:[1,0] neg_lo:[0,1]
	v_pk_add_f32 v[182:183], v[178:179], v[186:187]
	v_pk_add_f32 v[178:179], v[178:179], v[186:187] neg_lo:[0,1] neg_hi:[0,1]
	v_pk_add_f32 v[186:187], v[160:161], v[180:181] op_sel:[0,1] op_sel_hi:[1,0] neg_hi:[0,1]
	v_pk_add_f32 v[160:161], v[160:161], v[180:181] op_sel:[0,1] op_sel_hi:[1,0] neg_lo:[0,1]
	v_pk_add_f32 v[180:181], v[168:169], v[188:189]
	v_pk_fma_f32 v[30:31], v[30:31], v[136:137], v[34:35] op_sel_hi:[0,1,1]
	v_pk_mul_f32 v[34:35], v[54:55], v[152:153] op_sel:[0,1] op_sel_hi:[1,0]
	v_pk_mul_f32 v[2:3], v[72:73], v[4:5] op_sel:[0,1] op_sel_hi:[1,0]
	v_xor_b32_e32 v12, 0x80000000, v9
	v_pk_mul_f32 v[24:25], v[72:73], v[10:11] op_sel:[0,1] op_sel_hi:[1,0]
	v_xor_b32_e32 v38, 0x80000000, v33
	v_xor_b32_e32 v50, 0x80000000, v11
	v_pk_mul_f32 v[56:57], v[72:73], v[20:21] op_sel:[0,1] op_sel_hi:[1,0]
	v_xor_b32_e32 v64, 0x80000000, v63
	v_xor_b32_e32 v70, 0x80000000, v21
	v_pk_mul_f32 v[74:75], v[72:73], v[26:27] op_sel:[0,1] op_sel_hi:[1,0]
	v_xor_b32_e32 v80, 0x80000000, v79
	v_xor_b32_e32 v86, 0x80000000, v27
	v_pk_mul_f32 v[88:89], v[72:73], v[36:37] op_sel:[0,1] op_sel_hi:[1,0]
	v_xor_b32_e32 v94, 0x80000000, v93
	v_xor_b32_e32 v100, 0x80000000, v37
	v_pk_mul_f32 v[102:103], v[72:73], v[48:49] op_sel:[0,1] op_sel_hi:[1,0]
	v_xor_b32_e32 v108, 0x80000000, v107
	v_xor_b32_e32 v114, 0x80000000, v49
	v_pk_mul_f32 v[116:117], v[52:53], v[72:73] op_sel:[1,0] op_sel_hi:[0,1]
	v_xor_b32_e32 v122, 0x80000000, v121
	v_mov_b32_e32 v123, v121
	v_mov_b32_e32 v115, v49
	v_mov_b32_e32 v109, v107
	v_mov_b32_e32 v101, v37
	v_mov_b32_e32 v95, v93
	v_mov_b32_e32 v87, v27
	v_mov_b32_e32 v81, v79
	v_mov_b32_e32 v71, v21
	v_mov_b32_e32 v65, v63
	v_mov_b32_e32 v51, v11
	v_mov_b32_e32 v39, v33
	v_mov_b32_e32 v13, v9
	v_pk_fma_f32 v[34:35], v[44:45], v[152:153], v[34:35] op_sel_hi:[0,1,1]
	v_pk_mul_f32 v[44:45], v[72:73], v[180:181] op_sel:[0,1] op_sel_hi:[1,0]
	v_pk_mul_f32 v[22:23], v[150:151], v[22:23] op_sel:[1,0] op_sel_hi:[0,1]
	v_pk_fma_f32 v[2:3], v[46:47], v[4:5], v[2:3] op_sel_hi:[0,1,1]
	v_pk_fma_f32 v[24:25], v[46:47], v[10:11], v[24:25] op_sel_hi:[0,1,1]
	v_pk_fma_f32 v[56:57], v[46:47], v[20:21], v[56:57] op_sel_hi:[0,1,1]
	v_pk_fma_f32 v[74:75], v[46:47], v[26:27], v[74:75] op_sel_hi:[0,1,1]
	v_xor_b32_e32 v84, 0x80000000, v83
	v_pk_fma_f32 v[88:89], v[46:47], v[36:37], v[88:89] op_sel_hi:[0,1,1]
	v_pk_fma_f32 v[102:103], v[46:47], v[48:49], v[102:103] op_sel_hi:[0,1,1]
	v_pk_fma_f32 v[116:117], v[52:53], v[46:47], v[116:117] op_sel_hi:[1,0,1]
	v_mov_b32_e32 v85, v83
	v_pk_fma_f32 v[44:45], v[46:47], v[180:181], v[44:45] op_sel_hi:[0,1,1]
	v_pk_mul_f32 v[46:47], v[58:59], v[192:193] op_sel:[0,1] op_sel_hi:[1,0]
	v_pk_mul_f32 v[54:55], v[122:123], v[154:155] op_sel:[0,1] op_sel_hi:[1,0]
	v_pk_mul_f32 v[72:73], v[114:115], v[194:195] op_sel:[0,1] op_sel_hi:[1,0]
	v_pk_mul_f32 v[108:109], v[108:109], v[158:159] op_sel:[0,1] op_sel_hi:[1,0]
	v_pk_mul_f32 v[100:101], v[100:101], v[156:157] op_sel:[0,1] op_sel_hi:[1,0]
	v_pk_mul_f32 v[94:95], v[94:95], v[144:145] op_sel:[0,1] op_sel_hi:[1,0]
	v_pk_mul_f32 v[86:87], v[174:175], v[86:87] op_sel:[1,0] op_sel_hi:[0,1]
	v_pk_mul_f32 v[80:81], v[140:141], v[80:81] op_sel:[1,0] op_sel_hi:[0,1]
	v_pk_mul_f32 v[70:71], v[148:149], v[70:71] op_sel:[1,0] op_sel_hi:[0,1]
	v_pk_mul_f32 v[64:65], v[132:133], v[64:65] op_sel:[1,0] op_sel_hi:[0,1]
	v_pk_mul_f32 v[50:51], v[190:191], v[50:51] op_sel:[1,0] op_sel_hi:[0,1]
	v_pk_mul_f32 v[38:39], v[142:143], v[38:39] op_sel:[1,0] op_sel_hi:[0,1]
	v_pk_fma_f32 v[4:5], v[150:151], v[4:5], v[22:23] op_sel_hi:[1,0,1]
	v_pk_mul_f32 v[12:13], v[134:135], v[12:13] op_sel:[1,0] op_sel_hi:[0,1]
	v_xor_b32_e32 v112, 0x80000000, v111
	v_mov_b32_e32 v113, v111
	v_pk_fma_f32 v[46:47], v[52:53], v[192:193], v[46:47] op_sel_hi:[0,1,1]
	v_pk_fma_f32 v[54:55], v[120:121], v[154:155], v[54:55] op_sel_hi:[0,1,1]
	v_pk_fma_f32 v[48:49], v[48:49], v[194:195], v[72:73] op_sel_hi:[0,1,1]
	v_pk_fma_f32 v[106:107], v[106:107], v[158:159], v[108:109] op_sel_hi:[0,1,1]
	v_pk_fma_f32 v[36:37], v[36:37], v[156:157], v[100:101] op_sel_hi:[0,1,1]
	v_pk_fma_f32 v[92:93], v[92:93], v[144:145], v[94:95] op_sel_hi:[0,1,1]
	v_pk_fma_f32 v[26:27], v[174:175], v[26:27], v[86:87] op_sel_hi:[1,0,1]
	v_pk_mul_f32 v[84:85], v[130:131], v[84:85] op_sel:[1,0] op_sel_hi:[0,1]
	v_pk_fma_f32 v[78:79], v[140:141], v[78:79], v[80:81] op_sel_hi:[1,0,1]
	v_pk_fma_f32 v[20:21], v[148:149], v[20:21], v[70:71] op_sel_hi:[1,0,1]
	v_pk_fma_f32 v[62:63], v[132:133], v[62:63], v[64:65] op_sel_hi:[1,0,1]
	v_pk_fma_f32 v[10:11], v[190:191], v[10:11], v[50:51] op_sel_hi:[1,0,1]
	v_pk_fma_f32 v[32:33], v[142:143], v[32:33], v[38:39] op_sel_hi:[1,0,1]
	v_pk_fma_f32 v[8:9], v[134:135], v[8:9], v[12:13] op_sel_hi:[1,0,1]
	ds_write_b64 v18, v[162:163]
	ds_write_b64 v18, v[26:27] offset:4224
	ds_write_b64 v18, v[48:49] offset:8448
	ds_write_b64 v18, v[10:11] offset:12672
	ds_write_b64 v18, v[46:47] offset:16896
	ds_write_b64 v18, v[20:21] offset:21120
	ds_write_b64 v18, v[36:37] offset:25344
	ds_write_b64 v18, v[4:5] offset:29568
	ds_write_b64 v18, v[34:35] offset:33792
	ds_write_b64 v18, v[78:79] offset:38016
	ds_write_b64 v18, v[106:107] offset:42240
	ds_write_b64 v18, v[32:33] offset:46464
	ds_write_b64 v18, v[54:55] offset:50688
	ds_write_b64 v18, v[62:63] offset:54912
	ds_write_b64 v18, v[92:93] offset:59136
	ds_write_b64 v18, v[8:9] offset:63360
	v_add_u32_e32 v4, 0x10800, v18
	v_xor_b32_e32 v42, 0x80000000, v41
	v_mov_b32_e32 v43, v41
	v_pk_mul_f32 v[72:73], v[112:113], v[176:177] op_sel:[0,1] op_sel_hi:[1,0]
	v_pk_fma_f32 v[82:83], v[130:131], v[82:83], v[84:85] op_sel_hi:[1,0,1]
	ds_write_b64 v4, v[30:31]
	v_add_u32_e32 v4, 0x11880, v18
	v_xor_b32_e32 v126, 0x80000000, v125
	v_mov_b32_e32 v127, v125
	v_pk_fma_f32 v[72:73], v[110:111], v[176:177], v[72:73] op_sel_hi:[0,1,1]
	v_pk_mul_f32 v[42:43], v[138:139], v[42:43] op_sel:[1,0] op_sel_hi:[0,1]
	ds_write_b64 v4, v[82:83]
	v_add_u32_e32 v4, 0x12900, v18
	v_xor_b32_e32 v68, 0x80000000, v67
	v_mov_b32_e32 v69, v67
	v_pk_mul_f32 v[52:53], v[126:127], v[182:183] op_sel:[0,1] op_sel_hi:[1,0]
	v_pk_fma_f32 v[40:41], v[138:139], v[40:41], v[42:43] op_sel_hi:[1,0,1]
	ds_write_b64 v4, v[72:73]
	v_add_u32_e32 v4, 0x13980, v18
	v_xor_b32_e32 v98, 0x80000000, v97
	v_mov_b32_e32 v99, v97
	v_pk_fma_f32 v[52:53], v[124:125], v[182:183], v[52:53] op_sel_hi:[0,1,1]
	v_pk_mul_f32 v[68:69], v[178:179], v[68:69] op_sel:[1,0] op_sel_hi:[0,1]
	ds_write_b64 v4, v[40:41]
	v_add_u32_e32 v4, 0x14a00, v18
	v_xor_b32_e32 v16, 0x80000000, v15
	v_mov_b32_e32 v17, v15
	v_pk_mul_f32 v[98:99], v[98:99], v[186:187] op_sel:[0,1] op_sel_hi:[1,0]
	v_pk_fma_f32 v[66:67], v[178:179], v[66:67], v[68:69] op_sel_hi:[1,0,1]
	ds_write_b64 v4, v[52:53]
	v_add_u32_e32 v4, 0x15a80, v18
	v_pk_fma_f32 v[96:97], v[96:97], v[186:187], v[98:99] op_sel_hi:[0,1,1]
	v_pk_mul_f32 v[16:17], v[160:161], v[16:17] op_sel:[1,0] op_sel_hi:[0,1]
	ds_write_b64 v4, v[66:67]
	v_add_u32_e32 v4, 0x16b00, v18
	v_xor_b32_e32 v76, 0x80000000, v75
	v_mov_b32_e32 v77, v75
	v_pk_add_f32 v[168:169], v[168:169], v[188:189] neg_lo:[0,1] neg_hi:[0,1]
	v_pk_fma_f32 v[14:15], v[160:161], v[14:15], v[16:17] op_sel_hi:[1,0,1]
	ds_write_b64 v4, v[96:97]
	v_add_u32_e32 v4, 0x17b80, v18
	v_xor_b32_e32 v104, 0x80000000, v103
	v_mov_b32_e32 v105, v103
	v_pk_add_f32 v[188:189], v[170:171], v[184:185] op_sel:[0,1] op_sel_hi:[1,0] neg_hi:[0,1]
	v_pk_mul_f32 v[76:77], v[168:169], v[76:77] op_sel:[1,0] op_sel_hi:[0,1]
	ds_write_b64 v4, v[14:15]
	v_add_u32_e32 v4, 0x18c00, v18
	v_xor_b32_e32 v28, 0x80000000, v25
	v_mov_b32_e32 v29, v25
	v_pk_add_f32 v[170:171], v[170:171], v[184:185] op_sel:[0,1] op_sel_hi:[1,0] neg_lo:[0,1]
	v_pk_mul_f32 v[104:105], v[104:105], v[188:189] op_sel:[0,1] op_sel_hi:[1,0]
	v_pk_fma_f32 v[74:75], v[168:169], v[74:75], v[76:77] op_sel_hi:[1,0,1]
	ds_write_b64 v4, v[44:45]
	v_add_u32_e32 v4, 0x19c80, v18
	v_xor_b32_e32 v118, 0x80000000, v117
	v_mov_b32_e32 v119, v117
	v_pk_add_f32 v[184:185], v[164:165], v[172:173]
	v_pk_fma_f32 v[102:103], v[102:103], v[188:189], v[104:105] op_sel_hi:[0,1,1]
	v_pk_mul_f32 v[28:29], v[170:171], v[28:29] op_sel:[1,0] op_sel_hi:[0,1]
	ds_write_b64 v4, v[74:75]
	v_add_u32_e32 v4, 0x1ad00, v18
	v_xor_b32_e32 v60, 0x80000000, v57
	v_mov_b32_e32 v61, v57
	v_pk_add_f32 v[164:165], v[164:165], v[172:173] neg_lo:[0,1] neg_hi:[0,1]
	v_pk_mul_f32 v[58:59], v[118:119], v[184:185] op_sel:[0,1] op_sel_hi:[1,0]
	v_pk_fma_f32 v[24:25], v[170:171], v[24:25], v[28:29] op_sel_hi:[1,0,1]
	ds_write_b64 v4, v[102:103]
	v_add_u32_e32 v4, 0x1bd80, v18
	v_xor_b32_e32 v90, 0x80000000, v89
	v_mov_b32_e32 v91, v89
	v_pk_add_f32 v[172:173], v[128:129], v[166:167] op_sel:[0,1] op_sel_hi:[1,0] neg_hi:[0,1]
	v_pk_fma_f32 v[58:59], v[116:117], v[184:185], v[58:59] op_sel_hi:[0,1,1]
	v_pk_mul_f32 v[60:61], v[164:165], v[60:61] op_sel:[1,0] op_sel_hi:[0,1]
	ds_write_b64 v4, v[24:25]
	v_add_u32_e32 v4, 0x1ce00, v18
	v_xor_b32_e32 v6, 0x80000000, v3
	v_mov_b32_e32 v7, v3
	v_pk_add_f32 v[128:129], v[128:129], v[166:167] op_sel:[0,1] op_sel_hi:[1,0] neg_lo:[0,1]
	v_pk_mul_f32 v[90:91], v[90:91], v[172:173] op_sel:[0,1] op_sel_hi:[1,0]
	v_pk_fma_f32 v[56:57], v[164:165], v[56:57], v[60:61] op_sel_hi:[1,0,1]
	ds_write_b64 v4, v[58:59]
	v_add_u32_e32 v4, 0x1de80, v18
	v_pk_fma_f32 v[88:89], v[88:89], v[172:173], v[90:91] op_sel_hi:[0,1,1]
	v_pk_mul_f32 v[6:7], v[128:129], v[6:7] op_sel:[1,0] op_sel_hi:[0,1]
	ds_write_b64 v4, v[56:57]
	v_add_u32_e32 v4, 0x1ef00, v18
	v_pk_fma_f32 v[2:3], v[128:129], v[2:3], v[6:7] op_sel_hi:[1,0,1]
	ds_write_b64 v4, v[88:89]
	v_add_u32_e32 v4, 0x1ff80, v18
	ds_write_b64 v4, v[2:3]
	v_mov_b32_e32 v2, v210
	s_waitcnt lgkmcnt(0)
	s_barrier
	s_ashr_i32 s77, s76, 31
	v_and_b32_e32 v3, 15, v2
	v_lshlrev_b32_e32 v2, 5, v2
	v_and_b32_e32 v4, 0xfffffe00, v2
	v_lshl_add_u32 v5, v4, 3, 0
	v_lshlrev_b32_e32 v6, 3, v3
	v_ashrrev_i32_e32 v7, 2, v4
	v_add3_u32 v18, v5, v6, v7
	v_add_u32_e32 v196, 0x800, v18
	ds_read2_b64 v[128:131], v18 offset1:16
	ds_read2_b64 v[132:135], v18 offset0:33 offset1:49
	ds_read2_b64 v[136:139], v18 offset0:66 offset1:82
	ds_read2_b64 v[140:143], v18 offset0:99 offset1:115
	ds_read2_b64 v[148:151], v18 offset0:132 offset1:148
	ds_read2_b64 v[152:155], v18 offset0:165 offset1:181
	ds_read2_b64 v[156:159], v18 offset0:198 offset1:214
	ds_read2_b64 v[160:163], v18 offset0:231 offset1:247
	ds_read2_b64 v[164:167], v196 offset0:8 offset1:24
	ds_read2_b64 v[168:171], v196 offset0:41 offset1:57
	ds_read2_b64 v[172:175], v196 offset0:74 offset1:90
	ds_read2_b64 v[176:179], v196 offset0:107 offset1:123
	ds_read2_b64 v[180:183], v196 offset0:140 offset1:156
	ds_read2_b64 v[184:187], v196 offset0:173 offset1:189
	ds_read2_b64 v[188:191], v196 offset0:206 offset1:222
	ds_read2_b64 v[192:195], v196 offset0:239 offset1:255
	s_waitcnt lgkmcnt(7)
	v_pk_add_f32 v[144:145], v[128:129], v[164:165]
	v_pk_add_f32 v[128:129], v[128:129], v[164:165] neg_lo:[0,1] neg_hi:[0,1]
	v_pk_add_f32 v[164:165], v[130:131], v[166:167]
	v_pk_add_f32 v[130:131], v[130:131], v[166:167] neg_lo:[0,1] neg_hi:[0,1]
	v_cvt_f32_ubyte0_e32 v2, v3
	v_pk_mul_f32 v[166:167], v[130:131], s[10:11]
	v_mul_f32_e32 v3, 0x3b000000, v2
	v_pk_fma_f32 v[130:131], v[130:131], s[8:9], v[166:167] op_sel:[0,0,1] op_sel_hi:[1,0,0]
	s_waitcnt lgkmcnt(6)
	v_pk_add_f32 v[166:167], v[132:133], v[168:169]
	v_pk_add_f32 v[132:133], v[132:133], v[168:169] neg_lo:[0,1] neg_hi:[0,1]
	v_sin_f32_e32 v2, v3
	v_pk_mul_f32 v[168:169], v[132:133], s[18:19]
	v_cos_f32_e32 v4, v3
	v_pk_fma_f32 v[132:133], v[132:133], s[16:17], v[168:169] op_sel:[0,0,1] op_sel_hi:[1,0,0]
	v_pk_add_f32 v[168:169], v[134:135], v[170:171]
	v_pk_add_f32 v[134:135], v[134:135], v[170:171] neg_lo:[0,1] neg_hi:[0,1]
	v_xor_b32_e32 v5, 0x80000000, v2
	v_pk_mul_f32 v[170:171], v[134:135], s[26:27]
	v_mov_b32_e32 v3, v5
	v_pk_fma_f32 v[134:135], v[134:135], s[24:25], v[170:171] op_sel:[0,0,1] op_sel_hi:[1,0,0]
	s_waitcnt lgkmcnt(5)
	v_pk_add_f32 v[170:171], v[136:137], v[172:173]
	v_pk_add_f32 v[136:137], v[136:137], v[172:173] neg_lo:[0,1] neg_hi:[0,1]
	v_pk_mul_f32 v[6:7], v[4:5], v[2:3] op_sel:[1,0] op_sel_hi:[0,1]
	v_pk_mul_f32 v[172:173], v[136:137], s[36:37]
	v_pk_fma_f32 v[6:7], v[4:5], v[4:5], v[6:7] op_sel_hi:[1,0,1]
	v_pk_fma_f32 v[136:137], v[136:137], s[78:79], v[172:173] op_sel:[0,0,1] op_sel_hi:[1,0,0]
	v_pk_add_f32 v[172:173], v[138:139], v[174:175]
	v_pk_add_f32 v[138:139], v[138:139], v[174:175] neg_lo:[0,1] neg_hi:[0,1]
	v_xor_b32_e32 v12, 0x80000000, v7
	v_pk_mul_f32 v[174:175], v[138:139], s[38:39]
	v_mov_b32_e32 v13, v7
	v_pk_fma_f32 v[138:139], v[138:139], s[0:1], v[174:175] op_sel:[0,0,1] op_sel_hi:[1,0,0]
	s_waitcnt lgkmcnt(4)
	v_pk_add_f32 v[174:175], v[140:141], v[176:177]
	v_pk_add_f32 v[140:141], v[140:141], v[176:177] neg_lo:[0,1] neg_hi:[0,1]
	v_pk_mul_f32 v[10:11], v[6:7], v[12:13] op_sel:[1,0] op_sel_hi:[0,1]
	v_pk_mul_f32 v[176:177], v[140:141], s[40:41]
	v_pk_fma_f32 v[10:11], v[6:7], v[6:7], v[10:11] op_sel_hi:[1,0,1]
	v_pk_fma_f32 v[140:141], v[140:141], s[80:81], v[176:177] op_sel:[0,0,1] op_sel_hi:[1,0,0]
	v_pk_add_f32 v[176:177], v[142:143], v[178:179]
	v_pk_add_f32 v[142:143], v[142:143], v[178:179] neg_lo:[0,1] neg_hi:[0,1]
	v_xor_b32_e32 v14, 0x80000000, v11
	v_pk_mul_f32 v[178:179], v[142:143], s[42:43]
	v_mov_b32_e32 v15, v11
	v_pk_fma_f32 v[142:143], v[142:143], s[74:75], v[178:179] op_sel:[0,0,1] op_sel_hi:[1,0,0]
	s_waitcnt lgkmcnt(3)
	v_pk_add_f32 v[178:179], v[148:149], v[180:181]
	v_pk_add_f32 v[180:181], v[148:149], v[180:181] neg_lo:[0,1] neg_hi:[0,1]
	v_pk_mul_f32 v[28:29], v[10:11], v[14:15] op_sel:[1,0] op_sel_hi:[0,1]
	v_pk_add_f32 v[148:149], v[150:151], v[182:183]
	v_pk_add_f32 v[150:151], v[150:151], v[182:183] neg_lo:[0,1] neg_hi:[0,1]
	v_pk_fma_f32 v[28:29], v[10:11], v[10:11], v[28:29] op_sel_hi:[1,0,1]
	v_pk_mul_f32 v[182:183], v[150:151], s[42:43]
	v_pk_mul_f32 v[44:45], v[14:15], v[28:29] op_sel:[0,1] op_sel_hi:[1,0]
	v_pk_fma_f32 v[150:151], v[150:151], s[74:75], v[182:183] op_sel:[0,0,1] op_sel_hi:[1,0,0] neg_lo:[1,0,0] neg_hi:[1,0,0]
	s_waitcnt lgkmcnt(2)
	v_pk_add_f32 v[182:183], v[152:153], v[184:185]
	v_pk_add_f32 v[152:153], v[152:153], v[184:185] neg_lo:[0,1] neg_hi:[0,1]
	v_pk_fma_f32 v[44:45], v[10:11], v[28:29], v[44:45] op_sel_hi:[0,1,1]
	v_pk_mul_f32 v[184:185], v[152:153], s[40:41]
	v_pk_mul_f32 v[60:61], v[14:15], v[44:45] op_sel:[0,1] op_sel_hi:[1,0]
	v_pk_fma_f32 v[152:153], v[152:153], s[80:81], v[184:185] op_sel:[0,0,1] op_sel_hi:[1,0,0] neg_lo:[1,0,0] neg_hi:[1,0,0]
	v_pk_add_f32 v[184:185], v[154:155], v[186:187]
	v_pk_add_f32 v[154:155], v[154:155], v[186:187] neg_lo:[0,1] neg_hi:[0,1]
	v_pk_fma_f32 v[60:61], v[10:11], v[44:45], v[60:61] op_sel_hi:[0,1,1]
	v_pk_mul_f32 v[186:187], v[154:155], s[38:39]
	v_pk_mul_f32 v[76:77], v[14:15], v[60:61] op_sel:[0,1] op_sel_hi:[1,0]
	v_pk_fma_f32 v[154:155], v[154:155], s[0:1], v[186:187] op_sel:[0,0,1] op_sel_hi:[1,0,0] neg_lo:[1,0,0] neg_hi:[1,0,0]
	s_waitcnt lgkmcnt(1)
	v_pk_add_f32 v[186:187], v[156:157], v[188:189]
	v_pk_add_f32 v[156:157], v[156:157], v[188:189] neg_lo:[0,1] neg_hi:[0,1]
	v_pk_fma_f32 v[76:77], v[10:11], v[60:61], v[76:77] op_sel_hi:[0,1,1]
	v_pk_mul_f32 v[188:189], v[156:157], s[36:37]
	v_pk_mul_f32 v[92:93], v[14:15], v[76:77] op_sel:[0,1] op_sel_hi:[1,0]
	v_pk_fma_f32 v[156:157], v[156:157], s[78:79], v[188:189] op_sel:[0,0,1] op_sel_hi:[1,0,0] neg_lo:[1,0,0] neg_hi:[1,0,0]
	v_pk_add_f32 v[188:189], v[158:159], v[190:191]
	v_pk_add_f32 v[158:159], v[158:159], v[190:191] neg_lo:[0,1] neg_hi:[0,1]
	v_pk_fma_f32 v[92:93], v[10:11], v[76:77], v[92:93] op_sel_hi:[0,1,1]
	v_pk_mul_f32 v[190:191], v[158:159], s[26:27]
	v_pk_mul_f32 v[108:109], v[14:15], v[92:93] op_sel:[0,1] op_sel_hi:[1,0]
	v_pk_fma_f32 v[158:159], v[158:159], s[24:25], v[190:191] op_sel:[0,0,1] op_sel_hi:[1,0,0] neg_lo:[1,0,0] neg_hi:[1,0,0]
	s_waitcnt lgkmcnt(0)
	v_pk_add_f32 v[190:191], v[160:161], v[192:193]
	v_pk_add_f32 v[160:161], v[160:161], v[192:193] neg_lo:[0,1] neg_hi:[0,1]
	v_pk_mul_f32 v[8:9], v[2:3], v[6:7] op_sel:[0,1] op_sel_hi:[1,0]
	v_pk_mul_f32 v[192:193], v[160:161], s[18:19]
	v_pk_fma_f32 v[108:109], v[10:11], v[92:93], v[108:109] op_sel_hi:[0,1,1]
	v_pk_fma_f32 v[160:161], v[160:161], s[16:17], v[192:193] op_sel:[0,0,1] op_sel_hi:[1,0,0] neg_lo:[1,0,0] neg_hi:[1,0,0]
	v_pk_add_f32 v[192:193], v[162:163], v[194:195]
	v_pk_add_f32 v[162:163], v[162:163], v[194:195] neg_lo:[0,1] neg_hi:[0,1]
	v_pk_fma_f32 v[8:9], v[4:5], v[6:7], v[8:9] op_sel_hi:[0,1,1]
	v_pk_mul_f32 v[194:195], v[162:163], s[10:11]
	v_pk_mul_f32 v[16:17], v[2:3], v[10:11] op_sel:[0,1] op_sel_hi:[1,0]
	v_pk_fma_f32 v[162:163], v[162:163], s[8:9], v[194:195] op_sel:[0,0,1] op_sel_hi:[1,0,0] neg_lo:[1,0,0] neg_hi:[1,0,0]
	v_pk_add_f32 v[194:195], v[144:145], v[178:179]
	v_pk_add_f32 v[144:145], v[144:145], v[178:179] neg_lo:[0,1] neg_hi:[0,1]
	v_pk_add_f32 v[178:179], v[164:165], v[148:149]
	v_pk_add_f32 v[148:149], v[164:165], v[148:149] neg_lo:[0,1] neg_hi:[0,1]
	v_pk_mul_f32 v[32:33], v[2:3], v[28:29] op_sel:[0,1] op_sel_hi:[1,0]
	v_pk_mul_f32 v[164:165], v[148:149], s[18:19]
	v_pk_mul_f32 v[48:49], v[2:3], v[44:45] op_sel:[0,1] op_sel_hi:[1,0]
	v_pk_fma_f32 v[148:149], v[148:149], s[16:17], v[164:165] op_sel:[0,0,1] op_sel_hi:[1,0,0]
	v_pk_add_f32 v[164:165], v[166:167], v[182:183]
	v_pk_add_f32 v[166:167], v[166:167], v[182:183] neg_lo:[0,1] neg_hi:[0,1]
	v_pk_mul_f32 v[64:65], v[2:3], v[60:61] op_sel:[0,1] op_sel_hi:[1,0]
	v_pk_mul_f32 v[182:183], v[166:167], s[36:37]
	v_pk_mul_f32 v[80:81], v[2:3], v[76:77] op_sel:[0,1] op_sel_hi:[1,0]
	v_pk_fma_f32 v[166:167], v[166:167], s[78:79], v[182:183] op_sel:[0,0,1] op_sel_hi:[1,0,0]
	v_pk_add_f32 v[182:183], v[168:169], v[184:185]
	v_pk_add_f32 v[168:169], v[168:169], v[184:185] neg_lo:[0,1] neg_hi:[0,1]
	v_pk_mul_f32 v[96:97], v[2:3], v[92:93] op_sel:[0,1] op_sel_hi:[1,0]
	v_pk_mul_f32 v[184:185], v[168:169], s[40:41]
	v_pk_mul_f32 v[112:113], v[2:3], v[108:109] op_sel:[0,1] op_sel_hi:[1,0]
	v_pk_fma_f32 v[168:169], v[168:169], s[80:81], v[184:185] op_sel:[0,0,1] op_sel_hi:[1,0,0]
	v_pk_add_f32 v[184:185], v[170:171], v[186:187]
	v_pk_add_f32 v[186:187], v[170:171], v[186:187] neg_lo:[0,1] neg_hi:[0,1]
	v_xor_b32_e32 v22, 0x80000000, v9
	v_pk_add_f32 v[170:171], v[172:173], v[188:189]
	v_pk_add_f32 v[172:173], v[172:173], v[188:189] neg_lo:[0,1] neg_hi:[0,1]
	v_mov_b32_e32 v23, v9
	v_pk_mul_f32 v[188:189], v[172:173], s[40:41]
	v_pk_fma_f32 v[16:17], v[4:5], v[10:11], v[16:17] op_sel_hi:[0,1,1]
	v_pk_fma_f32 v[172:173], v[172:173], s[80:81], v[188:189] op_sel:[0,0,1] op_sel_hi:[1,0,0] neg_lo:[1,0,0] neg_hi:[1,0,0]
	v_pk_add_f32 v[188:189], v[174:175], v[190:191]
	v_pk_add_f32 v[174:175], v[174:175], v[190:191] neg_lo:[0,1] neg_hi:[0,1]
	v_pk_mul_f32 v[20:21], v[12:13], v[10:11] op_sel:[0,1] op_sel_hi:[1,0]
	v_pk_mul_f32 v[190:191], v[174:175], s[36:37]
	v_pk_fma_f32 v[32:33], v[4:5], v[28:29], v[32:33] op_sel_hi:[0,1,1]
	v_pk_fma_f32 v[174:175], v[174:175], s[78:79], v[190:191] op_sel:[0,0,1] op_sel_hi:[1,0,0] neg_lo:[1,0,0] neg_hi:[1,0,0]
	v_pk_add_f32 v[190:191], v[176:177], v[192:193]
	v_pk_add_f32 v[176:177], v[176:177], v[192:193] neg_lo:[0,1] neg_hi:[0,1]
	v_pk_mul_f32 v[36:37], v[12:13], v[28:29] op_sel:[0,1] op_sel_hi:[1,0]
	v_pk_mul_f32 v[192:193], v[176:177], s[18:19]
	v_pk_fma_f32 v[48:49], v[4:5], v[44:45], v[48:49] op_sel_hi:[0,1,1]
	v_pk_fma_f32 v[176:177], v[176:177], s[16:17], v[192:193] op_sel:[0,0,1] op_sel_hi:[1,0,0] neg_lo:[1,0,0] neg_hi:[1,0,0]
	v_pk_add_f32 v[192:193], v[128:129], v[180:181] op_sel:[0,1] op_sel_hi:[1,0] neg_hi:[0,1]
	v_pk_add_f32 v[128:129], v[128:129], v[180:181] op_sel:[0,1] op_sel_hi:[1,0] neg_lo:[0,1]
	v_pk_add_f32 v[180:181], v[130:131], v[150:151]
	v_pk_add_f32 v[130:131], v[130:131], v[150:151] neg_lo:[0,1] neg_hi:[0,1]
	v_pk_mul_f32 v[52:53], v[12:13], v[44:45] op_sel:[0,1] op_sel_hi:[1,0]
	v_pk_mul_f32 v[150:151], v[130:131], s[18:19]
	v_pk_fma_f32 v[64:65], v[4:5], v[60:61], v[64:65] op_sel_hi:[0,1,1]
	v_pk_fma_f32 v[130:131], v[130:131], s[16:17], v[150:151] op_sel:[0,0,1] op_sel_hi:[1,0,0]
	v_pk_add_f32 v[150:151], v[132:133], v[152:153]
	v_pk_add_f32 v[132:133], v[132:133], v[152:153] neg_lo:[0,1] neg_hi:[0,1]
	v_pk_mul_f32 v[68:69], v[12:13], v[60:61] op_sel:[0,1] op_sel_hi:[1,0]
	v_pk_mul_f32 v[152:153], v[132:133], s[36:37]
	v_pk_fma_f32 v[80:81], v[4:5], v[76:77], v[80:81] op_sel_hi:[0,1,1]
	v_pk_fma_f32 v[132:133], v[132:133], s[78:79], v[152:153] op_sel:[0,0,1] op_sel_hi:[1,0,0]
	v_pk_add_f32 v[152:153], v[134:135], v[154:155]
	v_pk_add_f32 v[134:135], v[134:135], v[154:155] neg_lo:[0,1] neg_hi:[0,1]
	v_pk_mul_f32 v[84:85], v[12:13], v[76:77] op_sel:[0,1] op_sel_hi:[1,0]
	v_pk_mul_f32 v[154:155], v[134:135], s[40:41]
	v_pk_fma_f32 v[96:97], v[4:5], v[92:93], v[96:97] op_sel_hi:[0,1,1]
	v_pk_fma_f32 v[134:135], v[134:135], s[80:81], v[154:155] op_sel:[0,0,1] op_sel_hi:[1,0,0]
	v_pk_add_f32 v[154:155], v[136:137], v[156:157]
	v_pk_add_f32 v[156:157], v[136:137], v[156:157] neg_lo:[0,1] neg_hi:[0,1]
	v_pk_mul_f32 v[100:101], v[12:13], v[92:93] op_sel:[0,1] op_sel_hi:[1,0]
	v_pk_add_f32 v[136:137], v[138:139], v[158:159]
	v_pk_add_f32 v[138:139], v[138:139], v[158:159] neg_lo:[0,1] neg_hi:[0,1]
	v_pk_fma_f32 v[112:113], v[4:5], v[108:109], v[112:113] op_sel_hi:[0,1,1]
	v_pk_mul_f32 v[158:159], v[138:139], s[40:41]
	v_pk_mul_f32 v[116:117], v[12:13], v[108:109] op_sel:[0,1] op_sel_hi:[1,0]
	v_pk_fma_f32 v[138:139], v[138:139], s[80:81], v[158:159] op_sel:[0,0,1] op_sel_hi:[1,0,0] neg_lo:[1,0,0] neg_hi:[1,0,0]
	v_pk_add_f32 v[158:159], v[140:141], v[160:161]
	v_pk_add_f32 v[140:141], v[140:141], v[160:161] neg_lo:[0,1] neg_hi:[0,1]
	v_pk_fma_f32 v[20:21], v[6:7], v[10:11], v[20:21] op_sel_hi:[0,1,1]
	v_pk_mul_f32 v[160:161], v[140:141], s[36:37]
	v_pk_mul_f32 v[24:25], v[10:11], v[22:23] op_sel:[1,0] op_sel_hi:[0,1]
	v_pk_fma_f32 v[140:141], v[140:141], s[78:79], v[160:161] op_sel:[0,0,1] op_sel_hi:[1,0,0] neg_lo:[1,0,0] neg_hi:[1,0,0]
	v_pk_add_f32 v[160:161], v[142:143], v[162:163]
	v_pk_add_f32 v[142:143], v[142:143], v[162:163] neg_lo:[0,1] neg_hi:[0,1]
	v_pk_fma_f32 v[36:37], v[6:7], v[28:29], v[36:37] op_sel_hi:[0,1,1]
	v_pk_mul_f32 v[162:163], v[142:143], s[18:19]
	v_pk_mul_f32 v[40:41], v[22:23], v[28:29] op_sel:[0,1] op_sel_hi:[1,0]
	v_pk_fma_f32 v[142:143], v[142:143], s[16:17], v[162:163] op_sel:[0,0,1] op_sel_hi:[1,0,0] neg_lo:[1,0,0] neg_hi:[1,0,0]
	v_pk_add_f32 v[162:163], v[194:195], v[184:185]
	v_pk_add_f32 v[184:185], v[194:195], v[184:185] neg_lo:[0,1] neg_hi:[0,1]
	v_pk_add_f32 v[194:195], v[178:179], v[170:171]
	v_pk_add_f32 v[170:171], v[178:179], v[170:171] neg_lo:[0,1] neg_hi:[0,1]
	v_pk_fma_f32 v[52:53], v[6:7], v[44:45], v[52:53] op_sel_hi:[0,1,1]
	v_pk_mul_f32 v[178:179], v[170:171], s[36:37]
	v_pk_mul_f32 v[56:57], v[22:23], v[44:45] op_sel:[0,1] op_sel_hi:[1,0]
	v_pk_fma_f32 v[170:171], v[170:171], s[78:79], v[178:179] op_sel:[0,0,1] op_sel_hi:[1,0,0]
	v_pk_add_f32 v[178:179], v[164:165], v[188:189]
	v_pk_add_f32 v[188:189], v[164:165], v[188:189] neg_lo:[0,1] neg_hi:[0,1]
	v_pk_fma_f32 v[68:69], v[6:7], v[60:61], v[68:69] op_sel_hi:[0,1,1]
	v_pk_add_f32 v[164:165], v[182:183], v[190:191]
	v_pk_add_f32 v[182:183], v[182:183], v[190:191] neg_lo:[0,1] neg_hi:[0,1]
	v_pk_mul_f32 v[72:73], v[22:23], v[60:61] op_sel:[0,1] op_sel_hi:[1,0]
	v_pk_mul_f32 v[190:191], v[182:183], s[36:37]
	v_pk_fma_f32 v[84:85], v[6:7], v[76:77], v[84:85] op_sel_hi:[0,1,1]
	v_pk_fma_f32 v[182:183], v[182:183], s[78:79], v[190:191] op_sel:[0,0,1] op_sel_hi:[1,0,0] neg_lo:[1,0,0] neg_hi:[1,0,0]
	v_pk_add_f32 v[190:191], v[144:145], v[186:187] op_sel:[0,1] op_sel_hi:[1,0] neg_hi:[0,1]
	v_pk_add_f32 v[144:145], v[144:145], v[186:187] op_sel:[0,1] op_sel_hi:[1,0] neg_lo:[0,1]
	v_pk_add_f32 v[186:187], v[148:149], v[172:173]
	v_pk_add_f32 v[148:149], v[148:149], v[172:173] neg_lo:[0,1] neg_hi:[0,1]
	v_pk_mul_f32 v[88:89], v[22:23], v[76:77] op_sel:[0,1] op_sel_hi:[1,0]
	v_pk_mul_f32 v[172:173], v[148:149], s[36:37]
	v_pk_fma_f32 v[100:101], v[6:7], v[92:93], v[100:101] op_sel_hi:[0,1,1]
	v_pk_fma_f32 v[148:149], v[148:149], s[78:79], v[172:173] op_sel:[0,0,1] op_sel_hi:[1,0,0]
	v_pk_add_f32 v[172:173], v[166:167], v[174:175]
	v_pk_add_f32 v[174:175], v[166:167], v[174:175] neg_lo:[0,1] neg_hi:[0,1]
	v_pk_mul_f32 v[104:105], v[22:23], v[92:93] op_sel:[0,1] op_sel_hi:[1,0]
	v_pk_add_f32 v[166:167], v[168:169], v[176:177]
	v_pk_add_f32 v[168:169], v[168:169], v[176:177] neg_lo:[0,1] neg_hi:[0,1]
	v_pk_fma_f32 v[116:117], v[6:7], v[108:109], v[116:117] op_sel_hi:[0,1,1]
	v_pk_mul_f32 v[176:177], v[168:169], s[36:37]
	v_pk_mul_f32 v[120:121], v[22:23], v[108:109] op_sel:[0,1] op_sel_hi:[1,0]
	v_pk_fma_f32 v[168:169], v[168:169], s[78:79], v[176:177] op_sel:[0,0,1] op_sel_hi:[1,0,0] neg_lo:[1,0,0] neg_hi:[1,0,0]
	v_pk_add_f32 v[176:177], v[192:193], v[154:155]
	v_pk_add_f32 v[154:155], v[192:193], v[154:155] neg_lo:[0,1] neg_hi:[0,1]
	v_pk_add_f32 v[192:193], v[180:181], v[136:137]
	v_pk_add_f32 v[136:137], v[180:181], v[136:137] neg_lo:[0,1] neg_hi:[0,1]
	v_xor_b32_e32 v26, 0x80000000, v17
	v_pk_mul_f32 v[180:181], v[136:137], s[36:37]
	v_xor_b32_e32 v30, 0x80000000, v21
	v_pk_fma_f32 v[136:137], v[136:137], s[78:79], v[180:181] op_sel:[0,0,1] op_sel_hi:[1,0,0]
	v_pk_add_f32 v[180:181], v[150:151], v[158:159]
	v_pk_add_f32 v[158:159], v[150:151], v[158:159] neg_lo:[0,1] neg_hi:[0,1]
	v_pk_fma_f32 v[24:25], v[10:11], v[8:9], v[24:25] op_sel_hi:[1,0,1]
	v_pk_add_f32 v[150:151], v[152:153], v[160:161]
	v_pk_add_f32 v[152:153], v[152:153], v[160:161] neg_lo:[0,1] neg_hi:[0,1]
	v_pk_fma_f32 v[40:41], v[8:9], v[28:29], v[40:41] op_sel_hi:[0,1,1]
	v_pk_mul_f32 v[160:161], v[152:153], s[36:37]
	v_pk_fma_f32 v[56:57], v[8:9], v[44:45], v[56:57] op_sel_hi:[0,1,1]
	v_pk_fma_f32 v[152:153], v[152:153], s[78:79], v[160:161] op_sel:[0,0,1] op_sel_hi:[1,0,0] neg_lo:[1,0,0] neg_hi:[1,0,0]
	v_pk_add_f32 v[160:161], v[128:129], v[156:157] op_sel:[0,1] op_sel_hi:[1,0] neg_hi:[0,1]
	v_pk_add_f32 v[128:129], v[128:129], v[156:157] op_sel:[0,1] op_sel_hi:[1,0] neg_lo:[0,1]
	v_pk_add_f32 v[156:157], v[130:131], v[138:139]
	v_pk_add_f32 v[130:131], v[130:131], v[138:139] neg_lo:[0,1] neg_hi:[0,1]
	v_pk_fma_f32 v[72:73], v[8:9], v[60:61], v[72:73] op_sel_hi:[0,1,1]
	v_pk_mul_f32 v[138:139], v[130:131], s[36:37]
	v_pk_fma_f32 v[88:89], v[8:9], v[76:77], v[88:89] op_sel_hi:[0,1,1]
	v_pk_fma_f32 v[130:131], v[130:131], s[78:79], v[138:139] op_sel:[0,0,1] op_sel_hi:[1,0,0]
	v_pk_add_f32 v[138:139], v[132:133], v[140:141]
	v_pk_add_f32 v[140:141], v[132:133], v[140:141] neg_lo:[0,1] neg_hi:[0,1]
	v_pk_fma_f32 v[104:105], v[8:9], v[92:93], v[104:105] op_sel_hi:[0,1,1]
	v_pk_add_f32 v[132:133], v[134:135], v[142:143]
	v_pk_add_f32 v[134:135], v[134:135], v[142:143] neg_lo:[0,1] neg_hi:[0,1]
	v_pk_fma_f32 v[120:121], v[8:9], v[108:109], v[120:121] op_sel_hi:[0,1,1]
	v_pk_mul_f32 v[142:143], v[134:135], s[36:37]
	v_mov_b32_e32 v27, v17
	v_pk_fma_f32 v[134:135], v[134:135], s[78:79], v[142:143] op_sel:[0,0,1] op_sel_hi:[1,0,0] neg_lo:[1,0,0] neg_hi:[1,0,0]
	v_pk_add_f32 v[142:143], v[162:163], v[178:179]
	v_pk_add_f32 v[162:163], v[162:163], v[178:179] neg_lo:[0,1] neg_hi:[0,1]
	v_pk_add_f32 v[178:179], v[194:195], v[164:165]
	v_pk_add_f32 v[194:195], v[194:195], v[164:165] neg_lo:[0,1] neg_hi:[0,1]
	v_mov_b32_e32 v31, v21
	v_pk_add_f32 v[164:165], v[184:185], v[188:189] op_sel:[0,1] op_sel_hi:[1,0] neg_hi:[0,1]
	v_pk_add_f32 v[184:185], v[184:185], v[188:189] op_sel:[0,1] op_sel_hi:[1,0] neg_lo:[0,1]
	v_pk_add_f32 v[188:189], v[170:171], v[182:183]
	v_pk_add_f32 v[182:183], v[170:171], v[182:183] neg_lo:[0,1] neg_hi:[0,1]
	v_xor_b32_e32 v34, 0x80000000, v25
	v_pk_add_f32 v[170:171], v[190:191], v[172:173]
	v_pk_add_f32 v[172:173], v[190:191], v[172:173] neg_lo:[0,1] neg_hi:[0,1]
	v_pk_add_f32 v[190:191], v[186:187], v[166:167]
	v_pk_add_f32 v[186:187], v[186:187], v[166:167] neg_lo:[0,1] neg_hi:[0,1]
	v_xor_b32_e32 v38, 0x80000000, v29
	v_pk_add_f32 v[166:167], v[144:145], v[174:175] op_sel:[0,1] op_sel_hi:[1,0] neg_hi:[0,1]
	v_pk_add_f32 v[144:145], v[144:145], v[174:175] op_sel:[0,1] op_sel_hi:[1,0] neg_lo:[0,1]
	v_pk_add_f32 v[174:175], v[148:149], v[168:169]
	v_pk_add_f32 v[168:169], v[148:149], v[168:169] neg_lo:[0,1] neg_hi:[0,1]
	v_xor_b32_e32 v42, 0x80000000, v33
	v_pk_add_f32 v[148:149], v[176:177], v[180:181]
	v_pk_add_f32 v[176:177], v[176:177], v[180:181] neg_lo:[0,1] neg_hi:[0,1]
	v_pk_add_f32 v[180:181], v[192:193], v[150:151]
	v_pk_add_f32 v[192:193], v[192:193], v[150:151] neg_lo:[0,1] neg_hi:[0,1]
	v_xor_b32_e32 v46, 0x80000000, v37
	v_pk_add_f32 v[150:151], v[154:155], v[158:159] op_sel:[0,1] op_sel_hi:[1,0] neg_hi:[0,1]
	v_pk_add_f32 v[154:155], v[154:155], v[158:159] op_sel:[0,1] op_sel_hi:[1,0] neg_lo:[0,1]
	v_pk_add_f32 v[158:159], v[136:137], v[152:153]
	v_pk_add_f32 v[152:153], v[136:137], v[152:153] neg_lo:[0,1] neg_hi:[0,1]
	v_mov_b32_e32 v35, v25
	v_pk_add_f32 v[136:137], v[160:161], v[138:139]
	v_pk_add_f32 v[138:139], v[160:161], v[138:139] neg_lo:[0,1] neg_hi:[0,1]
	v_pk_add_f32 v[160:161], v[156:157], v[132:133]
	v_pk_add_f32 v[156:157], v[156:157], v[132:133] neg_lo:[0,1] neg_hi:[0,1]
	v_mov_b32_e32 v39, v29
	v_pk_add_f32 v[132:133], v[128:129], v[140:141] op_sel:[0,1] op_sel_hi:[1,0] neg_hi:[0,1]
	v_pk_add_f32 v[128:129], v[128:129], v[140:141] op_sel:[0,1] op_sel_hi:[1,0] neg_lo:[0,1]
	v_pk_add_f32 v[140:141], v[130:131], v[134:135]
	v_pk_add_f32 v[134:135], v[130:131], v[134:135] neg_lo:[0,1] neg_hi:[0,1]
	v_mov_b32_e32 v43, v33
	v_pk_add_f32 v[130:131], v[142:143], v[178:179]
	v_pk_add_f32 v[142:143], v[142:143], v[178:179] neg_lo:[0,1] neg_hi:[0,1]
	v_pk_add_f32 v[178:179], v[162:163], v[194:195] op_sel:[0,1] op_sel_hi:[1,0] neg_hi:[0,1]
	v_pk_add_f32 v[162:163], v[162:163], v[194:195] op_sel:[0,1] op_sel_hi:[1,0] neg_lo:[0,1]
	v_pk_add_f32 v[194:195], v[164:165], v[188:189]
	v_pk_add_f32 v[164:165], v[164:165], v[188:189] neg_lo:[0,1] neg_hi:[0,1]
	v_pk_add_f32 v[188:189], v[184:185], v[182:183] op_sel:[0,1] op_sel_hi:[1,0] neg_hi:[0,1]
	v_pk_add_f32 v[182:183], v[184:185], v[182:183] op_sel:[0,1] op_sel_hi:[1,0] neg_lo:[0,1]
	v_pk_add_f32 v[184:185], v[170:171], v[190:191]
	v_pk_add_f32 v[170:171], v[170:171], v[190:191] neg_lo:[0,1] neg_hi:[0,1]
	v_pk_add_f32 v[190:191], v[172:173], v[186:187] op_sel:[0,1] op_sel_hi:[1,0] neg_hi:[0,1]
	v_pk_add_f32 v[172:173], v[172:173], v[186:187] op_sel:[0,1] op_sel_hi:[1,0] neg_lo:[0,1]
	v_pk_add_f32 v[186:187], v[166:167], v[174:175]
	v_pk_add_f32 v[166:167], v[166:167], v[174:175] neg_lo:[0,1] neg_hi:[0,1]
	v_pk_add_f32 v[174:175], v[144:145], v[168:169] op_sel:[0,1] op_sel_hi:[1,0] neg_hi:[0,1]
	v_pk_add_f32 v[144:145], v[144:145], v[168:169] op_sel:[0,1] op_sel_hi:[1,0] neg_lo:[0,1]
	v_pk_add_f32 v[168:169], v[148:149], v[180:181]
	v_pk_add_f32 v[148:149], v[148:149], v[180:181] neg_lo:[0,1] neg_hi:[0,1]
	v_pk_mul_f32 v[2:3], v[2:3], v[168:169] op_sel:[0,1] op_sel_hi:[1,0]
	v_pk_add_f32 v[180:181], v[176:177], v[192:193] op_sel:[0,1] op_sel_hi:[1,0] neg_hi:[0,1]
	v_pk_add_f32 v[176:177], v[176:177], v[192:193] op_sel:[0,1] op_sel_hi:[1,0] neg_lo:[0,1]
	v_pk_add_f32 v[192:193], v[150:151], v[158:159]
	v_pk_add_f32 v[150:151], v[150:151], v[158:159] neg_lo:[0,1] neg_hi:[0,1]
	v_pk_add_f32 v[158:159], v[154:155], v[152:153] op_sel:[0,1] op_sel_hi:[1,0] neg_hi:[0,1]
	v_pk_add_f32 v[152:153], v[154:155], v[152:153] op_sel:[0,1] op_sel_hi:[1,0] neg_lo:[0,1]
	v_pk_add_f32 v[154:155], v[136:137], v[160:161]
	v_pk_fma_f32 v[2:3], v[4:5], v[168:169], v[2:3] op_sel_hi:[0,1,1]
	v_pk_mul_f32 v[4:5], v[12:13], v[184:185] op_sel:[0,1] op_sel_hi:[1,0]
	v_mov_b32_e32 v47, v37
	v_pk_fma_f32 v[4:5], v[6:7], v[184:185], v[4:5] op_sel_hi:[0,1,1]
	v_pk_mul_f32 v[6:7], v[22:23], v[154:155] op_sel:[0,1] op_sel_hi:[1,0]
	v_pk_add_f32 v[136:137], v[136:137], v[160:161] neg_lo:[0,1] neg_hi:[0,1]
	v_pk_fma_f32 v[6:7], v[8:9], v[154:155], v[6:7] op_sel_hi:[0,1,1]
	v_pk_mul_f32 v[8:9], v[14:15], v[194:195] op_sel:[0,1] op_sel_hi:[1,0]
	v_pk_add_f32 v[160:161], v[138:139], v[156:157] op_sel:[0,1] op_sel_hi:[1,0] neg_hi:[0,1]
	v_pk_add_f32 v[138:139], v[138:139], v[156:157] op_sel:[0,1] op_sel_hi:[1,0] neg_lo:[0,1]
	v_pk_add_f32 v[156:157], v[132:133], v[140:141]
	v_pk_fma_f32 v[8:9], v[10:11], v[194:195], v[8:9] op_sel_hi:[0,1,1]
	v_pk_mul_f32 v[10:11], v[26:27], v[192:193] op_sel:[0,1] op_sel_hi:[1,0]
	v_pk_mul_f32 v[12:13], v[30:31], v[186:187] op_sel:[0,1] op_sel_hi:[1,0]
	v_xor_b32_e32 v50, 0x80000000, v41
	v_xor_b32_e32 v54, 0x80000000, v45
	v_xor_b32_e32 v58, 0x80000000, v49
	v_xor_b32_e32 v62, 0x80000000, v53
	v_xor_b32_e32 v66, 0x80000000, v57
	v_xor_b32_e32 v70, 0x80000000, v61
	v_xor_b32_e32 v74, 0x80000000, v65
	v_mov_b32_e32 v51, v41
	v_mov_b32_e32 v55, v45
	v_mov_b32_e32 v59, v49
	v_mov_b32_e32 v63, v53
	v_mov_b32_e32 v67, v57
	v_mov_b32_e32 v71, v61
	v_mov_b32_e32 v75, v65
	v_pk_add_f32 v[132:133], v[132:133], v[140:141] neg_lo:[0,1] neg_hi:[0,1]
	v_pk_add_f32 v[140:141], v[128:129], v[134:135] op_sel:[0,1] op_sel_hi:[1,0] neg_hi:[0,1]
	v_pk_fma_f32 v[10:11], v[16:17], v[192:193], v[10:11] op_sel_hi:[0,1,1]
	v_pk_fma_f32 v[12:13], v[20:21], v[186:187], v[12:13] op_sel_hi:[0,1,1]
	v_pk_mul_f32 v[14:15], v[34:35], v[156:157] op_sel:[0,1] op_sel_hi:[1,0]
	v_pk_mul_f32 v[16:17], v[38:39], v[178:179] op_sel:[0,1] op_sel_hi:[1,0]
	v_pk_mul_f32 v[20:21], v[42:43], v[180:181] op_sel:[0,1] op_sel_hi:[1,0]
	v_pk_mul_f32 v[22:23], v[46:47], v[190:191] op_sel:[0,1] op_sel_hi:[1,0]
	v_xor_b32_e32 v78, 0x80000000, v69
	v_xor_b32_e32 v82, 0x80000000, v73
	v_xor_b32_e32 v86, 0x80000000, v77
	v_xor_b32_e32 v90, 0x80000000, v81
	v_xor_b32_e32 v94, 0x80000000, v85
	v_xor_b32_e32 v98, 0x80000000, v89
	v_xor_b32_e32 v102, 0x80000000, v93
	v_xor_b32_e32 v106, 0x80000000, v97
	v_xor_b32_e32 v110, 0x80000000, v101
	v_xor_b32_e32 v114, 0x80000000, v105
	v_xor_b32_e32 v118, 0x80000000, v109
	v_xor_b32_e32 v122, 0x80000000, v113
	v_xor_b32_e32 v124, 0x80000000, v117
	v_xor_b32_e32 v126, 0x80000000, v121
	v_mov_b32_e32 v79, v69
	v_mov_b32_e32 v83, v73
	v_mov_b32_e32 v87, v77
	v_mov_b32_e32 v91, v81
	v_mov_b32_e32 v95, v85
	v_mov_b32_e32 v99, v89
	v_mov_b32_e32 v103, v93
	v_mov_b32_e32 v107, v97
	v_mov_b32_e32 v111, v101
	v_mov_b32_e32 v115, v105
	v_mov_b32_e32 v119, v109
	v_mov_b32_e32 v123, v113
	v_mov_b32_e32 v125, v117
	v_mov_b32_e32 v127, v121
	v_pk_add_f32 v[128:129], v[128:129], v[134:135] op_sel:[0,1] op_sel_hi:[1,0] neg_lo:[0,1]
	v_pk_fma_f32 v[14:15], v[24:25], v[156:157], v[14:15] op_sel_hi:[0,1,1]
	v_pk_fma_f32 v[16:17], v[28:29], v[178:179], v[16:17] op_sel_hi:[0,1,1]
	v_pk_fma_f32 v[20:21], v[32:33], v[180:181], v[20:21] op_sel_hi:[0,1,1]
	v_pk_fma_f32 v[22:23], v[36:37], v[190:191], v[22:23] op_sel_hi:[0,1,1]
	v_pk_mul_f32 v[24:25], v[50:51], v[160:161] op_sel:[0,1] op_sel_hi:[1,0]
	v_pk_mul_f32 v[26:27], v[54:55], v[188:189] op_sel:[0,1] op_sel_hi:[1,0]
	v_pk_mul_f32 v[28:29], v[58:59], v[158:159] op_sel:[0,1] op_sel_hi:[1,0]
	v_pk_mul_f32 v[30:31], v[62:63], v[174:175] op_sel:[0,1] op_sel_hi:[1,0]
	v_pk_mul_f32 v[32:33], v[66:67], v[140:141] op_sel:[0,1] op_sel_hi:[1,0]
	v_pk_mul_f32 v[34:35], v[70:71], v[142:143] op_sel:[0,1] op_sel_hi:[1,0]
	v_pk_mul_f32 v[36:37], v[74:75], v[148:149] op_sel:[0,1] op_sel_hi:[1,0]
	v_pk_fma_f32 v[24:25], v[40:41], v[160:161], v[24:25] op_sel_hi:[0,1,1]
	v_pk_fma_f32 v[26:27], v[44:45], v[188:189], v[26:27] op_sel_hi:[0,1,1]
	v_pk_fma_f32 v[28:29], v[48:49], v[158:159], v[28:29] op_sel_hi:[0,1,1]
	v_pk_fma_f32 v[30:31], v[52:53], v[174:175], v[30:31] op_sel_hi:[0,1,1]
	v_pk_fma_f32 v[32:33], v[56:57], v[140:141], v[32:33] op_sel_hi:[0,1,1]
	v_pk_fma_f32 v[34:35], v[60:61], v[142:143], v[34:35] op_sel_hi:[0,1,1]
	v_pk_fma_f32 v[36:37], v[64:65], v[148:149], v[36:37] op_sel_hi:[0,1,1]
	v_pk_mul_f32 v[38:39], v[78:79], v[170:171] op_sel:[0,1] op_sel_hi:[1,0]
	v_pk_mul_f32 v[40:41], v[82:83], v[136:137] op_sel:[0,1] op_sel_hi:[1,0]
	v_pk_mul_f32 v[42:43], v[86:87], v[164:165] op_sel:[0,1] op_sel_hi:[1,0]
	v_pk_mul_f32 v[44:45], v[90:91], v[150:151] op_sel:[0,1] op_sel_hi:[1,0]
	v_pk_mul_f32 v[46:47], v[94:95], v[166:167] op_sel:[0,1] op_sel_hi:[1,0]
	v_pk_mul_f32 v[48:49], v[98:99], v[132:133] op_sel:[0,1] op_sel_hi:[1,0]
	v_pk_mul_f32 v[50:51], v[102:103], v[162:163] op_sel:[0,1] op_sel_hi:[1,0]
	v_pk_mul_f32 v[52:53], v[106:107], v[176:177] op_sel:[0,1] op_sel_hi:[1,0]
	v_pk_mul_f32 v[54:55], v[110:111], v[172:173] op_sel:[0,1] op_sel_hi:[1,0]
	v_pk_mul_f32 v[56:57], v[114:115], v[138:139] op_sel:[0,1] op_sel_hi:[1,0]
	v_pk_mul_f32 v[58:59], v[118:119], v[182:183] op_sel:[0,1] op_sel_hi:[1,0]
	v_pk_mul_f32 v[60:61], v[122:123], v[152:153] op_sel:[0,1] op_sel_hi:[1,0]
	v_pk_mul_f32 v[62:63], v[124:125], v[144:145] op_sel:[0,1] op_sel_hi:[1,0]
	v_pk_mul_f32 v[64:65], v[126:127], v[128:129] op_sel:[0,1] op_sel_hi:[1,0]
	v_pk_fma_f32 v[38:39], v[68:69], v[170:171], v[38:39] op_sel_hi:[0,1,1]
	v_pk_fma_f32 v[40:41], v[72:73], v[136:137], v[40:41] op_sel_hi:[0,1,1]
	v_pk_fma_f32 v[42:43], v[76:77], v[164:165], v[42:43] op_sel_hi:[0,1,1]
	v_pk_fma_f32 v[44:45], v[80:81], v[150:151], v[44:45] op_sel_hi:[0,1,1]
	v_pk_fma_f32 v[46:47], v[84:85], v[166:167], v[46:47] op_sel_hi:[0,1,1]
	v_pk_fma_f32 v[48:49], v[88:89], v[132:133], v[48:49] op_sel_hi:[0,1,1]
	v_pk_fma_f32 v[50:51], v[92:93], v[162:163], v[50:51] op_sel_hi:[0,1,1]
	v_pk_fma_f32 v[52:53], v[96:97], v[176:177], v[52:53] op_sel_hi:[0,1,1]
	v_pk_fma_f32 v[54:55], v[100:101], v[172:173], v[54:55] op_sel_hi:[0,1,1]
	v_pk_fma_f32 v[56:57], v[104:105], v[138:139], v[56:57] op_sel_hi:[0,1,1]
	v_pk_fma_f32 v[58:59], v[108:109], v[182:183], v[58:59] op_sel_hi:[0,1,1]
	v_pk_fma_f32 v[60:61], v[112:113], v[152:153], v[60:61] op_sel_hi:[0,1,1]
	v_pk_fma_f32 v[62:63], v[116:117], v[144:145], v[62:63] op_sel_hi:[0,1,1]
	v_pk_fma_f32 v[64:65], v[120:121], v[128:129], v[64:65] op_sel_hi:[0,1,1]
	ds_write2_b64 v18, v[130:131], v[34:35] offset1:16
	ds_write2_b64 v18, v[16:17], v[50:51] offset0:33 offset1:49
	ds_write2_b64 v18, v[8:9], v[42:43] offset0:66 offset1:82
	ds_write2_b64 v18, v[26:27], v[58:59] offset0:99 offset1:115
	ds_write2_b64 v18, v[4:5], v[38:39] offset0:132 offset1:148
	ds_write2_b64 v18, v[22:23], v[54:55] offset0:165 offset1:181
	ds_write2_b64 v18, v[12:13], v[46:47] offset0:198 offset1:214
	ds_write2_b64 v18, v[30:31], v[62:63] offset0:231 offset1:247
	ds_write2_b64 v196, v[2:3], v[36:37] offset0:8 offset1:24
	ds_write2_b64 v196, v[20:21], v[52:53] offset0:41 offset1:57
	ds_write2_b64 v196, v[10:11], v[44:45] offset0:74 offset1:90
	ds_write2_b64 v196, v[28:29], v[60:61] offset0:107 offset1:123
	ds_write2_b64 v196, v[6:7], v[40:41] offset0:140 offset1:156
	ds_write2_b64 v196, v[24:25], v[56:57] offset0:173 offset1:189
	ds_write2_b64 v196, v[14:15], v[48:49] offset0:206 offset1:222
	ds_write2_b64 v196, v[32:33], v[64:65] offset0:239 offset1:255
	v_ashrrev_i32_e32 v2, 31, v210
	v_lshrrev_b32_e32 v2, 23, v2
	v_add_u32_e32 v2, v210, v2
	s_lshl_b64 s[74:75], s[76:77], 16
	v_and_b32_e32 v2, 0xfffffe00, v2
	s_add_u32 s0, s54, s74
	v_sub_u32_e32 v2, v210, v2
	s_addc_u32 s1, s55, s75
	v_ashrrev_i32_e32 v3, 31, v2
	v_lshl_add_u64 v[14:15], v[2:3], 3, s[0:1]
	v_add_co_u32_e32 v2, vcc, s92, v14
	s_mov_b32 s0, 0x8000
	s_nop 0
	v_addc_co_u32_e32 v3, vcc, 0, v15, vcc
	v_add_co_u32_e32 v4, vcc, s95, v14
	s_waitcnt lgkmcnt(0)
	s_nop 0
	v_addc_co_u32_e32 v5, vcc, 0, v15, vcc
	v_add_co_u32_e32 v8, vcc, s96, v14
	s_barrier
	s_nop 0
	v_addc_co_u32_e32 v9, vcc, 0, v15, vcc
	global_load_dwordx2 v[24:25], v[4:5], off offset:-4096 nt
	global_load_dwordx2 v[12:13], v[4:5], off nt
	global_load_dwordx2 v[6:7], v[8:9], off offset:-4096 nt
	s_nop 0
	global_load_dwordx2 v[4:5], v[8:9], off nt
	v_add_co_u32_e32 v8, vcc, s0, v14
	s_waitcnt vmcnt(3)
	v_cvt_f32_f16_sdwa v174, v24 dst_sel:DWORD dst_unused:UNUSED_PAD src0_sel:WORD_1
	v_addc_co_u32_e32 v9, vcc, 0, v15, vcc
	v_add_co_u32_e32 v10, vcc, s34, v14
	v_cvt_f32_f16_e32 v175, v25
	s_nop 0
	v_addc_co_u32_e32 v11, vcc, 0, v15, vcc
	global_load_dwordx2 v[16:17], v[8:9], off offset:-4096 nt
	global_load_dwordx2 v[122:123], v[8:9], off nt
	global_load_dwordx2 v[46:47], v[10:11], off offset:-4096 nt
	global_load_dwordx2 v[36:37], v[10:11], off nt
	v_add_co_u32_e32 v8, vcc, s35, v14
	v_cvt_f32_f16_sdwa v177, v25 dst_sel:DWORD dst_unused:UNUSED_PAD src0_sel:WORD_1
	s_nop 0
	v_addc_co_u32_e32 v9, vcc, 0, v15, vcc
	v_add_co_u32_e32 v22, vcc, s30, v14
	v_cvt_f32_f16_e32 v176, v24
	s_nop 0
	v_addc_co_u32_e32 v23, vcc, 0, v15, vcc
	global_load_dwordx2 v[26:27], v[8:9], off offset:-4096 nt
	global_load_dwordx2 v[20:21], v[8:9], off nt
	global_load_dwordx2 v[10:11], v[22:23], off offset:-4096 nt
	s_nop 0
	global_load_dwordx2 v[8:9], v[22:23], off nt
	v_add_co_u32_e32 v22, vcc, s31, v14
	s_waitcnt vmcnt(10)
	v_cvt_f32_f16_sdwa v164, v12 dst_sel:DWORD dst_unused:UNUSED_PAD src0_sel:WORD_1
	v_addc_co_u32_e32 v23, vcc, 0, v15, vcc
	global_load_dwordx2 v[30:31], v[2:3], off offset:-4096 nt
	global_load_dwordx2 v[28:29], v[2:3], off nt
	s_nop 0
	global_load_dwordx2 v[2:3], v[22:23], off nt
	global_load_dwordx2 v[32:33], v[14:15], off nt
	v_mov_b32_e32 v14, v210
	v_cvt_f32_f16_e32 v165, v13
	v_ashrrev_i32_e32 v15, 31, v14
	v_lshrrev_b32_e32 v15, 23, v15
	v_add_u32_e32 v15, v14, v15
	v_ashrrev_i32_e32 v15, 9, v15
	v_mul_i32_i24_e32 v18, 0x200, v15
	v_sub_u32_e32 v18, v14, v18
	v_lshlrev_b32_e32 v14, 14, v15
	v_lshlrev_b32_e32 v15, 1, v18
	v_bfrev_b32_e32 v15, v15
	v_lshrrev_b32_e32 v15, 22, v15
	v_sub_u32_e32 v15, 0x400, v15
	v_bfrev_b32_e32 v15, v15
	v_lshrrev_b32_e32 v15, 18, v15
	v_and_b32_e32 v15, 0x3ff0, v15
	v_cmp_eq_u32_e64 s[0:1], 0, v18
	v_lshl_add_u32 v22, v18, 5, v14
	v_lshl_add_u32 v23, v22, 3, 0
	v_cndmask_b32_e64 v15, v15, 16, s[0:1]
	v_or_b32_e32 v14, v15, v14
	v_ashrrev_i32_e32 v22, 2, v22
	v_ashrrev_i32_e32 v15, 5, v14
	v_add_u32_e32 v211, v23, v22
	v_lshlrev_b32_e32 v14, 3, v14
	v_lshlrev_b32_e32 v15, 3, v15
	v_add3_u32 v212, 0, v14, v15
	ds_read2_b64 v[38:41], v211 offset1:1
	ds_read2_b64 v[42:45], v211 offset0:2 offset1:3
	ds_read2_b64 v[48:51], v212 offset1:1
	ds_read2_b64 v[52:55], v212 offset0:2 offset1:3
	ds_read2_b64 v[56:59], v211 offset0:4 offset1:5
	ds_read2_b64 v[60:63], v211 offset0:6 offset1:7
	ds_read2_b64 v[68:71], v212 offset0:4 offset1:5
	ds_read2_b64 v[72:75], v212 offset0:6 offset1:7
	ds_read2_b64 v[64:67], v211 offset0:8 offset1:9
	ds_read2_b64 v[76:79], v211 offset0:10 offset1:11
	ds_read2_b64 v[80:83], v212 offset0:8 offset1:9
	ds_read2_b64 v[98:101], v212 offset0:10 offset1:11
	ds_read2_b64 v[84:87], v211 offset0:12 offset1:13
	ds_read2_b64 v[88:91], v211 offset0:14 offset1:15
	ds_read2_b64 v[102:105], v212 offset0:12 offset1:13
	ds_read2_b64 v[106:109], v212 offset0:14 offset1:15
	s_waitcnt lgkmcnt(7)
	v_pk_add_f32 v[14:15], v[38:39], v[64:65]
	v_pk_add_f32 v[22:23], v[38:39], v[64:65] neg_lo:[0,1] neg_hi:[0,1]
	v_pk_add_f32 v[38:39], v[40:41], v[66:67] neg_lo:[0,1] neg_hi:[0,1]
	v_pk_add_f32 v[34:35], v[40:41], v[66:67]
	v_pk_mul_f32 v[40:41], v[38:39], s[18:19]
	v_cmp_ne_u32_e32 vcc, 0, v18
	v_pk_fma_f32 v[38:39], v[38:39], s[16:17], v[40:41] op_sel:[0,0,1] op_sel_hi:[1,0,0]
	s_waitcnt lgkmcnt(6)
	v_pk_add_f32 v[40:41], v[42:43], v[76:77]
	v_pk_add_f32 v[42:43], v[42:43], v[76:77] neg_lo:[0,1] neg_hi:[0,1]
	v_bfrev_b32_e32 v18, v18
	v_pk_mul_f32 v[64:65], v[42:43], s[36:37]
	v_lshrrev_b32_e32 v18, 23, v18
	v_pk_fma_f32 v[42:43], v[42:43], s[78:79], v[64:65] op_sel:[0,0,1] op_sel_hi:[1,0,0]
	v_pk_add_f32 v[64:65], v[44:45], v[78:79]
	v_pk_add_f32 v[44:45], v[44:45], v[78:79] neg_lo:[0,1] neg_hi:[0,1]
	s_waitcnt lgkmcnt(3)
	v_pk_add_f32 v[78:79], v[58:59], v[86:87]
	v_pk_mul_f32 v[66:67], v[44:45], s[40:41]
	v_pk_add_f32 v[58:59], v[58:59], v[86:87] neg_lo:[0,1] neg_hi:[0,1]
	v_pk_fma_f32 v[44:45], v[44:45], s[80:81], v[66:67] op_sel:[0,0,1] op_sel_hi:[1,0,0]
	v_pk_add_f32 v[66:67], v[56:57], v[84:85]
	v_pk_add_f32 v[76:77], v[56:57], v[84:85] neg_lo:[0,1] neg_hi:[0,1]
	v_pk_mul_f32 v[84:85], v[58:59], s[40:41]
	v_pk_fma_f32 v[58:59], v[58:59], s[80:81], v[84:85] op_sel:[0,0,1] op_sel_hi:[1,0,0] neg_lo:[1,0,0] neg_hi:[1,0,0]
	s_waitcnt lgkmcnt(2)
	v_pk_add_f32 v[84:85], v[60:61], v[88:89]
	v_pk_add_f32 v[60:61], v[60:61], v[88:89] neg_lo:[0,1] neg_hi:[0,1]
	v_pk_mul_f32 v[86:87], v[60:61], s[36:37]
	v_pk_add_f32 v[56:57], v[22:23], v[76:77] op_sel:[0,1] op_sel_hi:[1,0] neg_hi:[0,1]
	v_pk_fma_f32 v[60:61], v[60:61], s[78:79], v[86:87] op_sel:[0,0,1] op_sel_hi:[1,0,0] neg_lo:[1,0,0] neg_hi:[1,0,0]
	v_pk_add_f32 v[86:87], v[62:63], v[90:91]
	v_pk_add_f32 v[62:63], v[62:63], v[90:91] neg_lo:[0,1] neg_hi:[0,1]
	v_pk_add_f32 v[90:91], v[64:65], v[86:87]
	v_pk_mul_f32 v[88:89], v[62:63], s[18:19]
	v_pk_add_f32 v[64:65], v[64:65], v[86:87] neg_lo:[0,1] neg_hi:[0,1]
	v_pk_fma_f32 v[62:63], v[62:63], s[16:17], v[88:89] op_sel:[0,0,1] op_sel_hi:[1,0,0] neg_lo:[1,0,0] neg_hi:[1,0,0]
	v_pk_add_f32 v[88:89], v[14:15], v[66:67]
	v_pk_add_f32 v[14:15], v[14:15], v[66:67] neg_lo:[0,1] neg_hi:[0,1]
	v_pk_add_f32 v[66:67], v[34:35], v[78:79]
	v_pk_add_f32 v[34:35], v[34:35], v[78:79] neg_lo:[0,1] neg_hi:[0,1]
	v_pk_add_f32 v[22:23], v[22:23], v[76:77] op_sel:[0,1] op_sel_hi:[1,0] neg_lo:[0,1]
	v_pk_mul_f32 v[78:79], v[34:35], s[36:37]
	v_pk_add_f32 v[76:77], v[38:39], v[58:59]
	v_pk_add_f32 v[38:39], v[38:39], v[58:59] neg_lo:[0,1] neg_hi:[0,1]
	v_pk_fma_f32 v[34:35], v[34:35], s[78:79], v[78:79] op_sel:[0,0,1] op_sel_hi:[1,0,0]
	v_pk_add_f32 v[78:79], v[40:41], v[84:85]
	v_pk_add_f32 v[84:85], v[40:41], v[84:85] neg_lo:[0,1] neg_hi:[0,1]
	v_pk_mul_f32 v[86:87], v[64:65], s[36:37]
	v_pk_mul_f32 v[58:59], v[38:39], s[36:37]
	v_pk_fma_f32 v[64:65], v[64:65], s[78:79], v[86:87] op_sel:[0,0,1] op_sel_hi:[1,0,0] neg_lo:[1,0,0] neg_hi:[1,0,0]
	v_pk_fma_f32 v[38:39], v[38:39], s[78:79], v[58:59] op_sel:[0,0,1] op_sel_hi:[1,0,0]
	v_pk_add_f32 v[58:59], v[42:43], v[60:61]
	v_pk_add_f32 v[86:87], v[44:45], v[62:63]
	v_pk_add_f32 v[44:45], v[44:45], v[62:63] neg_lo:[0,1] neg_hi:[0,1]
	v_pk_mul_f32 v[62:63], v[44:45], s[36:37]
	v_pk_add_f32 v[40:41], v[14:15], v[84:85] op_sel:[0,1] op_sel_hi:[1,0] neg_hi:[0,1]
	v_pk_add_f32 v[14:15], v[14:15], v[84:85] op_sel:[0,1] op_sel_hi:[1,0] neg_lo:[0,1]
	v_pk_add_f32 v[84:85], v[34:35], v[64:65]
	v_pk_add_f32 v[64:65], v[34:35], v[64:65] neg_lo:[0,1] neg_hi:[0,1]
	v_pk_add_f32 v[94:95], v[56:57], v[58:59]
	v_pk_add_f32 v[56:57], v[56:57], v[58:59] neg_lo:[0,1] neg_hi:[0,1]
	v_pk_add_f32 v[58:59], v[76:77], v[86:87]
	v_pk_fma_f32 v[44:45], v[44:45], s[78:79], v[62:63] op_sel:[0,0,1] op_sel_hi:[1,0,0] neg_lo:[1,0,0] neg_hi:[1,0,0]
	v_pk_add_f32 v[62:63], v[88:89], v[78:79]
	v_pk_add_f32 v[78:79], v[88:89], v[78:79] neg_lo:[0,1] neg_hi:[0,1]
	v_pk_add_f32 v[88:89], v[66:67], v[90:91]
	v_pk_add_f32 v[110:111], v[76:77], v[86:87] neg_lo:[0,1] neg_hi:[0,1]
	v_pk_add_f32 v[86:87], v[94:95], v[58:59]
	v_pk_add_f32 v[34:35], v[94:95], v[58:59] neg_lo:[0,1] neg_hi:[0,1]
	v_pk_add_f32 v[58:59], v[50:51], v[82:83]
	v_pk_add_f32 v[50:51], v[50:51], v[82:83] neg_lo:[0,1] neg_hi:[0,1]
	v_pk_add_f32 v[60:61], v[42:43], v[60:61] neg_lo:[0,1] neg_hi:[0,1]
	v_pk_add_f32 v[148:149], v[62:63], v[88:89]
	v_pk_add_f32 v[138:139], v[62:63], v[88:89] neg_lo:[0,1] neg_hi:[0,1]
	v_pk_mul_f32 v[62:63], v[50:51], s[18:19]
	v_pk_add_f32 v[90:91], v[66:67], v[90:91] neg_lo:[0,1] neg_hi:[0,1]
	v_pk_fma_f32 v[50:51], v[50:51], s[16:17], v[62:63] op_sel:[0,0,1] op_sel_hi:[1,0,0]
	v_pk_add_f32 v[62:63], v[52:53], v[98:99]
	v_pk_add_f32 v[52:53], v[52:53], v[98:99] neg_lo:[0,1] neg_hi:[0,1]
	v_pk_add_f32 v[112:113], v[22:23], v[60:61] op_sel:[0,1] op_sel_hi:[1,0] neg_hi:[0,1]
	v_pk_add_f32 v[114:115], v[22:23], v[60:61] op_sel:[0,1] op_sel_hi:[1,0] neg_lo:[0,1]
	v_pk_add_f32 v[96:97], v[40:41], v[84:85]
	v_pk_add_f32 v[66:67], v[40:41], v[84:85] neg_lo:[0,1] neg_hi:[0,1]
	v_pk_add_f32 v[60:61], v[14:15], v[64:65] op_sel:[0,1] op_sel_hi:[1,0] neg_hi:[0,1]
	v_pk_add_f32 v[84:85], v[14:15], v[64:65] op_sel:[0,1] op_sel_hi:[1,0] neg_lo:[0,1]
	v_pk_mul_f32 v[64:65], v[52:53], s[36:37]
	v_pk_fma_f32 v[52:53], v[52:53], s[78:79], v[64:65] op_sel:[0,0,1] op_sel_hi:[1,0,0]
	v_pk_add_f32 v[64:65], v[54:55], v[100:101]
	v_pk_add_f32 v[54:55], v[54:55], v[100:101] neg_lo:[0,1] neg_hi:[0,1]
	v_pk_mul_f32 v[76:77], v[54:55], s[40:41]
	v_pk_add_f32 v[92:93], v[78:79], v[90:91] op_sel:[0,1] op_sel_hi:[1,0] neg_hi:[0,1]
	v_pk_fma_f32 v[54:55], v[54:55], s[80:81], v[76:77] op_sel:[0,0,1] op_sel_hi:[1,0,0]
	s_waitcnt lgkmcnt(1)
	v_pk_add_f32 v[76:77], v[68:69], v[102:103]
	v_pk_add_f32 v[68:69], v[68:69], v[102:103] neg_lo:[0,1] neg_hi:[0,1]
	v_pk_add_f32 v[88:89], v[78:79], v[90:91] op_sel:[0,1] op_sel_hi:[1,0] neg_lo:[0,1]
	v_xor_b32_e32 v79, 0x80000000, v68
	v_mov_b32_e32 v78, v69
	v_pk_add_f32 v[68:69], v[70:71], v[104:105]
	v_pk_add_f32 v[70:71], v[70:71], v[104:105] neg_lo:[0,1] neg_hi:[0,1]
	v_pk_add_f32 v[22:23], v[38:39], v[44:45]
	v_pk_add_f32 v[116:117], v[38:39], v[44:45] neg_lo:[0,1] neg_hi:[0,1]
	v_pk_add_f32 v[40:41], v[56:57], v[110:111] op_sel:[0,1] op_sel_hi:[1,0] neg_hi:[0,1]
	v_pk_add_f32 v[44:45], v[56:57], v[110:111] op_sel:[0,1] op_sel_hi:[1,0] neg_lo:[0,1]
	v_pk_add_f32 v[56:57], v[48:49], v[80:81]
	v_pk_add_f32 v[48:49], v[48:49], v[80:81] neg_lo:[0,1] neg_hi:[0,1]
	v_pk_mul_f32 v[80:81], v[70:71], s[40:41]
	v_cvt_f32_u32_e32 v18, v18
	v_pk_fma_f32 v[70:71], v[70:71], s[80:81], v[80:81] op_sel:[0,0,1] op_sel_hi:[1,0,0] neg_lo:[1,0,0] neg_hi:[1,0,0]
	s_waitcnt lgkmcnt(0)
	v_pk_add_f32 v[80:81], v[72:73], v[106:107]
	v_pk_add_f32 v[72:73], v[72:73], v[106:107] neg_lo:[0,1] neg_hi:[0,1]
	v_mul_f32_e32 v18, 0x38000000, v18
	v_pk_mul_f32 v[82:83], v[72:73], s[36:37]
	v_cndmask_b32_e64 v18, v18, v208, s[0:1]
	v_pk_fma_f32 v[72:73], v[72:73], s[78:79], v[82:83] op_sel:[0,0,1] op_sel_hi:[1,0,0] neg_lo:[1,0,0] neg_hi:[1,0,0]
	v_pk_add_f32 v[82:83], v[74:75], v[108:109]
	v_pk_add_f32 v[74:75], v[74:75], v[108:109] neg_lo:[0,1] neg_hi:[0,1]
	s_nop 0
	v_pk_mul_f32 v[90:91], v[74:75], s[18:19]
	v_pk_fma_f32 v[74:75], v[74:75], s[16:17], v[90:91] op_sel:[0,0,1] op_sel_hi:[1,0,0] neg_lo:[1,0,0] neg_hi:[1,0,0]
	v_pk_add_f32 v[90:91], v[56:57], v[76:77]
	v_pk_add_f32 v[56:57], v[56:57], v[76:77] neg_lo:[0,1] neg_hi:[0,1]
	v_pk_add_f32 v[76:77], v[58:59], v[68:69]
	v_pk_add_f32 v[58:59], v[58:59], v[68:69] neg_lo:[0,1] neg_hi:[0,1]
	v_pk_add_f32 v[14:15], v[114:115], v[116:117] op_sel:[0,1] op_sel_hi:[1,0] neg_hi:[0,1]
	v_pk_mul_f32 v[68:69], v[58:59], s[36:37]
	v_pk_add_f32 v[38:39], v[114:115], v[116:117] op_sel:[0,1] op_sel_hi:[1,0] neg_lo:[0,1]
	v_pk_fma_f32 v[58:59], v[58:59], s[78:79], v[68:69] op_sel:[0,0,1] op_sel_hi:[1,0,0]
	v_pk_add_f32 v[68:69], v[62:63], v[80:81]
	v_pk_add_f32 v[80:81], v[62:63], v[80:81] neg_lo:[0,1] neg_hi:[0,1]
	s_waitcnt vmcnt(0)
	v_cvt_f32_f16_e32 v193, v33
	s_nop 0
	s_nop 0
	v_pk_add_f32 v[62:63], v[64:65], v[82:83]
	v_pk_add_f32 v[64:65], v[64:65], v[82:83] neg_lo:[0,1] neg_hi:[0,1]
	v_cvt_f32_f16_sdwa v192, v32 dst_sel:DWORD dst_unused:UNUSED_PAD src0_sel:WORD_1
	v_pk_mul_f32 v[82:83], v[64:65], s[36:37]
	v_cvt_f32_f16_e32 v194, v32
	v_pk_fma_f32 v[64:65], v[64:65], s[78:79], v[82:83] op_sel:[0,0,1] op_sel_hi:[1,0,0] neg_lo:[1,0,0] neg_hi:[1,0,0]
	v_pk_add_f32 v[82:83], v[48:49], v[78:79]
	v_pk_add_f32 v[48:49], v[48:49], v[78:79] neg_lo:[0,1] neg_hi:[0,1]
	v_pk_add_f32 v[78:79], v[50:51], v[70:71]
	v_pk_add_f32 v[50:51], v[50:51], v[70:71] neg_lo:[0,1] neg_hi:[0,1]
	v_cvt_f32_f16_sdwa v195, v33 dst_sel:DWORD dst_unused:UNUSED_PAD src0_sel:WORD_1
	v_pk_mul_f32 v[70:71], v[50:51], s[36:37]
	v_cvt_f32_f16_sdwa v170, v30 dst_sel:DWORD dst_unused:UNUSED_PAD src0_sel:WORD_1
	v_pk_fma_f32 v[50:51], v[50:51], s[78:79], v[70:71] op_sel:[0,0,1] op_sel_hi:[1,0,0]
	v_pk_add_f32 v[70:71], v[52:53], v[72:73]
	v_pk_add_f32 v[72:73], v[52:53], v[72:73] neg_lo:[0,1] neg_hi:[0,1]
	v_cvt_f32_f16_e32 v171, v31
	s_nop 0
	s_nop 0
	v_pk_add_f32 v[52:53], v[54:55], v[74:75]
	v_pk_add_f32 v[54:55], v[54:55], v[74:75] neg_lo:[0,1] neg_hi:[0,1]
	v_cvt_f32_f16_sdwa v185, v31 dst_sel:DWORD dst_unused:UNUSED_PAD src0_sel:WORD_1
	v_pk_mul_f32 v[74:75], v[54:55], s[36:37]
	v_cvt_f32_f16_e32 v184, v30
	v_pk_fma_f32 v[54:55], v[54:55], s[78:79], v[74:75] op_sel:[0,0,1] op_sel_hi:[1,0,0] neg_lo:[1,0,0] neg_hi:[1,0,0]
	v_pk_add_f32 v[74:75], v[90:91], v[68:69]
	v_pk_add_f32 v[68:69], v[90:91], v[68:69] neg_lo:[0,1] neg_hi:[0,1]
	v_pk_add_f32 v[90:91], v[76:77], v[62:63]
	v_pk_add_f32 v[62:63], v[76:77], v[62:63] neg_lo:[0,1] neg_hi:[0,1]
	v_cvt_f32_f16_sdwa v172, v28 dst_sel:DWORD dst_unused:UNUSED_PAD src0_sel:WORD_1
	v_xor_b32_e32 v77, 0x80000000, v62
	v_mov_b32_e32 v76, v63
	v_pk_add_f32 v[62:63], v[56:57], v[80:81] op_sel:[0,1] op_sel_hi:[1,0] neg_hi:[0,1]
	v_pk_add_f32 v[56:57], v[56:57], v[80:81] op_sel:[0,1] op_sel_hi:[1,0] neg_lo:[0,1]
	v_pk_add_f32 v[80:81], v[58:59], v[64:65]
	v_pk_add_f32 v[58:59], v[58:59], v[64:65] neg_lo:[0,1] neg_hi:[0,1]
	v_cvt_f32_f16_e32 v173, v29
	v_xor_b32_e32 v65, 0x80000000, v58
	v_mov_b32_e32 v64, v59
	v_pk_add_f32 v[58:59], v[82:83], v[70:71]
	v_pk_add_f32 v[70:71], v[82:83], v[70:71] neg_lo:[0,1] neg_hi:[0,1]
	v_pk_add_f32 v[82:83], v[78:79], v[52:53]
	v_pk_add_f32 v[52:53], v[78:79], v[52:53] neg_lo:[0,1] neg_hi:[0,1]
	v_pk_add_f32 v[118:119], v[58:59], v[82:83]
	v_pk_add_f32 v[134:135], v[58:59], v[82:83] neg_lo:[0,1] neg_hi:[0,1]
	v_cos_f32_e32 v83, v18
	v_sin_f32_e32 v82, v18
	v_cvt_f32_f16_sdwa v181, v29 dst_sel:DWORD dst_unused:UNUSED_PAD src0_sel:WORD_1
	v_cvt_f32_f16_e32 v180, v28
	v_cvt_f32_f16_sdwa v167, v13 dst_sel:DWORD dst_unused:UNUSED_PAD src0_sel:WORD_1
	v_cvt_f32_f16_e32 v166, v12
	v_cvt_f32_f16_e32 v154, v6
	v_cvt_f32_f16_e32 v155, v7
	v_cvt_f32_f16_sdwa v157, v7 dst_sel:DWORD dst_unused:UNUSED_PAD src0_sel:WORD_1
	v_cvt_f32_f16_sdwa v156, v6 dst_sel:DWORD dst_unused:UNUSED_PAD src0_sel:WORD_1
	v_cvt_f32_f16_sdwa v140, v4 dst_sel:DWORD dst_unused:UNUSED_PAD src0_sel:WORD_1
	v_cvt_f32_f16_e32 v141, v5
	v_cvt_f32_f16_sdwa v143, v5 dst_sel:DWORD dst_unused:UNUSED_PAD src0_sel:WORD_1
	v_cvt_f32_f16_e32 v142, v4
	v_cvt_f32_f16_e32 v124, v16
	v_cvt_f32_f16_e32 v125, v17
	v_cvt_f32_f16_sdwa v127, v17 dst_sel:DWORD dst_unused:UNUSED_PAD src0_sel:WORD_1
	v_cvt_f32_f16_sdwa v126, v16 dst_sel:DWORD dst_unused:UNUSED_PAD src0_sel:WORD_1
	v_cvt_f32_f16_sdwa v114, v122 dst_sel:DWORD dst_unused:UNUSED_PAD src0_sel:WORD_1
	v_cvt_f32_f16_e32 v115, v123
	v_cvt_f32_f16_sdwa v117, v123 dst_sel:DWORD dst_unused:UNUSED_PAD src0_sel:WORD_1
	v_cvt_f32_f16_e32 v116, v122
	v_xor_b32_e32 v79, 0x80000000, v52
	v_mov_b32_e32 v78, v53
	v_pk_add_f32 v[52:53], v[48:49], v[72:73] op_sel:[0,1] op_sel_hi:[1,0] neg_hi:[0,1]
	v_pk_add_f32 v[48:49], v[48:49], v[72:73] op_sel:[0,1] op_sel_hi:[1,0] neg_lo:[0,1]
	v_pk_add_f32 v[72:73], v[50:51], v[54:55]
	v_pk_add_f32 v[50:51], v[50:51], v[54:55] neg_lo:[0,1] neg_hi:[0,1]
	v_pk_fma_f32 v[160:161], v[82:83], 0, v[82:83] op_sel:[0,0,1] op_sel_hi:[1,0,0] neg_lo:[1,0,0] neg_hi:[1,0,0]
	v_xor_b32_e32 v55, 0x80000000, v50
	v_mov_b32_e32 v54, v51
	v_pk_fma_f32 v[198:199], v[82:83], 0, v[82:83] op_sel:[0,0,1] op_sel_hi:[1,0,0]
	v_pk_add_f32 v[42:43], v[112:113], v[22:23]
	v_pk_add_f32 v[22:23], v[112:113], v[22:23] neg_lo:[0,1] neg_hi:[0,1]
	v_pk_add_f32 v[98:99], v[74:75], v[90:91]
	v_pk_add_f32 v[100:101], v[74:75], v[90:91] neg_lo:[0,1] neg_hi:[0,1]
	v_pk_add_f32 v[102:103], v[68:69], v[76:77]
	v_pk_add_f32 v[106:107], v[68:69], v[76:77] neg_lo:[0,1] neg_hi:[0,1]
	v_pk_add_f32 v[104:105], v[62:63], v[80:81]
	v_pk_add_f32 v[108:109], v[62:63], v[80:81] neg_lo:[0,1] neg_hi:[0,1]
	v_pk_add_f32 v[110:111], v[56:57], v[64:65]
	v_pk_add_f32 v[112:113], v[56:57], v[64:65] neg_lo:[0,1] neg_hi:[0,1]
	v_pk_add_f32 v[152:153], v[70:71], v[78:79]
	v_pk_add_f32 v[162:163], v[70:71], v[78:79] neg_lo:[0,1] neg_hi:[0,1]
	v_pk_add_f32 v[178:179], v[52:53], v[72:73]
	v_pk_add_f32 v[182:183], v[52:53], v[72:73] neg_lo:[0,1] neg_hi:[0,1]
	v_pk_add_f32 v[188:189], v[48:49], v[54:55]
	v_pk_add_f32 v[196:197], v[48:49], v[54:55] neg_lo:[0,1] neg_hi:[0,1]
	v_pk_mul_f32 v[186:187], v[82:83], 0 op_sel_hi:[1,0]
	v_mov_b32_e32 v190, v160
	v_mov_b32_e32 v191, v199
	v_mul_f32_e32 v18, 0x3f3504f3, v83
	v_mul_f32_e32 v158, 0xbec3ef15, v83
	v_mul_f32_e32 v132, 0xbf6c835e, v83
	s_and_saveexec_b64 s[0:1], vcc
	s_xor_b64 s[0:1], exec, s[0:1]
	s_cbranch_execz .LBB0_501
	v_pk_add_f32 v[4:5], v[148:149], v[196:197]
	v_pk_add_f32 v[6:7], v[148:149], v[196:197] neg_lo:[0,1] neg_hi:[0,1]
	v_mul_f32_e32 v4, 0.5, v4
	v_mul_f32_e32 v12, 0.5, v7
	v_mov_b32_e32 v7, v5
	v_pk_mul_f32 v[6:7], v[6:7], s[44:45]
	v_pk_mov_b32 v[16:17], v[198:199], v[160:161] op_sel:[1,0]
	v_pk_mul_f32 v[24:25], v[190:191], v[6:7] op_sel:[0,1] op_sel_hi:[1,0]
	v_pk_mul_f32 v[6:7], v[190:191], v[6:7]
	v_pk_add_f32 v[24:25], v[24:25], v[24:25] op_sel:[0,1] op_sel_hi:[0,1]
	v_pk_add_f32 v[28:29], v[4:5], v[24:25]
	v_pk_add_f32 v[4:5], v[4:5], v[24:25] op_sel_hi:[0,1] neg_lo:[0,1] neg_hi:[0,1]
	v_mov_b32_e32 v29, v5
	v_pk_add_f32 v[4:5], v[6:7], v[6:7] op_sel:[0,1] op_sel_hi:[0,1] neg_lo:[0,1] neg_hi:[0,1]
	v_pk_add_f32 v[6:7], v[12:13], v[4:5]
	v_pk_add_f32 v[4:5], v[12:13], v[4:5] op_sel_hi:[0,1] neg_lo:[0,1] neg_hi:[0,1]
	v_mov_b32_e32 v7, v5
	v_pk_mul_f32 v[4:5], v[6:7], v[194:195]
	v_pk_mul_f32 v[6:7], v[6:7], v[192:193]
	v_pk_fma_f32 v[4:5], v[28:29], v[192:193], v[4:5]
	v_pk_fma_f32 v[6:7], v[28:29], v[194:195], v[6:7] neg_lo:[0,0,1] neg_hi:[0,0,1]
	s_mov_b32 s78, s19
	v_pk_add_f32 v[12:13], v[6:7], v[4:5] op_sel:[0,1] op_sel_hi:[1,0] neg_lo:[0,1] neg_hi:[0,1]
	v_pk_add_f32 v[28:29], v[6:7], v[4:5] op_sel:[0,1] op_sel_hi:[1,0]
	v_pk_add_f32 v[4:5], v[4:5], v[6:7] op_sel:[1,0] op_sel_hi:[0,1] neg_lo:[0,1] neg_hi:[0,1]
	v_mov_b32_e32 v13, v29
	v_pk_mul_f32 v[12:13], v[12:13], 0.5 op_sel_hi:[1,0]
	v_mov_b32_e32 v29, v5
	v_mul_f32_e32 v24, v190, v12
	v_pk_fma_f32 v[30:31], v[190:191], v[12:13], v[24:25] op_sel_hi:[1,1,0] neg_lo:[1,0,0] neg_hi:[1,0,0]
	v_mul_f32_e32 v24, v160, v13
	v_pk_fma_f32 v[12:13], v[16:17], v[12:13], v[24:25] op_sel_hi:[1,1,0]
	v_mov_b32_e32 v16, v83
	v_mov_b32_e32 v30, v12
	v_pk_fma_f32 v[4:5], v[28:29], 0.5, v[12:13] op_sel_hi:[1,0,1] neg_lo:[0,0,1] neg_hi:[0,0,1]
	v_pk_fma_f32 v[122:123], v[28:29], 0.5, v[30:31] op_sel_hi:[1,0,1]
	v_pk_fma_f32 v[6:7], v[28:29], 0.5, v[30:31] op_sel_hi:[1,0,1] neg_lo:[1,0,0] neg_hi:[1,0,0]
	v_mov_b32_e32 v5, v123
	v_pk_mul_f32 v[24:25], v[4:5], s[6:7] op_sel_hi:[1,0]
	v_pk_add_f32 v[4:5], v[138:139], v[188:189]
	v_pk_add_f32 v[12:13], v[138:139], v[188:189] neg_lo:[0,1] neg_hi:[0,1]
	v_mov_b32_e32 v17, v82
	v_mul_f32_e32 v6, 0.5, v13
	v_pk_add_f32 v[28:29], v[186:187], v[16:17] neg_lo:[0,1] neg_hi:[0,1]
	v_pk_add_f32 v[30:31], v[186:187], v[16:17]
	v_mov_b32_e32 v13, v5
	v_pk_mov_b32 v[32:33], v[28:29], v[30:31] op_sel:[1,0]
	v_pk_mul_f32 v[12:13], v[12:13], s[44:45]
	v_mul_f32_e32 v4, 0.5, v4
	v_pk_mul_f32 v[48:49], v[32:33], v[12:13] op_sel:[0,1] op_sel_hi:[1,0]
	v_pk_mul_f32 v[12:13], v[32:33], v[12:13]
	v_pk_add_f32 v[48:49], v[48:49], v[48:49] op_sel:[0,1] op_sel_hi:[0,1]
	v_pk_add_f32 v[50:51], v[4:5], v[48:49]
	v_pk_add_f32 v[4:5], v[4:5], v[48:49] op_sel_hi:[0,1] neg_lo:[0,1] neg_hi:[0,1]
	v_mov_b32_e32 v51, v5
	v_pk_add_f32 v[4:5], v[12:13], v[12:13] op_sel:[0,1] op_sel_hi:[0,1] neg_lo:[0,1] neg_hi:[0,1]
	v_pk_add_f32 v[12:13], v[6:7], v[4:5]
	v_pk_add_f32 v[4:5], v[6:7], v[4:5] op_sel_hi:[0,1] neg_lo:[0,1] neg_hi:[0,1]
	v_mov_b32_e32 v13, v5
	v_pk_mul_f32 v[4:5], v[12:13], v[184:185]
	v_pk_mul_f32 v[12:13], v[12:13], v[170:171]
	v_pk_fma_f32 v[4:5], v[50:51], v[170:171], v[4:5]
	v_pk_fma_f32 v[12:13], v[50:51], v[184:185], v[12:13] neg_lo:[0,0,1] neg_hi:[0,0,1]
	v_mov_b32_e32 v31, v29
	v_pk_add_f32 v[48:49], v[12:13], v[4:5] op_sel:[0,1] op_sel_hi:[1,0] neg_lo:[0,1] neg_hi:[0,1]
	v_pk_add_f32 v[50:51], v[12:13], v[4:5] op_sel:[0,1] op_sel_hi:[1,0]
	v_pk_add_f32 v[4:5], v[4:5], v[12:13] op_sel:[1,0] op_sel_hi:[0,1] neg_lo:[0,1] neg_hi:[0,1]
	v_mov_b32_e32 v49, v51
	v_pk_mul_f32 v[48:49], v[48:49], 0.5 op_sel_hi:[1,0]
	v_mov_b32_e32 v51, v5
	v_mul_f32_e32 v6, v29, v48
	v_pk_fma_f32 v[32:33], v[32:33], v[48:49], v[6:7] op_sel_hi:[1,1,0] neg_lo:[1,0,0] neg_hi:[1,0,0]
	v_mul_f32_e32 v6, v29, v49
	v_pk_fma_f32 v[28:29], v[30:31], v[48:49], v[6:7] op_sel_hi:[1,1,0]
	v_pk_mul_f32 v[12:13], v[16:17], s[36:37]
	v_mov_b32_e32 v32, v28
	v_pk_fma_f32 v[4:5], v[50:51], 0.5, v[28:29] op_sel_hi:[1,0,1] neg_lo:[0,0,1] neg_hi:[0,0,1]
	v_pk_fma_f32 v[138:139], v[50:51], 0.5, v[32:33] op_sel_hi:[1,0,1]
	v_pk_add_f32 v[16:17], v[92:93], v[182:183]
	v_mov_b32_e32 v5, v139
	v_pk_add_f32 v[28:29], v[92:93], v[182:183] neg_lo:[0,1] neg_hi:[0,1]
	v_pk_mul_f32 v[30:31], v[4:5], s[6:7] op_sel_hi:[1,0]
	v_pk_fma_f32 v[4:5], v[50:51], 0.5, v[32:33] op_sel_hi:[1,0,1] neg_lo:[1,0,0] neg_hi:[1,0,0]
	v_mul_f32_e32 v6, 0.5, v29
	v_pk_add_f32 v[32:33], v[18:19], v[12:13] op_sel:[0,1] op_sel_hi:[0,1] neg_lo:[0,1] neg_hi:[0,1]
	v_pk_add_f32 v[48:49], v[18:19], v[12:13] op_sel:[0,1] op_sel_hi:[0,1]
	v_mov_b32_e32 v29, v17
	v_mul_f32_e32 v4, 0.5, v16
	v_mov_b32_e32 v50, v32
	v_mov_b32_e32 v51, v49
	v_pk_mul_f32 v[16:17], v[28:29], s[44:45]
	v_pk_mov_b32 v[48:49], v[48:49], v[32:33] op_sel:[1,0]
	v_pk_mul_f32 v[28:29], v[50:51], v[16:17] op_sel:[0,1] op_sel_hi:[1,0]
	v_pk_mul_f32 v[16:17], v[50:51], v[16:17]
	v_pk_add_f32 v[28:29], v[28:29], v[28:29] op_sel:[0,1] op_sel_hi:[0,1]
	v_pk_add_f32 v[52:53], v[4:5], v[28:29]
	v_pk_add_f32 v[28:29], v[4:5], v[28:29] op_sel_hi:[0,1] neg_lo:[0,1] neg_hi:[0,1]
	v_pk_add_f32 v[16:17], v[16:17], v[16:17] op_sel:[0,1] op_sel_hi:[0,1] neg_lo:[0,1] neg_hi:[0,1]
	v_mov_b32_e32 v53, v29
	v_pk_add_f32 v[28:29], v[6:7], v[16:17]
	v_pk_add_f32 v[16:17], v[6:7], v[16:17] op_sel_hi:[0,1] neg_lo:[0,1] neg_hi:[0,1]
	v_mov_b32_e32 v29, v17
	v_pk_mul_f32 v[16:17], v[28:29], v[180:181]
	v_pk_mul_f32 v[28:29], v[28:29], v[172:173]
	v_pk_fma_f32 v[16:17], v[52:53], v[172:173], v[16:17]
	v_pk_fma_f32 v[28:29], v[52:53], v[180:181], v[28:29] neg_lo:[0,0,1] neg_hi:[0,0,1]
	v_sub_f32_e32 v6, v89, v179
	v_pk_add_f32 v[52:53], v[28:29], v[16:17] op_sel:[0,1] op_sel_hi:[1,0] neg_lo:[0,1] neg_hi:[0,1]
	v_pk_add_f32 v[54:55], v[28:29], v[16:17] op_sel:[0,1] op_sel_hi:[1,0]
	v_pk_add_f32 v[16:17], v[16:17], v[28:29] op_sel:[1,0] op_sel_hi:[0,1] neg_lo:[0,1] neg_hi:[0,1]
	v_mov_b32_e32 v53, v55
	v_pk_mul_f32 v[52:53], v[52:53], 0.5 op_sel_hi:[1,0]
	v_mov_b32_e32 v55, v17
	v_mul_f32_e32 v4, v32, v52
	v_pk_fma_f32 v[56:57], v[50:51], v[52:53], v[4:5] op_sel_hi:[1,1,0] neg_lo:[1,0,0] neg_hi:[1,0,0]
	v_mul_f32_e32 v4, v32, v53
	v_pk_fma_f32 v[48:49], v[48:49], v[52:53], v[4:5] op_sel_hi:[1,1,0]
	v_pk_add_f32 v[28:29], v[88:89], v[178:179]
	v_mov_b32_e32 v56, v48
	v_pk_fma_f32 v[16:17], v[54:55], 0.5, v[48:49] op_sel_hi:[1,0,1] neg_lo:[0,0,1] neg_hi:[0,0,1]
	v_mov_b32_e32 v48, v12
	v_mov_b32_e32 v49, v88
	v_pk_mov_b32 v[12:13], v[12:13], v[178:179] op_sel:[1,0]
	v_mul_f32_e32 v18, 0.5, v29
	v_pk_add_f32 v[12:13], v[48:49], v[12:13] neg_lo:[0,1] neg_hi:[0,1]
	v_mul_f32_e32 v4, 0.5, v28
	v_pk_mul_f32 v[48:49], v[12:13], v[18:19]
	v_mov_b32_e32 v13, v32
	v_pk_fma_f32 v[50:51], v[50:51], v[48:49], v[48:49] op_sel:[0,1,0] op_sel_hi:[1,0,1]
	v_mov_b32_e32 v48, v49
	v_mov_b32_e32 v49, v18
	v_pk_mul_f32 v[48:49], v[12:13], v[48:49]
	v_pk_add_f32 v[52:53], v[4:5], v[50:51]
	v_mul_f32_e32 v6, 0.5, v6
	v_fma_f32 v53, v28, 0.5, -v50
	v_pk_add_f32 v[28:29], v[48:49], v[48:49] op_sel:[0,1] op_sel_hi:[0,1] neg_lo:[0,1] neg_hi:[0,1]
	v_pk_add_f32 v[48:49], v[6:7], v[28:29]
	v_pk_add_f32 v[28:29], v[6:7], v[28:29] op_sel_hi:[0,1] neg_lo:[0,1] neg_hi:[0,1]
	v_mov_b32_e32 v49, v29
	v_pk_mul_f32 v[28:29], v[48:49], v[176:177]
	v_pk_mul_f32 v[48:49], v[48:49], v[174:175]
	v_pk_fma_f32 v[28:29], v[52:53], v[174:175], v[28:29]
	v_pk_fma_f32 v[48:49], v[52:53], v[176:177], v[48:49] neg_lo:[0,0,1] neg_hi:[0,0,1]
	v_pk_fma_f32 v[92:93], v[54:55], 0.5, v[56:57] op_sel_hi:[1,0,1]
	v_pk_add_f32 v[50:51], v[48:49], v[28:29] op_sel:[0,1] op_sel_hi:[1,0] neg_lo:[0,1] neg_hi:[0,1]
	v_pk_add_f32 v[52:53], v[48:49], v[28:29] op_sel:[0,1] op_sel_hi:[1,0]
	v_mov_b32_e32 v17, v93
	v_mov_b32_e32 v51, v53
	v_pk_mul_f32 v[50:51], v[50:51], 0.5 op_sel_hi:[1,0]
	v_pk_mul_f32 v[64:65], v[16:17], s[6:7] op_sel_hi:[1,0]
	v_mul_f32_e32 v4, v12, v50
	v_pk_fma_f32 v[16:17], v[54:55], 0.5, v[56:57] op_sel_hi:[1,0,1] neg_lo:[1,0,0] neg_hi:[1,0,0]
	v_pk_fma_f32 v[54:55], v[12:13], v[50:51], v[4:5] op_sel_hi:[1,1,0] neg_lo:[1,0,0] neg_hi:[1,0,0]
	v_mov_b32_e32 v33, v12
	v_mul_f32_e32 v4, v12, v51
	v_pk_fma_f32 v[12:13], v[32:33], v[50:51], v[4:5] op_sel_hi:[1,1,0]
	v_pk_add_f32 v[28:29], v[28:29], v[48:49] op_sel:[1,0] op_sel_hi:[0,1] neg_lo:[0,1] neg_hi:[0,1]
	v_mov_b32_e32 v53, v29
	v_mov_b32_e32 v54, v12
	v_pk_fma_f32 v[12:13], v[52:53], 0.5, v[12:13] op_sel_hi:[1,0,1] neg_lo:[0,0,1] neg_hi:[0,0,1]
	v_pk_fma_f32 v[88:89], v[52:53], 0.5, v[54:55] op_sel_hi:[1,0,1]
	s_mov_b32 s79, s16
	v_mov_b32_e32 v13, v89
	v_pk_mul_f32 v[68:69], v[12:13], s[6:7] op_sel_hi:[1,0]
	v_pk_fma_f32 v[12:13], v[52:53], 0.5, v[54:55] op_sel_hi:[1,0,1] neg_lo:[1,0,0] neg_hi:[1,0,0]
	v_mov_b32_e32 v4, v83
	s_mov_b32 s17, s19
	v_pk_mul_f32 v[48:49], v[82:83], s[78:79] op_sel_hi:[0,1]
	v_pk_add_f32 v[28:29], v[96:97], v[162:163]
	v_pk_add_f32 v[32:33], v[96:97], v[162:163] neg_lo:[0,1] neg_hi:[0,1]
	v_pk_fma_f32 v[52:53], v[4:5], s[16:17], v[48:49] op_sel_hi:[0,1,1] neg_lo:[0,0,1] neg_hi:[0,0,1]
	v_mul_f32_e32 v12, 0.5, v33
	v_pk_fma_f32 v[50:51], v[4:5], s[16:17], v[48:49] op_sel_hi:[0,1,1]
	v_mov_b32_e32 v33, v29
	v_mul_f32_e32 v6, 0.5, v28
	v_mov_b32_e32 v54, v52
	v_mov_b32_e32 v55, v51
	v_pk_mul_f32 v[28:29], v[32:33], s[44:45]
	v_pk_mov_b32 v[56:57], v[50:51], v[52:53] op_sel:[1,0]
	v_pk_mul_f32 v[32:33], v[54:55], v[28:29] op_sel:[0,1] op_sel_hi:[1,0]
	v_pk_mul_f32 v[28:29], v[54:55], v[28:29]
	v_pk_add_f32 v[32:33], v[32:33], v[32:33] op_sel:[0,1] op_sel_hi:[0,1]
	v_pk_add_f32 v[58:59], v[6:7], v[32:33]
	v_pk_add_f32 v[32:33], v[6:7], v[32:33] op_sel_hi:[0,1] neg_lo:[0,1] neg_hi:[0,1]
	v_pk_add_f32 v[28:29], v[28:29], v[28:29] op_sel:[0,1] op_sel_hi:[0,1] neg_lo:[0,1] neg_hi:[0,1]
	v_mov_b32_e32 v59, v33
	v_pk_add_f32 v[32:33], v[12:13], v[28:29]
	v_pk_add_f32 v[28:29], v[12:13], v[28:29] op_sel_hi:[0,1] neg_lo:[0,1] neg_hi:[0,1]
	v_mov_b32_e32 v33, v29
	v_pk_mul_f32 v[28:29], v[32:33], v[166:167]
	v_pk_mul_f32 v[32:33], v[32:33], v[164:165]
	v_pk_fma_f32 v[28:29], v[58:59], v[164:165], v[28:29]
	v_pk_fma_f32 v[32:33], v[58:59], v[166:167], v[32:33] neg_lo:[0,0,1] neg_hi:[0,0,1]
	v_mov_b32_e32 v159, v66
	v_pk_add_f32 v[58:59], v[32:33], v[28:29] op_sel:[0,1] op_sel_hi:[1,0] neg_lo:[0,1] neg_hi:[0,1]
	v_pk_add_f32 v[70:71], v[32:33], v[28:29] op_sel:[0,1] op_sel_hi:[1,0]
	v_pk_add_f32 v[28:29], v[28:29], v[32:33] op_sel:[1,0] op_sel_hi:[0,1] neg_lo:[0,1] neg_hi:[0,1]
	v_mov_b32_e32 v59, v71
	v_pk_mul_f32 v[58:59], v[58:59], 0.5 op_sel_hi:[1,0]
	v_mov_b32_e32 v71, v29
	v_mul_f32_e32 v6, v52, v58
	v_pk_fma_f32 v[72:73], v[54:55], v[58:59], v[6:7] op_sel_hi:[1,1,0] neg_lo:[1,0,0] neg_hi:[1,0,0]
	v_mul_f32_e32 v6, v52, v59
	v_pk_fma_f32 v[56:57], v[56:57], v[58:59], v[6:7] op_sel_hi:[1,1,0]
	v_sub_f32_e32 v12, v67, v153
	v_mov_b32_e32 v72, v56
	v_pk_fma_f32 v[28:29], v[70:71], 0.5, v[56:57] op_sel_hi:[1,0,1] neg_lo:[0,0,1] neg_hi:[0,0,1]
	v_pk_fma_f32 v[96:97], v[70:71], 0.5, v[72:73] op_sel_hi:[1,0,1]
	v_pk_mov_b32 v[56:57], v[48:49], v[152:153] op_sel:[1,0]
	v_mov_b32_e32 v29, v97
	v_pk_mul_f32 v[62:63], v[28:29], s[6:7] op_sel_hi:[1,0]
	v_pk_add_f32 v[28:29], v[66:67], v[152:153]
	v_pk_add_f32 v[56:57], v[158:159], v[56:57] neg_lo:[0,1] neg_hi:[0,1]
	v_mul_f32_e32 v18, 0.5, v29
	v_pk_mul_f32 v[58:59], v[56:57], v[18:19]
	v_mul_f32_e32 v6, 0.5, v28
	v_pk_fma_f32 v[54:55], v[54:55], v[58:59], v[58:59] op_sel:[0,1,0] op_sel_hi:[1,0,1]
	v_mov_b32_e32 v66, v56
	v_mov_b32_e32 v67, v52
	v_mov_b32_e32 v58, v59
	v_mov_b32_e32 v59, v18
	v_pk_mul_f32 v[58:59], v[66:67], v[58:59]
	v_pk_add_f32 v[66:67], v[6:7], v[54:55]
	v_mul_f32_e32 v12, 0.5, v12
	v_fma_f32 v67, v28, 0.5, -v54
	v_pk_add_f32 v[28:29], v[58:59], v[58:59] op_sel:[0,1] op_sel_hi:[0,1] neg_lo:[0,1] neg_hi:[0,1]
	v_pk_add_f32 v[54:55], v[12:13], v[28:29]
	v_pk_add_f32 v[28:29], v[12:13], v[28:29] op_sel_hi:[0,1] neg_lo:[0,1] neg_hi:[0,1]
	v_mov_b32_e32 v55, v29
	v_pk_mul_f32 v[28:29], v[54:55], v[156:157]
	v_pk_mul_f32 v[54:55], v[54:55], v[154:155]
	v_pk_fma_f32 v[32:33], v[70:71], 0.5, v[72:73] op_sel_hi:[1,0,1] neg_lo:[1,0,0] neg_hi:[1,0,0]
	v_pk_fma_f32 v[58:59], v[66:67], v[154:155], v[28:29] neg_lo:[0,0,1] neg_hi:[0,0,1]
	v_pk_fma_f32 v[28:29], v[66:67], v[154:155], v[28:29]
	v_pk_fma_f32 v[70:71], v[66:67], v[156:157], v[54:55]
	v_pk_fma_f32 v[54:55], v[66:67], v[156:157], v[54:55] neg_lo:[0,0,1] neg_hi:[0,0,1]
	v_pk_add_f32 v[72:73], v[58:59], v[28:29] op_sel:[0,1] op_sel_hi:[1,0]
	v_pk_add_f32 v[66:67], v[70:71], v[54:55] op_sel_hi:[0,1] neg_lo:[0,1] neg_hi:[0,1]
	v_pk_add_f32 v[28:29], v[58:59], v[28:29] op_sel_hi:[0,1] neg_lo:[0,1] neg_hi:[0,1]
	v_pk_add_f32 v[54:55], v[70:71], v[54:55] op_sel:[0,1] op_sel_hi:[1,0]
	v_mov_b32_e32 v73, v67
	v_mov_b32_e32 v55, v29
	v_pk_mul_f32 v[28:29], v[54:55], 0.5 op_sel_hi:[1,0]
	v_mov_b32_e32 v133, v84
	v_pk_mul_f32 v[54:55], v[52:53], v[28:29] op_sel:[0,1] op_sel_hi:[0,0]
	v_pk_fma_f32 v[58:59], v[56:57], v[28:29], v[54:55] op_sel_hi:[0,1,1]
	v_pk_fma_f32 v[28:29], v[56:57], v[28:29], v[54:55] op_sel_hi:[0,1,1] neg_lo:[0,0,1] neg_hi:[0,0,1]
	v_mov_b32_e32 v28, v58
	v_pk_fma_f32 v[54:55], v[72:73], 0.5, v[58:59] op_sel_hi:[1,0,1] neg_lo:[0,0,1] neg_hi:[0,0,1]
	v_pk_fma_f32 v[66:67], v[72:73], 0.5, v[28:29] op_sel_hi:[1,0,1]
	v_pk_add_f32 v[56:57], v[60:61], v[134:135] neg_lo:[0,1] neg_hi:[0,1]
	v_mov_b32_e32 v55, v67
	v_pk_mul_f32 v[90:91], v[54:55], s[6:7] op_sel_hi:[1,0]
	v_pk_add_f32 v[54:55], v[134:135], v[60:61]
	v_mul_f32_e32 v12, 0.5, v57
	v_mov_b32_e32 v57, v55
	v_mul_f32_e32 v6, 0.5, v54
	v_pk_mov_b32 v[58:59], v[52:53], v[50:51] op_sel:[1,0]
	v_pk_mul_f32 v[54:55], v[56:57], s[44:45]
	v_pk_fma_f32 v[28:29], v[72:73], 0.5, v[28:29] op_sel_hi:[1,0,1] neg_lo:[1,0,0] neg_hi:[1,0,0]
	v_pk_mul_f32 v[56:57], v[58:59], v[54:55] op_sel:[0,1] op_sel_hi:[1,0]
	v_pk_mul_f32 v[54:55], v[58:59], v[54:55]
	v_pk_add_f32 v[56:57], v[56:57], v[56:57] op_sel:[0,1] op_sel_hi:[0,1]
	v_pk_add_f32 v[60:61], v[6:7], v[56:57]
	v_pk_add_f32 v[56:57], v[6:7], v[56:57] op_sel_hi:[0,1] neg_lo:[0,1] neg_hi:[0,1]
	v_pk_add_f32 v[54:55], v[54:55], v[54:55] op_sel:[0,1] op_sel_hi:[0,1] neg_lo:[0,1] neg_hi:[0,1]
	v_mov_b32_e32 v61, v57
	v_pk_add_f32 v[56:57], v[12:13], v[54:55]
	v_pk_add_f32 v[54:55], v[12:13], v[54:55] op_sel_hi:[0,1] neg_lo:[0,1] neg_hi:[0,1]
	v_mov_b32_e32 v57, v55
	v_pk_mul_f32 v[54:55], v[56:57], v[142:143]
	v_pk_mul_f32 v[56:57], v[56:57], v[140:141]
	v_pk_fma_f32 v[54:55], v[60:61], v[140:141], v[54:55]
	v_pk_fma_f32 v[56:57], v[60:61], v[142:143], v[56:57] neg_lo:[0,0,1] neg_hi:[0,0,1]
	v_mov_b32_e32 v51, v53
	v_pk_add_f32 v[60:61], v[56:57], v[54:55] op_sel:[0,1] op_sel_hi:[1,0] neg_lo:[0,1] neg_hi:[0,1]
	v_pk_add_f32 v[70:71], v[56:57], v[54:55] op_sel:[0,1] op_sel_hi:[1,0]
	v_pk_add_f32 v[54:55], v[54:55], v[56:57] op_sel:[1,0] op_sel_hi:[0,1] neg_lo:[0,1] neg_hi:[0,1]
	v_mov_b32_e32 v61, v71
	v_pk_mul_f32 v[60:61], v[60:61], 0.5 op_sel_hi:[1,0]
	v_mov_b32_e32 v71, v55
	v_mul_f32_e32 v6, v53, v60
	v_pk_fma_f32 v[72:73], v[58:59], v[60:61], v[6:7] op_sel_hi:[1,1,0] neg_lo:[1,0,0] neg_hi:[1,0,0]
	v_mul_f32_e32 v6, v53, v61
	v_pk_fma_f32 v[50:51], v[50:51], v[60:61], v[6:7] op_sel_hi:[1,1,0]
	v_pk_add_f32 v[54:55], v[118:119], v[84:85]
	v_mov_b32_e32 v72, v50
	v_mov_b32_e32 v49, v118
	v_pk_fma_f32 v[50:51], v[70:71], 0.5, v[50:51] op_sel_hi:[1,0,1] neg_lo:[0,0,1] neg_hi:[0,0,1]
	v_pk_fma_f32 v[60:61], v[70:71], 0.5, v[72:73] op_sel_hi:[1,0,1]
	v_mul_f32_e32 v18, 0.5, v55
	v_pk_add_f32 v[48:49], v[132:133], v[48:49] neg_lo:[0,1] neg_hi:[0,1]
	v_mov_b32_e32 v51, v61
	v_pk_mul_f32 v[56:57], v[48:49], v[18:19]
	v_pk_mul_f32 v[94:95], v[50:51], s[6:7] op_sel_hi:[1,0]
	v_pk_fma_f32 v[50:51], v[70:71], 0.5, v[72:73] op_sel_hi:[1,0,1] neg_lo:[1,0,0] neg_hi:[1,0,0]
	v_mul_f32_e32 v6, 0.5, v54
	v_pk_fma_f32 v[58:59], v[58:59], v[56:57], v[56:57] op_sel:[0,1,0] op_sel_hi:[1,0,1]
	v_mov_b32_e32 v70, v48
	v_mov_b32_e32 v71, v53
	v_mov_b32_e32 v56, v57
	v_mov_b32_e32 v57, v18
	v_sub_f32_e32 v12, v85, v119
	v_pk_mul_f32 v[56:57], v[70:71], v[56:57]
	v_pk_add_f32 v[70:71], v[6:7], v[58:59]
	v_mul_f32_e32 v12, 0.5, v12
	v_fma_f32 v71, v54, 0.5, -v58
	v_pk_add_f32 v[54:55], v[56:57], v[56:57] op_sel:[0,1] op_sel_hi:[0,1] neg_lo:[0,1] neg_hi:[0,1]
	v_pk_add_f32 v[56:57], v[12:13], v[54:55]
	v_pk_add_f32 v[54:55], v[12:13], v[54:55] op_sel_hi:[0,1] neg_lo:[0,1] neg_hi:[0,1]
	v_mov_b32_e32 v57, v55
	v_pk_mul_f32 v[54:55], v[56:57], v[126:127]
	v_pk_mul_f32 v[56:57], v[56:57], v[124:125]
	v_pk_fma_f32 v[58:59], v[70:71], v[124:125], v[54:55] neg_lo:[0,0,1] neg_hi:[0,0,1]
	v_pk_fma_f32 v[54:55], v[70:71], v[124:125], v[54:55]
	v_pk_fma_f32 v[72:73], v[70:71], v[126:127], v[56:57]
	v_pk_fma_f32 v[56:57], v[70:71], v[126:127], v[56:57] neg_lo:[0,0,1] neg_hi:[0,0,1]
	v_pk_add_f32 v[70:71], v[58:59], v[54:55] op_sel:[0,1] op_sel_hi:[1,0]
	v_pk_add_f32 v[74:75], v[72:73], v[56:57] op_sel_hi:[0,1] neg_lo:[0,1] neg_hi:[0,1]
	v_pk_add_f32 v[54:55], v[58:59], v[54:55] op_sel_hi:[0,1] neg_lo:[0,1] neg_hi:[0,1]
	v_pk_add_f32 v[56:57], v[72:73], v[56:57] op_sel:[0,1] op_sel_hi:[1,0]
	v_mov_b32_e32 v71, v75
	v_mov_b32_e32 v57, v55
	v_pk_mul_f32 v[54:55], v[56:57], 0.5 op_sel_hi:[1,0]
	s_mov_b32 s78, s11
	v_pk_mul_f32 v[52:53], v[52:53], v[54:55] op_sel:[1,1] op_sel_hi:[1,0]
	s_mov_b32 s79, s8
	v_pk_fma_f32 v[56:57], v[48:49], v[54:55], v[52:53] op_sel_hi:[0,1,1]
	v_pk_fma_f32 v[48:49], v[48:49], v[54:55], v[52:53] op_sel_hi:[0,1,1] neg_lo:[0,0,1] neg_hi:[0,0,1]
	v_mov_b32_e32 v48, v56
	v_pk_fma_f32 v[52:53], v[70:71], 0.5, v[56:57] op_sel_hi:[1,0,1] neg_lo:[0,0,1] neg_hi:[0,0,1]
	v_pk_fma_f32 v[84:85], v[70:71], 0.5, v[48:49] op_sel_hi:[1,0,1]
	s_mov_b32 s9, s11
	v_mov_b32_e32 v53, v85
	v_pk_mul_f32 v[80:81], v[52:53], s[6:7] op_sel_hi:[1,0]
	v_pk_mul_f32 v[118:119], v[82:83], s[78:79] op_sel_hi:[0,1]
	v_pk_add_f32 v[52:53], v[86:87], v[112:113]
	v_pk_add_f32 v[54:55], v[86:87], v[112:113] neg_lo:[0,1] neg_hi:[0,1]
	v_pk_fma_f32 v[58:59], v[4:5], s[8:9], v[118:119] op_sel_hi:[0,1,1] neg_lo:[0,0,1] neg_hi:[0,0,1]
	v_mul_f32_e32 v12, 0.5, v55
	v_pk_fma_f32 v[72:73], v[4:5], s[8:9], v[118:119] op_sel_hi:[0,1,1]
	v_mov_b32_e32 v55, v53
	v_mul_f32_e32 v6, 0.5, v52
	v_mov_b32_e32 v56, v58
	v_mov_b32_e32 v57, v73
	v_pk_mul_f32 v[52:53], v[54:55], s[44:45]
	v_pk_fma_f32 v[48:49], v[70:71], 0.5, v[48:49] op_sel_hi:[1,0,1] neg_lo:[1,0,0] neg_hi:[1,0,0]
	v_pk_mul_f32 v[54:55], v[56:57], v[52:53] op_sel:[0,1] op_sel_hi:[1,0]
	v_pk_mul_f32 v[52:53], v[56:57], v[52:53]
	v_pk_add_f32 v[54:55], v[54:55], v[54:55] op_sel:[0,1] op_sel_hi:[0,1]
	v_pk_add_f32 v[74:75], v[6:7], v[54:55]
	v_pk_add_f32 v[54:55], v[6:7], v[54:55] op_sel_hi:[0,1] neg_lo:[0,1] neg_hi:[0,1]
	v_pk_add_f32 v[52:53], v[52:53], v[52:53] op_sel:[0,1] op_sel_hi:[0,1] neg_lo:[0,1] neg_hi:[0,1]
	v_mov_b32_e32 v75, v55
	v_pk_add_f32 v[54:55], v[12:13], v[52:53]
	v_pk_add_f32 v[52:53], v[12:13], v[52:53] op_sel_hi:[0,1] neg_lo:[0,1] neg_hi:[0,1]
	v_mov_b32_e32 v55, v53
	v_pk_mul_f32 v[52:53], v[54:55], v[116:117]
	v_pk_mul_f32 v[54:55], v[54:55], v[114:115]
	v_pk_fma_f32 v[52:53], v[74:75], v[114:115], v[52:53]
	v_pk_fma_f32 v[54:55], v[74:75], v[116:117], v[54:55] neg_lo:[0,0,1] neg_hi:[0,0,1]
	v_pk_mov_b32 v[70:71], v[72:73], v[58:59] op_sel:[1,0]
	v_pk_add_f32 v[74:75], v[54:55], v[52:53] op_sel:[0,1] op_sel_hi:[1,0] neg_lo:[0,1] neg_hi:[0,1]
	v_pk_add_f32 v[76:77], v[54:55], v[52:53] op_sel:[0,1] op_sel_hi:[1,0]
	v_pk_add_f32 v[52:53], v[52:53], v[54:55] op_sel:[1,0] op_sel_hi:[0,1] neg_lo:[0,1] neg_hi:[0,1]
	v_mov_b32_e32 v75, v77
	v_pk_mul_f32 v[74:75], v[74:75], 0.5 op_sel_hi:[1,0]
	v_mov_b32_e32 v77, v53
	v_mul_f32_e32 v6, v58, v74
	v_pk_fma_f32 v[112:113], v[56:57], v[74:75], v[6:7] op_sel_hi:[1,1,0] neg_lo:[1,0,0] neg_hi:[1,0,0]
	v_mul_f32_e32 v6, v58, v75
	v_pk_fma_f32 v[70:71], v[70:71], v[74:75], v[6:7] op_sel_hi:[1,1,0]
	v_pk_add_f32 v[54:55], v[34:35], v[110:111]
	v_mov_b32_e32 v112, v70
	v_pk_fma_f32 v[52:53], v[76:77], 0.5, v[70:71] op_sel_hi:[1,0,1] neg_lo:[0,0,1] neg_hi:[0,0,1]
	v_pk_fma_f32 v[86:87], v[76:77], 0.5, v[112:113] op_sel_hi:[1,0,1]
	v_sub_f32_e32 v12, v35, v111
	v_mov_b32_e32 v53, v87
	v_pk_mul_f32 v[78:79], v[52:53], s[6:7] op_sel_hi:[1,0]
	v_mul_f32_e32 v52, 0xbe47c5c2, v83
	v_mov_b32_e32 v53, v34
	v_pk_mov_b32 v[34:35], v[118:119], v[110:111] op_sel:[1,0]
	v_mul_f32_e32 v18, 0.5, v55
	v_pk_add_f32 v[34:35], v[52:53], v[34:35] neg_lo:[0,1] neg_hi:[0,1]
	v_mov_b32_e32 v71, v58
	v_pk_mul_f32 v[52:53], v[34:35], v[18:19]
	v_mov_b32_e32 v70, v34
	v_pk_fma_f32 v[56:57], v[56:57], v[52:53], v[52:53] op_sel:[0,1,0] op_sel_hi:[1,0,1]
	v_mov_b32_e32 v52, v53
	v_mov_b32_e32 v53, v18
	v_mul_f32_e32 v6, 0.5, v54
	v_pk_mul_f32 v[52:53], v[70:71], v[52:53]
	v_cvt_f32_f16_e32 v70, v46
	v_cvt_f32_f16_e32 v71, v47
	v_cvt_f32_f16_sdwa v47, v47 dst_sel:DWORD dst_unused:UNUSED_PAD src0_sel:WORD_1
	v_cvt_f32_f16_sdwa v46, v46 dst_sel:DWORD dst_unused:UNUSED_PAD src0_sel:WORD_1
	v_pk_fma_f32 v[74:75], v[76:77], 0.5, v[112:113] op_sel_hi:[1,0,1] neg_lo:[1,0,0] neg_hi:[1,0,0]
	v_mul_f32_e32 v12, 0.5, v12
	v_pk_add_f32 v[76:77], v[6:7], v[56:57]
	v_pk_add_f32 v[52:53], v[52:53], v[52:53] op_sel:[0,1] op_sel_hi:[0,1] neg_lo:[0,1] neg_hi:[0,1]
	v_fma_f32 v77, v54, 0.5, -v56
	v_pk_add_f32 v[54:55], v[12:13], v[52:53]
	v_pk_add_f32 v[52:53], v[12:13], v[52:53] op_sel_hi:[0,1] neg_lo:[0,1] neg_hi:[0,1]
	v_mov_b32_e32 v55, v53
	v_pk_mul_f32 v[52:53], v[54:55], v[46:47]
	v_pk_mul_f32 v[54:55], v[54:55], v[70:71]
	v_pk_fma_f32 v[56:57], v[76:77], v[70:71], v[52:53] neg_lo:[0,0,1] neg_hi:[0,0,1]
	v_pk_fma_f32 v[52:53], v[76:77], v[70:71], v[52:53]
	v_pk_fma_f32 v[70:71], v[76:77], v[46:47], v[54:55]
	v_pk_fma_f32 v[46:47], v[76:77], v[46:47], v[54:55] neg_lo:[0,0,1] neg_hi:[0,0,1]
	v_pk_add_f32 v[54:55], v[56:57], v[52:53] op_sel:[0,1] op_sel_hi:[1,0]
	v_pk_add_f32 v[76:77], v[70:71], v[46:47] op_sel_hi:[0,1] neg_lo:[0,1] neg_hi:[0,1]
	v_pk_add_f32 v[52:53], v[56:57], v[52:53] op_sel_hi:[0,1] neg_lo:[0,1] neg_hi:[0,1]
	v_pk_add_f32 v[46:47], v[70:71], v[46:47] op_sel:[0,1] op_sel_hi:[1,0]
	v_mov_b32_e32 v55, v77
	v_mov_b32_e32 v47, v53
	v_pk_mul_f32 v[46:47], v[46:47], 0.5 op_sel_hi:[1,0]
	s_mov_b32 s25, s27
	v_pk_mul_f32 v[52:53], v[58:59], v[46:47] op_sel:[0,1] op_sel_hi:[0,0]
	v_pk_fma_f32 v[56:57], v[34:35], v[46:47], v[52:53] op_sel_hi:[0,1,1]
	v_pk_fma_f32 v[46:47], v[34:35], v[46:47], v[52:53] op_sel_hi:[0,1,1] neg_lo:[0,0,1] neg_hi:[0,0,1]
	v_mov_b32_e32 v46, v56
	v_pk_fma_f32 v[52:53], v[54:55], 0.5, v[56:57] op_sel_hi:[1,0,1] neg_lo:[0,0,1] neg_hi:[0,0,1]
	v_pk_fma_f32 v[34:35], v[54:55], 0.5, v[46:47] op_sel_hi:[1,0,1]
	s_mov_b32 s78, s27
	v_mov_b32_e32 v53, v35
	v_pk_mul_f32 v[136:137], v[52:53], s[6:7] op_sel_hi:[1,0]
	v_pk_fma_f32 v[52:53], v[54:55], 0.5, v[46:47] op_sel_hi:[1,0,1] neg_lo:[1,0,0] neg_hi:[1,0,0]
	s_mov_b32 s79, s24
	v_pk_mul_f32 v[46:47], v[82:83], s[24:25] op_sel_hi:[0,1]
	v_pk_add_f32 v[54:55], v[108:109], v[40:41]
	v_pk_add_f32 v[40:41], v[40:41], v[108:109] neg_lo:[0,1] neg_hi:[0,1]
	v_pk_fma_f32 v[108:109], v[4:5], s[78:79], v[46:47] op_sel_hi:[0,1,1] neg_lo:[0,0,1] neg_hi:[0,0,1]
	v_mul_f32_e32 v12, 0.5, v41
	v_pk_fma_f32 v[70:71], v[4:5], s[78:79], v[46:47] op_sel_hi:[0,1,1]
	v_mov_b32_e32 v41, v55
	v_mov_b32_e32 v56, v108
	v_mov_b32_e32 v57, v71
	v_pk_mul_f32 v[40:41], v[40:41], s[44:45]
	v_mul_f32_e32 v6, 0.5, v54
	v_pk_mul_f32 v[54:55], v[56:57], v[40:41] op_sel:[0,1] op_sel_hi:[1,0]
	v_cvt_f32_f16_sdwa v76, v36 dst_sel:DWORD dst_unused:UNUSED_PAD src0_sel:WORD_1
	v_cvt_f32_f16_e32 v77, v37
	v_cvt_f32_f16_sdwa v37, v37 dst_sel:DWORD dst_unused:UNUSED_PAD src0_sel:WORD_1
	v_cvt_f32_f16_e32 v36, v36
	v_pk_mul_f32 v[40:41], v[56:57], v[40:41]
	v_pk_add_f32 v[54:55], v[54:55], v[54:55] op_sel:[0,1] op_sel_hi:[0,1]
	v_pk_add_f32 v[112:113], v[6:7], v[54:55]
	v_pk_add_f32 v[54:55], v[6:7], v[54:55] op_sel_hi:[0,1] neg_lo:[0,1] neg_hi:[0,1]
	v_pk_add_f32 v[40:41], v[40:41], v[40:41] op_sel:[0,1] op_sel_hi:[0,1] neg_lo:[0,1] neg_hi:[0,1]
	v_mov_b32_e32 v113, v55
	v_pk_add_f32 v[54:55], v[12:13], v[40:41]
	v_pk_add_f32 v[40:41], v[12:13], v[40:41] op_sel_hi:[0,1] neg_lo:[0,1] neg_hi:[0,1]
	v_mov_b32_e32 v55, v41
	v_pk_mul_f32 v[40:41], v[54:55], v[36:37]
	v_pk_mul_f32 v[54:55], v[54:55], v[76:77]
	v_pk_fma_f32 v[40:41], v[112:113], v[76:77], v[40:41]
	v_pk_fma_f32 v[36:37], v[112:113], v[36:37], v[54:55] neg_lo:[0,0,1] neg_hi:[0,0,1]
	v_pk_mov_b32 v[110:111], v[70:71], v[108:109] op_sel:[1,0]
	v_pk_add_f32 v[54:55], v[36:37], v[40:41] op_sel:[0,1] op_sel_hi:[1,0] neg_lo:[0,1] neg_hi:[0,1]
	v_pk_add_f32 v[76:77], v[36:37], v[40:41] op_sel:[0,1] op_sel_hi:[1,0]
	v_pk_add_f32 v[36:37], v[40:41], v[36:37] op_sel:[1,0] op_sel_hi:[0,1] neg_lo:[0,1] neg_hi:[0,1]
	v_mov_b32_e32 v55, v77
	v_pk_mul_f32 v[54:55], v[54:55], 0.5 op_sel_hi:[1,0]
	v_mov_b32_e32 v77, v37
	v_mul_f32_e32 v4, v108, v54
	v_pk_fma_f32 v[112:113], v[56:57], v[54:55], v[4:5] op_sel_hi:[1,1,0] neg_lo:[1,0,0] neg_hi:[1,0,0]
	v_mul_f32_e32 v4, v108, v55
	v_pk_fma_f32 v[54:55], v[110:111], v[54:55], v[4:5] op_sel_hi:[1,1,0]
	v_sub_f32_e32 v6, v45, v105
	v_mov_b32_e32 v112, v54
	v_pk_fma_f32 v[40:41], v[76:77], 0.5, v[54:55] op_sel_hi:[1,0,1] neg_lo:[0,0,1] neg_hi:[0,0,1]
	v_pk_fma_f32 v[36:37], v[76:77], 0.5, v[112:113] op_sel_hi:[1,0,1]
	v_pk_add_f32 v[54:55], v[104:105], v[44:45]
	v_mov_b32_e32 v41, v37
	v_pk_mul_f32 v[130:131], v[40:41], s[6:7] op_sel_hi:[1,0]
	v_mul_f32_e32 v40, 0xbf54db31, v83
	v_mov_b32_e32 v41, v44
	v_pk_mov_b32 v[44:45], v[46:47], v[104:105] op_sel:[1,0]
	v_mul_f32_e32 v18, 0.5, v55
	v_pk_add_f32 v[40:41], v[40:41], v[44:45] neg_lo:[0,1] neg_hi:[0,1]
	v_mov_b32_e32 v105, v108
	v_pk_mul_f32 v[44:45], v[40:41], v[18:19]
	v_mov_b32_e32 v104, v40
	v_pk_fma_f32 v[56:57], v[56:57], v[44:45], v[44:45] op_sel:[0,1,0] op_sel_hi:[1,0,1]
	v_mov_b32_e32 v44, v45
	v_mov_b32_e32 v45, v18
	v_mul_f32_e32 v4, 0.5, v54
	v_pk_mul_f32 v[44:45], v[104:105], v[44:45]
	v_cvt_f32_f16_e32 v104, v26
	v_cvt_f32_f16_e32 v105, v27
	v_cvt_f32_f16_sdwa v27, v27 dst_sel:DWORD dst_unused:UNUSED_PAD src0_sel:WORD_1
	v_cvt_f32_f16_sdwa v26, v26 dst_sel:DWORD dst_unused:UNUSED_PAD src0_sel:WORD_1
	v_mul_f32_e32 v6, 0.5, v6
	v_pk_add_f32 v[110:111], v[4:5], v[56:57]
	v_pk_add_f32 v[44:45], v[44:45], v[44:45] op_sel:[0,1] op_sel_hi:[0,1] neg_lo:[0,1] neg_hi:[0,1]
	v_fma_f32 v111, v54, 0.5, -v56
	v_pk_add_f32 v[54:55], v[6:7], v[44:45]
	v_pk_add_f32 v[44:45], v[6:7], v[44:45] op_sel_hi:[0,1] neg_lo:[0,1] neg_hi:[0,1]
	v_mov_b32_e32 v55, v45
	v_pk_mul_f32 v[44:45], v[54:55], v[26:27]
	v_pk_mul_f32 v[54:55], v[54:55], v[104:105]
	v_pk_fma_f32 v[56:57], v[110:111], v[104:105], v[44:45] neg_lo:[0,0,1] neg_hi:[0,0,1]
	v_pk_fma_f32 v[44:45], v[110:111], v[104:105], v[44:45]
	v_pk_fma_f32 v[104:105], v[110:111], v[26:27], v[54:55]
	v_pk_fma_f32 v[26:27], v[110:111], v[26:27], v[54:55] neg_lo:[0,0,1] neg_hi:[0,0,1]
	v_pk_add_f32 v[54:55], v[56:57], v[44:45] op_sel:[0,1] op_sel_hi:[1,0]
	v_pk_add_f32 v[110:111], v[104:105], v[26:27] op_sel_hi:[0,1] neg_lo:[0,1] neg_hi:[0,1]
	v_pk_add_f32 v[44:45], v[56:57], v[44:45] op_sel_hi:[0,1] neg_lo:[0,1] neg_hi:[0,1]
	v_pk_add_f32 v[26:27], v[104:105], v[26:27] op_sel:[0,1] op_sel_hi:[1,0]
	v_mov_b32_e32 v55, v111
	v_mov_b32_e32 v27, v45
	v_pk_mul_f32 v[26:27], v[26:27], 0.5 op_sel_hi:[1,0]
	v_mov_b32_e32 v47, v102
	v_pk_mul_f32 v[44:45], v[108:109], v[26:27] op_sel:[0,1] op_sel_hi:[0,0]
	v_pk_fma_f32 v[56:57], v[40:41], v[26:27], v[44:45] op_sel_hi:[0,1,1]
	v_pk_fma_f32 v[40:41], v[40:41], v[26:27], v[44:45] op_sel_hi:[0,1,1] neg_lo:[0,0,1] neg_hi:[0,0,1]
	v_mov_b32_e32 v40, v56
	v_pk_fma_f32 v[44:45], v[54:55], 0.5, v[56:57] op_sel_hi:[1,0,1] neg_lo:[0,0,1] neg_hi:[0,0,1]
	v_pk_fma_f32 v[26:27], v[54:55], 0.5, v[40:41] op_sel_hi:[1,0,1]
	v_pk_fma_f32 v[56:57], v[54:55], 0.5, v[40:41] op_sel_hi:[1,0,1] neg_lo:[1,0,0] neg_hi:[1,0,0]
	v_pk_add_f32 v[40:41], v[106:107], v[42:43]
	v_pk_add_f32 v[42:43], v[42:43], v[106:107] neg_lo:[0,1] neg_hi:[0,1]
	v_mov_b32_e32 v45, v27
	v_mul_f32_e32 v6, 0.5, v43
	v_mov_b32_e32 v43, v41
	v_pk_mul_f32 v[120:121], v[44:45], s[6:7] op_sel_hi:[1,0]
	v_mul_f32_e32 v4, 0.5, v40
	v_pk_mov_b32 v[44:45], v[108:109], v[70:71] op_sel:[1,0]
	v_pk_mul_f32 v[40:41], v[42:43], s[44:45]
	v_cvt_f32_f16_sdwa v54, v20 dst_sel:DWORD dst_unused:UNUSED_PAD src0_sel:WORD_1
	v_pk_mul_f32 v[42:43], v[44:45], v[40:41] op_sel:[0,1] op_sel_hi:[1,0]
	v_cvt_f32_f16_e32 v55, v21
	v_cvt_f32_f16_sdwa v21, v21 dst_sel:DWORD dst_unused:UNUSED_PAD src0_sel:WORD_1
	v_cvt_f32_f16_e32 v20, v20
	v_pk_mul_f32 v[40:41], v[44:45], v[40:41]
	v_pk_add_f32 v[42:43], v[42:43], v[42:43] op_sel:[0,1] op_sel_hi:[0,1]
	v_pk_add_f32 v[104:105], v[4:5], v[42:43]
	v_pk_add_f32 v[42:43], v[4:5], v[42:43] op_sel_hi:[0,1] neg_lo:[0,1] neg_hi:[0,1]
	v_pk_add_f32 v[40:41], v[40:41], v[40:41] op_sel:[0,1] op_sel_hi:[0,1] neg_lo:[0,1] neg_hi:[0,1]
	v_mov_b32_e32 v105, v43
	v_pk_add_f32 v[42:43], v[6:7], v[40:41]
	v_pk_add_f32 v[40:41], v[6:7], v[40:41] op_sel_hi:[0,1] neg_lo:[0,1] neg_hi:[0,1]
	v_mov_b32_e32 v43, v41
	v_pk_mul_f32 v[40:41], v[42:43], v[20:21]
	v_pk_mul_f32 v[42:43], v[42:43], v[54:55]
	v_pk_fma_f32 v[40:41], v[104:105], v[54:55], v[40:41]
	v_pk_fma_f32 v[20:21], v[104:105], v[20:21], v[42:43] neg_lo:[0,0,1] neg_hi:[0,0,1]
	v_mov_b32_e32 v71, v109
	v_pk_add_f32 v[42:43], v[20:21], v[40:41] op_sel:[0,1] op_sel_hi:[1,0] neg_lo:[0,1] neg_hi:[0,1]
	v_pk_add_f32 v[54:55], v[20:21], v[40:41] op_sel:[0,1] op_sel_hi:[1,0]
	v_pk_add_f32 v[20:21], v[40:41], v[20:21] op_sel:[1,0] op_sel_hi:[0,1] neg_lo:[0,1] neg_hi:[0,1]
	v_mov_b32_e32 v43, v55
	v_pk_mul_f32 v[42:43], v[42:43], 0.5 op_sel_hi:[1,0]
	v_mov_b32_e32 v55, v21
	v_mul_f32_e32 v4, v109, v42
	v_pk_fma_f32 v[104:105], v[44:45], v[42:43], v[4:5] op_sel_hi:[1,1,0] neg_lo:[1,0,0] neg_hi:[1,0,0]
	v_mul_f32_e32 v4, v109, v43
	v_pk_fma_f32 v[42:43], v[70:71], v[42:43], v[4:5] op_sel_hi:[1,1,0]
	v_sub_f32_e32 v6, v23, v103
	v_mov_b32_e32 v104, v42
	v_pk_fma_f32 v[40:41], v[54:55], 0.5, v[42:43] op_sel_hi:[1,0,1] neg_lo:[0,0,1] neg_hi:[0,0,1]
	v_pk_fma_f32 v[20:21], v[54:55], 0.5, v[104:105] op_sel_hi:[1,0,1]
	v_pk_add_f32 v[42:43], v[102:103], v[22:23]
	v_mov_b32_e32 v41, v21
	v_pk_mul_f32 v[128:129], v[40:41], s[6:7] op_sel_hi:[1,0]
	v_mul_f32_e32 v40, 0xbf0e39da, v83
	v_mov_b32_e32 v41, v22
	v_mul_f32_e32 v18, 0.5, v43
	v_pk_add_f32 v[22:23], v[40:41], v[46:47] neg_lo:[0,1] neg_hi:[0,1]
	v_mov_b32_e32 v47, v109
	v_pk_mul_f32 v[40:41], v[22:23], v[18:19]
	v_mov_b32_e32 v46, v22
	v_pk_fma_f32 v[44:45], v[44:45], v[40:41], v[40:41] op_sel:[0,1,0] op_sel_hi:[1,0,1]
	v_mov_b32_e32 v40, v41
	v_mov_b32_e32 v41, v18
	v_mul_f32_e32 v4, 0.5, v42
	v_pk_mul_f32 v[40:41], v[46:47], v[40:41]
	v_cvt_f32_f16_e32 v46, v10
	v_cvt_f32_f16_e32 v47, v11
	v_cvt_f32_f16_sdwa v11, v11 dst_sel:DWORD dst_unused:UNUSED_PAD src0_sel:WORD_1
	v_cvt_f32_f16_sdwa v10, v10 dst_sel:DWORD dst_unused:UNUSED_PAD src0_sel:WORD_1
	v_pk_fma_f32 v[70:71], v[54:55], 0.5, v[104:105] op_sel_hi:[1,0,1] neg_lo:[1,0,0] neg_hi:[1,0,0]
	v_mul_f32_e32 v6, 0.5, v6
	v_pk_add_f32 v[54:55], v[4:5], v[44:45]
	v_pk_add_f32 v[40:41], v[40:41], v[40:41] op_sel:[0,1] op_sel_hi:[0,1] neg_lo:[0,1] neg_hi:[0,1]
	v_fma_f32 v55, v42, 0.5, -v44
	v_pk_add_f32 v[42:43], v[6:7], v[40:41]
	v_pk_add_f32 v[40:41], v[6:7], v[40:41] op_sel_hi:[0,1] neg_lo:[0,1] neg_hi:[0,1]
	v_mov_b32_e32 v43, v41
	v_pk_mul_f32 v[40:41], v[42:43], v[10:11]
	v_pk_mul_f32 v[42:43], v[42:43], v[46:47]
	v_pk_fma_f32 v[44:45], v[54:55], v[46:47], v[40:41] neg_lo:[0,0,1] neg_hi:[0,0,1]
	v_pk_fma_f32 v[40:41], v[54:55], v[46:47], v[40:41]
	v_pk_fma_f32 v[46:47], v[54:55], v[10:11], v[42:43]
	v_pk_fma_f32 v[10:11], v[54:55], v[10:11], v[42:43] neg_lo:[0,0,1] neg_hi:[0,0,1]
	v_pk_add_f32 v[42:43], v[44:45], v[40:41] op_sel:[0,1] op_sel_hi:[1,0]
	v_pk_add_f32 v[54:55], v[46:47], v[10:11] op_sel_hi:[0,1] neg_lo:[0,1] neg_hi:[0,1]
	v_pk_add_f32 v[40:41], v[44:45], v[40:41] op_sel_hi:[0,1] neg_lo:[0,1] neg_hi:[0,1]
	v_pk_add_f32 v[10:11], v[46:47], v[10:11] op_sel:[0,1] op_sel_hi:[1,0]
	v_mov_b32_e32 v43, v55
	v_mov_b32_e32 v11, v41
	v_pk_mul_f32 v[10:11], v[10:11], 0.5 op_sel_hi:[1,0]
	v_mov_b32_e32 v119, v98
	v_pk_mul_f32 v[40:41], v[108:109], v[10:11] op_sel:[1,1] op_sel_hi:[1,0]
	v_pk_fma_f32 v[76:77], v[76:77], 0.5, v[112:113] op_sel_hi:[1,0,1] neg_lo:[1,0,0] neg_hi:[1,0,0]
	v_pk_fma_f32 v[44:45], v[22:23], v[10:11], v[40:41] op_sel_hi:[0,1,1]
	v_pk_fma_f32 v[10:11], v[22:23], v[10:11], v[40:41] op_sel_hi:[0,1,1] neg_lo:[0,0,1] neg_hi:[0,0,1]
	v_mov_b32_e32 v10, v44
	v_pk_fma_f32 v[22:23], v[42:43], 0.5, v[44:45] op_sel_hi:[1,0,1] neg_lo:[0,0,1] neg_hi:[0,0,1]
	v_pk_fma_f32 v[40:41], v[42:43], 0.5, v[10:11] op_sel_hi:[1,0,1]
	v_pk_fma_f32 v[54:55], v[42:43], 0.5, v[10:11] op_sel_hi:[1,0,1] neg_lo:[1,0,0] neg_hi:[1,0,0]
	v_pk_add_f32 v[10:11], v[100:101], v[14:15]
	v_pk_add_f32 v[14:15], v[14:15], v[100:101] neg_lo:[0,1] neg_hi:[0,1]
	v_mov_b32_e32 v23, v41
	v_mul_f32_e32 v6, 0.5, v15
	v_mov_b32_e32 v15, v11
	v_pk_mul_f32 v[150:151], v[22:23], s[6:7] op_sel_hi:[1,0]
	v_mul_f32_e32 v4, 0.5, v10
	v_pk_mov_b32 v[22:23], v[58:59], v[72:73] op_sel:[1,0]
	v_pk_mul_f32 v[10:11], v[14:15], s[44:45]
	v_cvt_f32_f16_sdwa v42, v8 dst_sel:DWORD dst_unused:UNUSED_PAD src0_sel:WORD_1
	v_pk_mul_f32 v[14:15], v[22:23], v[10:11] op_sel:[0,1] op_sel_hi:[1,0]
	v_cvt_f32_f16_e32 v43, v9
	v_cvt_f32_f16_sdwa v9, v9 dst_sel:DWORD dst_unused:UNUSED_PAD src0_sel:WORD_1
	v_cvt_f32_f16_e32 v8, v8
	v_pk_mul_f32 v[10:11], v[22:23], v[10:11]
	v_pk_add_f32 v[14:15], v[14:15], v[14:15] op_sel:[0,1] op_sel_hi:[0,1]
	v_pk_add_f32 v[44:45], v[4:5], v[14:15]
	v_pk_add_f32 v[14:15], v[4:5], v[14:15] op_sel_hi:[0,1] neg_lo:[0,1] neg_hi:[0,1]
	v_pk_add_f32 v[10:11], v[10:11], v[10:11] op_sel:[0,1] op_sel_hi:[0,1] neg_lo:[0,1] neg_hi:[0,1]
	v_mov_b32_e32 v45, v15
	v_pk_add_f32 v[14:15], v[6:7], v[10:11]
	v_pk_add_f32 v[10:11], v[6:7], v[10:11] op_sel_hi:[0,1] neg_lo:[0,1] neg_hi:[0,1]
	v_mov_b32_e32 v15, v11
	v_pk_mul_f32 v[10:11], v[14:15], v[8:9]
	v_pk_mul_f32 v[14:15], v[14:15], v[42:43]
	v_pk_fma_f32 v[10:11], v[44:45], v[42:43], v[10:11]
	v_pk_fma_f32 v[8:9], v[44:45], v[8:9], v[14:15] neg_lo:[0,0,1] neg_hi:[0,0,1]
	v_mov_b32_e32 v73, v59
	v_pk_add_f32 v[14:15], v[8:9], v[10:11] op_sel:[0,1] op_sel_hi:[1,0] neg_lo:[0,1] neg_hi:[0,1]
	v_pk_add_f32 v[42:43], v[8:9], v[10:11] op_sel:[0,1] op_sel_hi:[1,0]
	v_pk_add_f32 v[8:9], v[10:11], v[8:9] op_sel:[1,0] op_sel_hi:[0,1] neg_lo:[0,1] neg_hi:[0,1]
	v_mov_b32_e32 v15, v43
	v_pk_mul_f32 v[14:15], v[14:15], 0.5 op_sel_hi:[1,0]
	v_mov_b32_e32 v43, v9
	v_mul_f32_e32 v4, v59, v14
	v_pk_fma_f32 v[44:45], v[22:23], v[14:15], v[4:5] op_sel_hi:[1,1,0] neg_lo:[1,0,0] neg_hi:[1,0,0]
	v_mul_f32_e32 v4, v59, v15
	v_pk_fma_f32 v[14:15], v[72:73], v[14:15], v[4:5] op_sel_hi:[1,1,0]
	v_sub_f32_e32 v6, v39, v99
	v_mov_b32_e32 v44, v14
	v_pk_fma_f32 v[8:9], v[42:43], 0.5, v[14:15] op_sel_hi:[1,0,1] neg_lo:[0,0,1] neg_hi:[0,0,1]
	v_pk_fma_f32 v[10:11], v[42:43], 0.5, v[44:45] op_sel_hi:[1,0,1]
	v_pk_add_f32 v[14:15], v[98:99], v[38:39]
	v_mov_b32_e32 v9, v11
	v_pk_mul_f32 v[168:169], v[8:9], s[6:7] op_sel_hi:[1,0]
	v_mul_f32_e32 v8, 0xbf7b14be, v83
	v_mov_b32_e32 v9, v38
	v_mul_f32_e32 v18, 0.5, v15
	v_pk_add_f32 v[8:9], v[8:9], v[118:119] neg_lo:[0,1] neg_hi:[0,1]
	v_pk_fma_f32 v[72:73], v[42:43], 0.5, v[44:45] op_sel_hi:[1,0,1] neg_lo:[1,0,0] neg_hi:[1,0,0]
	v_pk_mul_f32 v[38:39], v[8:9], v[18:19]
	v_mov_b32_e32 v42, v8
	v_pk_fma_f32 v[22:23], v[22:23], v[38:39], v[38:39] op_sel:[0,1,0] op_sel_hi:[1,0,1]
	v_mov_b32_e32 v43, v59
	v_mov_b32_e32 v38, v39
	v_mov_b32_e32 v39, v18
	v_mul_f32_e32 v4, 0.5, v14
	v_pk_mul_f32 v[38:39], v[42:43], v[38:39]
	v_cvt_f32_f16_e32 v44, v2
	v_cvt_f32_f16_e32 v45, v3
	v_cvt_f32_f16_sdwa v3, v3 dst_sel:DWORD dst_unused:UNUSED_PAD src0_sel:WORD_1
	v_cvt_f32_f16_sdwa v2, v2 dst_sel:DWORD dst_unused:UNUSED_PAD src0_sel:WORD_1
	v_mul_f32_e32 v6, 0.5, v6
	v_pk_add_f32 v[46:47], v[4:5], v[22:23]
	v_fma_f32 v4, v14, 0.5, -v22
	v_pk_add_f32 v[22:23], v[38:39], v[38:39] op_sel:[0,1] op_sel_hi:[0,1] neg_lo:[0,1] neg_hi:[0,1]
	v_pk_add_f32 v[38:39], v[6:7], v[22:23]
	v_pk_add_f32 v[22:23], v[6:7], v[22:23] op_sel_hi:[0,1] neg_lo:[0,1] neg_hi:[0,1]
	v_mov_b32_e32 v39, v23
	v_mov_b32_e32 v14, v46
	v_mov_b32_e32 v15, v4
	v_pk_mul_f32 v[22:23], v[4:5], v[44:45] op_sel_hi:[0,1]
	v_pk_mul_f32 v[82:83], v[38:39], v[2:3]
	v_pk_mul_f32 v[46:47], v[46:47], v[2:3]
	v_pk_mul_f32 v[38:39], v[38:39], v[44:45]
	v_pk_fma_f32 v[98:99], v[14:15], v[44:45], v[82:83] neg_lo:[0,0,1] neg_hi:[0,0,1]
	v_pk_fma_f32 v[2:3], v[14:15], v[2:3], v[38:39] neg_lo:[0,0,1] neg_hi:[0,0,1]
	v_add_f32_e32 v4, v23, v83
	v_add_f32_e32 v6, v46, v38
	v_pk_add_f32 v[22:23], v[6:7], v[2:3] op_sel_hi:[0,1] neg_lo:[0,1] neg_hi:[0,1]
	v_pk_add_f32 v[38:39], v[98:99], v[4:5] op_sel_hi:[1,0] neg_lo:[0,1] neg_hi:[0,1]
	v_pk_add_f32 v[2:3], v[6:7], v[2:3] op_sel_hi:[0,1]
	v_mov_b32_e32 v39, v3
	v_pk_mul_f32 v[2:3], v[38:39], 0.5 op_sel_hi:[1,0]
	v_pk_add_f32 v[14:15], v[98:99], v[4:5] op_sel_hi:[1,0]
	v_mul_f32_e32 v4, v59, v3
	v_pk_fma_f32 v[38:39], v[42:43], v[2:3], v[4:5] op_sel_hi:[1,1,0] neg_lo:[0,0,1] neg_hi:[0,0,1]
	v_pk_mov_b32 v[42:43], v[58:59], v[8:9] op_sel:[1,0]
	v_mul_f32_e32 v4, v8, v3
	v_pk_fma_f32 v[2:3], v[42:43], v[2:3], v[4:5] op_sel_hi:[1,1,0]
	v_mov_b32_e32 v15, v23
	v_pk_fma_f32 v[8:9], v[14:15], 0.5, v[2:3] op_sel_hi:[1,0,1] neg_lo:[0,0,1] neg_hi:[0,0,1]
	v_pk_fma_f32 v[42:43], v[14:15], 0.5, v[38:39] op_sel_hi:[1,0,0]
	v_pk_fma_f32 v[2:3], v[14:15], 0.5, v[2:3] op_sel_hi:[1,0,1]
	v_mov_b32_e32 v9, v43
	v_pk_fma_f32 v[58:59], v[22:23], 0.5, v[38:39] op_sel_hi:[1,0,0] neg_lo:[1,0,0] neg_hi:[1,0,0]
	v_pk_mul_f32 v[144:145], v[8:9], s[6:7] op_sel_hi:[1,0]
	v_mov_b32_e32 v58, v2
	v_mov_b32_e32 v72, v10
	v_mov_b32_e32 v54, v40
	v_mov_b32_e32 v70, v20
	v_mov_b32_e32 v56, v26
	v_mov_b32_e32 v76, v36
	v_mov_b32_e32 v52, v34
	v_mov_b32_e32 v74, v86
	v_mov_b32_e32 v48, v84
	v_mov_b32_e32 v50, v60
	v_mov_b32_e32 v28, v66
	v_mov_b32_e32 v32, v96
	v_mov_b32_e32 v12, v88
	v_mov_b32_e32 v16, v92
	v_mov_b32_e32 v4, v138
	v_mov_b32_e32 v6, v122

.LBB0_534:
	v_mov_b32_e32 v2, v210
	s_mov_b32 s43, s8
	v_and_b32_e32 v3, 0xff, v2
	v_lshlrev_b32_e32 v4, 5, v2
	v_and_or_b32 v3, v4, s33, v3
	v_ashrrev_i32_e32 v4, 5, v3
	v_lshlrev_b32_e32 v3, 3, v3
	v_lshlrev_b32_e32 v4, 3, v4
	v_add3_u32 v18, 0, v3, v4
	ds_read_b64 v[128:129], v18
	ds_read_b64 v[132:133], v18 offset:2112
	ds_read_b64 v[134:135], v18 offset:4224
	ds_read_b64 v[136:137], v18 offset:6336
	ds_read_b64 v[138:139], v18 offset:8448
	ds_read_b64 v[140:141], v18 offset:10560
	ds_read_b64 v[142:143], v18 offset:12672
	ds_read_b64 v[130:131], v18 offset:14784
	ds_read_b64 v[144:145], v18 offset:16896
	ds_read_b64 v[148:149], v18 offset:19008
	ds_read_b64 v[150:151], v18 offset:21120
	ds_read_b64 v[152:153], v18 offset:23232
	s_waitcnt lgkmcnt(10)
	v_pk_mul_f32 v[162:163], v[132:133], s[10:11]
	s_mov_b32 s64, s11
	v_pk_fma_f32 v[162:163], v[132:133], s[8:9], v[162:163] op_sel:[0,0,1] op_sel_hi:[1,0,0]
	s_waitcnt lgkmcnt(2)
	v_pk_mul_f32 v[178:179], v[148:149], s[42:43]
	v_pk_add_f32 v[194:195], v[132:133], v[148:149]
	v_pk_add_f32 v[132:133], v[132:133], v[148:149] neg_lo:[0,1] neg_hi:[0,1]
	v_pk_mul_f32 v[164:165], v[134:135], s[18:19]
	s_mov_b32 s41, s16
	v_pk_fma_f32 v[178:179], v[148:149], s[64:65], v[178:179] op_sel:[0,0,1] op_sel_hi:[1,0,0] neg_lo:[1,0,0] neg_hi:[1,0,0]
	v_pk_mul_f32 v[148:149], v[132:133], s[18:19]
	v_pk_fma_f32 v[164:165], v[134:135], s[16:17], v[164:165] op_sel:[0,0,1] op_sel_hi:[1,0,0]
	s_mov_b32 s68, s19
	s_waitcnt lgkmcnt(1)
	v_pk_mul_f32 v[180:181], v[150:151], s[40:41]
	v_pk_fma_f32 v[132:133], v[132:133], s[16:17], v[148:149] op_sel:[0,0,1] op_sel_hi:[1,0,0]
	v_pk_add_f32 v[148:149], v[134:135], v[150:151]
	v_pk_add_f32 v[134:135], v[134:135], v[150:151] neg_lo:[0,1] neg_hi:[0,1]
	v_pk_mul_f32 v[166:167], v[136:137], s[26:27]
	s_mov_b32 s66, s37
	s_mov_b32 s39, s24
	v_pk_fma_f32 v[180:181], v[150:151], s[68:69], v[180:181] op_sel:[0,0,1] op_sel_hi:[1,0,0] neg_lo:[1,0,0] neg_hi:[1,0,0]
	v_pk_mul_f32 v[150:151], v[134:135], s[36:37]
	ds_read_b64 v[154:155], v18 offset:25344
	ds_read_b64 v[156:157], v18 offset:27456
	ds_read_b64 v[158:159], v18 offset:29568
	ds_read_b64 v[160:161], v18 offset:31680
	v_pk_fma_f32 v[166:167], v[136:137], s[24:25], v[166:167] op_sel:[0,0,1] op_sel_hi:[1,0,0]
	s_mov_b32 s0, s27
	s_waitcnt lgkmcnt(4)
	v_pk_mul_f32 v[182:183], v[152:153], s[38:39]
	v_pk_fma_f32 v[134:135], v[134:135], s[66:67], v[150:151] op_sel:[0,0,1] op_sel_hi:[1,0,0]
	v_pk_add_f32 v[150:151], v[136:137], v[152:153]
	v_pk_add_f32 v[136:137], v[136:137], v[152:153] neg_lo:[0,1] neg_hi:[0,1]
	v_pk_mul_f32 v[168:169], v[138:139], s[36:37]
	v_pk_fma_f32 v[182:183], v[152:153], s[0:1], v[182:183] op_sel:[0,0,1] op_sel_hi:[1,0,0] neg_lo:[1,0,0] neg_hi:[1,0,0]
	v_pk_mul_f32 v[152:153], v[136:137], s[40:41]
	v_pk_fma_f32 v[168:169], v[138:139], s[66:67], v[168:169] op_sel:[0,0,1] op_sel_hi:[1,0,0]
	v_pk_mul_f32 v[170:171], v[140:141], s[38:39]
	s_waitcnt lgkmcnt(3)
	v_pk_mul_f32 v[184:185], v[154:155], s[36:37]
	v_pk_fma_f32 v[136:137], v[136:137], s[68:69], v[152:153] op_sel:[0,0,1] op_sel_hi:[1,0,0]
	v_pk_add_f32 v[152:153], v[138:139], v[154:155]
	v_pk_add_f32 v[138:139], v[138:139], v[154:155] neg_lo:[0,1] neg_hi:[0,1]
	v_pk_fma_f32 v[170:171], v[140:141], s[0:1], v[170:171] op_sel:[0,0,1] op_sel_hi:[1,0,0]
	v_pk_fma_f32 v[184:185], v[154:155], s[66:67], v[184:185] op_sel:[0,0,1] op_sel_hi:[1,0,0] neg_lo:[1,0,0] neg_hi:[1,0,0]
	s_waitcnt lgkmcnt(2)
	v_pk_mul_f32 v[186:187], v[156:157], s[26:27]
	v_xor_b32_e32 v155, 0x80000000, v138
	v_mov_b32_e32 v154, v139
	v_pk_add_f32 v[138:139], v[140:141], v[156:157]
	v_pk_add_f32 v[140:141], v[140:141], v[156:157] neg_lo:[0,1] neg_hi:[0,1]
	v_pk_mul_f32 v[172:173], v[142:143], s[40:41]
	v_pk_fma_f32 v[186:187], v[156:157], s[24:25], v[186:187] op_sel:[0,0,1] op_sel_hi:[1,0,0] neg_lo:[1,0,0] neg_hi:[1,0,0]
	v_pk_mul_f32 v[156:157], v[140:141], s[40:41]
	v_pk_fma_f32 v[172:173], v[142:143], s[68:69], v[172:173] op_sel:[0,0,1] op_sel_hi:[1,0,0]
	s_waitcnt lgkmcnt(1)
	v_pk_mul_f32 v[188:189], v[158:159], s[18:19]
	v_pk_fma_f32 v[140:141], v[140:141], s[68:69], v[156:157] op_sel:[0,0,1] op_sel_hi:[1,0,0] neg_lo:[1,0,0] neg_hi:[1,0,0]
	v_pk_add_f32 v[156:157], v[142:143], v[158:159]
	v_pk_add_f32 v[142:143], v[142:143], v[158:159] neg_lo:[0,1] neg_hi:[0,1]
	v_pk_mul_f32 v[174:175], v[130:131], s[42:43]
	v_pk_fma_f32 v[188:189], v[158:159], s[16:17], v[188:189] op_sel:[0,0,1] op_sel_hi:[1,0,0] neg_lo:[1,0,0] neg_hi:[1,0,0]
	v_pk_mul_f32 v[158:159], v[142:143], s[36:37]
	v_pk_fma_f32 v[174:175], v[130:131], s[64:65], v[174:175] op_sel:[0,0,1] op_sel_hi:[1,0,0]
	s_waitcnt lgkmcnt(0)
	v_pk_mul_f32 v[190:191], v[160:161], s[10:11]
	v_pk_fma_f32 v[142:143], v[142:143], s[66:67], v[158:159] op_sel:[0,0,1] op_sel_hi:[1,0,0] neg_lo:[1,0,0] neg_hi:[1,0,0]
	v_pk_add_f32 v[158:159], v[130:131], v[160:161]
	v_pk_add_f32 v[130:131], v[130:131], v[160:161] neg_lo:[0,1] neg_hi:[0,1]
	v_xor_b32_e32 v177, 0x80000000, v144
	v_mov_b32_e32 v176, v145
	v_pk_fma_f32 v[190:191], v[160:161], s[8:9], v[190:191] op_sel:[0,0,1] op_sel_hi:[1,0,0] neg_lo:[1,0,0] neg_hi:[1,0,0]
	v_pk_mul_f32 v[160:161], v[130:131], s[18:19]
	v_pk_add_f32 v[192:193], v[128:129], v[144:145]
	v_pk_add_f32 v[144:145], v[128:129], v[144:145] neg_lo:[0,1] neg_hi:[0,1]
	v_pk_fma_f32 v[130:131], v[130:131], s[16:17], v[160:161] op_sel:[0,0,1] op_sel_hi:[1,0,0] neg_lo:[1,0,0] neg_hi:[1,0,0]
	v_pk_add_f32 v[160:161], v[128:129], v[176:177]
	v_pk_add_f32 v[128:129], v[128:129], v[176:177] neg_lo:[0,1] neg_hi:[0,1]
	v_pk_add_f32 v[176:177], v[162:163], v[178:179]
	v_pk_add_f32 v[162:163], v[162:163], v[178:179] neg_lo:[0,1] neg_hi:[0,1]
	v_cvt_f32_ubyte0_e32 v2, v2
	v_pk_mul_f32 v[178:179], v[162:163], s[18:19]
	v_mul_f32_e32 v2, 0x39000000, v2
	v_pk_fma_f32 v[162:163], v[162:163], s[16:17], v[178:179] op_sel:[0,0,1] op_sel_hi:[1,0,0]
	v_pk_add_f32 v[178:179], v[164:165], v[180:181]
	v_pk_add_f32 v[164:165], v[164:165], v[180:181] neg_lo:[0,1] neg_hi:[0,1]
	v_sin_f32_e32 v34, v2
	v_pk_mul_f32 v[180:181], v[164:165], s[36:37]
	v_cos_f32_e32 v30, v2
	v_pk_fma_f32 v[164:165], v[164:165], s[66:67], v[180:181] op_sel:[0,0,1] op_sel_hi:[1,0,0]
	v_pk_add_f32 v[180:181], v[166:167], v[182:183]
	v_pk_add_f32 v[166:167], v[166:167], v[182:183] neg_lo:[0,1] neg_hi:[0,1]
	v_xor_b32_e32 v31, 0x80000000, v34
	v_pk_mul_f32 v[182:183], v[166:167], s[40:41]
	v_mov_b32_e32 v35, v31
	v_pk_fma_f32 v[166:167], v[166:167], s[68:69], v[182:183] op_sel:[0,0,1] op_sel_hi:[1,0,0]
	v_pk_add_f32 v[182:183], v[168:169], v[184:185]
	v_pk_add_f32 v[184:185], v[168:169], v[184:185] neg_lo:[0,1] neg_hi:[0,1]
	v_pk_mul_f32 v[2:3], v[30:31], v[34:35] op_sel:[1,0] op_sel_hi:[0,1]
	v_pk_add_f32 v[168:169], v[170:171], v[186:187]
	v_pk_add_f32 v[170:171], v[170:171], v[186:187] neg_lo:[0,1] neg_hi:[0,1]
	v_pk_fma_f32 v[44:45], v[30:31], v[30:31], v[2:3] op_sel_hi:[1,0,1]
	v_pk_mul_f32 v[186:187], v[170:171], s[40:41]
	v_pk_mul_f32 v[2:3], v[34:35], v[44:45] op_sel:[0,1] op_sel_hi:[1,0]
	v_pk_fma_f32 v[170:171], v[170:171], s[68:69], v[186:187] op_sel:[0,0,1] op_sel_hi:[1,0,0] neg_lo:[1,0,0] neg_hi:[1,0,0]
	v_pk_add_f32 v[186:187], v[172:173], v[188:189]
	v_pk_add_f32 v[172:173], v[172:173], v[188:189] neg_lo:[0,1] neg_hi:[0,1]
	v_xor_b32_e32 v54, 0x80000000, v45
	v_pk_mul_f32 v[188:189], v[172:173], s[36:37]
	v_mov_b32_e32 v55, v45
	v_pk_fma_f32 v[172:173], v[172:173], s[66:67], v[188:189] op_sel:[0,0,1] op_sel_hi:[1,0,0] neg_lo:[1,0,0] neg_hi:[1,0,0]
	v_pk_add_f32 v[188:189], v[174:175], v[190:191]
	v_pk_add_f32 v[174:175], v[174:175], v[190:191] neg_lo:[0,1] neg_hi:[0,1]
	v_pk_fma_f32 v[46:47], v[30:31], v[44:45], v[2:3] op_sel_hi:[0,1,1]
	v_pk_mul_f32 v[190:191], v[174:175], s[18:19]
	v_pk_mul_f32 v[2:3], v[44:45], v[54:55] op_sel:[1,0] op_sel_hi:[0,1]
	v_pk_fma_f32 v[174:175], v[174:175], s[16:17], v[190:191] op_sel:[0,0,1] op_sel_hi:[1,0,0] neg_lo:[1,0,0] neg_hi:[1,0,0]
	v_pk_add_f32 v[190:191], v[192:193], v[152:153]
	v_pk_add_f32 v[152:153], v[192:193], v[152:153] neg_lo:[0,1] neg_hi:[0,1]
	v_pk_add_f32 v[192:193], v[194:195], v[138:139]
	v_pk_add_f32 v[138:139], v[194:195], v[138:139] neg_lo:[0,1] neg_hi:[0,1]
	v_pk_fma_f32 v[52:53], v[44:45], v[44:45], v[2:3] op_sel_hi:[1,0,1]
	v_pk_mul_f32 v[194:195], v[138:139], s[36:37]
	v_xor_b32_e32 v58, 0x80000000, v53
	v_pk_fma_f32 v[138:139], v[138:139], s[66:67], v[194:195] op_sel:[0,0,1] op_sel_hi:[1,0,0]
	v_pk_add_f32 v[194:195], v[148:149], v[156:157]
	v_pk_add_f32 v[156:157], v[148:149], v[156:157] neg_lo:[0,1] neg_hi:[0,1]
	v_mov_b32_e32 v59, v53
	v_pk_add_f32 v[148:149], v[150:151], v[158:159]
	v_pk_add_f32 v[150:151], v[150:151], v[158:159] neg_lo:[0,1] neg_hi:[0,1]
	v_pk_mul_f32 v[2:3], v[52:53], v[58:59] op_sel:[1,0] op_sel_hi:[0,1]
	v_pk_mul_f32 v[158:159], v[150:151], s[36:37]
	v_pk_fma_f32 v[48:49], v[52:53], v[52:53], v[2:3] op_sel_hi:[1,0,1]
	v_pk_fma_f32 v[150:151], v[150:151], s[66:67], v[158:159] op_sel:[0,0,1] op_sel_hi:[1,0,0] neg_lo:[1,0,0] neg_hi:[1,0,0]
	v_pk_add_f32 v[158:159], v[144:145], v[154:155]
	v_pk_add_f32 v[144:145], v[144:145], v[154:155] neg_lo:[0,1] neg_hi:[0,1]
	v_pk_add_f32 v[154:155], v[132:133], v[140:141]
	v_pk_add_f32 v[132:133], v[132:133], v[140:141] neg_lo:[0,1] neg_hi:[0,1]
	v_pk_mul_f32 v[2:3], v[58:59], v[48:49] op_sel:[0,1] op_sel_hi:[1,0]
	v_pk_mul_f32 v[140:141], v[132:133], s[36:37]
	v_pk_fma_f32 v[36:37], v[52:53], v[48:49], v[2:3] op_sel_hi:[0,1,1]
	v_pk_fma_f32 v[132:133], v[132:133], s[66:67], v[140:141] op_sel:[0,0,1] op_sel_hi:[1,0,0]
	v_pk_add_f32 v[140:141], v[134:135], v[142:143]
	v_pk_add_f32 v[142:143], v[134:135], v[142:143] neg_lo:[0,1] neg_hi:[0,1]
	v_pk_mul_f32 v[2:3], v[58:59], v[36:37] op_sel:[0,1] op_sel_hi:[1,0]
	v_pk_add_f32 v[134:135], v[136:137], v[130:131]
	v_pk_add_f32 v[130:131], v[136:137], v[130:131] neg_lo:[0,1] neg_hi:[0,1]
	v_pk_fma_f32 v[26:27], v[52:53], v[36:37], v[2:3] op_sel_hi:[0,1,1]
	v_pk_mul_f32 v[136:137], v[130:131], s[36:37]
	v_pk_mul_f32 v[2:3], v[58:59], v[26:27] op_sel:[0,1] op_sel_hi:[1,0]
	v_pk_fma_f32 v[130:131], v[130:131], s[66:67], v[136:137] op_sel:[0,0,1] op_sel_hi:[1,0,0] neg_lo:[1,0,0] neg_hi:[1,0,0]
	v_pk_add_f32 v[136:137], v[160:161], v[182:183]
	v_pk_add_f32 v[160:161], v[160:161], v[182:183] neg_lo:[0,1] neg_hi:[0,1]
	v_pk_add_f32 v[182:183], v[176:177], v[168:169]
	v_pk_add_f32 v[168:169], v[176:177], v[168:169] neg_lo:[0,1] neg_hi:[0,1]
	v_pk_fma_f32 v[20:21], v[52:53], v[26:27], v[2:3] op_sel_hi:[0,1,1]
	v_pk_mul_f32 v[176:177], v[168:169], s[36:37]
	v_pk_mul_f32 v[2:3], v[58:59], v[20:21] op_sel:[0,1] op_sel_hi:[1,0]
	v_pk_fma_f32 v[168:169], v[168:169], s[66:67], v[176:177] op_sel:[0,0,1] op_sel_hi:[1,0,0]
	v_pk_add_f32 v[176:177], v[178:179], v[186:187]
	v_pk_add_f32 v[186:187], v[178:179], v[186:187] neg_lo:[0,1] neg_hi:[0,1]
	v_pk_fma_f32 v[10:11], v[52:53], v[20:21], v[2:3] op_sel_hi:[0,1,1]
	v_pk_add_f32 v[178:179], v[180:181], v[188:189]
	v_pk_add_f32 v[180:181], v[180:181], v[188:189] neg_lo:[0,1] neg_hi:[0,1]
	v_pk_mul_f32 v[2:3], v[58:59], v[10:11] op_sel:[0,1] op_sel_hi:[1,0]
	v_pk_mul_f32 v[188:189], v[180:181], s[36:37]
	v_pk_fma_f32 v[4:5], v[52:53], v[10:11], v[2:3] op_sel_hi:[0,1,1]
	v_pk_fma_f32 v[180:181], v[180:181], s[66:67], v[188:189] op_sel:[0,0,1] op_sel_hi:[1,0,0] neg_lo:[1,0,0] neg_hi:[1,0,0]
	v_pk_add_f32 v[188:189], v[128:129], v[184:185] op_sel:[0,1] op_sel_hi:[1,0] neg_hi:[0,1]
	v_pk_add_f32 v[128:129], v[128:129], v[184:185] op_sel:[0,1] op_sel_hi:[1,0] neg_lo:[0,1]
	v_pk_add_f32 v[184:185], v[162:163], v[170:171]
	v_pk_add_f32 v[162:163], v[162:163], v[170:171] neg_lo:[0,1] neg_hi:[0,1]
	v_xor_b32_e32 v72, 0x80000000, v47
	v_pk_mul_f32 v[170:171], v[162:163], s[36:37]
	v_mov_b32_e32 v73, v47
	v_pk_fma_f32 v[162:163], v[162:163], s[66:67], v[170:171] op_sel:[0,0,1] op_sel_hi:[1,0,0]
	v_pk_add_f32 v[170:171], v[164:165], v[172:173]
	v_pk_add_f32 v[172:173], v[164:165], v[172:173] neg_lo:[0,1] neg_hi:[0,1]
	v_pk_mul_f32 v[2:3], v[72:73], v[4:5] op_sel:[0,1] op_sel_hi:[1,0]
	v_pk_add_f32 v[164:165], v[166:167], v[174:175]
	v_pk_add_f32 v[166:167], v[166:167], v[174:175] neg_lo:[0,1] neg_hi:[0,1]
	v_pk_mul_f32 v[14:15], v[34:35], v[4:5] op_sel:[0,1] op_sel_hi:[1,0]
	v_pk_mul_f32 v[174:175], v[166:167], s[36:37]
	v_pk_mul_f32 v[40:41], v[34:35], v[10:11] op_sel:[0,1] op_sel_hi:[1,0]
	v_pk_fma_f32 v[166:167], v[166:167], s[66:67], v[174:175] op_sel:[0,0,1] op_sel_hi:[1,0,0] neg_lo:[1,0,0] neg_hi:[1,0,0]
	v_pk_add_f32 v[174:175], v[190:191], v[194:195]
	v_pk_add_f32 v[190:191], v[190:191], v[194:195] neg_lo:[0,1] neg_hi:[0,1]
	v_pk_add_f32 v[194:195], v[192:193], v[148:149]
	v_pk_add_f32 v[192:193], v[192:193], v[148:149] neg_lo:[0,1] neg_hi:[0,1]
	v_pk_mul_f32 v[66:67], v[34:35], v[20:21] op_sel:[0,1] op_sel_hi:[1,0]
	v_pk_add_f32 v[148:149], v[152:153], v[156:157] op_sel:[0,1] op_sel_hi:[1,0] neg_hi:[0,1]
	v_pk_add_f32 v[152:153], v[152:153], v[156:157] op_sel:[0,1] op_sel_hi:[1,0] neg_lo:[0,1]
	v_pk_add_f32 v[156:157], v[138:139], v[150:151]
	v_pk_add_f32 v[150:151], v[138:139], v[150:151] neg_lo:[0,1] neg_hi:[0,1]
	v_pk_mul_f32 v[82:83], v[34:35], v[26:27] op_sel:[0,1] op_sel_hi:[1,0]
	v_pk_add_f32 v[138:139], v[158:159], v[140:141]
	v_pk_add_f32 v[140:141], v[158:159], v[140:141] neg_lo:[0,1] neg_hi:[0,1]
	v_pk_add_f32 v[158:159], v[154:155], v[134:135]
	v_pk_add_f32 v[154:155], v[154:155], v[134:135] neg_lo:[0,1] neg_hi:[0,1]
	v_pk_mul_f32 v[96:97], v[34:35], v[36:37] op_sel:[0,1] op_sel_hi:[1,0]
	v_pk_add_f32 v[134:135], v[144:145], v[142:143] op_sel:[0,1] op_sel_hi:[1,0] neg_hi:[0,1]
	v_pk_add_f32 v[142:143], v[144:145], v[142:143] op_sel:[0,1] op_sel_hi:[1,0] neg_lo:[0,1]
	v_pk_add_f32 v[144:145], v[132:133], v[130:131]
	v_pk_add_f32 v[132:133], v[132:133], v[130:131] neg_lo:[0,1] neg_hi:[0,1]
	v_pk_mul_f32 v[110:111], v[34:35], v[48:49] op_sel:[0,1] op_sel_hi:[1,0]
	v_pk_add_f32 v[130:131], v[136:137], v[176:177]
	v_pk_add_f32 v[136:137], v[136:137], v[176:177] neg_lo:[0,1] neg_hi:[0,1]
	v_pk_add_f32 v[176:177], v[182:183], v[178:179]
	v_pk_add_f32 v[182:183], v[182:183], v[178:179] neg_lo:[0,1] neg_hi:[0,1]
	v_pk_mul_f32 v[124:125], v[34:35], v[52:53] op_sel:[0,1] op_sel_hi:[1,0]
	v_pk_add_f32 v[178:179], v[160:161], v[186:187] op_sel:[0,1] op_sel_hi:[1,0] neg_hi:[0,1]
	v_pk_add_f32 v[160:161], v[160:161], v[186:187] op_sel:[0,1] op_sel_hi:[1,0] neg_lo:[0,1]
	v_pk_add_f32 v[186:187], v[168:169], v[180:181]
	v_pk_add_f32 v[180:181], v[168:169], v[180:181] neg_lo:[0,1] neg_hi:[0,1]
	v_pk_fma_f32 v[2:3], v[46:47], v[4:5], v[2:3] op_sel_hi:[0,1,1]
	v_pk_add_f32 v[168:169], v[188:189], v[170:171]
	v_pk_add_f32 v[170:171], v[188:189], v[170:171] neg_lo:[0,1] neg_hi:[0,1]
	v_pk_add_f32 v[188:189], v[184:185], v[164:165]
	v_pk_add_f32 v[184:185], v[184:185], v[164:165] neg_lo:[0,1] neg_hi:[0,1]
	v_pk_mul_f32 v[8:9], v[54:55], v[4:5] op_sel:[0,1] op_sel_hi:[1,0]
	v_pk_add_f32 v[164:165], v[128:129], v[172:173] op_sel:[0,1] op_sel_hi:[1,0] neg_hi:[0,1]
	v_pk_add_f32 v[128:129], v[128:129], v[172:173] op_sel:[0,1] op_sel_hi:[1,0] neg_lo:[0,1]
	v_pk_add_f32 v[172:173], v[162:163], v[166:167]
	v_pk_add_f32 v[166:167], v[162:163], v[166:167] neg_lo:[0,1] neg_hi:[0,1]
	v_pk_fma_f32 v[14:15], v[30:31], v[4:5], v[14:15] op_sel_hi:[0,1,1]
	v_pk_add_f32 v[162:163], v[174:175], v[194:195]
	v_pk_add_f32 v[174:175], v[174:175], v[194:195] neg_lo:[0,1] neg_hi:[0,1]
	v_pk_add_f32 v[194:195], v[190:191], v[192:193] op_sel:[0,1] op_sel_hi:[1,0] neg_hi:[0,1]
	v_pk_add_f32 v[190:191], v[190:191], v[192:193] op_sel:[0,1] op_sel_hi:[1,0] neg_lo:[0,1]
	v_pk_add_f32 v[192:193], v[148:149], v[156:157]
	v_pk_add_f32 v[148:149], v[148:149], v[156:157] neg_lo:[0,1] neg_hi:[0,1]
	v_pk_add_f32 v[156:157], v[152:153], v[150:151] op_sel:[0,1] op_sel_hi:[1,0] neg_hi:[0,1]
	v_pk_add_f32 v[150:151], v[152:153], v[150:151] op_sel:[0,1] op_sel_hi:[1,0] neg_lo:[0,1]
	v_pk_add_f32 v[152:153], v[138:139], v[158:159]
	v_pk_add_f32 v[138:139], v[138:139], v[158:159] neg_lo:[0,1] neg_hi:[0,1]
	v_pk_add_f32 v[158:159], v[140:141], v[154:155] op_sel:[0,1] op_sel_hi:[1,0] neg_hi:[0,1]
	v_pk_add_f32 v[140:141], v[140:141], v[154:155] op_sel:[0,1] op_sel_hi:[1,0] neg_lo:[0,1]
	v_pk_add_f32 v[154:155], v[134:135], v[144:145]
	v_pk_add_f32 v[134:135], v[134:135], v[144:145] neg_lo:[0,1] neg_hi:[0,1]
	v_pk_add_f32 v[144:145], v[142:143], v[132:133] op_sel:[0,1] op_sel_hi:[1,0] neg_hi:[0,1]
	v_pk_add_f32 v[132:133], v[142:143], v[132:133] op_sel:[0,1] op_sel_hi:[1,0] neg_lo:[0,1]
	v_pk_add_f32 v[142:143], v[130:131], v[176:177]
	v_pk_mul_f32 v[24:25], v[72:73], v[10:11] op_sel:[0,1] op_sel_hi:[1,0]
	v_pk_mul_f32 v[34:35], v[34:35], v[142:143] op_sel:[0,1] op_sel_hi:[1,0]
	v_pk_mul_f32 v[32:33], v[54:55], v[10:11] op_sel:[0,1] op_sel_hi:[1,0]
	v_pk_fma_f32 v[40:41], v[30:31], v[10:11], v[40:41] op_sel_hi:[0,1,1]
	v_pk_mul_f32 v[56:57], v[72:73], v[20:21] op_sel:[0,1] op_sel_hi:[1,0]
	v_pk_mul_f32 v[62:63], v[54:55], v[20:21] op_sel:[0,1] op_sel_hi:[1,0]
	v_pk_fma_f32 v[66:67], v[30:31], v[20:21], v[66:67] op_sel_hi:[0,1,1]
	v_pk_mul_f32 v[74:75], v[72:73], v[26:27] op_sel:[0,1] op_sel_hi:[1,0]
	v_pk_mul_f32 v[78:79], v[54:55], v[26:27] op_sel:[0,1] op_sel_hi:[1,0]
	v_pk_fma_f32 v[82:83], v[30:31], v[26:27], v[82:83] op_sel_hi:[0,1,1]
	v_pk_mul_f32 v[88:89], v[72:73], v[36:37] op_sel:[0,1] op_sel_hi:[1,0]
	v_pk_mul_f32 v[92:93], v[54:55], v[36:37] op_sel:[0,1] op_sel_hi:[1,0]
	v_pk_fma_f32 v[96:97], v[30:31], v[36:37], v[96:97] op_sel_hi:[0,1,1]
	v_pk_mul_f32 v[102:103], v[72:73], v[48:49] op_sel:[0,1] op_sel_hi:[1,0]
	v_pk_mul_f32 v[106:107], v[54:55], v[48:49] op_sel:[0,1] op_sel_hi:[1,0]
	v_pk_fma_f32 v[110:111], v[30:31], v[48:49], v[110:111] op_sel_hi:[0,1,1]
	v_pk_mul_f32 v[116:117], v[52:53], v[72:73] op_sel:[1,0] op_sel_hi:[0,1]
	v_pk_mul_f32 v[120:121], v[54:55], v[52:53] op_sel:[0,1] op_sel_hi:[1,0]
	v_pk_fma_f32 v[124:125], v[30:31], v[52:53], v[124:125] op_sel_hi:[0,1,1]
	v_pk_add_f32 v[130:131], v[130:131], v[176:177] neg_lo:[0,1] neg_hi:[0,1]
	v_pk_add_f32 v[176:177], v[136:137], v[182:183] op_sel:[0,1] op_sel_hi:[1,0] neg_hi:[0,1]
	v_pk_add_f32 v[136:137], v[136:137], v[182:183] op_sel:[0,1] op_sel_hi:[1,0] neg_lo:[0,1]
	v_pk_add_f32 v[182:183], v[178:179], v[186:187]
	v_pk_add_f32 v[178:179], v[178:179], v[186:187] neg_lo:[0,1] neg_hi:[0,1]
	v_pk_add_f32 v[186:187], v[160:161], v[180:181] op_sel:[0,1] op_sel_hi:[1,0] neg_hi:[0,1]
	v_pk_add_f32 v[160:161], v[160:161], v[180:181] op_sel:[0,1] op_sel_hi:[1,0] neg_lo:[0,1]
	v_pk_add_f32 v[180:181], v[168:169], v[188:189]
	v_pk_fma_f32 v[30:31], v[30:31], v[142:143], v[34:35] op_sel_hi:[0,1,1]
	v_pk_mul_f32 v[34:35], v[54:55], v[152:153] op_sel:[0,1] op_sel_hi:[1,0]
	v_xor_b32_e32 v6, 0x80000000, v3
	v_pk_fma_f32 v[8:9], v[44:45], v[4:5], v[8:9] op_sel_hi:[0,1,1]
	v_pk_fma_f32 v[24:25], v[46:47], v[10:11], v[24:25] op_sel_hi:[0,1,1]
	v_pk_fma_f32 v[32:33], v[44:45], v[10:11], v[32:33] op_sel_hi:[0,1,1]
	v_pk_fma_f32 v[56:57], v[46:47], v[20:21], v[56:57] op_sel_hi:[0,1,1]
	v_pk_fma_f32 v[62:63], v[44:45], v[20:21], v[62:63] op_sel_hi:[0,1,1]
	v_pk_fma_f32 v[74:75], v[46:47], v[26:27], v[74:75] op_sel_hi:[0,1,1]
	v_pk_fma_f32 v[78:79], v[44:45], v[26:27], v[78:79] op_sel_hi:[0,1,1]
	v_pk_fma_f32 v[88:89], v[46:47], v[36:37], v[88:89] op_sel_hi:[0,1,1]
	v_pk_fma_f32 v[92:93], v[44:45], v[36:37], v[92:93] op_sel_hi:[0,1,1]
	v_pk_fma_f32 v[102:103], v[46:47], v[48:49], v[102:103] op_sel_hi:[0,1,1]
	v_pk_fma_f32 v[106:107], v[44:45], v[48:49], v[106:107] op_sel_hi:[0,1,1]
	v_xor_b32_e32 v114, 0x80000000, v49
	v_pk_fma_f32 v[116:117], v[52:53], v[46:47], v[116:117] op_sel_hi:[1,0,1]
	v_pk_fma_f32 v[120:121], v[44:45], v[52:53], v[120:121] op_sel_hi:[0,1,1]
	v_mov_b32_e32 v115, v49
	v_mov_b32_e32 v7, v3
	v_pk_add_f32 v[168:169], v[168:169], v[188:189] neg_lo:[0,1] neg_hi:[0,1]
	v_pk_add_f32 v[188:189], v[170:171], v[184:185] op_sel:[0,1] op_sel_hi:[1,0] neg_hi:[0,1]
	v_pk_add_f32 v[170:171], v[170:171], v[184:185] op_sel:[0,1] op_sel_hi:[1,0] neg_lo:[0,1]
	v_pk_add_f32 v[184:185], v[164:165], v[172:173]
	v_pk_add_f32 v[164:165], v[164:165], v[172:173] neg_lo:[0,1] neg_hi:[0,1]
	v_pk_add_f32 v[172:173], v[128:129], v[166:167] op_sel:[0,1] op_sel_hi:[1,0] neg_hi:[0,1]
	v_pk_add_f32 v[128:129], v[128:129], v[166:167] op_sel:[0,1] op_sel_hi:[1,0] neg_lo:[0,1]
	v_pk_fma_f32 v[34:35], v[44:45], v[152:153], v[34:35] op_sel_hi:[0,1,1]
	v_pk_mul_f32 v[44:45], v[72:73], v[180:181] op_sel:[0,1] op_sel_hi:[1,0]
	v_xor_b32_e32 v12, 0x80000000, v9
	v_xor_b32_e32 v16, 0x80000000, v15
	v_xor_b32_e32 v22, 0x80000000, v5
	v_xor_b32_e32 v28, 0x80000000, v25
	v_xor_b32_e32 v38, 0x80000000, v33
	v_xor_b32_e32 v42, 0x80000000, v41
	v_xor_b32_e32 v50, 0x80000000, v11
	v_xor_b32_e32 v60, 0x80000000, v57
	v_xor_b32_e32 v64, 0x80000000, v63
	v_xor_b32_e32 v68, 0x80000000, v67
	v_xor_b32_e32 v70, 0x80000000, v21
	v_xor_b32_e32 v76, 0x80000000, v75
	v_xor_b32_e32 v80, 0x80000000, v79
	v_xor_b32_e32 v84, 0x80000000, v83
	v_xor_b32_e32 v86, 0x80000000, v27
	v_xor_b32_e32 v90, 0x80000000, v89
	v_xor_b32_e32 v94, 0x80000000, v93
	v_xor_b32_e32 v98, 0x80000000, v97
	v_xor_b32_e32 v100, 0x80000000, v37
	v_xor_b32_e32 v104, 0x80000000, v103
	v_xor_b32_e32 v108, 0x80000000, v107
	v_xor_b32_e32 v112, 0x80000000, v111
	v_xor_b32_e32 v118, 0x80000000, v117
	v_xor_b32_e32 v122, 0x80000000, v121
	v_xor_b32_e32 v126, 0x80000000, v125
	v_mov_b32_e32 v127, v125
	v_mov_b32_e32 v123, v121
	v_mov_b32_e32 v119, v117
	v_mov_b32_e32 v113, v111
	v_mov_b32_e32 v109, v107
	v_mov_b32_e32 v105, v103
	v_mov_b32_e32 v101, v37
	v_mov_b32_e32 v99, v97
	v_mov_b32_e32 v95, v93
	v_mov_b32_e32 v91, v89
	v_mov_b32_e32 v87, v27
	v_mov_b32_e32 v85, v83
	v_mov_b32_e32 v81, v79
	v_mov_b32_e32 v77, v75
	v_mov_b32_e32 v71, v21
	v_mov_b32_e32 v69, v67
	v_mov_b32_e32 v65, v63
	v_mov_b32_e32 v61, v57
	v_mov_b32_e32 v51, v11
	v_mov_b32_e32 v43, v41
	v_mov_b32_e32 v39, v33
	v_mov_b32_e32 v29, v25
	v_mov_b32_e32 v23, v5
	v_mov_b32_e32 v17, v15
	v_mov_b32_e32 v13, v9
	v_pk_fma_f32 v[44:45], v[46:47], v[180:181], v[44:45] op_sel_hi:[0,1,1]
	v_pk_mul_f32 v[46:47], v[58:59], v[192:193] op_sel:[0,1] op_sel_hi:[1,0]
	v_pk_mul_f32 v[72:73], v[114:115], v[194:195] op_sel:[0,1] op_sel_hi:[1,0]
	v_pk_mul_f32 v[6:7], v[128:129], v[6:7] op_sel:[1,0] op_sel_hi:[0,1]
	v_pk_fma_f32 v[46:47], v[52:53], v[192:193], v[46:47] op_sel_hi:[0,1,1]
	v_pk_mul_f32 v[52:53], v[126:127], v[182:183] op_sel:[0,1] op_sel_hi:[1,0]
	v_pk_mul_f32 v[54:55], v[122:123], v[154:155] op_sel:[0,1] op_sel_hi:[1,0]
	v_pk_mul_f32 v[58:59], v[118:119], v[184:185] op_sel:[0,1] op_sel_hi:[1,0]
	v_pk_fma_f32 v[48:49], v[48:49], v[194:195], v[72:73] op_sel_hi:[0,1,1]
	v_pk_mul_f32 v[72:73], v[112:113], v[176:177] op_sel:[0,1] op_sel_hi:[1,0]
	v_pk_mul_f32 v[108:109], v[108:109], v[158:159] op_sel:[0,1] op_sel_hi:[1,0]
	v_pk_mul_f32 v[104:105], v[104:105], v[188:189] op_sel:[0,1] op_sel_hi:[1,0]
	v_pk_mul_f32 v[100:101], v[100:101], v[156:157] op_sel:[0,1] op_sel_hi:[1,0]
	v_pk_mul_f32 v[98:99], v[98:99], v[186:187] op_sel:[0,1] op_sel_hi:[1,0]
	v_pk_mul_f32 v[94:95], v[94:95], v[144:145] op_sel:[0,1] op_sel_hi:[1,0]
	v_pk_mul_f32 v[90:91], v[90:91], v[172:173] op_sel:[0,1] op_sel_hi:[1,0]
	v_pk_mul_f32 v[86:87], v[174:175], v[86:87] op_sel:[1,0] op_sel_hi:[0,1]
	v_pk_mul_f32 v[84:85], v[130:131], v[84:85] op_sel:[1,0] op_sel_hi:[0,1]
	v_pk_mul_f32 v[80:81], v[138:139], v[80:81] op_sel:[1,0] op_sel_hi:[0,1]
	v_pk_mul_f32 v[76:77], v[168:169], v[76:77] op_sel:[1,0] op_sel_hi:[0,1]
	v_pk_mul_f32 v[70:71], v[148:149], v[70:71] op_sel:[1,0] op_sel_hi:[0,1]
	v_pk_mul_f32 v[68:69], v[178:179], v[68:69] op_sel:[1,0] op_sel_hi:[0,1]
	v_pk_mul_f32 v[64:65], v[134:135], v[64:65] op_sel:[1,0] op_sel_hi:[0,1]
	v_pk_mul_f32 v[60:61], v[164:165], v[60:61] op_sel:[1,0] op_sel_hi:[0,1]
	v_pk_mul_f32 v[50:51], v[190:191], v[50:51] op_sel:[1,0] op_sel_hi:[0,1]
	v_pk_mul_f32 v[42:43], v[136:137], v[42:43] op_sel:[1,0] op_sel_hi:[0,1]
	v_pk_mul_f32 v[38:39], v[140:141], v[38:39] op_sel:[1,0] op_sel_hi:[0,1]
	v_pk_mul_f32 v[28:29], v[170:171], v[28:29] op_sel:[1,0] op_sel_hi:[0,1]
	v_pk_mul_f32 v[22:23], v[150:151], v[22:23] op_sel:[1,0] op_sel_hi:[0,1]
	v_pk_mul_f32 v[16:17], v[160:161], v[16:17] op_sel:[1,0] op_sel_hi:[0,1]
	v_pk_mul_f32 v[12:13], v[132:133], v[12:13] op_sel:[1,0] op_sel_hi:[0,1]
	v_pk_fma_f32 v[2:3], v[128:129], v[2:3], v[6:7] op_sel_hi:[1,0,1]
	v_pk_fma_f32 v[52:53], v[124:125], v[182:183], v[52:53] op_sel_hi:[0,1,1]
	v_pk_fma_f32 v[54:55], v[120:121], v[154:155], v[54:55] op_sel_hi:[0,1,1]
	v_pk_fma_f32 v[58:59], v[116:117], v[184:185], v[58:59] op_sel_hi:[0,1,1]
	v_pk_fma_f32 v[72:73], v[110:111], v[176:177], v[72:73] op_sel_hi:[0,1,1]
	v_pk_fma_f32 v[106:107], v[106:107], v[158:159], v[108:109] op_sel_hi:[0,1,1]
	v_pk_fma_f32 v[102:103], v[102:103], v[188:189], v[104:105] op_sel_hi:[0,1,1]
	v_pk_fma_f32 v[36:37], v[36:37], v[156:157], v[100:101] op_sel_hi:[0,1,1]
	v_pk_fma_f32 v[96:97], v[96:97], v[186:187], v[98:99] op_sel_hi:[0,1,1]
	v_pk_fma_f32 v[92:93], v[92:93], v[144:145], v[94:95] op_sel_hi:[0,1,1]
	v_pk_fma_f32 v[88:89], v[88:89], v[172:173], v[90:91] op_sel_hi:[0,1,1]
	v_pk_fma_f32 v[26:27], v[174:175], v[26:27], v[86:87] op_sel_hi:[1,0,1]
	v_pk_fma_f32 v[82:83], v[130:131], v[82:83], v[84:85] op_sel_hi:[1,0,1]
	v_pk_fma_f32 v[78:79], v[138:139], v[78:79], v[80:81] op_sel_hi:[1,0,1]
	v_pk_fma_f32 v[74:75], v[168:169], v[74:75], v[76:77] op_sel_hi:[1,0,1]
	v_pk_fma_f32 v[20:21], v[148:149], v[20:21], v[70:71] op_sel_hi:[1,0,1]
	v_pk_fma_f32 v[66:67], v[178:179], v[66:67], v[68:69] op_sel_hi:[1,0,1]
	v_pk_fma_f32 v[62:63], v[134:135], v[62:63], v[64:65] op_sel_hi:[1,0,1]
	v_pk_fma_f32 v[56:57], v[164:165], v[56:57], v[60:61] op_sel_hi:[1,0,1]
	v_pk_fma_f32 v[10:11], v[190:191], v[10:11], v[50:51] op_sel_hi:[1,0,1]
	v_pk_fma_f32 v[40:41], v[136:137], v[40:41], v[42:43] op_sel_hi:[1,0,1]
	v_pk_fma_f32 v[32:33], v[140:141], v[32:33], v[38:39] op_sel_hi:[1,0,1]
	v_pk_fma_f32 v[24:25], v[170:171], v[24:25], v[28:29] op_sel_hi:[1,0,1]
	v_pk_fma_f32 v[4:5], v[150:151], v[4:5], v[22:23] op_sel_hi:[1,0,1]
	v_pk_fma_f32 v[14:15], v[160:161], v[14:15], v[16:17] op_sel_hi:[1,0,1]
	v_pk_fma_f32 v[8:9], v[132:133], v[8:9], v[12:13] op_sel_hi:[1,0,1]
	ds_write_b64 v18, v[162:163]
	ds_write_b64 v18, v[26:27] offset:2112
	ds_write_b64 v18, v[48:49] offset:4224
	ds_write_b64 v18, v[10:11] offset:6336
	ds_write_b64 v18, v[46:47] offset:8448
	ds_write_b64 v18, v[20:21] offset:10560
	ds_write_b64 v18, v[36:37] offset:12672
	ds_write_b64 v18, v[4:5] offset:14784
	ds_write_b64 v18, v[34:35] offset:16896
	ds_write_b64 v18, v[78:79] offset:19008
	ds_write_b64 v18, v[106:107] offset:21120
	ds_write_b64 v18, v[32:33] offset:23232
	ds_write_b64 v18, v[54:55] offset:25344
	ds_write_b64 v18, v[62:63] offset:27456
	ds_write_b64 v18, v[92:93] offset:29568
	ds_write_b64 v18, v[8:9] offset:31680
	ds_write_b64 v18, v[30:31] offset:33792
	ds_write_b64 v18, v[82:83] offset:35904
	ds_write_b64 v18, v[72:73] offset:38016
	ds_write_b64 v18, v[40:41] offset:40128
	ds_write_b64 v18, v[52:53] offset:42240
	ds_write_b64 v18, v[66:67] offset:44352
	ds_write_b64 v18, v[96:97] offset:46464
	ds_write_b64 v18, v[14:15] offset:48576
	ds_write_b64 v18, v[44:45] offset:50688
	ds_write_b64 v18, v[74:75] offset:52800
	ds_write_b64 v18, v[102:103] offset:54912
	ds_write_b64 v18, v[24:25] offset:57024
	ds_write_b64 v18, v[58:59] offset:59136
	ds_write_b64 v18, v[56:57] offset:61248
	ds_write_b64 v18, v[88:89] offset:63360
	ds_write_b64 v18, v[2:3] offset:65472
	v_mov_b32_e32 v3, v210
	s_waitcnt lgkmcnt(0)
	s_barrier
	s_add_i32 s64, s62, s48
	v_and_b32_e32 v5, 15, v3
	v_cvt_f32_ubyte0_e32 v2, v5
	v_mul_f32_e32 v4, 0x3b800000, v2
	v_sin_f32_e32 v2, v4
	v_cos_f32_e32 v4, v4
	v_lshlrev_b32_e32 v64, 3, v5
	v_lshlrev_b32_e32 v18, 4, v3
	v_xor_b32_e32 v5, 0x80000000, v2
	v_mov_b32_e32 v3, v5
	v_pk_mul_f32 v[6:7], v[4:5], v[2:3] op_sel:[1,0] op_sel_hi:[0,1]
	v_pk_fma_f32 v[6:7], v[4:5], v[4:5], v[6:7] op_sel_hi:[1,0,1]
	s_ashr_i32 s65, s64, 31
	v_xor_b32_e32 v12, 0x80000000, v7
	v_mov_b32_e32 v13, v7
	v_pk_mul_f32 v[10:11], v[6:7], v[12:13] op_sel:[1,0] op_sel_hi:[0,1]
	v_pk_fma_f32 v[10:11], v[6:7], v[6:7], v[10:11] op_sel_hi:[1,0,1]
	v_pk_mul_f32 v[8:9], v[2:3], v[6:7] op_sel:[0,1] op_sel_hi:[1,0]
	v_xor_b32_e32 v14, 0x80000000, v11
	v_mov_b32_e32 v15, v11
	v_pk_mul_f32 v[32:33], v[10:11], v[14:15] op_sel:[1,0] op_sel_hi:[0,1]
	v_pk_fma_f32 v[32:33], v[10:11], v[10:11], v[32:33] op_sel_hi:[1,0,1]
	v_pk_mul_f32 v[16:17], v[2:3], v[10:11] op_sel:[0,1] op_sel_hi:[1,0]
	v_pk_mul_f32 v[48:49], v[14:15], v[32:33] op_sel:[0,1] op_sel_hi:[1,0]
	v_pk_mul_f32 v[36:37], v[2:3], v[32:33] op_sel:[0,1] op_sel_hi:[1,0]
	v_pk_fma_f32 v[48:49], v[10:11], v[32:33], v[48:49] op_sel_hi:[0,1,1]
	v_pk_mul_f32 v[52:53], v[2:3], v[48:49] op_sel:[0,1] op_sel_hi:[1,0]
	v_pk_fma_f32 v[8:9], v[4:5], v[6:7], v[8:9] op_sel_hi:[0,1,1]
	v_pk_fma_f32 v[16:17], v[4:5], v[10:11], v[16:17] op_sel_hi:[0,1,1]
	v_pk_fma_f32 v[36:37], v[4:5], v[32:33], v[36:37] op_sel_hi:[0,1,1]
	v_pk_fma_f32 v[52:53], v[4:5], v[48:49], v[52:53] op_sel_hi:[0,1,1]
	v_and_b32_e32 v5, 0xffffff00, v18
	v_lshlrev_b32_e32 v18, 3, v5
	v_add3_u32 v18, 0, v64, v18
	v_ashrrev_i32_e32 v64, 2, v5
	v_add_u32_e32 v106, v18, v64
	ds_read2_b64 v[64:67], v106 offset1:16
	ds_read2_b64 v[68:71], v106 offset0:33 offset1:49
	ds_read2_b64 v[72:75], v106 offset0:66 offset1:82
	ds_read2_b64 v[76:79], v106 offset0:132 offset1:148
	ds_read2_b64 v[80:83], v106 offset0:99 offset1:115
	ds_read2_b64 v[84:87], v106 offset0:165 offset1:181
	ds_read2_b64 v[88:91], v106 offset0:198 offset1:214
	ds_read2_b64 v[92:95], v106 offset0:231 offset1:247
	s_waitcnt lgkmcnt(4)
	v_pk_add_f32 v[96:97], v[64:65], v[76:77]
	v_pk_add_f32 v[64:65], v[64:65], v[76:77] neg_lo:[0,1] neg_hi:[0,1]
	v_pk_add_f32 v[76:77], v[66:67], v[78:79]
	v_pk_add_f32 v[66:67], v[66:67], v[78:79] neg_lo:[0,1] neg_hi:[0,1]
	s_waitcnt lgkmcnt(1)
	v_pk_add_f32 v[98:99], v[74:75], v[90:91]
	v_pk_mul_f32 v[78:79], v[66:67], s[18:19]
	v_pk_add_f32 v[74:75], v[74:75], v[90:91] neg_lo:[0,1] neg_hi:[0,1]
	v_pk_fma_f32 v[66:67], v[66:67], s[16:17], v[78:79] op_sel:[0,0,1] op_sel_hi:[1,0,0]
	v_pk_add_f32 v[78:79], v[68:69], v[84:85]
	v_pk_add_f32 v[68:69], v[68:69], v[84:85] neg_lo:[0,1] neg_hi:[0,1]
	v_pk_mul_f32 v[90:91], v[74:75], s[40:41]
	v_pk_mul_f32 v[84:85], v[68:69], s[36:37]
	v_pk_fma_f32 v[74:75], v[74:75], s[68:69], v[90:91] op_sel:[0,0,1] op_sel_hi:[1,0,0] neg_lo:[1,0,0] neg_hi:[1,0,0]
	v_pk_fma_f32 v[68:69], v[68:69], s[66:67], v[84:85] op_sel:[0,0,1] op_sel_hi:[1,0,0]
	v_pk_add_f32 v[84:85], v[70:71], v[86:87]
	v_pk_add_f32 v[70:71], v[70:71], v[86:87] neg_lo:[0,1] neg_hi:[0,1]
	s_waitcnt lgkmcnt(0)
	v_pk_add_f32 v[90:91], v[80:81], v[92:93]
	v_pk_add_f32 v[80:81], v[80:81], v[92:93] neg_lo:[0,1] neg_hi:[0,1]
	v_pk_mul_f32 v[86:87], v[70:71], s[40:41]
	v_pk_mul_f32 v[92:93], v[80:81], s[36:37]
	v_pk_fma_f32 v[70:71], v[70:71], s[68:69], v[86:87] op_sel:[0,0,1] op_sel_hi:[1,0,0]
	v_pk_add_f32 v[86:87], v[72:73], v[88:89]
	v_pk_add_f32 v[88:89], v[72:73], v[88:89] neg_lo:[0,1] neg_hi:[0,1]
	v_pk_fma_f32 v[80:81], v[80:81], s[66:67], v[92:93] op_sel:[0,0,1] op_sel_hi:[1,0,0] neg_lo:[1,0,0] neg_hi:[1,0,0]
	v_pk_add_f32 v[92:93], v[82:83], v[94:95]
	v_pk_add_f32 v[82:83], v[82:83], v[94:95] neg_lo:[0,1] neg_hi:[0,1]
	v_pk_mul_f32 v[94:95], v[82:83], s[18:19]
	v_pk_fma_f32 v[82:83], v[82:83], s[16:17], v[94:95] op_sel:[0,0,1] op_sel_hi:[1,0,0] neg_lo:[1,0,0] neg_hi:[1,0,0]
	v_pk_add_f32 v[94:95], v[96:97], v[86:87]
	v_pk_add_f32 v[86:87], v[96:97], v[86:87] neg_lo:[0,1] neg_hi:[0,1]
	v_pk_add_f32 v[96:97], v[76:77], v[98:99]
	v_pk_add_f32 v[76:77], v[76:77], v[98:99] neg_lo:[0,1] neg_hi:[0,1]
	v_pk_add_f32 v[100:101], v[84:85], v[92:93]
	v_pk_add_f32 v[84:85], v[84:85], v[92:93] neg_lo:[0,1] neg_hi:[0,1]
	v_pk_add_f32 v[72:73], v[64:65], v[88:89] op_sel:[0,1] op_sel_hi:[1,0] neg_hi:[0,1]
	v_pk_add_f32 v[64:65], v[64:65], v[88:89] op_sel:[0,1] op_sel_hi:[1,0] neg_lo:[0,1]
	v_pk_add_f32 v[88:89], v[66:67], v[74:75]
	v_pk_add_f32 v[66:67], v[66:67], v[74:75] neg_lo:[0,1] neg_hi:[0,1]
	v_pk_mul_f32 v[98:99], v[76:77], s[36:37]
	v_pk_mul_f32 v[92:93], v[84:85], s[36:37]
	v_pk_mul_f32 v[74:75], v[66:67], s[36:37]
	v_pk_fma_f32 v[76:77], v[76:77], s[66:67], v[98:99] op_sel:[0,0,1] op_sel_hi:[1,0,0]
	v_pk_add_f32 v[98:99], v[78:79], v[90:91]
	v_pk_add_f32 v[90:91], v[78:79], v[90:91] neg_lo:[0,1] neg_hi:[0,1]
	v_pk_fma_f32 v[84:85], v[84:85], s[66:67], v[92:93] op_sel:[0,0,1] op_sel_hi:[1,0,0] neg_lo:[1,0,0] neg_hi:[1,0,0]
	v_pk_fma_f32 v[66:67], v[66:67], s[66:67], v[74:75] op_sel:[0,0,1] op_sel_hi:[1,0,0]
	v_pk_add_f32 v[74:75], v[68:69], v[80:81]
	v_pk_add_f32 v[92:93], v[70:71], v[82:83]
	v_pk_add_f32 v[70:71], v[70:71], v[82:83] neg_lo:[0,1] neg_hi:[0,1]
	v_pk_add_f32 v[68:69], v[68:69], v[80:81] neg_lo:[0,1] neg_hi:[0,1]
	v_pk_mul_f32 v[82:83], v[70:71], s[36:37]
	v_pk_add_f32 v[102:103], v[72:73], v[74:75]
	v_pk_add_f32 v[72:73], v[72:73], v[74:75] neg_lo:[0,1] neg_hi:[0,1]
	v_pk_add_f32 v[74:75], v[88:89], v[92:93]
	v_pk_add_f32 v[92:93], v[88:89], v[92:93] neg_lo:[0,1] neg_hi:[0,1]
	v_xor_b32_e32 v20, 0x80000000, v9
	v_mov_b32_e32 v21, v9
	v_pk_mul_f32 v[24:25], v[12:13], v[10:11] op_sel:[0,1] op_sel_hi:[1,0]
	v_xor_b32_e32 v81, 0x80000000, v68
	v_pk_fma_f32 v[70:71], v[70:71], s[66:67], v[82:83] op_sel:[0,0,1] op_sel_hi:[1,0,0] neg_lo:[1,0,0] neg_hi:[1,0,0]
	v_pk_add_f32 v[78:79], v[86:87], v[90:91] op_sel:[0,1] op_sel_hi:[1,0] neg_hi:[0,1]
	v_pk_add_f32 v[86:87], v[86:87], v[90:91] op_sel:[0,1] op_sel_hi:[1,0] neg_lo:[0,1]
	v_pk_add_f32 v[90:91], v[76:77], v[84:85]
	v_pk_add_f32 v[84:85], v[76:77], v[84:85] neg_lo:[0,1] neg_hi:[0,1]
	v_mov_b32_e32 v80, v69
	v_xor_b32_e32 v22, 0x80000000, v17
	v_mov_b32_e32 v23, v17
	v_pk_fma_f32 v[24:25], v[6:7], v[10:11], v[24:25] op_sel_hi:[0,1,1]
	v_pk_mul_f32 v[28:29], v[10:11], v[20:21] op_sel:[1,0] op_sel_hi:[0,1]
	v_pk_add_f32 v[68:69], v[64:65], v[80:81]
	v_pk_add_f32 v[64:65], v[64:65], v[80:81] neg_lo:[0,1] neg_hi:[0,1]
	v_pk_add_f32 v[80:81], v[66:67], v[70:71]
	v_pk_add_f32 v[70:71], v[66:67], v[70:71] neg_lo:[0,1] neg_hi:[0,1]
	v_pk_add_f32 v[88:89], v[72:73], v[92:93] op_sel:[0,1] op_sel_hi:[1,0] neg_hi:[0,1]
	v_xor_b32_e32 v26, 0x80000000, v25
	v_mov_b32_e32 v27, v25
	v_pk_fma_f32 v[28:29], v[10:11], v[8:9], v[28:29] op_sel_hi:[1,0,1]
	v_pk_add_f32 v[76:77], v[86:87], v[84:85] op_sel:[0,1] op_sel_hi:[1,0] neg_hi:[0,1]
	v_pk_add_f32 v[72:73], v[72:73], v[92:93] op_sel:[0,1] op_sel_hi:[1,0] neg_lo:[0,1]
	v_pk_mul_f32 v[92:93], v[22:23], v[88:89] op_sel:[0,1] op_sel_hi:[1,0]
	v_xor_b32_e32 v30, 0x80000000, v29
	v_mov_b32_e32 v31, v29
	v_pk_add_f32 v[82:83], v[94:95], v[98:99]
	v_pk_add_f32 v[94:95], v[94:95], v[98:99] neg_lo:[0,1] neg_hi:[0,1]
	v_pk_add_f32 v[98:99], v[96:97], v[100:101]
	v_pk_add_f32 v[66:67], v[64:65], v[70:71] op_sel:[0,1] op_sel_hi:[1,0] neg_hi:[0,1]
	v_pk_fma_f32 v[88:89], v[16:17], v[88:89], v[92:93] op_sel_hi:[0,1,1]
	v_pk_mul_f32 v[92:93], v[26:27], v[76:77] op_sel:[0,1] op_sel_hi:[1,0]
	v_xor_b32_e32 v34, 0x80000000, v33
	v_mov_b32_e32 v35, v33
	v_pk_mul_f32 v[40:41], v[12:13], v[32:33] op_sel:[0,1] op_sel_hi:[1,0]
	v_pk_add_f32 v[104:105], v[82:83], v[98:99]
	v_pk_add_f32 v[82:83], v[82:83], v[98:99] neg_lo:[0,1] neg_hi:[0,1]
	v_pk_fma_f32 v[76:77], v[24:25], v[76:77], v[92:93] op_sel_hi:[0,1,1]
	v_pk_mul_f32 v[92:93], v[30:31], v[66:67] op_sel:[0,1] op_sel_hi:[1,0]
	v_xor_b32_e32 v38, 0x80000000, v37
	v_mov_b32_e32 v39, v37
	v_pk_fma_f32 v[40:41], v[6:7], v[32:33], v[40:41] op_sel_hi:[0,1,1]
	v_pk_mul_f32 v[44:45], v[20:21], v[32:33] op_sel:[0,1] op_sel_hi:[1,0]
	v_pk_add_f32 v[84:85], v[86:87], v[84:85] op_sel:[0,1] op_sel_hi:[1,0] neg_lo:[0,1]
	v_pk_add_f32 v[86:87], v[102:103], v[74:75]
	v_pk_add_f32 v[74:75], v[102:103], v[74:75] neg_lo:[0,1] neg_hi:[0,1]
	v_pk_fma_f32 v[66:67], v[28:29], v[66:67], v[92:93] op_sel_hi:[0,1,1]
	v_pk_mul_f32 v[92:93], v[34:35], v[82:83] op_sel:[0,1] op_sel_hi:[1,0]
	v_xor_b32_e32 v42, 0x80000000, v41
	v_mov_b32_e32 v43, v41
	v_pk_fma_f32 v[44:45], v[8:9], v[32:33], v[44:45] op_sel_hi:[0,1,1]
	v_pk_add_f32 v[100:101], v[96:97], v[100:101] neg_lo:[0,1] neg_hi:[0,1]
	v_pk_add_f32 v[98:99], v[78:79], v[90:91]
	v_pk_add_f32 v[78:79], v[78:79], v[90:91] neg_lo:[0,1] neg_hi:[0,1]
	v_pk_fma_f32 v[82:83], v[32:33], v[82:83], v[92:93] op_sel_hi:[0,1,1]
	v_pk_mul_f32 v[92:93], v[38:39], v[74:75] op_sel:[0,1] op_sel_hi:[1,0]
	v_xor_b32_e32 v46, 0x80000000, v45
	v_mov_b32_e32 v47, v45
	v_pk_add_f32 v[90:91], v[68:69], v[80:81]
	v_pk_add_f32 v[68:69], v[68:69], v[80:81] neg_lo:[0,1] neg_hi:[0,1]
	v_pk_fma_f32 v[74:75], v[36:37], v[74:75], v[92:93] op_sel_hi:[0,1,1]
	v_pk_mul_f32 v[92:93], v[42:43], v[78:79] op_sel:[0,1] op_sel_hi:[1,0]
	v_xor_b32_e32 v50, 0x80000000, v49
	v_mov_b32_e32 v51, v49
	v_pk_mul_f32 v[56:57], v[12:13], v[48:49] op_sel:[0,1] op_sel_hi:[1,0]
	v_pk_add_f32 v[96:97], v[94:95], v[100:101] op_sel:[0,1] op_sel_hi:[1,0] neg_hi:[0,1]
	v_pk_add_f32 v[94:95], v[94:95], v[100:101] op_sel:[0,1] op_sel_hi:[1,0] neg_lo:[0,1]
	v_pk_fma_f32 v[78:79], v[40:41], v[78:79], v[92:93] op_sel_hi:[0,1,1]
	v_pk_mul_f32 v[92:93], v[46:47], v[68:69] op_sel:[0,1] op_sel_hi:[1,0]
	v_xor_b32_e32 v54, 0x80000000, v53
	v_mov_b32_e32 v55, v53
	v_pk_fma_f32 v[56:57], v[6:7], v[48:49], v[56:57] op_sel_hi:[0,1,1]
	v_pk_mul_f32 v[60:61], v[20:21], v[48:49] op_sel:[0,1] op_sel_hi:[1,0]
	v_pk_fma_f32 v[68:69], v[44:45], v[68:69], v[92:93] op_sel_hi:[0,1,1]
	v_pk_mul_f32 v[92:93], v[50:51], v[94:95] op_sel:[0,1] op_sel_hi:[1,0]
	v_xor_b32_e32 v58, 0x80000000, v57
	v_mov_b32_e32 v59, v57
	v_pk_fma_f32 v[60:61], v[8:9], v[48:49], v[60:61] op_sel_hi:[0,1,1]
	v_pk_add_f32 v[64:65], v[64:65], v[70:71] op_sel:[0,1] op_sel_hi:[1,0] neg_lo:[0,1]
	v_pk_mul_f32 v[70:71], v[2:3], v[86:87] op_sel:[0,1] op_sel_hi:[1,0]
	v_pk_fma_f32 v[92:93], v[48:49], v[94:95], v[92:93] op_sel_hi:[0,1,1]
	v_pk_mul_f32 v[94:95], v[54:55], v[72:73] op_sel:[0,1] op_sel_hi:[1,0]
	v_xor_b32_e32 v62, 0x80000000, v61
	v_mov_b32_e32 v63, v61
	v_pk_fma_f32 v[70:71], v[4:5], v[86:87], v[70:71] op_sel_hi:[0,1,1]
	v_pk_mul_f32 v[86:87], v[20:21], v[90:91] op_sel:[0,1] op_sel_hi:[1,0]
	v_pk_fma_f32 v[72:73], v[52:53], v[72:73], v[94:95] op_sel_hi:[0,1,1]
	v_pk_mul_f32 v[94:95], v[58:59], v[84:85] op_sel:[0,1] op_sel_hi:[1,0]
	v_add_u32_e32 v5, 0x2000, v5
	v_pk_mul_f32 v[80:81], v[12:13], v[98:99] op_sel:[0,1] op_sel_hi:[1,0]
	v_pk_fma_f32 v[86:87], v[8:9], v[90:91], v[86:87] op_sel_hi:[0,1,1]
	v_pk_mul_f32 v[90:91], v[14:15], v[96:97] op_sel:[0,1] op_sel_hi:[1,0]
	v_pk_fma_f32 v[84:85], v[56:57], v[84:85], v[94:95] op_sel_hi:[0,1,1]
	v_pk_mul_f32 v[94:95], v[62:63], v[64:65] op_sel:[0,1] op_sel_hi:[1,0]
	v_ashrrev_i32_e32 v5, 2, v5
	v_pk_fma_f32 v[80:81], v[6:7], v[98:99], v[80:81] op_sel_hi:[0,1,1]
	v_pk_fma_f32 v[90:91], v[10:11], v[96:97], v[90:91] op_sel_hi:[0,1,1]
	v_pk_fma_f32 v[64:65], v[60:61], v[64:65], v[94:95] op_sel_hi:[0,1,1]
	ds_write2_b64 v106, v[104:105], v[82:83] offset1:16
	ds_write2_b64 v106, v[90:91], v[92:93] offset0:33 offset1:49
	ds_write2_b64 v106, v[80:81], v[78:79] offset0:66 offset1:82
	ds_write2_b64 v106, v[76:77], v[84:85] offset0:99 offset1:115
	ds_write2_b64 v106, v[70:71], v[74:75] offset0:132 offset1:148
	ds_write2_b64 v106, v[88:89], v[72:73] offset0:165 offset1:181
	ds_write2_b64 v106, v[86:87], v[68:69] offset0:198 offset1:214
	ds_write2_b64 v106, v[66:67], v[64:65] offset0:231 offset1:247
	v_add3_u32 v18, v18, v5, s5
	ds_read2_b64 v[64:67], v18 offset1:16
	ds_read2_b64 v[68:71], v18 offset0:33 offset1:49
	ds_read2_b64 v[72:75], v18 offset0:66 offset1:82
	ds_read2_b64 v[76:79], v18 offset0:132 offset1:148
	ds_read2_b64 v[80:83], v18 offset0:99 offset1:115
	ds_read2_b64 v[84:87], v18 offset0:165 offset1:181
	ds_read2_b64 v[88:91], v18 offset0:198 offset1:214
	ds_read2_b64 v[92:95], v18 offset0:231 offset1:247
	s_waitcnt lgkmcnt(4)
	v_pk_add_f32 v[96:97], v[64:65], v[76:77]
	v_pk_add_f32 v[64:65], v[64:65], v[76:77] neg_lo:[0,1] neg_hi:[0,1]
	v_pk_add_f32 v[76:77], v[66:67], v[78:79]
	v_pk_add_f32 v[66:67], v[66:67], v[78:79] neg_lo:[0,1] neg_hi:[0,1]
	s_waitcnt lgkmcnt(1)
	v_pk_add_f32 v[98:99], v[74:75], v[90:91]
	v_pk_mul_f32 v[78:79], v[66:67], s[18:19]
	v_pk_add_f32 v[74:75], v[74:75], v[90:91] neg_lo:[0,1] neg_hi:[0,1]
	v_pk_fma_f32 v[66:67], v[66:67], s[16:17], v[78:79] op_sel:[0,0,1] op_sel_hi:[1,0,0]
	v_pk_add_f32 v[78:79], v[68:69], v[84:85]
	v_pk_add_f32 v[68:69], v[68:69], v[84:85] neg_lo:[0,1] neg_hi:[0,1]
	v_pk_mul_f32 v[90:91], v[74:75], s[40:41]
	v_pk_mul_f32 v[84:85], v[68:69], s[36:37]
	v_pk_fma_f32 v[74:75], v[74:75], s[68:69], v[90:91] op_sel:[0,0,1] op_sel_hi:[1,0,0] neg_lo:[1,0,0] neg_hi:[1,0,0]
	s_waitcnt lgkmcnt(0)
	v_pk_add_f32 v[90:91], v[80:81], v[92:93]
	v_pk_add_f32 v[80:81], v[80:81], v[92:93] neg_lo:[0,1] neg_hi:[0,1]
	v_pk_fma_f32 v[68:69], v[68:69], s[66:67], v[84:85] op_sel:[0,0,1] op_sel_hi:[1,0,0]
	v_pk_add_f32 v[84:85], v[70:71], v[86:87]
	v_pk_add_f32 v[70:71], v[70:71], v[86:87] neg_lo:[0,1] neg_hi:[0,1]
	v_pk_mul_f32 v[92:93], v[80:81], s[36:37]
	v_pk_mul_f32 v[86:87], v[70:71], s[40:41]
	v_pk_fma_f32 v[80:81], v[80:81], s[66:67], v[92:93] op_sel:[0,0,1] op_sel_hi:[1,0,0] neg_lo:[1,0,0] neg_hi:[1,0,0]
	v_pk_add_f32 v[92:93], v[82:83], v[94:95]
	v_pk_add_f32 v[82:83], v[82:83], v[94:95] neg_lo:[0,1] neg_hi:[0,1]
	v_pk_fma_f32 v[70:71], v[70:71], s[68:69], v[86:87] op_sel:[0,0,1] op_sel_hi:[1,0,0]
	v_pk_add_f32 v[86:87], v[72:73], v[88:89]
	v_pk_mul_f32 v[94:95], v[82:83], s[18:19]
	v_pk_add_f32 v[88:89], v[72:73], v[88:89] neg_lo:[0,1] neg_hi:[0,1]
	v_pk_fma_f32 v[82:83], v[82:83], s[16:17], v[94:95] op_sel:[0,0,1] op_sel_hi:[1,0,0] neg_lo:[1,0,0] neg_hi:[1,0,0]
	v_pk_add_f32 v[94:95], v[96:97], v[86:87]
	v_pk_add_f32 v[86:87], v[96:97], v[86:87] neg_lo:[0,1] neg_hi:[0,1]
	v_pk_add_f32 v[96:97], v[76:77], v[98:99]
	v_pk_add_f32 v[76:77], v[76:77], v[98:99] neg_lo:[0,1] neg_hi:[0,1]
	v_pk_mul_f32 v[98:99], v[76:77], s[36:37]
	v_pk_add_f32 v[100:101], v[84:85], v[92:93]
	v_pk_add_f32 v[84:85], v[84:85], v[92:93] neg_lo:[0,1] neg_hi:[0,1]
	v_pk_fma_f32 v[76:77], v[76:77], s[66:67], v[98:99] op_sel:[0,0,1] op_sel_hi:[1,0,0]
	v_pk_add_f32 v[98:99], v[78:79], v[90:91]
	v_pk_add_f32 v[90:91], v[78:79], v[90:91] neg_lo:[0,1] neg_hi:[0,1]
	v_pk_mul_f32 v[92:93], v[84:85], s[36:37]
	v_pk_add_f32 v[72:73], v[64:65], v[88:89] op_sel:[0,1] op_sel_hi:[1,0] neg_hi:[0,1]
	v_pk_add_f32 v[64:65], v[64:65], v[88:89] op_sel:[0,1] op_sel_hi:[1,0] neg_lo:[0,1]
	v_pk_add_f32 v[88:89], v[66:67], v[74:75]
	v_pk_add_f32 v[66:67], v[66:67], v[74:75] neg_lo:[0,1] neg_hi:[0,1]
	v_pk_fma_f32 v[84:85], v[84:85], s[66:67], v[92:93] op_sel:[0,0,1] op_sel_hi:[1,0,0] neg_lo:[1,0,0] neg_hi:[1,0,0]
	v_pk_mul_f32 v[74:75], v[66:67], s[36:37]
	v_pk_fma_f32 v[66:67], v[66:67], s[66:67], v[74:75] op_sel:[0,0,1] op_sel_hi:[1,0,0]
	v_pk_add_f32 v[74:75], v[68:69], v[80:81]
	v_pk_add_f32 v[92:93], v[70:71], v[82:83]
	v_pk_add_f32 v[70:71], v[70:71], v[82:83] neg_lo:[0,1] neg_hi:[0,1]
	v_pk_add_f32 v[78:79], v[86:87], v[90:91] op_sel:[0,1] op_sel_hi:[1,0] neg_hi:[0,1]
	v_pk_add_f32 v[86:87], v[86:87], v[90:91] op_sel:[0,1] op_sel_hi:[1,0] neg_lo:[0,1]
	v_pk_add_f32 v[90:91], v[76:77], v[84:85]
	v_pk_add_f32 v[84:85], v[76:77], v[84:85] neg_lo:[0,1] neg_hi:[0,1]
	v_pk_add_f32 v[80:81], v[68:69], v[80:81] neg_lo:[0,1] neg_hi:[0,1]
	v_pk_mul_f32 v[82:83], v[70:71], s[36:37]
	v_pk_add_f32 v[102:103], v[72:73], v[74:75]
	v_pk_add_f32 v[72:73], v[72:73], v[74:75] neg_lo:[0,1] neg_hi:[0,1]
	v_pk_add_f32 v[74:75], v[88:89], v[92:93]
	v_pk_fma_f32 v[70:71], v[70:71], s[66:67], v[82:83] op_sel:[0,0,1] op_sel_hi:[1,0,0] neg_lo:[1,0,0] neg_hi:[1,0,0]
	v_pk_add_f32 v[82:83], v[94:95], v[98:99]
	v_pk_add_f32 v[94:95], v[94:95], v[98:99] neg_lo:[0,1] neg_hi:[0,1]
	v_pk_add_f32 v[98:99], v[96:97], v[100:101]
	v_pk_add_f32 v[76:77], v[86:87], v[84:85] op_sel:[0,1] op_sel_hi:[1,0] neg_hi:[0,1]
	v_pk_add_f32 v[84:85], v[86:87], v[84:85] op_sel:[0,1] op_sel_hi:[1,0] neg_lo:[0,1]
	v_pk_add_f32 v[86:87], v[102:103], v[74:75]
	v_pk_add_f32 v[100:101], v[96:97], v[100:101] neg_lo:[0,1] neg_hi:[0,1]
	v_pk_add_f32 v[68:69], v[64:65], v[80:81] op_sel:[0,1] op_sel_hi:[1,0] neg_hi:[0,1]
	v_pk_add_f32 v[64:65], v[64:65], v[80:81] op_sel:[0,1] op_sel_hi:[1,0] neg_lo:[0,1]
	v_pk_add_f32 v[80:81], v[66:67], v[70:71]
	v_pk_add_f32 v[104:105], v[82:83], v[98:99]
	v_pk_add_f32 v[82:83], v[82:83], v[98:99] neg_lo:[0,1] neg_hi:[0,1]
	v_pk_add_f32 v[98:99], v[78:79], v[90:91]
	v_pk_mul_f32 v[2:3], v[2:3], v[86:87] op_sel:[0,1] op_sel_hi:[1,0]
	v_pk_add_f32 v[92:93], v[88:89], v[92:93] neg_lo:[0,1] neg_hi:[0,1]
	v_pk_add_f32 v[78:79], v[78:79], v[90:91] neg_lo:[0,1] neg_hi:[0,1]
	v_pk_add_f32 v[90:91], v[68:69], v[80:81]
	v_pk_fma_f32 v[2:3], v[4:5], v[86:87], v[2:3] op_sel_hi:[0,1,1]
	v_pk_mul_f32 v[4:5], v[12:13], v[98:99] op_sel:[0,1] op_sel_hi:[1,0]
	v_pk_add_f32 v[70:71], v[66:67], v[70:71] neg_lo:[0,1] neg_hi:[0,1]
	v_pk_add_f32 v[96:97], v[94:95], v[100:101] op_sel:[0,1] op_sel_hi:[1,0] neg_hi:[0,1]
	v_pk_fma_f32 v[4:5], v[6:7], v[98:99], v[4:5] op_sel_hi:[0,1,1]
	v_pk_mul_f32 v[6:7], v[20:21], v[90:91] op_sel:[0,1] op_sel_hi:[1,0]
	v_pk_add_f32 v[88:89], v[72:73], v[92:93] op_sel:[0,1] op_sel_hi:[1,0] neg_hi:[0,1]
	v_pk_fma_f32 v[6:7], v[8:9], v[90:91], v[6:7] op_sel_hi:[0,1,1]
	v_pk_mul_f32 v[8:9], v[14:15], v[96:97] op_sel:[0,1] op_sel_hi:[1,0]
	v_pk_add_f32 v[66:67], v[64:65], v[70:71] op_sel:[0,1] op_sel_hi:[1,0] neg_hi:[0,1]
	v_pk_fma_f32 v[8:9], v[10:11], v[96:97], v[8:9] op_sel_hi:[0,1,1]
	v_pk_mul_f32 v[10:11], v[22:23], v[88:89] op_sel:[0,1] op_sel_hi:[1,0]
	v_pk_add_f32 v[94:95], v[94:95], v[100:101] op_sel:[0,1] op_sel_hi:[1,0] neg_lo:[0,1]
	v_pk_add_f32 v[74:75], v[102:103], v[74:75] neg_lo:[0,1] neg_hi:[0,1]
	v_pk_add_f32 v[72:73], v[72:73], v[92:93] op_sel:[0,1] op_sel_hi:[1,0] neg_lo:[0,1]
	v_pk_add_f32 v[68:69], v[68:69], v[80:81] neg_lo:[0,1] neg_hi:[0,1]
	v_pk_add_f32 v[64:65], v[64:65], v[70:71] op_sel:[0,1] op_sel_hi:[1,0] neg_lo:[0,1]
	v_pk_fma_f32 v[10:11], v[16:17], v[88:89], v[10:11] op_sel_hi:[0,1,1]
	v_pk_mul_f32 v[12:13], v[26:27], v[76:77] op_sel:[0,1] op_sel_hi:[1,0]
	v_pk_mul_f32 v[14:15], v[30:31], v[66:67] op_sel:[0,1] op_sel_hi:[1,0]
	v_pk_mul_f32 v[16:17], v[34:35], v[82:83] op_sel:[0,1] op_sel_hi:[1,0]
	v_pk_fma_f32 v[12:13], v[24:25], v[76:77], v[12:13] op_sel_hi:[0,1,1]
	v_pk_fma_f32 v[14:15], v[28:29], v[66:67], v[14:15] op_sel_hi:[0,1,1]
	v_pk_fma_f32 v[16:17], v[32:33], v[82:83], v[16:17] op_sel_hi:[0,1,1]
	v_pk_mul_f32 v[20:21], v[38:39], v[74:75] op_sel:[0,1] op_sel_hi:[1,0]
	v_pk_mul_f32 v[22:23], v[42:43], v[78:79] op_sel:[0,1] op_sel_hi:[1,0]
	v_pk_mul_f32 v[24:25], v[46:47], v[68:69] op_sel:[0,1] op_sel_hi:[1,0]
	v_pk_mul_f32 v[26:27], v[50:51], v[94:95] op_sel:[0,1] op_sel_hi:[1,0]
	v_pk_mul_f32 v[28:29], v[54:55], v[72:73] op_sel:[0,1] op_sel_hi:[1,0]
	v_pk_mul_f32 v[30:31], v[58:59], v[84:85] op_sel:[0,1] op_sel_hi:[1,0]
	v_pk_mul_f32 v[32:33], v[62:63], v[64:65] op_sel:[0,1] op_sel_hi:[1,0]
	v_pk_fma_f32 v[20:21], v[36:37], v[74:75], v[20:21] op_sel_hi:[0,1,1]
	v_pk_fma_f32 v[22:23], v[40:41], v[78:79], v[22:23] op_sel_hi:[0,1,1]
	v_pk_fma_f32 v[24:25], v[44:45], v[68:69], v[24:25] op_sel_hi:[0,1,1]
	v_pk_fma_f32 v[26:27], v[48:49], v[94:95], v[26:27] op_sel_hi:[0,1,1]
	v_pk_fma_f32 v[28:29], v[52:53], v[72:73], v[28:29] op_sel_hi:[0,1,1]
	v_pk_fma_f32 v[30:31], v[56:57], v[84:85], v[30:31] op_sel_hi:[0,1,1]
	v_pk_fma_f32 v[32:33], v[60:61], v[64:65], v[32:33] op_sel_hi:[0,1,1]
	ds_write2_b64 v18, v[104:105], v[16:17] offset1:16
	ds_write2_b64 v18, v[8:9], v[26:27] offset0:33 offset1:49
	ds_write2_b64 v18, v[4:5], v[22:23] offset0:66 offset1:82
	ds_write2_b64 v18, v[12:13], v[30:31] offset0:99 offset1:115
	ds_write2_b64 v18, v[2:3], v[20:21] offset0:132 offset1:148
	ds_write2_b64 v18, v[10:11], v[28:29] offset0:165 offset1:181
	ds_write2_b64 v18, v[6:7], v[24:25] offset0:198 offset1:214
	ds_write2_b64 v18, v[14:15], v[32:33] offset0:231 offset1:247
	v_ashrrev_i32_e32 v2, 31, v210
	v_add_u32_sdwa v2, v210, v2 dst_sel:DWORD dst_unused:UNUSED_PAD src0_sel:DWORD src1_sel:BYTE_3
	s_lshl_b64 s[0:1], s[64:65], 15
	v_and_b32_e32 v2, 0xffffff00, v2
	s_add_u32 s0, s29, s0
	v_sub_u32_e32 v2, v210, v2
	s_addc_u32 s1, s85, s1
	v_ashrrev_i32_e32 v3, 31, v2
	v_lshl_add_u64 v[14:15], v[2:3], 3, s[0:1]
	s_movk_i32 s0, 0x1000
	v_add_co_u32_e32 v16, vcc, s0, v14
	s_movk_i32 s0, 0x3000
	s_nop 0
	v_addc_co_u32_e32 v17, vcc, 0, v15, vcc
	v_add_co_u32_e32 v2, vcc, s92, v14
	s_waitcnt lgkmcnt(0)
	s_nop 0
	v_addc_co_u32_e32 v3, vcc, 0, v15, vcc
	v_add_co_u32_e32 v22, vcc, s0, v14
	s_movk_i32 s0, 0x5000
	s_nop 0
	v_addc_co_u32_e32 v23, vcc, 0, v15, vcc
	v_add_co_u32_e32 v8, vcc, s95, v14
	s_barrier
	s_nop 0
	v_addc_co_u32_e32 v9, vcc, 0, v15, vcc
	v_add_co_u32_e32 v26, vcc, s0, v14
	s_nop 1
	v_addc_co_u32_e32 v27, vcc, 0, v15, vcc
	v_add_co_u32_e32 v10, vcc, s96, v14
	global_load_dwordx2 v[12:13], v[2:3], off nt
	global_load_dwordx2 v[6:7], v[2:3], off offset:2048 nt
	global_load_dwordx2 v[4:5], v[8:9], off offset:-4096 nt
	global_load_dwordx2 v[122:123], v[8:9], off nt
	v_addc_co_u32_e32 v11, vcc, 0, v15, vcc
	v_add_co_u32_e32 v28, vcc, s97, v14
	global_load_dwordx2 v[46:47], v[8:9], off offset:2048 nt
	global_load_dwordx2 v[38:39], v[10:11], off offset:-4096 nt
	global_load_dwordx2 v[20:21], v[10:11], off nt
	s_nop 0
	global_load_dwordx2 v[10:11], v[10:11], off offset:2048 nt
	v_addc_co_u32_e32 v29, vcc, 0, v15, vcc
	global_load_dwordx2 v[24:25], v[2:3], off offset:-4096 nt
	s_nop 0
	global_load_dwordx2 v[26:27], v[26:27], off offset:2048 nt
	s_nop 0
	global_load_dwordx2 v[8:9], v[28:29], off nt
	global_load_dwordx2 v[2:3], v[28:29], off offset:2048 nt
	global_load_dwordx2 v[30:31], v[14:15], off offset:2048 nt
	s_nop 0
	global_load_dwordx2 v[28:29], v[16:17], off offset:2048 nt
	s_nop 0
	global_load_dwordx2 v[16:17], v[22:23], off offset:2048 nt
	global_load_dwordx2 v[32:33], v[14:15], off nt
	v_mov_b32_e32 v14, v210
	s_waitcnt vmcnt(15)
	v_cvt_f32_f16_sdwa v164, v12 dst_sel:DWORD dst_unused:UNUSED_PAD src0_sel:WORD_1
	v_ashrrev_i32_e32 v15, 31, v14
	v_add_u32_sdwa v15, v14, v15 dst_sel:DWORD dst_unused:UNUSED_PAD src0_sel:DWORD src1_sel:BYTE_3
	v_ashrrev_i32_e32 v15, 8, v15
	v_mul_i32_i24_e32 v18, 0x100, v15
	v_sub_u32_e32 v18, v14, v18
	v_lshlrev_b32_e32 v14, 13, v15
	v_lshlrev_b32_e32 v15, 1, v18
	v_bfrev_b32_e32 v15, v15
	v_lshrrev_b32_e32 v15, 23, v15
	v_sub_u32_e32 v15, 0x200, v15
	v_bfrev_b32_e32 v15, v15
	v_lshrrev_b32_e32 v15, 19, v15
	v_and_b32_e32 v15, 0x1ff0, v15
	v_cmp_eq_u32_e64 s[0:1], 0, v18
	v_lshl_add_u32 v22, v18, 5, v14
	v_lshl_add_u32 v23, v22, 3, 0
	v_cndmask_b32_e64 v15, v15, 16, s[0:1]
	v_or_b32_e32 v14, v15, v14
	v_ashrrev_i32_e32 v22, 2, v22
	v_ashrrev_i32_e32 v15, 5, v14
	v_add_u32_e32 v211, v23, v22
	v_lshlrev_b32_e32 v14, 3, v14
	v_lshlrev_b32_e32 v15, 3, v15
	v_add3_u32 v212, 0, v14, v15
	ds_read2_b64 v[34:37], v211 offset1:1
	ds_read2_b64 v[40:43], v211 offset0:2 offset1:3
	ds_read2_b64 v[48:51], v212 offset1:1
	ds_read2_b64 v[52:55], v212 offset0:2 offset1:3
	ds_read2_b64 v[56:59], v211 offset0:4 offset1:5
	ds_read2_b64 v[60:63], v211 offset0:6 offset1:7
	ds_read2_b64 v[68:71], v212 offset0:4 offset1:5
	ds_read2_b64 v[72:75], v212 offset0:6 offset1:7
	ds_read2_b64 v[64:67], v211 offset0:8 offset1:9
	ds_read2_b64 v[76:79], v211 offset0:10 offset1:11
	ds_read2_b64 v[80:83], v212 offset0:8 offset1:9
	ds_read2_b64 v[98:101], v212 offset0:10 offset1:11
	ds_read2_b64 v[84:87], v211 offset0:12 offset1:13
	ds_read2_b64 v[88:91], v211 offset0:14 offset1:15
	ds_read2_b64 v[102:105], v212 offset0:12 offset1:13
	ds_read2_b64 v[106:109], v212 offset0:14 offset1:15
	s_waitcnt lgkmcnt(7)
	v_pk_add_f32 v[14:15], v[34:35], v[64:65]
	v_pk_add_f32 v[22:23], v[34:35], v[64:65] neg_lo:[0,1] neg_hi:[0,1]
	v_pk_add_f32 v[34:35], v[36:37], v[66:67]
	v_pk_add_f32 v[36:37], v[36:37], v[66:67] neg_lo:[0,1] neg_hi:[0,1]
	v_cmp_ne_u32_e32 vcc, 0, v18
	v_pk_mul_f32 v[44:45], v[36:37], s[18:19]
	v_bfrev_b32_e32 v18, v18
	v_pk_fma_f32 v[36:37], v[36:37], s[16:17], v[44:45] op_sel:[0,0,1] op_sel_hi:[1,0,0]
	s_waitcnt lgkmcnt(6)
	v_pk_add_f32 v[44:45], v[40:41], v[76:77]
	v_pk_add_f32 v[40:41], v[40:41], v[76:77] neg_lo:[0,1] neg_hi:[0,1]
	v_cvt_f32_ubyte3_e32 v18, v18
	v_pk_mul_f32 v[64:65], v[40:41], s[36:37]
	v_mul_f32_e32 v18, 0x38800000, v18
	v_pk_fma_f32 v[40:41], v[40:41], s[66:67], v[64:65] op_sel:[0,0,1] op_sel_hi:[1,0,0]
	v_pk_add_f32 v[64:65], v[42:43], v[78:79]
	v_pk_add_f32 v[42:43], v[42:43], v[78:79] neg_lo:[0,1] neg_hi:[0,1]
	s_waitcnt lgkmcnt(3)
	v_pk_add_f32 v[78:79], v[58:59], v[86:87]
	v_pk_mul_f32 v[66:67], v[42:43], s[40:41]
	v_pk_add_f32 v[58:59], v[58:59], v[86:87] neg_lo:[0,1] neg_hi:[0,1]
	v_pk_fma_f32 v[42:43], v[42:43], s[68:69], v[66:67] op_sel:[0,0,1] op_sel_hi:[1,0,0]
	v_pk_add_f32 v[66:67], v[56:57], v[84:85]
	v_pk_add_f32 v[76:77], v[56:57], v[84:85] neg_lo:[0,1] neg_hi:[0,1]
	v_pk_mul_f32 v[84:85], v[58:59], s[40:41]
	v_pk_fma_f32 v[58:59], v[58:59], s[68:69], v[84:85] op_sel:[0,0,1] op_sel_hi:[1,0,0] neg_lo:[1,0,0] neg_hi:[1,0,0]
	s_waitcnt lgkmcnt(2)
	v_pk_add_f32 v[84:85], v[60:61], v[88:89]
	v_pk_add_f32 v[60:61], v[60:61], v[88:89] neg_lo:[0,1] neg_hi:[0,1]
	v_pk_mul_f32 v[86:87], v[60:61], s[36:37]
	v_pk_add_f32 v[56:57], v[22:23], v[76:77] op_sel:[0,1] op_sel_hi:[1,0] neg_hi:[0,1]
	v_pk_fma_f32 v[60:61], v[60:61], s[66:67], v[86:87] op_sel:[0,0,1] op_sel_hi:[1,0,0] neg_lo:[1,0,0] neg_hi:[1,0,0]
	v_pk_add_f32 v[86:87], v[62:63], v[90:91]
	v_pk_add_f32 v[62:63], v[62:63], v[90:91] neg_lo:[0,1] neg_hi:[0,1]
	v_pk_add_f32 v[90:91], v[64:65], v[86:87]
	v_pk_mul_f32 v[88:89], v[62:63], s[18:19]
	v_pk_add_f32 v[64:65], v[64:65], v[86:87] neg_lo:[0,1] neg_hi:[0,1]
	v_pk_fma_f32 v[62:63], v[62:63], s[16:17], v[88:89] op_sel:[0,0,1] op_sel_hi:[1,0,0] neg_lo:[1,0,0] neg_hi:[1,0,0]
	v_pk_add_f32 v[88:89], v[14:15], v[66:67]
	v_pk_add_f32 v[14:15], v[14:15], v[66:67] neg_lo:[0,1] neg_hi:[0,1]
	v_pk_add_f32 v[66:67], v[34:35], v[78:79]
	v_pk_add_f32 v[34:35], v[34:35], v[78:79] neg_lo:[0,1] neg_hi:[0,1]
	v_pk_add_f32 v[22:23], v[22:23], v[76:77] op_sel:[0,1] op_sel_hi:[1,0] neg_lo:[0,1]
	v_pk_mul_f32 v[78:79], v[34:35], s[36:37]
	v_pk_add_f32 v[76:77], v[36:37], v[58:59]
	v_pk_add_f32 v[36:37], v[36:37], v[58:59] neg_lo:[0,1] neg_hi:[0,1]
	v_pk_fma_f32 v[34:35], v[34:35], s[66:67], v[78:79] op_sel:[0,0,1] op_sel_hi:[1,0,0]
	v_pk_add_f32 v[78:79], v[44:45], v[84:85]
	v_pk_add_f32 v[84:85], v[44:45], v[84:85] neg_lo:[0,1] neg_hi:[0,1]
	v_pk_mul_f32 v[86:87], v[64:65], s[36:37]
	v_pk_mul_f32 v[58:59], v[36:37], s[36:37]
	v_pk_fma_f32 v[64:65], v[64:65], s[66:67], v[86:87] op_sel:[0,0,1] op_sel_hi:[1,0,0] neg_lo:[1,0,0] neg_hi:[1,0,0]
	v_pk_fma_f32 v[36:37], v[36:37], s[66:67], v[58:59] op_sel:[0,0,1] op_sel_hi:[1,0,0]
	v_pk_add_f32 v[58:59], v[40:41], v[60:61]
	v_pk_add_f32 v[86:87], v[42:43], v[62:63]
	v_pk_add_f32 v[42:43], v[42:43], v[62:63] neg_lo:[0,1] neg_hi:[0,1]
	v_pk_mul_f32 v[62:63], v[42:43], s[36:37]
	v_pk_add_f32 v[44:45], v[14:15], v[84:85] op_sel:[0,1] op_sel_hi:[1,0] neg_hi:[0,1]
	v_pk_add_f32 v[14:15], v[14:15], v[84:85] op_sel:[0,1] op_sel_hi:[1,0] neg_lo:[0,1]
	v_pk_add_f32 v[84:85], v[34:35], v[64:65]
	v_pk_add_f32 v[64:65], v[34:35], v[64:65] neg_lo:[0,1] neg_hi:[0,1]
	v_pk_add_f32 v[94:95], v[56:57], v[58:59]
	v_pk_add_f32 v[56:57], v[56:57], v[58:59] neg_lo:[0,1] neg_hi:[0,1]
	v_pk_add_f32 v[58:59], v[76:77], v[86:87]
	v_pk_fma_f32 v[42:43], v[42:43], s[66:67], v[62:63] op_sel:[0,0,1] op_sel_hi:[1,0,0] neg_lo:[1,0,0] neg_hi:[1,0,0]
	v_pk_add_f32 v[62:63], v[88:89], v[78:79]
	v_pk_add_f32 v[78:79], v[88:89], v[78:79] neg_lo:[0,1] neg_hi:[0,1]
	v_pk_add_f32 v[88:89], v[66:67], v[90:91]
	v_pk_add_f32 v[110:111], v[76:77], v[86:87] neg_lo:[0,1] neg_hi:[0,1]
	v_pk_add_f32 v[86:87], v[94:95], v[58:59]
	v_pk_add_f32 v[34:35], v[94:95], v[58:59] neg_lo:[0,1] neg_hi:[0,1]
	v_pk_add_f32 v[58:59], v[50:51], v[82:83]
	v_pk_add_f32 v[50:51], v[50:51], v[82:83] neg_lo:[0,1] neg_hi:[0,1]
	v_pk_add_f32 v[60:61], v[40:41], v[60:61] neg_lo:[0,1] neg_hi:[0,1]
	v_pk_add_f32 v[148:149], v[62:63], v[88:89]
	v_pk_add_f32 v[138:139], v[62:63], v[88:89] neg_lo:[0,1] neg_hi:[0,1]
	v_pk_mul_f32 v[62:63], v[50:51], s[18:19]
	v_pk_add_f32 v[90:91], v[66:67], v[90:91] neg_lo:[0,1] neg_hi:[0,1]
	v_pk_fma_f32 v[50:51], v[50:51], s[16:17], v[62:63] op_sel:[0,0,1] op_sel_hi:[1,0,0]
	v_pk_add_f32 v[62:63], v[52:53], v[98:99]
	v_pk_add_f32 v[52:53], v[52:53], v[98:99] neg_lo:[0,1] neg_hi:[0,1]
	v_pk_add_f32 v[112:113], v[22:23], v[60:61] op_sel:[0,1] op_sel_hi:[1,0] neg_hi:[0,1]
	v_pk_add_f32 v[114:115], v[22:23], v[60:61] op_sel:[0,1] op_sel_hi:[1,0] neg_lo:[0,1]
	v_pk_add_f32 v[96:97], v[44:45], v[84:85]
	v_pk_add_f32 v[66:67], v[44:45], v[84:85] neg_lo:[0,1] neg_hi:[0,1]
	v_pk_add_f32 v[60:61], v[14:15], v[64:65] op_sel:[0,1] op_sel_hi:[1,0] neg_hi:[0,1]
	v_pk_add_f32 v[84:85], v[14:15], v[64:65] op_sel:[0,1] op_sel_hi:[1,0] neg_lo:[0,1]
	v_pk_mul_f32 v[64:65], v[52:53], s[36:37]
	v_pk_fma_f32 v[52:53], v[52:53], s[66:67], v[64:65] op_sel:[0,0,1] op_sel_hi:[1,0,0]
	v_pk_add_f32 v[64:65], v[54:55], v[100:101]
	v_pk_add_f32 v[54:55], v[54:55], v[100:101] neg_lo:[0,1] neg_hi:[0,1]
	v_pk_mul_f32 v[76:77], v[54:55], s[40:41]
	v_pk_add_f32 v[92:93], v[78:79], v[90:91] op_sel:[0,1] op_sel_hi:[1,0] neg_hi:[0,1]
	v_pk_fma_f32 v[54:55], v[54:55], s[68:69], v[76:77] op_sel:[0,0,1] op_sel_hi:[1,0,0]
	s_waitcnt lgkmcnt(1)
	v_pk_add_f32 v[76:77], v[68:69], v[102:103]
	v_pk_add_f32 v[68:69], v[68:69], v[102:103] neg_lo:[0,1] neg_hi:[0,1]
	v_pk_add_f32 v[88:89], v[78:79], v[90:91] op_sel:[0,1] op_sel_hi:[1,0] neg_lo:[0,1]
	v_xor_b32_e32 v79, 0x80000000, v68
	v_mov_b32_e32 v78, v69
	v_pk_add_f32 v[68:69], v[70:71], v[104:105]
	v_pk_add_f32 v[70:71], v[70:71], v[104:105] neg_lo:[0,1] neg_hi:[0,1]
	v_pk_add_f32 v[40:41], v[56:57], v[110:111] op_sel:[0,1] op_sel_hi:[1,0] neg_hi:[0,1]
	v_pk_add_f32 v[44:45], v[56:57], v[110:111] op_sel:[0,1] op_sel_hi:[1,0] neg_lo:[0,1]
	v_pk_add_f32 v[56:57], v[48:49], v[80:81]
	v_pk_add_f32 v[48:49], v[48:49], v[80:81] neg_lo:[0,1] neg_hi:[0,1]
	v_pk_mul_f32 v[80:81], v[70:71], s[40:41]
	v_cndmask_b32_e64 v18, v18, v208, s[0:1]
	v_pk_fma_f32 v[70:71], v[70:71], s[68:69], v[80:81] op_sel:[0,0,1] op_sel_hi:[1,0,0] neg_lo:[1,0,0] neg_hi:[1,0,0]
	s_waitcnt lgkmcnt(0)
	v_pk_add_f32 v[80:81], v[72:73], v[106:107]
	v_pk_add_f32 v[72:73], v[72:73], v[106:107] neg_lo:[0,1] neg_hi:[0,1]
	v_pk_add_f32 v[22:23], v[36:37], v[42:43]
	v_pk_mul_f32 v[82:83], v[72:73], s[36:37]
	v_pk_add_f32 v[116:117], v[36:37], v[42:43] neg_lo:[0,1] neg_hi:[0,1]
	v_pk_fma_f32 v[72:73], v[72:73], s[66:67], v[82:83] op_sel:[0,0,1] op_sel_hi:[1,0,0] neg_lo:[1,0,0] neg_hi:[1,0,0]
	v_pk_add_f32 v[82:83], v[74:75], v[108:109]
	v_pk_add_f32 v[74:75], v[74:75], v[108:109] neg_lo:[0,1] neg_hi:[0,1]
	v_pk_mul_f32 v[90:91], v[74:75], s[18:19]
	v_pk_fma_f32 v[74:75], v[74:75], s[16:17], v[90:91] op_sel:[0,0,1] op_sel_hi:[1,0,0] neg_lo:[1,0,0] neg_hi:[1,0,0]
	v_pk_add_f32 v[90:91], v[56:57], v[76:77]
	v_pk_add_f32 v[56:57], v[56:57], v[76:77] neg_lo:[0,1] neg_hi:[0,1]
	v_pk_add_f32 v[76:77], v[58:59], v[68:69]
	v_pk_add_f32 v[58:59], v[58:59], v[68:69] neg_lo:[0,1] neg_hi:[0,1]
	v_pk_add_f32 v[14:15], v[114:115], v[116:117] op_sel:[0,1] op_sel_hi:[1,0] neg_hi:[0,1]
	v_pk_mul_f32 v[68:69], v[58:59], s[36:37]
	v_pk_add_f32 v[36:37], v[114:115], v[116:117] op_sel:[0,1] op_sel_hi:[1,0] neg_lo:[0,1]
	v_pk_fma_f32 v[58:59], v[58:59], s[66:67], v[68:69] op_sel:[0,0,1] op_sel_hi:[1,0,0]
	v_pk_add_f32 v[68:69], v[62:63], v[80:81]
	v_pk_add_f32 v[80:81], v[62:63], v[80:81] neg_lo:[0,1] neg_hi:[0,1]
	s_waitcnt vmcnt(0)
	v_cvt_f32_f16_e32 v193, v33
	s_nop 0
	s_nop 0
	v_pk_add_f32 v[62:63], v[64:65], v[82:83]
	v_pk_add_f32 v[64:65], v[64:65], v[82:83] neg_lo:[0,1] neg_hi:[0,1]
	v_cvt_f32_f16_sdwa v192, v32 dst_sel:DWORD dst_unused:UNUSED_PAD src0_sel:WORD_1
	v_pk_mul_f32 v[82:83], v[64:65], s[36:37]
	v_cvt_f32_f16_e32 v194, v32
	v_pk_fma_f32 v[64:65], v[64:65], s[66:67], v[82:83] op_sel:[0,0,1] op_sel_hi:[1,0,0] neg_lo:[1,0,0] neg_hi:[1,0,0]
	v_pk_add_f32 v[82:83], v[48:49], v[78:79]
	v_pk_add_f32 v[48:49], v[48:49], v[78:79] neg_lo:[0,1] neg_hi:[0,1]
	v_pk_add_f32 v[78:79], v[50:51], v[70:71]
	v_pk_add_f32 v[50:51], v[50:51], v[70:71] neg_lo:[0,1] neg_hi:[0,1]
	v_cvt_f32_f16_sdwa v195, v33 dst_sel:DWORD dst_unused:UNUSED_PAD src0_sel:WORD_1
	v_pk_mul_f32 v[70:71], v[50:51], s[36:37]
	v_cvt_f32_f16_sdwa v170, v30 dst_sel:DWORD dst_unused:UNUSED_PAD src0_sel:WORD_1
	v_pk_fma_f32 v[50:51], v[50:51], s[66:67], v[70:71] op_sel:[0,0,1] op_sel_hi:[1,0,0]
	v_pk_add_f32 v[70:71], v[52:53], v[72:73]
	v_pk_add_f32 v[72:73], v[52:53], v[72:73] neg_lo:[0,1] neg_hi:[0,1]
	v_cvt_f32_f16_e32 v171, v31
	s_nop 0
	s_nop 0
	v_pk_add_f32 v[52:53], v[54:55], v[74:75]
	v_pk_add_f32 v[54:55], v[54:55], v[74:75] neg_lo:[0,1] neg_hi:[0,1]
	v_cvt_f32_f16_sdwa v185, v31 dst_sel:DWORD dst_unused:UNUSED_PAD src0_sel:WORD_1
	v_pk_mul_f32 v[74:75], v[54:55], s[36:37]
	v_cvt_f32_f16_e32 v184, v30
	v_pk_fma_f32 v[54:55], v[54:55], s[66:67], v[74:75] op_sel:[0,0,1] op_sel_hi:[1,0,0] neg_lo:[1,0,0] neg_hi:[1,0,0]
	v_pk_add_f32 v[74:75], v[90:91], v[68:69]
	v_pk_add_f32 v[68:69], v[90:91], v[68:69] neg_lo:[0,1] neg_hi:[0,1]
	v_pk_add_f32 v[90:91], v[76:77], v[62:63]
	v_pk_add_f32 v[62:63], v[76:77], v[62:63] neg_lo:[0,1] neg_hi:[0,1]
	v_cvt_f32_f16_sdwa v172, v24 dst_sel:DWORD dst_unused:UNUSED_PAD src0_sel:WORD_1
	v_xor_b32_e32 v77, 0x80000000, v62
	v_mov_b32_e32 v76, v63
	v_pk_add_f32 v[62:63], v[56:57], v[80:81] op_sel:[0,1] op_sel_hi:[1,0] neg_hi:[0,1]
	v_pk_add_f32 v[56:57], v[56:57], v[80:81] op_sel:[0,1] op_sel_hi:[1,0] neg_lo:[0,1]
	v_pk_add_f32 v[80:81], v[58:59], v[64:65]
	v_pk_add_f32 v[58:59], v[58:59], v[64:65] neg_lo:[0,1] neg_hi:[0,1]
	v_cvt_f32_f16_e32 v173, v25
	v_xor_b32_e32 v65, 0x80000000, v58
	v_mov_b32_e32 v64, v59
	v_pk_add_f32 v[58:59], v[82:83], v[70:71]
	v_pk_add_f32 v[70:71], v[82:83], v[70:71] neg_lo:[0,1] neg_hi:[0,1]
	v_pk_add_f32 v[82:83], v[78:79], v[52:53]
	v_pk_add_f32 v[52:53], v[78:79], v[52:53] neg_lo:[0,1] neg_hi:[0,1]
	v_pk_add_f32 v[118:119], v[58:59], v[82:83]
	v_pk_add_f32 v[134:135], v[58:59], v[82:83] neg_lo:[0,1] neg_hi:[0,1]
	v_cos_f32_e32 v83, v18
	v_sin_f32_e32 v82, v18
	v_cvt_f32_f16_sdwa v181, v25 dst_sel:DWORD dst_unused:UNUSED_PAD src0_sel:WORD_1
	v_cvt_f32_f16_e32 v180, v24
	v_cvt_f32_f16_sdwa v174, v28 dst_sel:DWORD dst_unused:UNUSED_PAD src0_sel:WORD_1
	v_cvt_f32_f16_e32 v175, v29
	v_cvt_f32_f16_sdwa v179, v29 dst_sel:DWORD dst_unused:UNUSED_PAD src0_sel:WORD_1
	v_cvt_f32_f16_e32 v178, v28
	v_cvt_f32_f16_e32 v165, v13
	v_cvt_f32_f16_sdwa v167, v13 dst_sel:DWORD dst_unused:UNUSED_PAD src0_sel:WORD_1
	v_cvt_f32_f16_e32 v166, v12
	v_cvt_f32_f16_e32 v154, v6
	v_cvt_f32_f16_e32 v155, v7
	v_cvt_f32_f16_sdwa v157, v7 dst_sel:DWORD dst_unused:UNUSED_PAD src0_sel:WORD_1
	v_cvt_f32_f16_sdwa v156, v6 dst_sel:DWORD dst_unused:UNUSED_PAD src0_sel:WORD_1
	v_cvt_f32_f16_sdwa v140, v4 dst_sel:DWORD dst_unused:UNUSED_PAD src0_sel:WORD_1
	v_cvt_f32_f16_e32 v141, v5
	v_cvt_f32_f16_sdwa v143, v5 dst_sel:DWORD dst_unused:UNUSED_PAD src0_sel:WORD_1
	v_cvt_f32_f16_e32 v142, v4
	v_cvt_f32_f16_e32 v124, v16
	v_cvt_f32_f16_e32 v125, v17
	v_cvt_f32_f16_sdwa v127, v17 dst_sel:DWORD dst_unused:UNUSED_PAD src0_sel:WORD_1
	v_cvt_f32_f16_sdwa v126, v16 dst_sel:DWORD dst_unused:UNUSED_PAD src0_sel:WORD_1
	v_cvt_f32_f16_sdwa v114, v122 dst_sel:DWORD dst_unused:UNUSED_PAD src0_sel:WORD_1
	v_cvt_f32_f16_e32 v115, v123
	v_cvt_f32_f16_sdwa v117, v123 dst_sel:DWORD dst_unused:UNUSED_PAD src0_sel:WORD_1
	v_cvt_f32_f16_e32 v116, v122
	v_xor_b32_e32 v79, 0x80000000, v52
	v_mov_b32_e32 v78, v53
	v_pk_add_f32 v[52:53], v[48:49], v[72:73] op_sel:[0,1] op_sel_hi:[1,0] neg_hi:[0,1]
	v_pk_add_f32 v[48:49], v[48:49], v[72:73] op_sel:[0,1] op_sel_hi:[1,0] neg_lo:[0,1]
	v_pk_add_f32 v[72:73], v[50:51], v[54:55]
	v_pk_add_f32 v[50:51], v[50:51], v[54:55] neg_lo:[0,1] neg_hi:[0,1]
	v_pk_fma_f32 v[160:161], v[82:83], 0, v[82:83] op_sel:[0,0,1] op_sel_hi:[1,0,0] neg_lo:[1,0,0] neg_hi:[1,0,0]
	v_xor_b32_e32 v55, 0x80000000, v50
	v_mov_b32_e32 v54, v51
	v_pk_fma_f32 v[198:199], v[82:83], 0, v[82:83] op_sel:[0,0,1] op_sel_hi:[1,0,0]
	v_pk_add_f32 v[42:43], v[112:113], v[22:23]
	v_pk_add_f32 v[22:23], v[112:113], v[22:23] neg_lo:[0,1] neg_hi:[0,1]
	v_pk_add_f32 v[98:99], v[74:75], v[90:91]
	v_pk_add_f32 v[100:101], v[74:75], v[90:91] neg_lo:[0,1] neg_hi:[0,1]
	v_pk_add_f32 v[102:103], v[68:69], v[76:77]
	v_pk_add_f32 v[106:107], v[68:69], v[76:77] neg_lo:[0,1] neg_hi:[0,1]
	v_pk_add_f32 v[104:105], v[62:63], v[80:81]
	v_pk_add_f32 v[108:109], v[62:63], v[80:81] neg_lo:[0,1] neg_hi:[0,1]
	v_pk_add_f32 v[110:111], v[56:57], v[64:65]
	v_pk_add_f32 v[112:113], v[56:57], v[64:65] neg_lo:[0,1] neg_hi:[0,1]
	v_pk_add_f32 v[152:153], v[70:71], v[78:79]
	v_pk_add_f32 v[162:163], v[70:71], v[78:79] neg_lo:[0,1] neg_hi:[0,1]
	v_pk_add_f32 v[176:177], v[52:53], v[72:73]
	v_pk_add_f32 v[182:183], v[52:53], v[72:73] neg_lo:[0,1] neg_hi:[0,1]
	v_pk_add_f32 v[188:189], v[48:49], v[54:55]
	v_pk_add_f32 v[196:197], v[48:49], v[54:55] neg_lo:[0,1] neg_hi:[0,1]
	v_pk_mul_f32 v[186:187], v[82:83], 0 op_sel_hi:[1,0]
	v_mov_b32_e32 v190, v160
	v_mov_b32_e32 v191, v199
	v_mul_f32_e32 v18, 0x3f3504f3, v83
	v_mul_f32_e32 v158, 0xbec3ef15, v83
	v_mul_f32_e32 v132, 0xbf6c835e, v83
	s_and_saveexec_b64 s[0:1], vcc
	s_xor_b64 s[0:1], exec, s[0:1]
	s_cbranch_execz .LBB0_536
	v_pk_add_f32 v[4:5], v[148:149], v[196:197]
	v_pk_add_f32 v[6:7], v[148:149], v[196:197] neg_lo:[0,1] neg_hi:[0,1]
	v_mul_f32_e32 v4, 0.5, v4
	v_mul_f32_e32 v12, 0.5, v7
	v_mov_b32_e32 v7, v5
	v_pk_mul_f32 v[6:7], v[6:7], s[44:45]
	v_pk_mov_b32 v[16:17], v[198:199], v[160:161] op_sel:[1,0]
	v_pk_mul_f32 v[24:25], v[190:191], v[6:7] op_sel:[0,1] op_sel_hi:[1,0]
	v_pk_mul_f32 v[6:7], v[190:191], v[6:7]
	v_pk_add_f32 v[24:25], v[24:25], v[24:25] op_sel:[0,1] op_sel_hi:[0,1]
	v_pk_add_f32 v[28:29], v[4:5], v[24:25]
	v_pk_add_f32 v[4:5], v[4:5], v[24:25] op_sel_hi:[0,1] neg_lo:[0,1] neg_hi:[0,1]
	v_mov_b32_e32 v29, v5
	v_pk_add_f32 v[4:5], v[6:7], v[6:7] op_sel:[0,1] op_sel_hi:[0,1] neg_lo:[0,1] neg_hi:[0,1]
	v_pk_add_f32 v[6:7], v[12:13], v[4:5]
	v_pk_add_f32 v[4:5], v[12:13], v[4:5] op_sel_hi:[0,1] neg_lo:[0,1] neg_hi:[0,1]
	v_mov_b32_e32 v7, v5
	v_pk_mul_f32 v[4:5], v[6:7], v[194:195]
	v_pk_mul_f32 v[6:7], v[6:7], v[192:193]
	v_pk_fma_f32 v[4:5], v[28:29], v[192:193], v[4:5]
	v_pk_fma_f32 v[6:7], v[28:29], v[194:195], v[6:7] neg_lo:[0,0,1] neg_hi:[0,0,1]
	s_mov_b32 s66, s19
	v_pk_add_f32 v[12:13], v[6:7], v[4:5] op_sel:[0,1] op_sel_hi:[1,0] neg_lo:[0,1] neg_hi:[0,1]
	v_pk_add_f32 v[28:29], v[6:7], v[4:5] op_sel:[0,1] op_sel_hi:[1,0]
	v_pk_add_f32 v[4:5], v[4:5], v[6:7] op_sel:[1,0] op_sel_hi:[0,1] neg_lo:[0,1] neg_hi:[0,1]
	v_mov_b32_e32 v13, v29
	v_pk_mul_f32 v[12:13], v[12:13], 0.5 op_sel_hi:[1,0]
	v_mov_b32_e32 v29, v5
	v_mul_f32_e32 v24, v190, v12
	v_pk_fma_f32 v[30:31], v[190:191], v[12:13], v[24:25] op_sel_hi:[1,1,0] neg_lo:[1,0,0] neg_hi:[1,0,0]
	v_mul_f32_e32 v24, v160, v13
	v_pk_fma_f32 v[12:13], v[16:17], v[12:13], v[24:25] op_sel_hi:[1,1,0]
	v_mov_b32_e32 v16, v83
	v_mov_b32_e32 v30, v12
	v_pk_fma_f32 v[4:5], v[28:29], 0.5, v[12:13] op_sel_hi:[1,0,1] neg_lo:[0,0,1] neg_hi:[0,0,1]
	v_pk_fma_f32 v[122:123], v[28:29], 0.5, v[30:31] op_sel_hi:[1,0,1]
	v_pk_fma_f32 v[6:7], v[28:29], 0.5, v[30:31] op_sel_hi:[1,0,1] neg_lo:[1,0,0] neg_hi:[1,0,0]
	v_mov_b32_e32 v5, v123
	v_pk_mul_f32 v[24:25], v[4:5], s[46:47] op_sel_hi:[1,0]
	v_pk_add_f32 v[4:5], v[138:139], v[188:189]
	v_pk_add_f32 v[12:13], v[138:139], v[188:189] neg_lo:[0,1] neg_hi:[0,1]
	v_mov_b32_e32 v17, v82
	v_mul_f32_e32 v6, 0.5, v13
	v_pk_add_f32 v[28:29], v[186:187], v[16:17] neg_lo:[0,1] neg_hi:[0,1]
	v_pk_add_f32 v[30:31], v[186:187], v[16:17]
	v_mov_b32_e32 v13, v5
	v_pk_mov_b32 v[32:33], v[28:29], v[30:31] op_sel:[1,0]
	v_pk_mul_f32 v[12:13], v[12:13], s[44:45]
	v_mul_f32_e32 v4, 0.5, v4
	v_pk_mul_f32 v[48:49], v[32:33], v[12:13] op_sel:[0,1] op_sel_hi:[1,0]
	v_pk_mul_f32 v[12:13], v[32:33], v[12:13]
	v_pk_add_f32 v[48:49], v[48:49], v[48:49] op_sel:[0,1] op_sel_hi:[0,1]
	v_pk_add_f32 v[50:51], v[4:5], v[48:49]
	v_pk_add_f32 v[4:5], v[4:5], v[48:49] op_sel_hi:[0,1] neg_lo:[0,1] neg_hi:[0,1]
	v_mov_b32_e32 v51, v5
	v_pk_add_f32 v[4:5], v[12:13], v[12:13] op_sel:[0,1] op_sel_hi:[0,1] neg_lo:[0,1] neg_hi:[0,1]
	v_pk_add_f32 v[12:13], v[6:7], v[4:5]
	v_pk_add_f32 v[4:5], v[6:7], v[4:5] op_sel_hi:[0,1] neg_lo:[0,1] neg_hi:[0,1]
	v_mov_b32_e32 v13, v5
	v_pk_mul_f32 v[4:5], v[12:13], v[184:185]
	v_pk_mul_f32 v[12:13], v[12:13], v[170:171]
	v_pk_fma_f32 v[4:5], v[50:51], v[170:171], v[4:5]
	v_pk_fma_f32 v[12:13], v[50:51], v[184:185], v[12:13] neg_lo:[0,0,1] neg_hi:[0,0,1]
	v_mov_b32_e32 v31, v29
	v_pk_add_f32 v[48:49], v[12:13], v[4:5] op_sel:[0,1] op_sel_hi:[1,0] neg_lo:[0,1] neg_hi:[0,1]
	v_pk_add_f32 v[50:51], v[12:13], v[4:5] op_sel:[0,1] op_sel_hi:[1,0]
	v_pk_add_f32 v[4:5], v[4:5], v[12:13] op_sel:[1,0] op_sel_hi:[0,1] neg_lo:[0,1] neg_hi:[0,1]
	v_mov_b32_e32 v49, v51
	v_pk_mul_f32 v[48:49], v[48:49], 0.5 op_sel_hi:[1,0]
	v_mov_b32_e32 v51, v5
	v_mul_f32_e32 v6, v29, v48
	v_pk_fma_f32 v[32:33], v[32:33], v[48:49], v[6:7] op_sel_hi:[1,1,0] neg_lo:[1,0,0] neg_hi:[1,0,0]
	v_mul_f32_e32 v6, v29, v49
	v_pk_fma_f32 v[28:29], v[30:31], v[48:49], v[6:7] op_sel_hi:[1,1,0]
	v_pk_mul_f32 v[12:13], v[16:17], s[36:37]
	v_mov_b32_e32 v32, v28
	v_pk_fma_f32 v[4:5], v[50:51], 0.5, v[28:29] op_sel_hi:[1,0,1] neg_lo:[0,0,1] neg_hi:[0,0,1]
	v_pk_fma_f32 v[138:139], v[50:51], 0.5, v[32:33] op_sel_hi:[1,0,1]
	v_pk_add_f32 v[16:17], v[92:93], v[182:183]
	v_mov_b32_e32 v5, v139
	v_pk_add_f32 v[28:29], v[92:93], v[182:183] neg_lo:[0,1] neg_hi:[0,1]
	v_pk_mul_f32 v[30:31], v[4:5], s[46:47] op_sel_hi:[1,0]
	v_pk_fma_f32 v[4:5], v[50:51], 0.5, v[32:33] op_sel_hi:[1,0,1] neg_lo:[1,0,0] neg_hi:[1,0,0]
	v_mul_f32_e32 v6, 0.5, v29
	v_pk_add_f32 v[32:33], v[18:19], v[12:13] op_sel:[0,1] op_sel_hi:[0,1] neg_lo:[0,1] neg_hi:[0,1]
	v_pk_add_f32 v[48:49], v[18:19], v[12:13] op_sel:[0,1] op_sel_hi:[0,1]
	v_mov_b32_e32 v29, v17
	v_mul_f32_e32 v4, 0.5, v16
	v_mov_b32_e32 v50, v32
	v_mov_b32_e32 v51, v49
	v_pk_mul_f32 v[16:17], v[28:29], s[44:45]
	v_pk_mov_b32 v[48:49], v[48:49], v[32:33] op_sel:[1,0]
	v_pk_mul_f32 v[28:29], v[50:51], v[16:17] op_sel:[0,1] op_sel_hi:[1,0]
	v_pk_mul_f32 v[16:17], v[50:51], v[16:17]
	v_pk_add_f32 v[28:29], v[28:29], v[28:29] op_sel:[0,1] op_sel_hi:[0,1]
	v_pk_add_f32 v[52:53], v[4:5], v[28:29]
	v_pk_add_f32 v[28:29], v[4:5], v[28:29] op_sel_hi:[0,1] neg_lo:[0,1] neg_hi:[0,1]
	v_pk_add_f32 v[16:17], v[16:17], v[16:17] op_sel:[0,1] op_sel_hi:[0,1] neg_lo:[0,1] neg_hi:[0,1]
	v_mov_b32_e32 v53, v29
	v_pk_add_f32 v[28:29], v[6:7], v[16:17]
	v_pk_add_f32 v[16:17], v[6:7], v[16:17] op_sel_hi:[0,1] neg_lo:[0,1] neg_hi:[0,1]
	v_mov_b32_e32 v29, v17
	v_pk_mul_f32 v[16:17], v[28:29], v[180:181]
	v_pk_mul_f32 v[28:29], v[28:29], v[172:173]
	v_pk_fma_f32 v[16:17], v[52:53], v[172:173], v[16:17]
	v_pk_fma_f32 v[28:29], v[52:53], v[180:181], v[28:29] neg_lo:[0,0,1] neg_hi:[0,0,1]
	v_sub_f32_e32 v6, v89, v177
	v_pk_add_f32 v[52:53], v[28:29], v[16:17] op_sel:[0,1] op_sel_hi:[1,0] neg_lo:[0,1] neg_hi:[0,1]
	v_pk_add_f32 v[54:55], v[28:29], v[16:17] op_sel:[0,1] op_sel_hi:[1,0]
	v_pk_add_f32 v[16:17], v[16:17], v[28:29] op_sel:[1,0] op_sel_hi:[0,1] neg_lo:[0,1] neg_hi:[0,1]
	v_mov_b32_e32 v53, v55
	v_pk_mul_f32 v[52:53], v[52:53], 0.5 op_sel_hi:[1,0]
	v_mov_b32_e32 v55, v17
	v_mul_f32_e32 v4, v32, v52
	v_pk_fma_f32 v[56:57], v[50:51], v[52:53], v[4:5] op_sel_hi:[1,1,0] neg_lo:[1,0,0] neg_hi:[1,0,0]
	v_mul_f32_e32 v4, v32, v53
	v_pk_fma_f32 v[48:49], v[48:49], v[52:53], v[4:5] op_sel_hi:[1,1,0]
	v_pk_add_f32 v[28:29], v[88:89], v[176:177]
	v_mov_b32_e32 v56, v48
	v_pk_fma_f32 v[16:17], v[54:55], 0.5, v[48:49] op_sel_hi:[1,0,1] neg_lo:[0,0,1] neg_hi:[0,0,1]
	v_mov_b32_e32 v48, v12
	v_mov_b32_e32 v49, v88
	v_pk_mov_b32 v[12:13], v[12:13], v[176:177] op_sel:[1,0]
	v_mul_f32_e32 v18, 0.5, v29
	v_pk_add_f32 v[12:13], v[48:49], v[12:13] neg_lo:[0,1] neg_hi:[0,1]
	v_mul_f32_e32 v4, 0.5, v28
	v_pk_mul_f32 v[48:49], v[12:13], v[18:19]
	v_mov_b32_e32 v13, v32
	v_pk_fma_f32 v[50:51], v[50:51], v[48:49], v[48:49] op_sel:[0,1,0] op_sel_hi:[1,0,1]
	v_mov_b32_e32 v48, v49
	v_mov_b32_e32 v49, v18
	v_pk_mul_f32 v[48:49], v[12:13], v[48:49]
	v_pk_add_f32 v[52:53], v[4:5], v[50:51]
	v_mul_f32_e32 v6, 0.5, v6
	v_fma_f32 v53, v28, 0.5, -v50
	v_pk_add_f32 v[28:29], v[48:49], v[48:49] op_sel:[0,1] op_sel_hi:[0,1] neg_lo:[0,1] neg_hi:[0,1]
	v_pk_add_f32 v[48:49], v[6:7], v[28:29]
	v_pk_add_f32 v[28:29], v[6:7], v[28:29] op_sel_hi:[0,1] neg_lo:[0,1] neg_hi:[0,1]
	v_mov_b32_e32 v49, v29
	v_pk_mul_f32 v[28:29], v[48:49], v[178:179]
	v_pk_mul_f32 v[48:49], v[48:49], v[174:175]
	v_pk_fma_f32 v[28:29], v[52:53], v[174:175], v[28:29]
	v_pk_fma_f32 v[48:49], v[52:53], v[178:179], v[48:49] neg_lo:[0,0,1] neg_hi:[0,0,1]
	v_pk_fma_f32 v[92:93], v[54:55], 0.5, v[56:57] op_sel_hi:[1,0,1]
	v_pk_add_f32 v[50:51], v[48:49], v[28:29] op_sel:[0,1] op_sel_hi:[1,0] neg_lo:[0,1] neg_hi:[0,1]
	v_pk_add_f32 v[52:53], v[48:49], v[28:29] op_sel:[0,1] op_sel_hi:[1,0]
	v_mov_b32_e32 v17, v93
	v_mov_b32_e32 v51, v53
	v_pk_mul_f32 v[50:51], v[50:51], 0.5 op_sel_hi:[1,0]
	v_pk_mul_f32 v[64:65], v[16:17], s[46:47] op_sel_hi:[1,0]
	v_mul_f32_e32 v4, v12, v50
	v_pk_fma_f32 v[16:17], v[54:55], 0.5, v[56:57] op_sel_hi:[1,0,1] neg_lo:[1,0,0] neg_hi:[1,0,0]
	v_pk_fma_f32 v[54:55], v[12:13], v[50:51], v[4:5] op_sel_hi:[1,1,0] neg_lo:[1,0,0] neg_hi:[1,0,0]
	v_mov_b32_e32 v33, v12
	v_mul_f32_e32 v4, v12, v51
	v_pk_fma_f32 v[12:13], v[32:33], v[50:51], v[4:5] op_sel_hi:[1,1,0]
	v_pk_add_f32 v[28:29], v[28:29], v[48:49] op_sel:[1,0] op_sel_hi:[0,1] neg_lo:[0,1] neg_hi:[0,1]
	v_mov_b32_e32 v53, v29
	v_mov_b32_e32 v54, v12
	v_pk_fma_f32 v[12:13], v[52:53], 0.5, v[12:13] op_sel_hi:[1,0,1] neg_lo:[0,0,1] neg_hi:[0,0,1]
	v_pk_fma_f32 v[88:89], v[52:53], 0.5, v[54:55] op_sel_hi:[1,0,1]
	s_mov_b32 s67, s16
	v_mov_b32_e32 v13, v89
	v_pk_mul_f32 v[68:69], v[12:13], s[46:47] op_sel_hi:[1,0]
	v_pk_fma_f32 v[12:13], v[52:53], 0.5, v[54:55] op_sel_hi:[1,0,1] neg_lo:[1,0,0] neg_hi:[1,0,0]
	v_mov_b32_e32 v4, v83
	s_mov_b32 s17, s19
	v_pk_mul_f32 v[48:49], v[82:83], s[66:67] op_sel_hi:[0,1]
	v_pk_add_f32 v[28:29], v[96:97], v[162:163]
	v_pk_add_f32 v[32:33], v[96:97], v[162:163] neg_lo:[0,1] neg_hi:[0,1]
	v_pk_fma_f32 v[52:53], v[4:5], s[16:17], v[48:49] op_sel_hi:[0,1,1] neg_lo:[0,0,1] neg_hi:[0,0,1]
	v_mul_f32_e32 v12, 0.5, v33
	v_pk_fma_f32 v[50:51], v[4:5], s[16:17], v[48:49] op_sel_hi:[0,1,1]
	v_mov_b32_e32 v33, v29
	v_mul_f32_e32 v6, 0.5, v28
	v_mov_b32_e32 v54, v52
	v_mov_b32_e32 v55, v51
	v_pk_mul_f32 v[28:29], v[32:33], s[44:45]
	v_pk_mov_b32 v[56:57], v[50:51], v[52:53] op_sel:[1,0]
	v_pk_mul_f32 v[32:33], v[54:55], v[28:29] op_sel:[0,1] op_sel_hi:[1,0]
	v_pk_mul_f32 v[28:29], v[54:55], v[28:29]
	v_pk_add_f32 v[32:33], v[32:33], v[32:33] op_sel:[0,1] op_sel_hi:[0,1]
	v_pk_add_f32 v[58:59], v[6:7], v[32:33]
	v_pk_add_f32 v[32:33], v[6:7], v[32:33] op_sel_hi:[0,1] neg_lo:[0,1] neg_hi:[0,1]
	v_pk_add_f32 v[28:29], v[28:29], v[28:29] op_sel:[0,1] op_sel_hi:[0,1] neg_lo:[0,1] neg_hi:[0,1]
	v_mov_b32_e32 v59, v33
	v_pk_add_f32 v[32:33], v[12:13], v[28:29]
	v_pk_add_f32 v[28:29], v[12:13], v[28:29] op_sel_hi:[0,1] neg_lo:[0,1] neg_hi:[0,1]
	v_mov_b32_e32 v33, v29
	v_pk_mul_f32 v[28:29], v[32:33], v[166:167]
	v_pk_mul_f32 v[32:33], v[32:33], v[164:165]
	v_pk_fma_f32 v[28:29], v[58:59], v[164:165], v[28:29]
	v_pk_fma_f32 v[32:33], v[58:59], v[166:167], v[32:33] neg_lo:[0,0,1] neg_hi:[0,0,1]
	v_mov_b32_e32 v159, v66
	v_pk_add_f32 v[58:59], v[32:33], v[28:29] op_sel:[0,1] op_sel_hi:[1,0] neg_lo:[0,1] neg_hi:[0,1]
	v_pk_add_f32 v[70:71], v[32:33], v[28:29] op_sel:[0,1] op_sel_hi:[1,0]
	v_pk_add_f32 v[28:29], v[28:29], v[32:33] op_sel:[1,0] op_sel_hi:[0,1] neg_lo:[0,1] neg_hi:[0,1]
	v_mov_b32_e32 v59, v71
	v_pk_mul_f32 v[58:59], v[58:59], 0.5 op_sel_hi:[1,0]
	v_mov_b32_e32 v71, v29
	v_mul_f32_e32 v6, v52, v58
	v_pk_fma_f32 v[72:73], v[54:55], v[58:59], v[6:7] op_sel_hi:[1,1,0] neg_lo:[1,0,0] neg_hi:[1,0,0]
	v_mul_f32_e32 v6, v52, v59
	v_pk_fma_f32 v[56:57], v[56:57], v[58:59], v[6:7] op_sel_hi:[1,1,0]
	v_sub_f32_e32 v12, v67, v153
	v_mov_b32_e32 v72, v56
	v_pk_fma_f32 v[28:29], v[70:71], 0.5, v[56:57] op_sel_hi:[1,0,1] neg_lo:[0,0,1] neg_hi:[0,0,1]
	v_pk_fma_f32 v[96:97], v[70:71], 0.5, v[72:73] op_sel_hi:[1,0,1]
	v_pk_mov_b32 v[56:57], v[48:49], v[152:153] op_sel:[1,0]
	v_mov_b32_e32 v29, v97
	v_pk_mul_f32 v[62:63], v[28:29], s[46:47] op_sel_hi:[1,0]
	v_pk_add_f32 v[28:29], v[66:67], v[152:153]
	v_pk_add_f32 v[56:57], v[158:159], v[56:57] neg_lo:[0,1] neg_hi:[0,1]
	v_mul_f32_e32 v18, 0.5, v29
	v_pk_mul_f32 v[58:59], v[56:57], v[18:19]
	v_mul_f32_e32 v6, 0.5, v28
	v_pk_fma_f32 v[54:55], v[54:55], v[58:59], v[58:59] op_sel:[0,1,0] op_sel_hi:[1,0,1]
	v_mov_b32_e32 v66, v56
	v_mov_b32_e32 v67, v52
	v_mov_b32_e32 v58, v59
	v_mov_b32_e32 v59, v18
	v_pk_mul_f32 v[58:59], v[66:67], v[58:59]
	v_pk_add_f32 v[66:67], v[6:7], v[54:55]
	v_mul_f32_e32 v12, 0.5, v12
	v_fma_f32 v67, v28, 0.5, -v54
	v_pk_add_f32 v[28:29], v[58:59], v[58:59] op_sel:[0,1] op_sel_hi:[0,1] neg_lo:[0,1] neg_hi:[0,1]
	v_pk_add_f32 v[54:55], v[12:13], v[28:29]
	v_pk_add_f32 v[28:29], v[12:13], v[28:29] op_sel_hi:[0,1] neg_lo:[0,1] neg_hi:[0,1]
	v_mov_b32_e32 v55, v29
	v_pk_mul_f32 v[28:29], v[54:55], v[156:157]
	v_pk_mul_f32 v[54:55], v[54:55], v[154:155]
	v_pk_fma_f32 v[32:33], v[70:71], 0.5, v[72:73] op_sel_hi:[1,0,1] neg_lo:[1,0,0] neg_hi:[1,0,0]
	v_pk_fma_f32 v[58:59], v[66:67], v[154:155], v[28:29] neg_lo:[0,0,1] neg_hi:[0,0,1]
	v_pk_fma_f32 v[28:29], v[66:67], v[154:155], v[28:29]
	v_pk_fma_f32 v[70:71], v[66:67], v[156:157], v[54:55]
	v_pk_fma_f32 v[54:55], v[66:67], v[156:157], v[54:55] neg_lo:[0,0,1] neg_hi:[0,0,1]
	v_pk_add_f32 v[72:73], v[58:59], v[28:29] op_sel:[0,1] op_sel_hi:[1,0]
	v_pk_add_f32 v[66:67], v[70:71], v[54:55] op_sel_hi:[0,1] neg_lo:[0,1] neg_hi:[0,1]
	v_pk_add_f32 v[28:29], v[58:59], v[28:29] op_sel_hi:[0,1] neg_lo:[0,1] neg_hi:[0,1]
	v_pk_add_f32 v[54:55], v[70:71], v[54:55] op_sel:[0,1] op_sel_hi:[1,0]
	v_mov_b32_e32 v73, v67
	v_mov_b32_e32 v55, v29
	v_pk_mul_f32 v[28:29], v[54:55], 0.5 op_sel_hi:[1,0]
	v_mov_b32_e32 v133, v84
	v_pk_mul_f32 v[54:55], v[52:53], v[28:29] op_sel:[0,1] op_sel_hi:[0,0]
	v_pk_fma_f32 v[58:59], v[56:57], v[28:29], v[54:55] op_sel_hi:[0,1,1]
	v_pk_fma_f32 v[28:29], v[56:57], v[28:29], v[54:55] op_sel_hi:[0,1,1] neg_lo:[0,0,1] neg_hi:[0,0,1]
	v_mov_b32_e32 v28, v58
	v_pk_fma_f32 v[54:55], v[72:73], 0.5, v[58:59] op_sel_hi:[1,0,1] neg_lo:[0,0,1] neg_hi:[0,0,1]
	v_pk_fma_f32 v[66:67], v[72:73], 0.5, v[28:29] op_sel_hi:[1,0,1]
	v_pk_add_f32 v[56:57], v[60:61], v[134:135] neg_lo:[0,1] neg_hi:[0,1]
	v_mov_b32_e32 v55, v67
	v_pk_mul_f32 v[90:91], v[54:55], s[46:47] op_sel_hi:[1,0]
	v_pk_add_f32 v[54:55], v[134:135], v[60:61]
	v_mul_f32_e32 v12, 0.5, v57
	v_mov_b32_e32 v57, v55
	v_mul_f32_e32 v6, 0.5, v54
	v_pk_mov_b32 v[58:59], v[52:53], v[50:51] op_sel:[1,0]
	v_pk_mul_f32 v[54:55], v[56:57], s[44:45]
	v_pk_fma_f32 v[28:29], v[72:73], 0.5, v[28:29] op_sel_hi:[1,0,1] neg_lo:[1,0,0] neg_hi:[1,0,0]
	v_pk_mul_f32 v[56:57], v[58:59], v[54:55] op_sel:[0,1] op_sel_hi:[1,0]
	v_pk_mul_f32 v[54:55], v[58:59], v[54:55]
	v_pk_add_f32 v[56:57], v[56:57], v[56:57] op_sel:[0,1] op_sel_hi:[0,1]
	v_pk_add_f32 v[60:61], v[6:7], v[56:57]
	v_pk_add_f32 v[56:57], v[6:7], v[56:57] op_sel_hi:[0,1] neg_lo:[0,1] neg_hi:[0,1]
	v_pk_add_f32 v[54:55], v[54:55], v[54:55] op_sel:[0,1] op_sel_hi:[0,1] neg_lo:[0,1] neg_hi:[0,1]
	v_mov_b32_e32 v61, v57
	v_pk_add_f32 v[56:57], v[12:13], v[54:55]
	v_pk_add_f32 v[54:55], v[12:13], v[54:55] op_sel_hi:[0,1] neg_lo:[0,1] neg_hi:[0,1]
	v_mov_b32_e32 v57, v55
	v_pk_mul_f32 v[54:55], v[56:57], v[142:143]
	v_pk_mul_f32 v[56:57], v[56:57], v[140:141]
	v_pk_fma_f32 v[54:55], v[60:61], v[140:141], v[54:55]
	v_pk_fma_f32 v[56:57], v[60:61], v[142:143], v[56:57] neg_lo:[0,0,1] neg_hi:[0,0,1]
	v_mov_b32_e32 v51, v53
	v_pk_add_f32 v[60:61], v[56:57], v[54:55] op_sel:[0,1] op_sel_hi:[1,0] neg_lo:[0,1] neg_hi:[0,1]
	v_pk_add_f32 v[70:71], v[56:57], v[54:55] op_sel:[0,1] op_sel_hi:[1,0]
	v_pk_add_f32 v[54:55], v[54:55], v[56:57] op_sel:[1,0] op_sel_hi:[0,1] neg_lo:[0,1] neg_hi:[0,1]
	v_mov_b32_e32 v61, v71
	v_pk_mul_f32 v[60:61], v[60:61], 0.5 op_sel_hi:[1,0]
	v_mov_b32_e32 v71, v55
	v_mul_f32_e32 v6, v53, v60
	v_pk_fma_f32 v[72:73], v[58:59], v[60:61], v[6:7] op_sel_hi:[1,1,0] neg_lo:[1,0,0] neg_hi:[1,0,0]
	v_mul_f32_e32 v6, v53, v61
	v_pk_fma_f32 v[50:51], v[50:51], v[60:61], v[6:7] op_sel_hi:[1,1,0]
	v_pk_add_f32 v[54:55], v[118:119], v[84:85]
	v_mov_b32_e32 v72, v50
	v_mov_b32_e32 v49, v118
	v_pk_fma_f32 v[50:51], v[70:71], 0.5, v[50:51] op_sel_hi:[1,0,1] neg_lo:[0,0,1] neg_hi:[0,0,1]
	v_pk_fma_f32 v[60:61], v[70:71], 0.5, v[72:73] op_sel_hi:[1,0,1]
	v_mul_f32_e32 v18, 0.5, v55
	v_pk_add_f32 v[48:49], v[132:133], v[48:49] neg_lo:[0,1] neg_hi:[0,1]
	v_mov_b32_e32 v51, v61
	v_pk_mul_f32 v[56:57], v[48:49], v[18:19]
	v_pk_mul_f32 v[94:95], v[50:51], s[46:47] op_sel_hi:[1,0]
	v_pk_fma_f32 v[50:51], v[70:71], 0.5, v[72:73] op_sel_hi:[1,0,1] neg_lo:[1,0,0] neg_hi:[1,0,0]
	v_mul_f32_e32 v6, 0.5, v54
	v_pk_fma_f32 v[58:59], v[58:59], v[56:57], v[56:57] op_sel:[0,1,0] op_sel_hi:[1,0,1]
	v_mov_b32_e32 v70, v48
	v_mov_b32_e32 v71, v53
	v_mov_b32_e32 v56, v57
	v_mov_b32_e32 v57, v18
	v_sub_f32_e32 v12, v85, v119
	v_pk_mul_f32 v[56:57], v[70:71], v[56:57]
	v_pk_add_f32 v[70:71], v[6:7], v[58:59]
	v_mul_f32_e32 v12, 0.5, v12
	v_fma_f32 v71, v54, 0.5, -v58
	v_pk_add_f32 v[54:55], v[56:57], v[56:57] op_sel:[0,1] op_sel_hi:[0,1] neg_lo:[0,1] neg_hi:[0,1]
	v_pk_add_f32 v[56:57], v[12:13], v[54:55]
	v_pk_add_f32 v[54:55], v[12:13], v[54:55] op_sel_hi:[0,1] neg_lo:[0,1] neg_hi:[0,1]
	v_mov_b32_e32 v57, v55
	v_pk_mul_f32 v[54:55], v[56:57], v[126:127]
	v_pk_mul_f32 v[56:57], v[56:57], v[124:125]
	v_pk_fma_f32 v[58:59], v[70:71], v[124:125], v[54:55] neg_lo:[0,0,1] neg_hi:[0,0,1]
	v_pk_fma_f32 v[54:55], v[70:71], v[124:125], v[54:55]
	v_pk_fma_f32 v[72:73], v[70:71], v[126:127], v[56:57]
	v_pk_fma_f32 v[56:57], v[70:71], v[126:127], v[56:57] neg_lo:[0,0,1] neg_hi:[0,0,1]
	v_pk_add_f32 v[70:71], v[58:59], v[54:55] op_sel:[0,1] op_sel_hi:[1,0]
	v_pk_add_f32 v[74:75], v[72:73], v[56:57] op_sel_hi:[0,1] neg_lo:[0,1] neg_hi:[0,1]
	v_pk_add_f32 v[54:55], v[58:59], v[54:55] op_sel_hi:[0,1] neg_lo:[0,1] neg_hi:[0,1]
	v_pk_add_f32 v[56:57], v[72:73], v[56:57] op_sel:[0,1] op_sel_hi:[1,0]
	v_mov_b32_e32 v71, v75
	v_mov_b32_e32 v57, v55
	v_pk_mul_f32 v[54:55], v[56:57], 0.5 op_sel_hi:[1,0]
	s_mov_b32 s66, s11
	v_pk_mul_f32 v[52:53], v[52:53], v[54:55] op_sel:[1,1] op_sel_hi:[1,0]
	s_mov_b32 s67, s8
	v_pk_fma_f32 v[56:57], v[48:49], v[54:55], v[52:53] op_sel_hi:[0,1,1]
	v_pk_fma_f32 v[48:49], v[48:49], v[54:55], v[52:53] op_sel_hi:[0,1,1] neg_lo:[0,0,1] neg_hi:[0,0,1]
	v_mov_b32_e32 v48, v56
	v_pk_fma_f32 v[52:53], v[70:71], 0.5, v[56:57] op_sel_hi:[1,0,1] neg_lo:[0,0,1] neg_hi:[0,0,1]
	v_pk_fma_f32 v[84:85], v[70:71], 0.5, v[48:49] op_sel_hi:[1,0,1]
	s_mov_b32 s9, s11
	v_mov_b32_e32 v53, v85
	v_pk_mul_f32 v[80:81], v[52:53], s[46:47] op_sel_hi:[1,0]
	v_pk_mul_f32 v[118:119], v[82:83], s[66:67] op_sel_hi:[0,1]
	v_pk_add_f32 v[52:53], v[86:87], v[112:113]
	v_pk_add_f32 v[54:55], v[86:87], v[112:113] neg_lo:[0,1] neg_hi:[0,1]
	v_pk_fma_f32 v[58:59], v[4:5], s[8:9], v[118:119] op_sel_hi:[0,1,1] neg_lo:[0,0,1] neg_hi:[0,0,1]
	v_mul_f32_e32 v12, 0.5, v55
	v_pk_fma_f32 v[72:73], v[4:5], s[8:9], v[118:119] op_sel_hi:[0,1,1]
	v_mov_b32_e32 v55, v53
	v_mul_f32_e32 v6, 0.5, v52
	v_mov_b32_e32 v56, v58
	v_mov_b32_e32 v57, v73
	v_pk_mul_f32 v[52:53], v[54:55], s[44:45]
	v_pk_fma_f32 v[48:49], v[70:71], 0.5, v[48:49] op_sel_hi:[1,0,1] neg_lo:[1,0,0] neg_hi:[1,0,0]
	v_pk_mul_f32 v[54:55], v[56:57], v[52:53] op_sel:[0,1] op_sel_hi:[1,0]
	v_pk_mul_f32 v[52:53], v[56:57], v[52:53]
	v_pk_add_f32 v[54:55], v[54:55], v[54:55] op_sel:[0,1] op_sel_hi:[0,1]
	v_pk_add_f32 v[74:75], v[6:7], v[54:55]
	v_pk_add_f32 v[54:55], v[6:7], v[54:55] op_sel_hi:[0,1] neg_lo:[0,1] neg_hi:[0,1]
	v_pk_add_f32 v[52:53], v[52:53], v[52:53] op_sel:[0,1] op_sel_hi:[0,1] neg_lo:[0,1] neg_hi:[0,1]
	v_mov_b32_e32 v75, v55
	v_pk_add_f32 v[54:55], v[12:13], v[52:53]
	v_pk_add_f32 v[52:53], v[12:13], v[52:53] op_sel_hi:[0,1] neg_lo:[0,1] neg_hi:[0,1]
	v_mov_b32_e32 v55, v53
	v_pk_mul_f32 v[52:53], v[54:55], v[116:117]
	v_pk_mul_f32 v[54:55], v[54:55], v[114:115]
	v_pk_fma_f32 v[52:53], v[74:75], v[114:115], v[52:53]
	v_pk_fma_f32 v[54:55], v[74:75], v[116:117], v[54:55] neg_lo:[0,0,1] neg_hi:[0,0,1]
	v_pk_mov_b32 v[70:71], v[72:73], v[58:59] op_sel:[1,0]
	v_pk_add_f32 v[74:75], v[54:55], v[52:53] op_sel:[0,1] op_sel_hi:[1,0] neg_lo:[0,1] neg_hi:[0,1]
	v_pk_add_f32 v[76:77], v[54:55], v[52:53] op_sel:[0,1] op_sel_hi:[1,0]
	v_pk_add_f32 v[52:53], v[52:53], v[54:55] op_sel:[1,0] op_sel_hi:[0,1] neg_lo:[0,1] neg_hi:[0,1]
	v_mov_b32_e32 v75, v77
	v_pk_mul_f32 v[74:75], v[74:75], 0.5 op_sel_hi:[1,0]
	v_mov_b32_e32 v77, v53
	v_mul_f32_e32 v6, v58, v74
	v_pk_fma_f32 v[112:113], v[56:57], v[74:75], v[6:7] op_sel_hi:[1,1,0] neg_lo:[1,0,0] neg_hi:[1,0,0]
	v_mul_f32_e32 v6, v58, v75
	v_pk_fma_f32 v[70:71], v[70:71], v[74:75], v[6:7] op_sel_hi:[1,1,0]
	v_pk_add_f32 v[54:55], v[34:35], v[110:111]
	v_mov_b32_e32 v112, v70
	v_pk_fma_f32 v[52:53], v[76:77], 0.5, v[70:71] op_sel_hi:[1,0,1] neg_lo:[0,0,1] neg_hi:[0,0,1]
	v_pk_fma_f32 v[86:87], v[76:77], 0.5, v[112:113] op_sel_hi:[1,0,1]
	v_sub_f32_e32 v12, v35, v111
	v_mov_b32_e32 v53, v87
	v_pk_mul_f32 v[78:79], v[52:53], s[46:47] op_sel_hi:[1,0]
	v_mul_f32_e32 v52, 0xbe47c5c2, v83
	v_mov_b32_e32 v53, v34
	v_pk_mov_b32 v[34:35], v[118:119], v[110:111] op_sel:[1,0]
	v_mul_f32_e32 v18, 0.5, v55
	v_pk_add_f32 v[34:35], v[52:53], v[34:35] neg_lo:[0,1] neg_hi:[0,1]
	v_mov_b32_e32 v71, v58
	v_pk_mul_f32 v[52:53], v[34:35], v[18:19]
	v_mov_b32_e32 v70, v34
	v_pk_fma_f32 v[56:57], v[56:57], v[52:53], v[52:53] op_sel:[0,1,0] op_sel_hi:[1,0,1]
	v_mov_b32_e32 v52, v53
	v_mov_b32_e32 v53, v18
	v_mul_f32_e32 v6, 0.5, v54
	v_pk_mul_f32 v[52:53], v[70:71], v[52:53]
	v_cvt_f32_f16_e32 v70, v46
	v_cvt_f32_f16_e32 v71, v47
	v_cvt_f32_f16_sdwa v47, v47 dst_sel:DWORD dst_unused:UNUSED_PAD src0_sel:WORD_1
	v_cvt_f32_f16_sdwa v46, v46 dst_sel:DWORD dst_unused:UNUSED_PAD src0_sel:WORD_1
	v_pk_fma_f32 v[74:75], v[76:77], 0.5, v[112:113] op_sel_hi:[1,0,1] neg_lo:[1,0,0] neg_hi:[1,0,0]
	v_mul_f32_e32 v12, 0.5, v12
	v_pk_add_f32 v[76:77], v[6:7], v[56:57]
	v_pk_add_f32 v[52:53], v[52:53], v[52:53] op_sel:[0,1] op_sel_hi:[0,1] neg_lo:[0,1] neg_hi:[0,1]
	v_fma_f32 v77, v54, 0.5, -v56
	v_pk_add_f32 v[54:55], v[12:13], v[52:53]
	v_pk_add_f32 v[52:53], v[12:13], v[52:53] op_sel_hi:[0,1] neg_lo:[0,1] neg_hi:[0,1]
	v_mov_b32_e32 v55, v53
	v_pk_mul_f32 v[52:53], v[54:55], v[46:47]
	v_pk_mul_f32 v[54:55], v[54:55], v[70:71]
	v_pk_fma_f32 v[56:57], v[76:77], v[70:71], v[52:53] neg_lo:[0,0,1] neg_hi:[0,0,1]
	v_pk_fma_f32 v[52:53], v[76:77], v[70:71], v[52:53]
	v_pk_fma_f32 v[70:71], v[76:77], v[46:47], v[54:55]
	v_pk_fma_f32 v[46:47], v[76:77], v[46:47], v[54:55] neg_lo:[0,0,1] neg_hi:[0,0,1]
	v_pk_add_f32 v[54:55], v[56:57], v[52:53] op_sel:[0,1] op_sel_hi:[1,0]
	v_pk_add_f32 v[76:77], v[70:71], v[46:47] op_sel_hi:[0,1] neg_lo:[0,1] neg_hi:[0,1]
	v_pk_add_f32 v[52:53], v[56:57], v[52:53] op_sel_hi:[0,1] neg_lo:[0,1] neg_hi:[0,1]
	v_pk_add_f32 v[46:47], v[70:71], v[46:47] op_sel:[0,1] op_sel_hi:[1,0]
	v_mov_b32_e32 v55, v77
	v_mov_b32_e32 v47, v53
	v_pk_mul_f32 v[46:47], v[46:47], 0.5 op_sel_hi:[1,0]
	s_mov_b32 s25, s27
	v_pk_mul_f32 v[52:53], v[58:59], v[46:47] op_sel:[0,1] op_sel_hi:[0,0]
	v_pk_fma_f32 v[56:57], v[34:35], v[46:47], v[52:53] op_sel_hi:[0,1,1]
	v_pk_fma_f32 v[46:47], v[34:35], v[46:47], v[52:53] op_sel_hi:[0,1,1] neg_lo:[0,0,1] neg_hi:[0,0,1]
	v_mov_b32_e32 v46, v56
	v_pk_fma_f32 v[52:53], v[54:55], 0.5, v[56:57] op_sel_hi:[1,0,1] neg_lo:[0,0,1] neg_hi:[0,0,1]
	v_pk_fma_f32 v[34:35], v[54:55], 0.5, v[46:47] op_sel_hi:[1,0,1]
	s_mov_b32 s66, s27
	v_mov_b32_e32 v53, v35
	v_pk_mul_f32 v[136:137], v[52:53], s[46:47] op_sel_hi:[1,0]
	v_pk_fma_f32 v[52:53], v[54:55], 0.5, v[46:47] op_sel_hi:[1,0,1] neg_lo:[1,0,0] neg_hi:[1,0,0]
	s_mov_b32 s67, s24
	v_pk_mul_f32 v[46:47], v[82:83], s[24:25] op_sel_hi:[0,1]
	v_pk_add_f32 v[54:55], v[108:109], v[40:41]
	v_pk_add_f32 v[40:41], v[40:41], v[108:109] neg_lo:[0,1] neg_hi:[0,1]
	v_pk_fma_f32 v[108:109], v[4:5], s[66:67], v[46:47] op_sel_hi:[0,1,1] neg_lo:[0,0,1] neg_hi:[0,0,1]
	v_mul_f32_e32 v12, 0.5, v41
	v_pk_fma_f32 v[70:71], v[4:5], s[66:67], v[46:47] op_sel_hi:[0,1,1]
	v_mov_b32_e32 v41, v55
	v_mov_b32_e32 v56, v108
	v_mov_b32_e32 v57, v71
	v_pk_mul_f32 v[40:41], v[40:41], s[44:45]
	v_mul_f32_e32 v6, 0.5, v54
	v_pk_mul_f32 v[54:55], v[56:57], v[40:41] op_sel:[0,1] op_sel_hi:[1,0]
	v_cvt_f32_f16_sdwa v76, v38 dst_sel:DWORD dst_unused:UNUSED_PAD src0_sel:WORD_1
	v_cvt_f32_f16_e32 v77, v39
	v_cvt_f32_f16_sdwa v39, v39 dst_sel:DWORD dst_unused:UNUSED_PAD src0_sel:WORD_1
	v_cvt_f32_f16_e32 v38, v38
	v_pk_mul_f32 v[40:41], v[56:57], v[40:41]
	v_pk_add_f32 v[54:55], v[54:55], v[54:55] op_sel:[0,1] op_sel_hi:[0,1]
	v_pk_add_f32 v[112:113], v[6:7], v[54:55]
	v_pk_add_f32 v[54:55], v[6:7], v[54:55] op_sel_hi:[0,1] neg_lo:[0,1] neg_hi:[0,1]
	v_pk_add_f32 v[40:41], v[40:41], v[40:41] op_sel:[0,1] op_sel_hi:[0,1] neg_lo:[0,1] neg_hi:[0,1]
	v_mov_b32_e32 v113, v55
	v_pk_add_f32 v[54:55], v[12:13], v[40:41]
	v_pk_add_f32 v[40:41], v[12:13], v[40:41] op_sel_hi:[0,1] neg_lo:[0,1] neg_hi:[0,1]
	v_mov_b32_e32 v55, v41
	v_pk_mul_f32 v[40:41], v[54:55], v[38:39]
	v_pk_mul_f32 v[54:55], v[54:55], v[76:77]
	v_pk_fma_f32 v[40:41], v[112:113], v[76:77], v[40:41]
	v_pk_fma_f32 v[38:39], v[112:113], v[38:39], v[54:55] neg_lo:[0,0,1] neg_hi:[0,0,1]
	v_pk_mov_b32 v[110:111], v[70:71], v[108:109] op_sel:[1,0]
	v_pk_add_f32 v[54:55], v[38:39], v[40:41] op_sel:[0,1] op_sel_hi:[1,0] neg_lo:[0,1] neg_hi:[0,1]
	v_pk_add_f32 v[76:77], v[38:39], v[40:41] op_sel:[0,1] op_sel_hi:[1,0]
	v_pk_add_f32 v[38:39], v[40:41], v[38:39] op_sel:[1,0] op_sel_hi:[0,1] neg_lo:[0,1] neg_hi:[0,1]
	v_mov_b32_e32 v55, v77
	v_pk_mul_f32 v[54:55], v[54:55], 0.5 op_sel_hi:[1,0]
	v_mov_b32_e32 v77, v39
	v_mul_f32_e32 v4, v108, v54
	v_pk_fma_f32 v[112:113], v[56:57], v[54:55], v[4:5] op_sel_hi:[1,1,0] neg_lo:[1,0,0] neg_hi:[1,0,0]
	v_mul_f32_e32 v4, v108, v55
	v_pk_fma_f32 v[54:55], v[110:111], v[54:55], v[4:5] op_sel_hi:[1,1,0]
	v_sub_f32_e32 v6, v45, v105
	v_mov_b32_e32 v112, v54
	v_pk_fma_f32 v[40:41], v[76:77], 0.5, v[54:55] op_sel_hi:[1,0,1] neg_lo:[0,0,1] neg_hi:[0,0,1]
	v_pk_fma_f32 v[38:39], v[76:77], 0.5, v[112:113] op_sel_hi:[1,0,1]
	v_pk_add_f32 v[54:55], v[104:105], v[44:45]
	v_mov_b32_e32 v41, v39
	v_pk_mul_f32 v[130:131], v[40:41], s[46:47] op_sel_hi:[1,0]
	v_mul_f32_e32 v40, 0xbf54db31, v83
	v_mov_b32_e32 v41, v44
	v_pk_mov_b32 v[44:45], v[46:47], v[104:105] op_sel:[1,0]
	v_mul_f32_e32 v18, 0.5, v55
	v_pk_add_f32 v[40:41], v[40:41], v[44:45] neg_lo:[0,1] neg_hi:[0,1]
	v_mov_b32_e32 v105, v108
	v_pk_mul_f32 v[44:45], v[40:41], v[18:19]
	v_mov_b32_e32 v104, v40
	v_pk_fma_f32 v[56:57], v[56:57], v[44:45], v[44:45] op_sel:[0,1,0] op_sel_hi:[1,0,1]
	v_mov_b32_e32 v44, v45
	v_mov_b32_e32 v45, v18
	v_mul_f32_e32 v4, 0.5, v54
	v_pk_mul_f32 v[44:45], v[104:105], v[44:45]
	v_cvt_f32_f16_e32 v104, v26
	v_cvt_f32_f16_e32 v105, v27
	v_cvt_f32_f16_sdwa v27, v27 dst_sel:DWORD dst_unused:UNUSED_PAD src0_sel:WORD_1
	v_cvt_f32_f16_sdwa v26, v26 dst_sel:DWORD dst_unused:UNUSED_PAD src0_sel:WORD_1
	v_mul_f32_e32 v6, 0.5, v6
	v_pk_add_f32 v[110:111], v[4:5], v[56:57]
	v_pk_add_f32 v[44:45], v[44:45], v[44:45] op_sel:[0,1] op_sel_hi:[0,1] neg_lo:[0,1] neg_hi:[0,1]
	v_fma_f32 v111, v54, 0.5, -v56
	v_pk_add_f32 v[54:55], v[6:7], v[44:45]
	v_pk_add_f32 v[44:45], v[6:7], v[44:45] op_sel_hi:[0,1] neg_lo:[0,1] neg_hi:[0,1]
	v_mov_b32_e32 v55, v45
	v_pk_mul_f32 v[44:45], v[54:55], v[26:27]
	v_pk_mul_f32 v[54:55], v[54:55], v[104:105]
	v_pk_fma_f32 v[56:57], v[110:111], v[104:105], v[44:45] neg_lo:[0,0,1] neg_hi:[0,0,1]
	v_pk_fma_f32 v[44:45], v[110:111], v[104:105], v[44:45]
	v_pk_fma_f32 v[104:105], v[110:111], v[26:27], v[54:55]
	v_pk_fma_f32 v[26:27], v[110:111], v[26:27], v[54:55] neg_lo:[0,0,1] neg_hi:[0,0,1]
	v_pk_add_f32 v[54:55], v[56:57], v[44:45] op_sel:[0,1] op_sel_hi:[1,0]
	v_pk_add_f32 v[110:111], v[104:105], v[26:27] op_sel_hi:[0,1] neg_lo:[0,1] neg_hi:[0,1]
	v_pk_add_f32 v[44:45], v[56:57], v[44:45] op_sel_hi:[0,1] neg_lo:[0,1] neg_hi:[0,1]
	v_pk_add_f32 v[26:27], v[104:105], v[26:27] op_sel:[0,1] op_sel_hi:[1,0]
	v_mov_b32_e32 v55, v111
	v_mov_b32_e32 v27, v45
	v_pk_mul_f32 v[26:27], v[26:27], 0.5 op_sel_hi:[1,0]
	v_mov_b32_e32 v47, v102
	v_pk_mul_f32 v[44:45], v[108:109], v[26:27] op_sel:[0,1] op_sel_hi:[0,0]
	v_pk_fma_f32 v[56:57], v[40:41], v[26:27], v[44:45] op_sel_hi:[0,1,1]
	v_pk_fma_f32 v[40:41], v[40:41], v[26:27], v[44:45] op_sel_hi:[0,1,1] neg_lo:[0,0,1] neg_hi:[0,0,1]
	v_mov_b32_e32 v40, v56
	v_pk_fma_f32 v[44:45], v[54:55], 0.5, v[56:57] op_sel_hi:[1,0,1] neg_lo:[0,0,1] neg_hi:[0,0,1]
	v_pk_fma_f32 v[26:27], v[54:55], 0.5, v[40:41] op_sel_hi:[1,0,1]
	v_pk_fma_f32 v[56:57], v[54:55], 0.5, v[40:41] op_sel_hi:[1,0,1] neg_lo:[1,0,0] neg_hi:[1,0,0]
	v_pk_add_f32 v[40:41], v[106:107], v[42:43]
	v_pk_add_f32 v[42:43], v[42:43], v[106:107] neg_lo:[0,1] neg_hi:[0,1]
	v_mov_b32_e32 v45, v27
	v_mul_f32_e32 v6, 0.5, v43
	v_mov_b32_e32 v43, v41
	v_pk_mul_f32 v[120:121], v[44:45], s[46:47] op_sel_hi:[1,0]
	v_mul_f32_e32 v4, 0.5, v40
	v_pk_mov_b32 v[44:45], v[108:109], v[70:71] op_sel:[1,0]
	v_pk_mul_f32 v[40:41], v[42:43], s[44:45]
	v_cvt_f32_f16_sdwa v54, v20 dst_sel:DWORD dst_unused:UNUSED_PAD src0_sel:WORD_1
	v_pk_mul_f32 v[42:43], v[44:45], v[40:41] op_sel:[0,1] op_sel_hi:[1,0]
	v_cvt_f32_f16_e32 v55, v21
	v_cvt_f32_f16_sdwa v21, v21 dst_sel:DWORD dst_unused:UNUSED_PAD src0_sel:WORD_1
	v_cvt_f32_f16_e32 v20, v20
	v_pk_mul_f32 v[40:41], v[44:45], v[40:41]
	v_pk_add_f32 v[42:43], v[42:43], v[42:43] op_sel:[0,1] op_sel_hi:[0,1]
	v_pk_add_f32 v[104:105], v[4:5], v[42:43]
	v_pk_add_f32 v[42:43], v[4:5], v[42:43] op_sel_hi:[0,1] neg_lo:[0,1] neg_hi:[0,1]
	v_pk_add_f32 v[40:41], v[40:41], v[40:41] op_sel:[0,1] op_sel_hi:[0,1] neg_lo:[0,1] neg_hi:[0,1]
	v_mov_b32_e32 v105, v43
	v_pk_add_f32 v[42:43], v[6:7], v[40:41]
	v_pk_add_f32 v[40:41], v[6:7], v[40:41] op_sel_hi:[0,1] neg_lo:[0,1] neg_hi:[0,1]
	v_mov_b32_e32 v43, v41
	v_pk_mul_f32 v[40:41], v[42:43], v[20:21]
	v_pk_mul_f32 v[42:43], v[42:43], v[54:55]
	v_pk_fma_f32 v[40:41], v[104:105], v[54:55], v[40:41]
	v_pk_fma_f32 v[20:21], v[104:105], v[20:21], v[42:43] neg_lo:[0,0,1] neg_hi:[0,0,1]
	v_mov_b32_e32 v71, v109
	v_pk_add_f32 v[42:43], v[20:21], v[40:41] op_sel:[0,1] op_sel_hi:[1,0] neg_lo:[0,1] neg_hi:[0,1]
	v_pk_add_f32 v[54:55], v[20:21], v[40:41] op_sel:[0,1] op_sel_hi:[1,0]
	v_pk_add_f32 v[20:21], v[40:41], v[20:21] op_sel:[1,0] op_sel_hi:[0,1] neg_lo:[0,1] neg_hi:[0,1]
	v_mov_b32_e32 v43, v55
	v_pk_mul_f32 v[42:43], v[42:43], 0.5 op_sel_hi:[1,0]
	v_mov_b32_e32 v55, v21
	v_mul_f32_e32 v4, v109, v42
	v_pk_fma_f32 v[104:105], v[44:45], v[42:43], v[4:5] op_sel_hi:[1,1,0] neg_lo:[1,0,0] neg_hi:[1,0,0]
	v_mul_f32_e32 v4, v109, v43
	v_pk_fma_f32 v[42:43], v[70:71], v[42:43], v[4:5] op_sel_hi:[1,1,0]
	v_sub_f32_e32 v6, v23, v103
	v_mov_b32_e32 v104, v42
	v_pk_fma_f32 v[40:41], v[54:55], 0.5, v[42:43] op_sel_hi:[1,0,1] neg_lo:[0,0,1] neg_hi:[0,0,1]
	v_pk_fma_f32 v[20:21], v[54:55], 0.5, v[104:105] op_sel_hi:[1,0,1]
	v_pk_add_f32 v[42:43], v[102:103], v[22:23]
	v_mov_b32_e32 v41, v21
	v_pk_mul_f32 v[128:129], v[40:41], s[46:47] op_sel_hi:[1,0]
	v_mul_f32_e32 v40, 0xbf0e39da, v83
	v_mov_b32_e32 v41, v22
	v_mul_f32_e32 v18, 0.5, v43
	v_pk_add_f32 v[22:23], v[40:41], v[46:47] neg_lo:[0,1] neg_hi:[0,1]
	v_mov_b32_e32 v47, v109
	v_pk_mul_f32 v[40:41], v[22:23], v[18:19]
	v_mov_b32_e32 v46, v22
	v_pk_fma_f32 v[44:45], v[44:45], v[40:41], v[40:41] op_sel:[0,1,0] op_sel_hi:[1,0,1]
	v_mov_b32_e32 v40, v41
	v_mov_b32_e32 v41, v18
	v_mul_f32_e32 v4, 0.5, v42
	v_pk_mul_f32 v[40:41], v[46:47], v[40:41]
	v_cvt_f32_f16_e32 v46, v10
	v_cvt_f32_f16_e32 v47, v11
	v_cvt_f32_f16_sdwa v11, v11 dst_sel:DWORD dst_unused:UNUSED_PAD src0_sel:WORD_1
	v_cvt_f32_f16_sdwa v10, v10 dst_sel:DWORD dst_unused:UNUSED_PAD src0_sel:WORD_1
	v_pk_fma_f32 v[70:71], v[54:55], 0.5, v[104:105] op_sel_hi:[1,0,1] neg_lo:[1,0,0] neg_hi:[1,0,0]
	v_mul_f32_e32 v6, 0.5, v6
	v_pk_add_f32 v[54:55], v[4:5], v[44:45]
	v_pk_add_f32 v[40:41], v[40:41], v[40:41] op_sel:[0,1] op_sel_hi:[0,1] neg_lo:[0,1] neg_hi:[0,1]
	v_fma_f32 v55, v42, 0.5, -v44
	v_pk_add_f32 v[42:43], v[6:7], v[40:41]
	v_pk_add_f32 v[40:41], v[6:7], v[40:41] op_sel_hi:[0,1] neg_lo:[0,1] neg_hi:[0,1]
	v_mov_b32_e32 v43, v41
	v_pk_mul_f32 v[40:41], v[42:43], v[10:11]
	v_pk_mul_f32 v[42:43], v[42:43], v[46:47]
	v_pk_fma_f32 v[44:45], v[54:55], v[46:47], v[40:41] neg_lo:[0,0,1] neg_hi:[0,0,1]
	v_pk_fma_f32 v[40:41], v[54:55], v[46:47], v[40:41]
	v_pk_fma_f32 v[46:47], v[54:55], v[10:11], v[42:43]
	v_pk_fma_f32 v[10:11], v[54:55], v[10:11], v[42:43] neg_lo:[0,0,1] neg_hi:[0,0,1]
	v_pk_add_f32 v[42:43], v[44:45], v[40:41] op_sel:[0,1] op_sel_hi:[1,0]
	v_pk_add_f32 v[54:55], v[46:47], v[10:11] op_sel_hi:[0,1] neg_lo:[0,1] neg_hi:[0,1]
	v_pk_add_f32 v[40:41], v[44:45], v[40:41] op_sel_hi:[0,1] neg_lo:[0,1] neg_hi:[0,1]
	v_pk_add_f32 v[10:11], v[46:47], v[10:11] op_sel:[0,1] op_sel_hi:[1,0]
	v_mov_b32_e32 v43, v55
	v_mov_b32_e32 v11, v41
	v_pk_mul_f32 v[10:11], v[10:11], 0.5 op_sel_hi:[1,0]
	v_mov_b32_e32 v119, v98
	v_pk_mul_f32 v[40:41], v[108:109], v[10:11] op_sel:[1,1] op_sel_hi:[1,0]
	v_pk_fma_f32 v[76:77], v[76:77], 0.5, v[112:113] op_sel_hi:[1,0,1] neg_lo:[1,0,0] neg_hi:[1,0,0]
	v_pk_fma_f32 v[44:45], v[22:23], v[10:11], v[40:41] op_sel_hi:[0,1,1]
	v_pk_fma_f32 v[10:11], v[22:23], v[10:11], v[40:41] op_sel_hi:[0,1,1] neg_lo:[0,0,1] neg_hi:[0,0,1]
	v_mov_b32_e32 v10, v44
	v_pk_fma_f32 v[22:23], v[42:43], 0.5, v[44:45] op_sel_hi:[1,0,1] neg_lo:[0,0,1] neg_hi:[0,0,1]
	v_pk_fma_f32 v[40:41], v[42:43], 0.5, v[10:11] op_sel_hi:[1,0,1]
	v_pk_fma_f32 v[54:55], v[42:43], 0.5, v[10:11] op_sel_hi:[1,0,1] neg_lo:[1,0,0] neg_hi:[1,0,0]
	v_pk_add_f32 v[10:11], v[100:101], v[14:15]
	v_pk_add_f32 v[14:15], v[14:15], v[100:101] neg_lo:[0,1] neg_hi:[0,1]
	v_mov_b32_e32 v23, v41
	v_mul_f32_e32 v6, 0.5, v15
	v_mov_b32_e32 v15, v11
	v_pk_mul_f32 v[150:151], v[22:23], s[46:47] op_sel_hi:[1,0]
	v_mul_f32_e32 v4, 0.5, v10
	v_pk_mov_b32 v[22:23], v[58:59], v[72:73] op_sel:[1,0]
	v_pk_mul_f32 v[10:11], v[14:15], s[44:45]
	v_cvt_f32_f16_sdwa v42, v8 dst_sel:DWORD dst_unused:UNUSED_PAD src0_sel:WORD_1
	v_pk_mul_f32 v[14:15], v[22:23], v[10:11] op_sel:[0,1] op_sel_hi:[1,0]
	v_cvt_f32_f16_e32 v43, v9
	v_cvt_f32_f16_sdwa v9, v9 dst_sel:DWORD dst_unused:UNUSED_PAD src0_sel:WORD_1
	v_cvt_f32_f16_e32 v8, v8
	v_pk_mul_f32 v[10:11], v[22:23], v[10:11]
	v_pk_add_f32 v[14:15], v[14:15], v[14:15] op_sel:[0,1] op_sel_hi:[0,1]
	v_pk_add_f32 v[44:45], v[4:5], v[14:15]
	v_pk_add_f32 v[14:15], v[4:5], v[14:15] op_sel_hi:[0,1] neg_lo:[0,1] neg_hi:[0,1]
	v_pk_add_f32 v[10:11], v[10:11], v[10:11] op_sel:[0,1] op_sel_hi:[0,1] neg_lo:[0,1] neg_hi:[0,1]
	v_mov_b32_e32 v45, v15
	v_pk_add_f32 v[14:15], v[6:7], v[10:11]
	v_pk_add_f32 v[10:11], v[6:7], v[10:11] op_sel_hi:[0,1] neg_lo:[0,1] neg_hi:[0,1]
	v_mov_b32_e32 v15, v11
	v_pk_mul_f32 v[10:11], v[14:15], v[8:9]
	v_pk_mul_f32 v[14:15], v[14:15], v[42:43]
	v_pk_fma_f32 v[10:11], v[44:45], v[42:43], v[10:11]
	v_pk_fma_f32 v[8:9], v[44:45], v[8:9], v[14:15] neg_lo:[0,0,1] neg_hi:[0,0,1]
	v_mov_b32_e32 v73, v59
	v_pk_add_f32 v[14:15], v[8:9], v[10:11] op_sel:[0,1] op_sel_hi:[1,0] neg_lo:[0,1] neg_hi:[0,1]
	v_pk_add_f32 v[42:43], v[8:9], v[10:11] op_sel:[0,1] op_sel_hi:[1,0]
	v_pk_add_f32 v[8:9], v[10:11], v[8:9] op_sel:[1,0] op_sel_hi:[0,1] neg_lo:[0,1] neg_hi:[0,1]
	v_mov_b32_e32 v15, v43
	v_pk_mul_f32 v[14:15], v[14:15], 0.5 op_sel_hi:[1,0]
	v_mov_b32_e32 v43, v9
	v_mul_f32_e32 v4, v59, v14
	v_pk_fma_f32 v[44:45], v[22:23], v[14:15], v[4:5] op_sel_hi:[1,1,0] neg_lo:[1,0,0] neg_hi:[1,0,0]
	v_mul_f32_e32 v4, v59, v15
	v_pk_fma_f32 v[14:15], v[72:73], v[14:15], v[4:5] op_sel_hi:[1,1,0]
	v_sub_f32_e32 v6, v37, v99
	v_mov_b32_e32 v44, v14
	v_pk_fma_f32 v[8:9], v[42:43], 0.5, v[14:15] op_sel_hi:[1,0,1] neg_lo:[0,0,1] neg_hi:[0,0,1]
	v_pk_fma_f32 v[10:11], v[42:43], 0.5, v[44:45] op_sel_hi:[1,0,1]
	v_pk_add_f32 v[14:15], v[98:99], v[36:37]
	v_mov_b32_e32 v9, v11
	v_pk_mul_f32 v[168:169], v[8:9], s[46:47] op_sel_hi:[1,0]
	v_mul_f32_e32 v8, 0xbf7b14be, v83
	v_mov_b32_e32 v9, v36
	v_mul_f32_e32 v18, 0.5, v15
	v_pk_add_f32 v[8:9], v[8:9], v[118:119] neg_lo:[0,1] neg_hi:[0,1]
	v_pk_fma_f32 v[72:73], v[42:43], 0.5, v[44:45] op_sel_hi:[1,0,1] neg_lo:[1,0,0] neg_hi:[1,0,0]
	v_pk_mul_f32 v[36:37], v[8:9], v[18:19]
	v_mov_b32_e32 v42, v8
	v_pk_fma_f32 v[22:23], v[22:23], v[36:37], v[36:37] op_sel:[0,1,0] op_sel_hi:[1,0,1]
	v_mov_b32_e32 v43, v59
	v_mov_b32_e32 v36, v37
	v_mov_b32_e32 v37, v18
	v_mul_f32_e32 v4, 0.5, v14
	v_pk_mul_f32 v[36:37], v[42:43], v[36:37]
	v_cvt_f32_f16_e32 v44, v2
	v_cvt_f32_f16_e32 v45, v3
	v_cvt_f32_f16_sdwa v3, v3 dst_sel:DWORD dst_unused:UNUSED_PAD src0_sel:WORD_1
	v_cvt_f32_f16_sdwa v2, v2 dst_sel:DWORD dst_unused:UNUSED_PAD src0_sel:WORD_1
	v_mul_f32_e32 v6, 0.5, v6
	v_pk_add_f32 v[46:47], v[4:5], v[22:23]
	v_fma_f32 v4, v14, 0.5, -v22
	v_pk_add_f32 v[22:23], v[36:37], v[36:37] op_sel:[0,1] op_sel_hi:[0,1] neg_lo:[0,1] neg_hi:[0,1]
	v_pk_add_f32 v[36:37], v[6:7], v[22:23]
	v_pk_add_f32 v[22:23], v[6:7], v[22:23] op_sel_hi:[0,1] neg_lo:[0,1] neg_hi:[0,1]
	v_mov_b32_e32 v37, v23
	v_mov_b32_e32 v14, v46
	v_mov_b32_e32 v15, v4
	v_pk_mul_f32 v[22:23], v[4:5], v[44:45] op_sel_hi:[0,1]
	v_pk_mul_f32 v[82:83], v[36:37], v[2:3]
	v_pk_mul_f32 v[46:47], v[46:47], v[2:3]
	v_pk_mul_f32 v[36:37], v[36:37], v[44:45]
	v_pk_fma_f32 v[98:99], v[14:15], v[44:45], v[82:83] neg_lo:[0,0,1] neg_hi:[0,0,1]
	v_pk_fma_f32 v[2:3], v[14:15], v[2:3], v[36:37] neg_lo:[0,0,1] neg_hi:[0,0,1]
	v_add_f32_e32 v4, v23, v83
	v_add_f32_e32 v6, v46, v36
	v_pk_add_f32 v[22:23], v[6:7], v[2:3] op_sel_hi:[0,1] neg_lo:[0,1] neg_hi:[0,1]
	v_pk_add_f32 v[36:37], v[98:99], v[4:5] op_sel_hi:[1,0] neg_lo:[0,1] neg_hi:[0,1]
	v_pk_add_f32 v[2:3], v[6:7], v[2:3] op_sel_hi:[0,1]
	v_mov_b32_e32 v37, v3
	v_pk_mul_f32 v[2:3], v[36:37], 0.5 op_sel_hi:[1,0]
	v_pk_add_f32 v[14:15], v[98:99], v[4:5] op_sel_hi:[1,0]
	v_mul_f32_e32 v4, v59, v3
	v_pk_fma_f32 v[36:37], v[42:43], v[2:3], v[4:5] op_sel_hi:[1,1,0] neg_lo:[0,0,1] neg_hi:[0,0,1]
	v_pk_mov_b32 v[42:43], v[58:59], v[8:9] op_sel:[1,0]
	v_mul_f32_e32 v4, v8, v3
	v_pk_fma_f32 v[2:3], v[42:43], v[2:3], v[4:5] op_sel_hi:[1,1,0]
	v_mov_b32_e32 v15, v23
	v_pk_fma_f32 v[8:9], v[14:15], 0.5, v[2:3] op_sel_hi:[1,0,1] neg_lo:[0,0,1] neg_hi:[0,0,1]
	v_pk_fma_f32 v[42:43], v[14:15], 0.5, v[36:37] op_sel_hi:[1,0,0]
	v_pk_fma_f32 v[2:3], v[14:15], 0.5, v[2:3] op_sel_hi:[1,0,1]
	v_mov_b32_e32 v9, v43
	v_pk_fma_f32 v[58:59], v[22:23], 0.5, v[36:37] op_sel_hi:[1,0,0] neg_lo:[1,0,0] neg_hi:[1,0,0]
	v_pk_mul_f32 v[144:145], v[8:9], s[46:47] op_sel_hi:[1,0]
	v_mov_b32_e32 v58, v2
	v_mov_b32_e32 v72, v10
	v_mov_b32_e32 v54, v40
	v_mov_b32_e32 v70, v20
	v_mov_b32_e32 v56, v26
	v_mov_b32_e32 v76, v38
	v_mov_b32_e32 v52, v34
	v_mov_b32_e32 v74, v86
	v_mov_b32_e32 v48, v84
	v_mov_b32_e32 v50, v60
	v_mov_b32_e32 v28, v66
	v_mov_b32_e32 v32, v96
	v_mov_b32_e32 v12, v88
	v_mov_b32_e32 v16, v92
	v_mov_b32_e32 v4, v138
	v_mov_b32_e32 v6, v122

.LBB0_560:
	s_or_b64 exec, exec, s[0:1]
	v_mov_b32_e32 v2, v142
	s_waitcnt lgkmcnt(0)
	s_barrier
	s_mov_b32 s41, s38
	v_and_b32_e32 v4, 0x1ff, v2
	v_lshlrev_b32_e32 v2, 5, v2
	v_and_or_b32 v2, v2, s34, v4
	v_ashrrev_i32_e32 v6, 5, v2
	v_lshlrev_b32_e32 v2, 3, v2
	v_lshlrev_b32_e32 v7, 3, v6
	v_add3_u32 v2, 0, v2, v7
	v_add_u32_e32 v143, 0x10800, v2
	ds_read_b64 v[128:129], v2
	ds_read_b64 v[130:131], v2 offset:4224
	ds_read_b64 v[144:145], v2 offset:8448
	ds_read_b64 v[148:149], v2 offset:12672
	ds_read_b64 v[150:151], v2 offset:16896
	ds_read_b64 v[152:153], v2 offset:21120
	ds_read_b64 v[154:155], v2 offset:25344
	ds_read_b64 v[156:157], v2 offset:29568
	ds_read_b64 v[158:159], v2 offset:33792
	ds_read_b64 v[160:161], v2 offset:38016
	ds_read_b64 v[162:163], v2 offset:42240
	ds_read_b64 v[164:165], v2 offset:46464
	ds_read_b64 v[166:167], v2 offset:50688
	ds_read_b64 v[168:169], v2 offset:54912
	ds_read_b64 v[170:171], v2 offset:59136
	ds_read_b64 v[172:173], v2 offset:63360
	v_add_u32_e32 v212, 0x11880, v2
	v_add_u32_e32 v213, 0x12900, v2
	v_add_u32_e32 v214, 0x13980, v2
	ds_read_b64 v[174:175], v143
	ds_read_b64 v[176:177], v212
	ds_read_b64 v[178:179], v213
	ds_read_b64 v[180:181], v214
	v_add_u32_e32 v215, 0x14a00, v2
	s_waitcnt lgkmcnt(3)
	v_pk_add_f32 v[210:211], v[128:129], v[174:175]
	v_pk_add_f32 v[128:129], v[128:129], v[174:175] neg_lo:[0,1] neg_hi:[0,1]
	s_waitcnt lgkmcnt(2)
	v_pk_add_f32 v[174:175], v[130:131], v[176:177]
	v_pk_add_f32 v[130:131], v[130:131], v[176:177] neg_lo:[0,1] neg_hi:[0,1]
	v_add_u32_e32 v216, 0x15a80, v2
	v_pk_mul_f32 v[176:177], v[130:131], s[20:21]
	v_add_u32_e32 v217, 0x16b00, v2
	v_pk_fma_f32 v[130:131], v[130:131], s[10:11], v[176:177] op_sel:[0,0,1] op_sel_hi:[1,0,0]
	s_waitcnt lgkmcnt(1)
	v_pk_add_f32 v[176:177], v[144:145], v[178:179]
	v_pk_add_f32 v[144:145], v[144:145], v[178:179] neg_lo:[0,1] neg_hi:[0,1]
	v_add_u32_e32 v218, 0x17b80, v2
	v_pk_mul_f32 v[178:179], v[144:145], s[24:25]
	ds_read_b64 v[182:183], v215
	ds_read_b64 v[184:185], v216
	ds_read_b64 v[186:187], v217
	ds_read_b64 v[188:189], v218
	v_pk_fma_f32 v[144:145], v[144:145], s[22:23], v[178:179] op_sel:[0,0,1] op_sel_hi:[1,0,0]
	s_waitcnt lgkmcnt(4)
	v_pk_add_f32 v[178:179], v[148:149], v[180:181]
	v_pk_add_f32 v[148:149], v[148:149], v[180:181] neg_lo:[0,1] neg_hi:[0,1]
	s_mov_b32 s43, s26
	v_pk_mul_f32 v[180:181], v[148:149], s[36:37]
	s_mov_b32 s0, s37
	v_pk_fma_f32 v[148:149], v[148:149], s[26:27], v[180:181] op_sel:[0,0,1] op_sel_hi:[1,0,0]
	s_waitcnt lgkmcnt(3)
	v_pk_add_f32 v[180:181], v[150:151], v[182:183]
	v_pk_add_f32 v[150:151], v[150:151], v[182:183] neg_lo:[0,1] neg_hi:[0,1]
	s_mov_b32 s45, s22
	v_pk_mul_f32 v[182:183], v[150:151], s[40:41]
	v_add_u32_e32 v219, 0x18c00, v2
	v_pk_fma_f32 v[150:151], v[150:151], s[38:39], v[182:183] op_sel:[0,0,1] op_sel_hi:[1,0,0]
	s_waitcnt lgkmcnt(2)
	v_pk_add_f32 v[182:183], v[152:153], v[184:185]
	v_pk_add_f32 v[152:153], v[152:153], v[184:185] neg_lo:[0,1] neg_hi:[0,1]
	s_mov_b32 s50, s25
	v_pk_mul_f32 v[184:185], v[152:153], s[42:43]
	v_add_u32_e32 v220, 0x19c80, v2
	v_pk_fma_f32 v[152:153], v[152:153], s[0:1], v[184:185] op_sel:[0,0,1] op_sel_hi:[1,0,0]
	s_waitcnt lgkmcnt(1)
	v_pk_add_f32 v[184:185], v[154:155], v[186:187]
	v_pk_add_f32 v[154:155], v[154:155], v[186:187] neg_lo:[0,1] neg_hi:[0,1]
	v_add_u32_e32 v221, 0x1ad00, v2
	v_pk_mul_f32 v[186:187], v[154:155], s[44:45]
	v_add_u32_e32 v222, 0x1bd80, v2
	ds_read_b64 v[190:191], v219
	ds_read_b64 v[192:193], v220
	ds_read_b64 v[194:195], v221
	ds_read_b64 v[196:197], v222
	v_pk_fma_f32 v[154:155], v[154:155], s[50:51], v[186:187] op_sel:[0,0,1] op_sel_hi:[1,0,0]
	s_waitcnt lgkmcnt(4)
	v_pk_add_f32 v[186:187], v[156:157], v[188:189]
	v_pk_add_f32 v[156:157], v[156:157], v[188:189] neg_lo:[0,1] neg_hi:[0,1]
	v_add_u32_e32 v223, 0x1ce00, v2
	v_pk_mul_f32 v[188:189], v[156:157], s[8:9]
	v_add_u32_e32 v224, 0x1de80, v2
	v_pk_fma_f32 v[156:157], v[156:157], s[16:17], v[188:189] op_sel:[0,0,1] op_sel_hi:[1,0,0]
	s_waitcnt lgkmcnt(3)
	v_pk_add_f32 v[188:189], v[158:159], v[190:191]
	v_pk_add_f32 v[190:191], v[158:159], v[190:191] neg_lo:[0,1] neg_hi:[0,1]
	v_add_u32_e32 v225, 0x1ef00, v2
	s_waitcnt lgkmcnt(2)
	v_pk_add_f32 v[158:159], v[160:161], v[192:193]
	v_pk_add_f32 v[160:161], v[160:161], v[192:193] neg_lo:[0,1] neg_hi:[0,1]
	v_add_u32_e32 v226, 0x1ff80, v2
	v_pk_mul_f32 v[192:193], v[160:161], s[8:9]
	ds_read_b64 v[198:199], v223
	ds_read_b64 v[204:205], v224
	ds_read_b64 v[206:207], v225
	ds_read_b64 v[208:209], v226
	v_pk_fma_f32 v[160:161], v[160:161], s[16:17], v[192:193] op_sel:[0,0,1] op_sel_hi:[1,0,0] neg_lo:[1,0,0] neg_hi:[1,0,0]
	s_waitcnt lgkmcnt(5)
	v_pk_add_f32 v[192:193], v[162:163], v[194:195]
	v_pk_add_f32 v[162:163], v[162:163], v[194:195] neg_lo:[0,1] neg_hi:[0,1]
	v_cvt_f32_u32_e32 v5, v4
	v_pk_mul_f32 v[194:195], v[162:163], s[44:45]
	v_mul_f32_e32 v5, 0x38800000, v5
	v_pk_fma_f32 v[162:163], v[162:163], s[50:51], v[194:195] op_sel:[0,0,1] op_sel_hi:[1,0,0] neg_lo:[1,0,0] neg_hi:[1,0,0]
	s_waitcnt lgkmcnt(4)
	v_pk_add_f32 v[194:195], v[164:165], v[196:197]
	v_pk_add_f32 v[164:165], v[164:165], v[196:197] neg_lo:[0,1] neg_hi:[0,1]
	v_sin_f32_e32 v4, v5
	v_pk_mul_f32 v[196:197], v[164:165], s[42:43]
	v_cos_f32_e32 v6, v5
	v_pk_fma_f32 v[164:165], v[164:165], s[0:1], v[196:197] op_sel:[0,0,1] op_sel_hi:[1,0,0] neg_lo:[1,0,0] neg_hi:[1,0,0]
	s_waitcnt lgkmcnt(3)
	v_pk_add_f32 v[196:197], v[166:167], v[198:199]
	v_pk_add_f32 v[166:167], v[166:167], v[198:199] neg_lo:[0,1] neg_hi:[0,1]
	v_xor_b32_e32 v7, 0x80000000, v4
	v_pk_mul_f32 v[198:199], v[166:167], s[40:41]
	v_mov_b32_e32 v5, v7
	v_pk_fma_f32 v[166:167], v[166:167], s[38:39], v[198:199] op_sel:[0,0,1] op_sel_hi:[1,0,0] neg_lo:[1,0,0] neg_hi:[1,0,0]
	s_waitcnt lgkmcnt(2)
	v_pk_add_f32 v[198:199], v[168:169], v[204:205]
	v_pk_add_f32 v[168:169], v[168:169], v[204:205] neg_lo:[0,1] neg_hi:[0,1]
	v_pk_mul_f32 v[8:9], v[6:7], v[4:5] op_sel:[1,0] op_sel_hi:[0,1]
	v_pk_mul_f32 v[204:205], v[168:169], s[36:37]
	v_pk_fma_f32 v[8:9], v[6:7], v[6:7], v[8:9] op_sel_hi:[1,0,1]
	v_pk_fma_f32 v[168:169], v[168:169], s[26:27], v[204:205] op_sel:[0,0,1] op_sel_hi:[1,0,0] neg_lo:[1,0,0] neg_hi:[1,0,0]
	s_waitcnt lgkmcnt(1)
	v_pk_add_f32 v[204:205], v[170:171], v[206:207]
	v_pk_add_f32 v[170:171], v[170:171], v[206:207] neg_lo:[0,1] neg_hi:[0,1]
	v_xor_b32_e32 v14, 0x80000000, v9
	v_pk_mul_f32 v[206:207], v[170:171], s[24:25]
	v_mov_b32_e32 v15, v9
	v_pk_fma_f32 v[170:171], v[170:171], s[22:23], v[206:207] op_sel:[0,0,1] op_sel_hi:[1,0,0] neg_lo:[1,0,0] neg_hi:[1,0,0]
	s_waitcnt lgkmcnt(0)
	v_pk_add_f32 v[206:207], v[172:173], v[208:209]
	v_pk_add_f32 v[172:173], v[172:173], v[208:209] neg_lo:[0,1] neg_hi:[0,1]
	v_pk_mul_f32 v[12:13], v[8:9], v[14:15] op_sel:[1,0] op_sel_hi:[0,1]
	v_pk_mul_f32 v[208:209], v[172:173], s[20:21]
	v_pk_fma_f32 v[12:13], v[8:9], v[8:9], v[12:13] op_sel_hi:[1,0,1]
	v_pk_fma_f32 v[172:173], v[172:173], s[10:11], v[208:209] op_sel:[0,0,1] op_sel_hi:[1,0,0] neg_lo:[1,0,0] neg_hi:[1,0,0]
	v_pk_add_f32 v[208:209], v[210:211], v[188:189]
	v_pk_add_f32 v[188:189], v[210:211], v[188:189] neg_lo:[0,1] neg_hi:[0,1]
	v_pk_add_f32 v[210:211], v[174:175], v[158:159]
	v_pk_add_f32 v[158:159], v[174:175], v[158:159] neg_lo:[0,1] neg_hi:[0,1]
	v_xor_b32_e32 v16, 0x80000000, v13
	v_pk_mul_f32 v[174:175], v[158:159], s[24:25]
	v_mov_b32_e32 v17, v13
	v_pk_fma_f32 v[158:159], v[158:159], s[22:23], v[174:175] op_sel:[0,0,1] op_sel_hi:[1,0,0]
	v_pk_add_f32 v[174:175], v[176:177], v[192:193]
	v_pk_add_f32 v[176:177], v[176:177], v[192:193] neg_lo:[0,1] neg_hi:[0,1]
	v_pk_mul_f32 v[28:29], v[12:13], v[16:17] op_sel:[1,0] op_sel_hi:[0,1]
	v_pk_mul_f32 v[192:193], v[176:177], s[40:41]
	v_pk_fma_f32 v[28:29], v[12:13], v[12:13], v[28:29] op_sel_hi:[1,0,1]
	v_pk_fma_f32 v[176:177], v[176:177], s[38:39], v[192:193] op_sel:[0,0,1] op_sel_hi:[1,0,0]
	v_pk_add_f32 v[192:193], v[178:179], v[194:195]
	v_pk_add_f32 v[178:179], v[178:179], v[194:195] neg_lo:[0,1] neg_hi:[0,1]
	v_pk_mul_f32 v[44:45], v[16:17], v[28:29] op_sel:[0,1] op_sel_hi:[1,0]
	v_pk_mul_f32 v[194:195], v[178:179], s[44:45]
	v_pk_fma_f32 v[44:45], v[12:13], v[28:29], v[44:45] op_sel_hi:[0,1,1]
	v_pk_fma_f32 v[178:179], v[178:179], s[50:51], v[194:195] op_sel:[0,0,1] op_sel_hi:[1,0,0]
	v_pk_add_f32 v[194:195], v[180:181], v[196:197]
	v_pk_add_f32 v[196:197], v[180:181], v[196:197] neg_lo:[0,1] neg_hi:[0,1]
	v_pk_mul_f32 v[60:61], v[16:17], v[44:45] op_sel:[0,1] op_sel_hi:[1,0]
	v_pk_add_f32 v[180:181], v[182:183], v[198:199]
	v_pk_add_f32 v[182:183], v[182:183], v[198:199] neg_lo:[0,1] neg_hi:[0,1]
	v_pk_fma_f32 v[60:61], v[12:13], v[44:45], v[60:61] op_sel_hi:[0,1,1]
	v_pk_mul_f32 v[198:199], v[182:183], s[44:45]
	v_pk_mul_f32 v[76:77], v[16:17], v[60:61] op_sel:[0,1] op_sel_hi:[1,0]
	v_pk_fma_f32 v[182:183], v[182:183], s[50:51], v[198:199] op_sel:[0,0,1] op_sel_hi:[1,0,0] neg_lo:[1,0,0] neg_hi:[1,0,0]
	v_pk_add_f32 v[198:199], v[184:185], v[204:205]
	v_pk_add_f32 v[184:185], v[184:185], v[204:205] neg_lo:[0,1] neg_hi:[0,1]
	v_pk_fma_f32 v[76:77], v[12:13], v[60:61], v[76:77] op_sel_hi:[0,1,1]
	v_pk_mul_f32 v[204:205], v[184:185], s[40:41]
	v_pk_mul_f32 v[92:93], v[16:17], v[76:77] op_sel:[0,1] op_sel_hi:[1,0]
	v_pk_fma_f32 v[184:185], v[184:185], s[38:39], v[204:205] op_sel:[0,0,1] op_sel_hi:[1,0,0] neg_lo:[1,0,0] neg_hi:[1,0,0]
	v_pk_add_f32 v[204:205], v[186:187], v[206:207]
	v_pk_add_f32 v[186:187], v[186:187], v[206:207] neg_lo:[0,1] neg_hi:[0,1]
	v_pk_fma_f32 v[92:93], v[12:13], v[76:77], v[92:93] op_sel_hi:[0,1,1]
	v_pk_mul_f32 v[206:207], v[186:187], s[24:25]
	v_pk_mul_f32 v[108:109], v[16:17], v[92:93] op_sel:[0,1] op_sel_hi:[1,0]
	v_pk_fma_f32 v[186:187], v[186:187], s[22:23], v[206:207] op_sel:[0,0,1] op_sel_hi:[1,0,0] neg_lo:[1,0,0] neg_hi:[1,0,0]
	v_pk_add_f32 v[206:207], v[128:129], v[190:191] op_sel:[0,1] op_sel_hi:[1,0] neg_hi:[0,1]
	v_pk_add_f32 v[128:129], v[128:129], v[190:191] op_sel:[0,1] op_sel_hi:[1,0] neg_lo:[0,1]
	v_pk_add_f32 v[190:191], v[130:131], v[160:161]
	v_pk_add_f32 v[130:131], v[130:131], v[160:161] neg_lo:[0,1] neg_hi:[0,1]
	v_pk_mul_f32 v[10:11], v[4:5], v[8:9] op_sel:[0,1] op_sel_hi:[1,0]
	v_pk_mul_f32 v[160:161], v[130:131], s[24:25]
	v_pk_fma_f32 v[108:109], v[12:13], v[92:93], v[108:109] op_sel_hi:[0,1,1]
	v_pk_fma_f32 v[130:131], v[130:131], s[22:23], v[160:161] op_sel:[0,0,1] op_sel_hi:[1,0,0]
	v_pk_add_f32 v[160:161], v[144:145], v[162:163]
	v_pk_add_f32 v[144:145], v[144:145], v[162:163] neg_lo:[0,1] neg_hi:[0,1]
	v_pk_fma_f32 v[10:11], v[6:7], v[8:9], v[10:11] op_sel_hi:[0,1,1]
	v_pk_mul_f32 v[162:163], v[144:145], s[40:41]
	v_pk_mul_f32 v[18:19], v[4:5], v[12:13] op_sel:[0,1] op_sel_hi:[1,0]
	v_pk_fma_f32 v[144:145], v[144:145], s[38:39], v[162:163] op_sel:[0,0,1] op_sel_hi:[1,0,0]
	v_pk_add_f32 v[162:163], v[148:149], v[164:165]
	v_pk_add_f32 v[148:149], v[148:149], v[164:165] neg_lo:[0,1] neg_hi:[0,1]
	v_pk_mul_f32 v[32:33], v[4:5], v[28:29] op_sel:[0,1] op_sel_hi:[1,0]
	v_pk_mul_f32 v[164:165], v[148:149], s[44:45]
	v_pk_mul_f32 v[48:49], v[4:5], v[44:45] op_sel:[0,1] op_sel_hi:[1,0]
	v_pk_fma_f32 v[148:149], v[148:149], s[50:51], v[164:165] op_sel:[0,0,1] op_sel_hi:[1,0,0]
	v_pk_add_f32 v[164:165], v[150:151], v[166:167]
	v_pk_add_f32 v[166:167], v[150:151], v[166:167] neg_lo:[0,1] neg_hi:[0,1]
	v_pk_mul_f32 v[64:65], v[4:5], v[60:61] op_sel:[0,1] op_sel_hi:[1,0]
	v_pk_add_f32 v[150:151], v[152:153], v[168:169]
	v_pk_add_f32 v[152:153], v[152:153], v[168:169] neg_lo:[0,1] neg_hi:[0,1]
	v_pk_mul_f32 v[80:81], v[4:5], v[76:77] op_sel:[0,1] op_sel_hi:[1,0]
	v_pk_mul_f32 v[168:169], v[152:153], s[44:45]
	v_pk_mul_f32 v[96:97], v[4:5], v[92:93] op_sel:[0,1] op_sel_hi:[1,0]
	v_pk_fma_f32 v[152:153], v[152:153], s[50:51], v[168:169] op_sel:[0,0,1] op_sel_hi:[1,0,0] neg_lo:[1,0,0] neg_hi:[1,0,0]
	v_pk_add_f32 v[168:169], v[154:155], v[170:171]
	v_pk_add_f32 v[154:155], v[154:155], v[170:171] neg_lo:[0,1] neg_hi:[0,1]
	v_pk_mul_f32 v[112:113], v[4:5], v[108:109] op_sel:[0,1] op_sel_hi:[1,0]
	v_pk_mul_f32 v[170:171], v[154:155], s[40:41]
	v_xor_b32_e32 v22, 0x80000000, v11
	v_pk_fma_f32 v[154:155], v[154:155], s[38:39], v[170:171] op_sel:[0,0,1] op_sel_hi:[1,0,0] neg_lo:[1,0,0] neg_hi:[1,0,0]
	v_pk_add_f32 v[170:171], v[156:157], v[172:173]
	v_pk_add_f32 v[156:157], v[156:157], v[172:173] neg_lo:[0,1] neg_hi:[0,1]
	v_mov_b32_e32 v23, v11
	v_pk_mul_f32 v[172:173], v[156:157], s[24:25]
	v_pk_fma_f32 v[18:19], v[6:7], v[12:13], v[18:19] op_sel_hi:[0,1,1]
	v_pk_fma_f32 v[156:157], v[156:157], s[22:23], v[172:173] op_sel:[0,0,1] op_sel_hi:[1,0,0] neg_lo:[1,0,0] neg_hi:[1,0,0]
	v_pk_add_f32 v[172:173], v[208:209], v[194:195]
	v_pk_add_f32 v[194:195], v[208:209], v[194:195] neg_lo:[0,1] neg_hi:[0,1]
	v_pk_add_f32 v[208:209], v[210:211], v[180:181]
	v_pk_add_f32 v[180:181], v[210:211], v[180:181] neg_lo:[0,1] neg_hi:[0,1]
	v_pk_mul_f32 v[20:21], v[14:15], v[12:13] op_sel:[0,1] op_sel_hi:[1,0]
	v_pk_mul_f32 v[210:211], v[180:181], s[40:41]
	v_pk_fma_f32 v[32:33], v[6:7], v[28:29], v[32:33] op_sel_hi:[0,1,1]
	v_pk_fma_f32 v[180:181], v[180:181], s[38:39], v[210:211] op_sel:[0,0,1] op_sel_hi:[1,0,0]
	v_pk_add_f32 v[210:211], v[174:175], v[198:199]
	v_pk_add_f32 v[198:199], v[174:175], v[198:199] neg_lo:[0,1] neg_hi:[0,1]
	v_pk_mul_f32 v[36:37], v[14:15], v[28:29] op_sel:[0,1] op_sel_hi:[1,0]
	v_pk_add_f32 v[174:175], v[192:193], v[204:205]
	v_pk_add_f32 v[192:193], v[192:193], v[204:205] neg_lo:[0,1] neg_hi:[0,1]
	v_pk_fma_f32 v[48:49], v[6:7], v[44:45], v[48:49] op_sel_hi:[0,1,1]
	v_pk_mul_f32 v[204:205], v[192:193], s[40:41]
	v_pk_mul_f32 v[52:53], v[14:15], v[44:45] op_sel:[0,1] op_sel_hi:[1,0]
	v_pk_fma_f32 v[192:193], v[192:193], s[38:39], v[204:205] op_sel:[0,0,1] op_sel_hi:[1,0,0] neg_lo:[1,0,0] neg_hi:[1,0,0]
	v_pk_add_f32 v[204:205], v[188:189], v[196:197] op_sel:[0,1] op_sel_hi:[1,0] neg_hi:[0,1]
	v_pk_add_f32 v[188:189], v[188:189], v[196:197] op_sel:[0,1] op_sel_hi:[1,0] neg_lo:[0,1]
	v_pk_add_f32 v[196:197], v[158:159], v[182:183]
	v_pk_add_f32 v[158:159], v[158:159], v[182:183] neg_lo:[0,1] neg_hi:[0,1]
	v_pk_fma_f32 v[64:65], v[6:7], v[60:61], v[64:65] op_sel_hi:[0,1,1]
	v_pk_mul_f32 v[182:183], v[158:159], s[40:41]
	v_pk_mul_f32 v[68:69], v[14:15], v[60:61] op_sel:[0,1] op_sel_hi:[1,0]
	v_pk_fma_f32 v[158:159], v[158:159], s[38:39], v[182:183] op_sel:[0,0,1] op_sel_hi:[1,0,0]
	v_pk_add_f32 v[182:183], v[176:177], v[184:185]
	v_pk_add_f32 v[184:185], v[176:177], v[184:185] neg_lo:[0,1] neg_hi:[0,1]
	v_pk_fma_f32 v[80:81], v[6:7], v[76:77], v[80:81] op_sel_hi:[0,1,1]
	v_pk_add_f32 v[176:177], v[178:179], v[186:187]
	v_pk_add_f32 v[178:179], v[178:179], v[186:187] neg_lo:[0,1] neg_hi:[0,1]
	v_pk_mul_f32 v[84:85], v[14:15], v[76:77] op_sel:[0,1] op_sel_hi:[1,0]
	v_pk_mul_f32 v[186:187], v[178:179], s[40:41]
	v_pk_fma_f32 v[96:97], v[6:7], v[92:93], v[96:97] op_sel_hi:[0,1,1]
	v_pk_fma_f32 v[178:179], v[178:179], s[38:39], v[186:187] op_sel:[0,0,1] op_sel_hi:[1,0,0] neg_lo:[1,0,0] neg_hi:[1,0,0]
	v_pk_add_f32 v[186:187], v[206:207], v[164:165]
	v_pk_add_f32 v[164:165], v[206:207], v[164:165] neg_lo:[0,1] neg_hi:[0,1]
	v_pk_add_f32 v[206:207], v[190:191], v[150:151]
	v_pk_add_f32 v[150:151], v[190:191], v[150:151] neg_lo:[0,1] neg_hi:[0,1]
	v_pk_mul_f32 v[100:101], v[14:15], v[92:93] op_sel:[0,1] op_sel_hi:[1,0]
	v_pk_mul_f32 v[190:191], v[150:151], s[40:41]
	v_pk_fma_f32 v[112:113], v[6:7], v[108:109], v[112:113] op_sel_hi:[0,1,1]
	v_pk_fma_f32 v[150:151], v[150:151], s[38:39], v[190:191] op_sel:[0,0,1] op_sel_hi:[1,0,0]
	v_pk_add_f32 v[190:191], v[160:161], v[168:169]
	v_pk_add_f32 v[168:169], v[160:161], v[168:169] neg_lo:[0,1] neg_hi:[0,1]
	v_pk_mul_f32 v[116:117], v[14:15], v[108:109] op_sel:[0,1] op_sel_hi:[1,0]
	v_pk_add_f32 v[160:161], v[162:163], v[170:171]
	v_pk_add_f32 v[162:163], v[162:163], v[170:171] neg_lo:[0,1] neg_hi:[0,1]
	v_pk_fma_f32 v[20:21], v[8:9], v[12:13], v[20:21] op_sel_hi:[0,1,1]
	v_pk_mul_f32 v[170:171], v[162:163], s[40:41]
	v_pk_mul_f32 v[24:25], v[12:13], v[22:23] op_sel:[1,0] op_sel_hi:[0,1]
	v_pk_fma_f32 v[162:163], v[162:163], s[38:39], v[170:171] op_sel:[0,0,1] op_sel_hi:[1,0,0] neg_lo:[1,0,0] neg_hi:[1,0,0]
	v_pk_add_f32 v[170:171], v[128:129], v[166:167] op_sel:[0,1] op_sel_hi:[1,0] neg_hi:[0,1]
	v_pk_add_f32 v[128:129], v[128:129], v[166:167] op_sel:[0,1] op_sel_hi:[1,0] neg_lo:[0,1]
	v_pk_add_f32 v[166:167], v[130:131], v[152:153]
	v_pk_add_f32 v[130:131], v[130:131], v[152:153] neg_lo:[0,1] neg_hi:[0,1]
	v_pk_fma_f32 v[36:37], v[8:9], v[28:29], v[36:37] op_sel_hi:[0,1,1]
	v_pk_mul_f32 v[152:153], v[130:131], s[40:41]
	v_pk_mul_f32 v[40:41], v[22:23], v[28:29] op_sel:[0,1] op_sel_hi:[1,0]
	v_pk_fma_f32 v[130:131], v[130:131], s[38:39], v[152:153] op_sel:[0,0,1] op_sel_hi:[1,0,0]
	v_pk_add_f32 v[152:153], v[144:145], v[154:155]
	v_pk_add_f32 v[154:155], v[144:145], v[154:155] neg_lo:[0,1] neg_hi:[0,1]
	v_pk_fma_f32 v[52:53], v[8:9], v[44:45], v[52:53] op_sel_hi:[0,1,1]
	v_pk_add_f32 v[144:145], v[148:149], v[156:157]
	v_pk_add_f32 v[148:149], v[148:149], v[156:157] neg_lo:[0,1] neg_hi:[0,1]
	v_pk_mul_f32 v[56:57], v[22:23], v[44:45] op_sel:[0,1] op_sel_hi:[1,0]
	v_pk_mul_f32 v[156:157], v[148:149], s[40:41]
	v_pk_fma_f32 v[68:69], v[8:9], v[60:61], v[68:69] op_sel_hi:[0,1,1]
	v_pk_fma_f32 v[148:149], v[148:149], s[38:39], v[156:157] op_sel:[0,0,1] op_sel_hi:[1,0,0] neg_lo:[1,0,0] neg_hi:[1,0,0]
	v_pk_add_f32 v[156:157], v[172:173], v[210:211]
	v_pk_add_f32 v[172:173], v[172:173], v[210:211] neg_lo:[0,1] neg_hi:[0,1]
	v_pk_add_f32 v[210:211], v[208:209], v[174:175]
	v_pk_add_f32 v[208:209], v[208:209], v[174:175] neg_lo:[0,1] neg_hi:[0,1]
	v_pk_mul_f32 v[72:73], v[22:23], v[60:61] op_sel:[0,1] op_sel_hi:[1,0]
	v_pk_add_f32 v[174:175], v[194:195], v[198:199] op_sel:[0,1] op_sel_hi:[1,0] neg_hi:[0,1]
	v_pk_add_f32 v[194:195], v[194:195], v[198:199] op_sel:[0,1] op_sel_hi:[1,0] neg_lo:[0,1]
	v_pk_add_f32 v[198:199], v[180:181], v[192:193]
	v_pk_add_f32 v[192:193], v[180:181], v[192:193] neg_lo:[0,1] neg_hi:[0,1]
	v_pk_fma_f32 v[84:85], v[8:9], v[76:77], v[84:85] op_sel_hi:[0,1,1]
	v_pk_add_f32 v[180:181], v[204:205], v[182:183]
	v_pk_add_f32 v[182:183], v[204:205], v[182:183] neg_lo:[0,1] neg_hi:[0,1]
	v_pk_add_f32 v[204:205], v[196:197], v[176:177]
	v_pk_add_f32 v[196:197], v[196:197], v[176:177] neg_lo:[0,1] neg_hi:[0,1]
	v_pk_mul_f32 v[88:89], v[22:23], v[76:77] op_sel:[0,1] op_sel_hi:[1,0]
	v_pk_add_f32 v[176:177], v[188:189], v[184:185] op_sel:[0,1] op_sel_hi:[1,0] neg_hi:[0,1]
	v_pk_add_f32 v[184:185], v[188:189], v[184:185] op_sel:[0,1] op_sel_hi:[1,0] neg_lo:[0,1]
	v_pk_add_f32 v[188:189], v[158:159], v[178:179]
	v_pk_add_f32 v[178:179], v[158:159], v[178:179] neg_lo:[0,1] neg_hi:[0,1]
	v_pk_fma_f32 v[100:101], v[8:9], v[92:93], v[100:101] op_sel_hi:[0,1,1]
	v_pk_add_f32 v[158:159], v[186:187], v[190:191]
	v_pk_add_f32 v[186:187], v[186:187], v[190:191] neg_lo:[0,1] neg_hi:[0,1]
	v_pk_add_f32 v[190:191], v[206:207], v[160:161]
	v_pk_add_f32 v[206:207], v[206:207], v[160:161] neg_lo:[0,1] neg_hi:[0,1]
	v_pk_mul_f32 v[104:105], v[22:23], v[92:93] op_sel:[0,1] op_sel_hi:[1,0]
	v_pk_add_f32 v[160:161], v[164:165], v[168:169] op_sel:[0,1] op_sel_hi:[1,0] neg_hi:[0,1]
	v_pk_add_f32 v[164:165], v[164:165], v[168:169] op_sel:[0,1] op_sel_hi:[1,0] neg_lo:[0,1]
	v_pk_add_f32 v[168:169], v[150:151], v[162:163]
	v_pk_add_f32 v[162:163], v[150:151], v[162:163] neg_lo:[0,1] neg_hi:[0,1]
	v_pk_fma_f32 v[116:117], v[8:9], v[108:109], v[116:117] op_sel_hi:[0,1,1]
	v_pk_add_f32 v[150:151], v[170:171], v[152:153]
	v_pk_add_f32 v[152:153], v[170:171], v[152:153] neg_lo:[0,1] neg_hi:[0,1]
	v_pk_add_f32 v[170:171], v[166:167], v[144:145]
	v_pk_add_f32 v[166:167], v[166:167], v[144:145] neg_lo:[0,1] neg_hi:[0,1]
	v_pk_mul_f32 v[120:121], v[22:23], v[108:109] op_sel:[0,1] op_sel_hi:[1,0]
	v_pk_add_f32 v[144:145], v[128:129], v[154:155] op_sel:[0,1] op_sel_hi:[1,0] neg_hi:[0,1]
	v_pk_add_f32 v[128:129], v[128:129], v[154:155] op_sel:[0,1] op_sel_hi:[1,0] neg_lo:[0,1]
	v_pk_add_f32 v[154:155], v[130:131], v[148:149]
	v_pk_add_f32 v[148:149], v[130:131], v[148:149] neg_lo:[0,1] neg_hi:[0,1]
	v_xor_b32_e32 v26, 0x80000000, v19
	v_pk_add_f32 v[130:131], v[156:157], v[210:211]
	v_pk_add_f32 v[156:157], v[156:157], v[210:211] neg_lo:[0,1] neg_hi:[0,1]
	v_pk_add_f32 v[210:211], v[172:173], v[208:209] op_sel:[0,1] op_sel_hi:[1,0] neg_hi:[0,1]
	v_pk_add_f32 v[172:173], v[172:173], v[208:209] op_sel:[0,1] op_sel_hi:[1,0] neg_lo:[0,1]
	v_pk_add_f32 v[208:209], v[174:175], v[198:199]
	v_pk_add_f32 v[174:175], v[174:175], v[198:199] neg_lo:[0,1] neg_hi:[0,1]
	v_pk_add_f32 v[198:199], v[194:195], v[192:193] op_sel:[0,1] op_sel_hi:[1,0] neg_hi:[0,1]
	v_pk_add_f32 v[192:193], v[194:195], v[192:193] op_sel:[0,1] op_sel_hi:[1,0] neg_lo:[0,1]
	v_pk_add_f32 v[194:195], v[180:181], v[204:205]
	v_pk_add_f32 v[180:181], v[180:181], v[204:205] neg_lo:[0,1] neg_hi:[0,1]
	v_pk_add_f32 v[204:205], v[182:183], v[196:197] op_sel:[0,1] op_sel_hi:[1,0] neg_hi:[0,1]
	v_pk_add_f32 v[182:183], v[182:183], v[196:197] op_sel:[0,1] op_sel_hi:[1,0] neg_lo:[0,1]
	v_pk_add_f32 v[196:197], v[176:177], v[188:189]
	v_pk_add_f32 v[176:177], v[176:177], v[188:189] neg_lo:[0,1] neg_hi:[0,1]
	v_pk_add_f32 v[188:189], v[184:185], v[178:179] op_sel:[0,1] op_sel_hi:[1,0] neg_hi:[0,1]
	v_pk_add_f32 v[178:179], v[184:185], v[178:179] op_sel:[0,1] op_sel_hi:[1,0] neg_lo:[0,1]
	v_pk_add_f32 v[184:185], v[158:159], v[190:191]
	v_pk_add_f32 v[158:159], v[158:159], v[190:191] neg_lo:[0,1] neg_hi:[0,1]
	v_pk_mul_f32 v[4:5], v[4:5], v[184:185] op_sel:[0,1] op_sel_hi:[1,0]
	v_pk_add_f32 v[190:191], v[186:187], v[206:207] op_sel:[0,1] op_sel_hi:[1,0] neg_hi:[0,1]
	v_pk_add_f32 v[186:187], v[186:187], v[206:207] op_sel:[0,1] op_sel_hi:[1,0] neg_lo:[0,1]
	v_pk_add_f32 v[206:207], v[160:161], v[168:169]
	v_pk_add_f32 v[160:161], v[160:161], v[168:169] neg_lo:[0,1] neg_hi:[0,1]
	v_pk_add_f32 v[168:169], v[164:165], v[162:163] op_sel:[0,1] op_sel_hi:[1,0] neg_hi:[0,1]
	v_pk_add_f32 v[162:163], v[164:165], v[162:163] op_sel:[0,1] op_sel_hi:[1,0] neg_lo:[0,1]
	v_pk_add_f32 v[164:165], v[150:151], v[170:171]
	v_pk_fma_f32 v[4:5], v[6:7], v[184:185], v[4:5] op_sel_hi:[0,1,1]
	v_pk_mul_f32 v[6:7], v[14:15], v[194:195] op_sel:[0,1] op_sel_hi:[1,0]
	v_xor_b32_e32 v30, 0x80000000, v21
	v_pk_fma_f32 v[6:7], v[8:9], v[194:195], v[6:7] op_sel_hi:[0,1,1]
	v_pk_mul_f32 v[8:9], v[22:23], v[164:165] op_sel:[0,1] op_sel_hi:[1,0]
	v_pk_fma_f32 v[24:25], v[12:13], v[10:11], v[24:25] op_sel_hi:[1,0,1]
	v_pk_fma_f32 v[40:41], v[10:11], v[28:29], v[40:41] op_sel_hi:[0,1,1]
	v_pk_fma_f32 v[56:57], v[10:11], v[44:45], v[56:57] op_sel_hi:[0,1,1]
	v_pk_fma_f32 v[72:73], v[10:11], v[60:61], v[72:73] op_sel_hi:[0,1,1]
	v_pk_fma_f32 v[88:89], v[10:11], v[76:77], v[88:89] op_sel_hi:[0,1,1]
	v_pk_fma_f32 v[104:105], v[10:11], v[92:93], v[104:105] op_sel_hi:[0,1,1]
	v_pk_fma_f32 v[120:121], v[10:11], v[108:109], v[120:121] op_sel_hi:[0,1,1]
	v_mov_b32_e32 v27, v19
	v_mov_b32_e32 v31, v21
	v_pk_fma_f32 v[8:9], v[10:11], v[164:165], v[8:9] op_sel_hi:[0,1,1]
	v_pk_mul_f32 v[10:11], v[16:17], v[208:209] op_sel:[0,1] op_sel_hi:[1,0]
	v_xor_b32_e32 v34, 0x80000000, v25
	v_xor_b32_e32 v38, 0x80000000, v29
	v_xor_b32_e32 v42, 0x80000000, v33
	v_xor_b32_e32 v46, 0x80000000, v37
	v_mov_b32_e32 v35, v25
	v_mov_b32_e32 v39, v29
	v_mov_b32_e32 v43, v33
	v_mov_b32_e32 v47, v37
	v_pk_add_f32 v[150:151], v[150:151], v[170:171] neg_lo:[0,1] neg_hi:[0,1]
	v_pk_add_f32 v[170:171], v[152:153], v[166:167] op_sel:[0,1] op_sel_hi:[1,0] neg_hi:[0,1]
	v_pk_add_f32 v[152:153], v[152:153], v[166:167] op_sel:[0,1] op_sel_hi:[1,0] neg_lo:[0,1]
	v_pk_add_f32 v[166:167], v[144:145], v[154:155]
	v_pk_fma_f32 v[10:11], v[12:13], v[208:209], v[10:11] op_sel_hi:[0,1,1]
	v_pk_mul_f32 v[12:13], v[26:27], v[206:207] op_sel:[0,1] op_sel_hi:[1,0]
	v_pk_mul_f32 v[14:15], v[30:31], v[196:197] op_sel:[0,1] op_sel_hi:[1,0]
	v_xor_b32_e32 v50, 0x80000000, v41
	v_xor_b32_e32 v54, 0x80000000, v45
	v_xor_b32_e32 v58, 0x80000000, v49
	v_xor_b32_e32 v62, 0x80000000, v53
	v_xor_b32_e32 v66, 0x80000000, v57
	v_xor_b32_e32 v70, 0x80000000, v61
	v_xor_b32_e32 v74, 0x80000000, v65
	v_mov_b32_e32 v51, v41
	v_mov_b32_e32 v55, v45
	v_mov_b32_e32 v59, v49
	v_mov_b32_e32 v63, v53
	v_mov_b32_e32 v67, v57
	v_mov_b32_e32 v71, v61
	v_mov_b32_e32 v75, v65
	v_pk_add_f32 v[144:145], v[144:145], v[154:155] neg_lo:[0,1] neg_hi:[0,1]
	v_pk_add_f32 v[154:155], v[128:129], v[148:149] op_sel:[0,1] op_sel_hi:[1,0] neg_hi:[0,1]
	v_pk_fma_f32 v[12:13], v[18:19], v[206:207], v[12:13] op_sel_hi:[0,1,1]
	v_pk_fma_f32 v[14:15], v[20:21], v[196:197], v[14:15] op_sel_hi:[0,1,1]
	v_pk_mul_f32 v[16:17], v[34:35], v[166:167] op_sel:[0,1] op_sel_hi:[1,0]
	v_pk_mul_f32 v[18:19], v[38:39], v[210:211] op_sel:[0,1] op_sel_hi:[1,0]
	v_pk_mul_f32 v[20:21], v[42:43], v[190:191] op_sel:[0,1] op_sel_hi:[1,0]
	v_pk_mul_f32 v[22:23], v[46:47], v[204:205] op_sel:[0,1] op_sel_hi:[1,0]
	v_xor_b32_e32 v78, 0x80000000, v69
	v_xor_b32_e32 v82, 0x80000000, v73
	v_xor_b32_e32 v86, 0x80000000, v77
	v_xor_b32_e32 v90, 0x80000000, v81
	v_xor_b32_e32 v94, 0x80000000, v85
	v_xor_b32_e32 v98, 0x80000000, v89
	v_xor_b32_e32 v102, 0x80000000, v93
	v_xor_b32_e32 v106, 0x80000000, v97
	v_xor_b32_e32 v110, 0x80000000, v101
	v_xor_b32_e32 v114, 0x80000000, v105
	v_xor_b32_e32 v118, 0x80000000, v109
	v_xor_b32_e32 v122, 0x80000000, v113
	v_xor_b32_e32 v124, 0x80000000, v117
	v_xor_b32_e32 v126, 0x80000000, v121
	v_mov_b32_e32 v79, v69
	v_mov_b32_e32 v83, v73
	v_mov_b32_e32 v87, v77
	v_mov_b32_e32 v91, v81
	v_mov_b32_e32 v95, v85
	v_mov_b32_e32 v99, v89
	v_mov_b32_e32 v103, v93
	v_mov_b32_e32 v107, v97
	v_mov_b32_e32 v111, v101
	v_mov_b32_e32 v115, v105
	v_mov_b32_e32 v119, v109
	v_mov_b32_e32 v123, v113
	v_mov_b32_e32 v125, v117
	v_mov_b32_e32 v127, v121
	v_pk_add_f32 v[128:129], v[128:129], v[148:149] op_sel:[0,1] op_sel_hi:[1,0] neg_lo:[0,1]
	v_pk_fma_f32 v[16:17], v[24:25], v[166:167], v[16:17] op_sel_hi:[0,1,1]
	v_pk_fma_f32 v[18:19], v[28:29], v[210:211], v[18:19] op_sel_hi:[0,1,1]
	v_pk_fma_f32 v[20:21], v[32:33], v[190:191], v[20:21] op_sel_hi:[0,1,1]
	v_pk_fma_f32 v[22:23], v[36:37], v[204:205], v[22:23] op_sel_hi:[0,1,1]
	v_pk_mul_f32 v[24:25], v[50:51], v[170:171] op_sel:[0,1] op_sel_hi:[1,0]
	v_pk_mul_f32 v[26:27], v[54:55], v[198:199] op_sel:[0,1] op_sel_hi:[1,0]
	v_pk_mul_f32 v[28:29], v[58:59], v[168:169] op_sel:[0,1] op_sel_hi:[1,0]
	v_pk_mul_f32 v[30:31], v[62:63], v[188:189] op_sel:[0,1] op_sel_hi:[1,0]
	v_pk_mul_f32 v[32:33], v[66:67], v[154:155] op_sel:[0,1] op_sel_hi:[1,0]
	v_pk_mul_f32 v[34:35], v[70:71], v[156:157] op_sel:[0,1] op_sel_hi:[1,0]
	v_pk_mul_f32 v[36:37], v[74:75], v[158:159] op_sel:[0,1] op_sel_hi:[1,0]
	v_pk_fma_f32 v[24:25], v[40:41], v[170:171], v[24:25] op_sel_hi:[0,1,1]
	v_pk_fma_f32 v[26:27], v[44:45], v[198:199], v[26:27] op_sel_hi:[0,1,1]
	v_pk_fma_f32 v[28:29], v[48:49], v[168:169], v[28:29] op_sel_hi:[0,1,1]
	v_pk_fma_f32 v[30:31], v[52:53], v[188:189], v[30:31] op_sel_hi:[0,1,1]
	v_pk_fma_f32 v[32:33], v[56:57], v[154:155], v[32:33] op_sel_hi:[0,1,1]
	v_pk_fma_f32 v[34:35], v[60:61], v[156:157], v[34:35] op_sel_hi:[0,1,1]
	v_pk_fma_f32 v[36:37], v[64:65], v[158:159], v[36:37] op_sel_hi:[0,1,1]
	v_pk_mul_f32 v[38:39], v[78:79], v[180:181] op_sel:[0,1] op_sel_hi:[1,0]
	v_pk_mul_f32 v[40:41], v[82:83], v[150:151] op_sel:[0,1] op_sel_hi:[1,0]
	v_pk_mul_f32 v[42:43], v[86:87], v[174:175] op_sel:[0,1] op_sel_hi:[1,0]
	v_pk_mul_f32 v[44:45], v[90:91], v[160:161] op_sel:[0,1] op_sel_hi:[1,0]
	v_pk_mul_f32 v[46:47], v[94:95], v[176:177] op_sel:[0,1] op_sel_hi:[1,0]
	v_pk_mul_f32 v[48:49], v[98:99], v[144:145] op_sel:[0,1] op_sel_hi:[1,0]
	v_pk_mul_f32 v[50:51], v[102:103], v[172:173] op_sel:[0,1] op_sel_hi:[1,0]
	v_pk_mul_f32 v[52:53], v[106:107], v[186:187] op_sel:[0,1] op_sel_hi:[1,0]
	v_pk_mul_f32 v[54:55], v[110:111], v[182:183] op_sel:[0,1] op_sel_hi:[1,0]
	v_pk_mul_f32 v[56:57], v[114:115], v[152:153] op_sel:[0,1] op_sel_hi:[1,0]
	v_pk_mul_f32 v[58:59], v[118:119], v[192:193] op_sel:[0,1] op_sel_hi:[1,0]
	v_pk_mul_f32 v[60:61], v[122:123], v[162:163] op_sel:[0,1] op_sel_hi:[1,0]
	v_pk_mul_f32 v[62:63], v[124:125], v[178:179] op_sel:[0,1] op_sel_hi:[1,0]
	v_pk_mul_f32 v[64:65], v[126:127], v[128:129] op_sel:[0,1] op_sel_hi:[1,0]
	v_pk_fma_f32 v[38:39], v[68:69], v[180:181], v[38:39] op_sel_hi:[0,1,1]
	v_pk_fma_f32 v[40:41], v[72:73], v[150:151], v[40:41] op_sel_hi:[0,1,1]
	v_pk_fma_f32 v[42:43], v[76:77], v[174:175], v[42:43] op_sel_hi:[0,1,1]
	v_pk_fma_f32 v[44:45], v[80:81], v[160:161], v[44:45] op_sel_hi:[0,1,1]
	v_pk_fma_f32 v[46:47], v[84:85], v[176:177], v[46:47] op_sel_hi:[0,1,1]
	v_pk_fma_f32 v[48:49], v[88:89], v[144:145], v[48:49] op_sel_hi:[0,1,1]
	v_pk_fma_f32 v[50:51], v[92:93], v[172:173], v[50:51] op_sel_hi:[0,1,1]
	v_pk_fma_f32 v[52:53], v[96:97], v[186:187], v[52:53] op_sel_hi:[0,1,1]
	v_pk_fma_f32 v[54:55], v[100:101], v[182:183], v[54:55] op_sel_hi:[0,1,1]
	v_pk_fma_f32 v[56:57], v[104:105], v[152:153], v[56:57] op_sel_hi:[0,1,1]
	v_pk_fma_f32 v[58:59], v[108:109], v[192:193], v[58:59] op_sel_hi:[0,1,1]
	v_pk_fma_f32 v[60:61], v[112:113], v[162:163], v[60:61] op_sel_hi:[0,1,1]
	v_pk_fma_f32 v[62:63], v[116:117], v[178:179], v[62:63] op_sel_hi:[0,1,1]
	v_pk_fma_f32 v[64:65], v[120:121], v[128:129], v[64:65] op_sel_hi:[0,1,1]
	ds_write_b64 v2, v[130:131]
	ds_write_b64 v2, v[34:35] offset:4224
	ds_write_b64 v2, v[18:19] offset:8448
	ds_write_b64 v2, v[50:51] offset:12672
	ds_write_b64 v2, v[10:11] offset:16896
	ds_write_b64 v2, v[42:43] offset:21120
	ds_write_b64 v2, v[26:27] offset:25344
	ds_write_b64 v2, v[58:59] offset:29568
	ds_write_b64 v2, v[6:7] offset:33792
	ds_write_b64 v2, v[38:39] offset:38016
	ds_write_b64 v2, v[22:23] offset:42240
	ds_write_b64 v2, v[54:55] offset:46464
	ds_write_b64 v2, v[14:15] offset:50688
	ds_write_b64 v2, v[46:47] offset:54912
	ds_write_b64 v2, v[30:31] offset:59136
	ds_write_b64 v2, v[62:63] offset:63360
	ds_write_b64 v143, v[4:5]
	ds_write_b64 v212, v[36:37]
	ds_write_b64 v213, v[20:21]
	ds_write_b64 v214, v[52:53]
	ds_write_b64 v215, v[12:13]
	ds_write_b64 v216, v[44:45]
	ds_write_b64 v217, v[28:29]
	ds_write_b64 v218, v[60:61]
	ds_write_b64 v219, v[8:9]
	ds_write_b64 v220, v[40:41]
	ds_write_b64 v221, v[24:25]
	ds_write_b64 v222, v[56:57]
	ds_write_b64 v223, v[16:17]
	ds_write_b64 v224, v[48:49]
	ds_write_b64 v225, v[32:33]
	ds_write_b64 v226, v[64:65]
	v_mov_b32_e32 v2, v142
	s_waitcnt lgkmcnt(0)
	s_barrier
	s_nop 0
	v_and_b32_e32 v4, 15, v2
	v_lshlrev_b32_e32 v2, 5, v2
	v_and_b32_e32 v2, 0xfffffe00, v2
	v_lshl_add_u32 v5, v2, 3, 0
	v_lshlrev_b32_e32 v7, 3, v4
	v_ashrrev_i32_e32 v2, 2, v2
	v_add3_u32 v2, v5, v7, v2
	v_add_u32_e32 v143, 0x800, v2
	ds_read2_b64 v[128:131], v2 offset1:16
	ds_read2_b64 v[148:151], v2 offset0:33 offset1:49
	ds_read2_b64 v[152:155], v2 offset0:66 offset1:82
	ds_read2_b64 v[156:159], v2 offset0:99 offset1:115
	ds_read2_b64 v[160:163], v2 offset0:132 offset1:148
	ds_read2_b64 v[164:167], v2 offset0:165 offset1:181
	ds_read2_b64 v[168:171], v2 offset0:198 offset1:214
	ds_read2_b64 v[172:175], v2 offset0:231 offset1:247
	ds_read2_b64 v[176:179], v143 offset0:8 offset1:24
	ds_read2_b64 v[180:183], v143 offset0:41 offset1:57
	ds_read2_b64 v[184:187], v143 offset0:74 offset1:90
	ds_read2_b64 v[188:191], v143 offset0:107 offset1:123
	ds_read2_b64 v[192:195], v143 offset0:140 offset1:156
	ds_read2_b64 v[196:199], v143 offset0:173 offset1:189
	ds_read2_b64 v[204:207], v143 offset0:206 offset1:222
	ds_read2_b64 v[208:211], v143 offset0:239 offset1:255
	s_waitcnt lgkmcnt(7)
	v_pk_add_f32 v[144:145], v[128:129], v[176:177]
	v_pk_add_f32 v[128:129], v[128:129], v[176:177] neg_lo:[0,1] neg_hi:[0,1]
	v_pk_add_f32 v[176:177], v[130:131], v[178:179]
	v_pk_add_f32 v[130:131], v[130:131], v[178:179] neg_lo:[0,1] neg_hi:[0,1]
	v_cvt_f32_ubyte0_e32 v4, v4
	v_pk_mul_f32 v[178:179], v[130:131], s[20:21]
	v_mul_f32_e32 v6, 0x3b000000, v4
	v_pk_fma_f32 v[130:131], v[130:131], s[10:11], v[178:179] op_sel:[0,0,1] op_sel_hi:[1,0,0]
	s_waitcnt lgkmcnt(6)
	v_pk_add_f32 v[178:179], v[148:149], v[180:181]
	v_pk_add_f32 v[148:149], v[148:149], v[180:181] neg_lo:[0,1] neg_hi:[0,1]
	v_sin_f32_e32 v4, v6
	v_pk_mul_f32 v[180:181], v[148:149], s[24:25]
	v_cos_f32_e32 v6, v6
	v_pk_fma_f32 v[148:149], v[148:149], s[22:23], v[180:181] op_sel:[0,0,1] op_sel_hi:[1,0,0]
	v_pk_add_f32 v[180:181], v[150:151], v[182:183]
	v_pk_add_f32 v[150:151], v[150:151], v[182:183] neg_lo:[0,1] neg_hi:[0,1]
	v_xor_b32_e32 v7, 0x80000000, v4
	v_pk_mul_f32 v[182:183], v[150:151], s[36:37]
	v_mov_b32_e32 v5, v7
	v_pk_fma_f32 v[150:151], v[150:151], s[26:27], v[182:183] op_sel:[0,0,1] op_sel_hi:[1,0,0]
	s_waitcnt lgkmcnt(5)
	v_pk_add_f32 v[182:183], v[152:153], v[184:185]
	v_pk_add_f32 v[152:153], v[152:153], v[184:185] neg_lo:[0,1] neg_hi:[0,1]
	v_pk_mul_f32 v[8:9], v[6:7], v[4:5] op_sel:[1,0] op_sel_hi:[0,1]
	v_pk_mul_f32 v[184:185], v[152:153], s[40:41]
	v_pk_fma_f32 v[8:9], v[6:7], v[6:7], v[8:9] op_sel_hi:[1,0,1]
	v_pk_fma_f32 v[152:153], v[152:153], s[38:39], v[184:185] op_sel:[0,0,1] op_sel_hi:[1,0,0]
	v_pk_add_f32 v[184:185], v[154:155], v[186:187]
	v_pk_add_f32 v[154:155], v[154:155], v[186:187] neg_lo:[0,1] neg_hi:[0,1]
	v_xor_b32_e32 v14, 0x80000000, v9
	v_pk_mul_f32 v[186:187], v[154:155], s[42:43]
	v_mov_b32_e32 v15, v9
	v_pk_fma_f32 v[154:155], v[154:155], s[0:1], v[186:187] op_sel:[0,0,1] op_sel_hi:[1,0,0]
	s_waitcnt lgkmcnt(4)
	v_pk_add_f32 v[186:187], v[156:157], v[188:189]
	v_pk_add_f32 v[156:157], v[156:157], v[188:189] neg_lo:[0,1] neg_hi:[0,1]
	v_pk_mul_f32 v[12:13], v[8:9], v[14:15] op_sel:[1,0] op_sel_hi:[0,1]
	v_pk_mul_f32 v[188:189], v[156:157], s[44:45]
	v_pk_fma_f32 v[12:13], v[8:9], v[8:9], v[12:13] op_sel_hi:[1,0,1]
	v_pk_fma_f32 v[156:157], v[156:157], s[50:51], v[188:189] op_sel:[0,0,1] op_sel_hi:[1,0,0]
	v_pk_add_f32 v[188:189], v[158:159], v[190:191]
	v_pk_add_f32 v[158:159], v[158:159], v[190:191] neg_lo:[0,1] neg_hi:[0,1]
	v_xor_b32_e32 v16, 0x80000000, v13
	v_pk_mul_f32 v[190:191], v[158:159], s[8:9]
	v_mov_b32_e32 v17, v13
	v_pk_fma_f32 v[158:159], v[158:159], s[16:17], v[190:191] op_sel:[0,0,1] op_sel_hi:[1,0,0]
	s_waitcnt lgkmcnt(3)
	v_pk_add_f32 v[190:191], v[160:161], v[192:193]
	v_pk_add_f32 v[192:193], v[160:161], v[192:193] neg_lo:[0,1] neg_hi:[0,1]
	v_pk_mul_f32 v[28:29], v[12:13], v[16:17] op_sel:[1,0] op_sel_hi:[0,1]
	v_pk_add_f32 v[160:161], v[162:163], v[194:195]
	v_pk_add_f32 v[162:163], v[162:163], v[194:195] neg_lo:[0,1] neg_hi:[0,1]
	v_pk_fma_f32 v[28:29], v[12:13], v[12:13], v[28:29] op_sel_hi:[1,0,1]
	v_pk_mul_f32 v[194:195], v[162:163], s[8:9]
	v_pk_mul_f32 v[44:45], v[16:17], v[28:29] op_sel:[0,1] op_sel_hi:[1,0]
	v_pk_fma_f32 v[162:163], v[162:163], s[16:17], v[194:195] op_sel:[0,0,1] op_sel_hi:[1,0,0] neg_lo:[1,0,0] neg_hi:[1,0,0]
	s_waitcnt lgkmcnt(2)
	v_pk_add_f32 v[194:195], v[164:165], v[196:197]
	v_pk_add_f32 v[164:165], v[164:165], v[196:197] neg_lo:[0,1] neg_hi:[0,1]
	v_pk_fma_f32 v[44:45], v[12:13], v[28:29], v[44:45] op_sel_hi:[0,1,1]
	v_pk_mul_f32 v[196:197], v[164:165], s[44:45]
	v_pk_mul_f32 v[60:61], v[16:17], v[44:45] op_sel:[0,1] op_sel_hi:[1,0]
	v_pk_fma_f32 v[164:165], v[164:165], s[50:51], v[196:197] op_sel:[0,0,1] op_sel_hi:[1,0,0] neg_lo:[1,0,0] neg_hi:[1,0,0]
	v_pk_add_f32 v[196:197], v[166:167], v[198:199]
	v_pk_add_f32 v[166:167], v[166:167], v[198:199] neg_lo:[0,1] neg_hi:[0,1]
	v_pk_fma_f32 v[60:61], v[12:13], v[44:45], v[60:61] op_sel_hi:[0,1,1]
	v_pk_mul_f32 v[198:199], v[166:167], s[42:43]
	v_pk_mul_f32 v[76:77], v[16:17], v[60:61] op_sel:[0,1] op_sel_hi:[1,0]
	v_pk_fma_f32 v[166:167], v[166:167], s[0:1], v[198:199] op_sel:[0,0,1] op_sel_hi:[1,0,0] neg_lo:[1,0,0] neg_hi:[1,0,0]
	s_waitcnt lgkmcnt(1)
	v_pk_add_f32 v[198:199], v[168:169], v[204:205]
	v_pk_add_f32 v[168:169], v[168:169], v[204:205] neg_lo:[0,1] neg_hi:[0,1]
	v_pk_fma_f32 v[76:77], v[12:13], v[60:61], v[76:77] op_sel_hi:[0,1,1]
	v_pk_mul_f32 v[204:205], v[168:169], s[40:41]
	v_pk_mul_f32 v[92:93], v[16:17], v[76:77] op_sel:[0,1] op_sel_hi:[1,0]
	v_pk_fma_f32 v[168:169], v[168:169], s[38:39], v[204:205] op_sel:[0,0,1] op_sel_hi:[1,0,0] neg_lo:[1,0,0] neg_hi:[1,0,0]
	v_pk_add_f32 v[204:205], v[170:171], v[206:207]
	v_pk_add_f32 v[170:171], v[170:171], v[206:207] neg_lo:[0,1] neg_hi:[0,1]
	v_pk_fma_f32 v[92:93], v[12:13], v[76:77], v[92:93] op_sel_hi:[0,1,1]
	v_pk_mul_f32 v[206:207], v[170:171], s[36:37]
	v_pk_mul_f32 v[108:109], v[16:17], v[92:93] op_sel:[0,1] op_sel_hi:[1,0]
	v_pk_fma_f32 v[170:171], v[170:171], s[26:27], v[206:207] op_sel:[0,0,1] op_sel_hi:[1,0,0] neg_lo:[1,0,0] neg_hi:[1,0,0]
	s_waitcnt lgkmcnt(0)
	v_pk_add_f32 v[206:207], v[172:173], v[208:209]
	v_pk_add_f32 v[172:173], v[172:173], v[208:209] neg_lo:[0,1] neg_hi:[0,1]
	v_pk_mul_f32 v[10:11], v[4:5], v[8:9] op_sel:[0,1] op_sel_hi:[1,0]
	v_pk_mul_f32 v[208:209], v[172:173], s[24:25]
	v_pk_fma_f32 v[108:109], v[12:13], v[92:93], v[108:109] op_sel_hi:[0,1,1]
	v_pk_fma_f32 v[172:173], v[172:173], s[22:23], v[208:209] op_sel:[0,0,1] op_sel_hi:[1,0,0] neg_lo:[1,0,0] neg_hi:[1,0,0]
	v_pk_add_f32 v[208:209], v[174:175], v[210:211]
	v_pk_add_f32 v[174:175], v[174:175], v[210:211] neg_lo:[0,1] neg_hi:[0,1]
	v_pk_fma_f32 v[10:11], v[6:7], v[8:9], v[10:11] op_sel_hi:[0,1,1]
	v_pk_mul_f32 v[210:211], v[174:175], s[20:21]
	v_pk_mul_f32 v[18:19], v[4:5], v[12:13] op_sel:[0,1] op_sel_hi:[1,0]
	v_pk_fma_f32 v[174:175], v[174:175], s[10:11], v[210:211] op_sel:[0,0,1] op_sel_hi:[1,0,0] neg_lo:[1,0,0] neg_hi:[1,0,0]
	v_pk_add_f32 v[210:211], v[144:145], v[190:191]
	v_pk_add_f32 v[144:145], v[144:145], v[190:191] neg_lo:[0,1] neg_hi:[0,1]
	v_pk_add_f32 v[190:191], v[176:177], v[160:161]
	v_pk_add_f32 v[160:161], v[176:177], v[160:161] neg_lo:[0,1] neg_hi:[0,1]
	v_pk_mul_f32 v[32:33], v[4:5], v[28:29] op_sel:[0,1] op_sel_hi:[1,0]
	v_pk_mul_f32 v[176:177], v[160:161], s[24:25]
	v_pk_mul_f32 v[48:49], v[4:5], v[44:45] op_sel:[0,1] op_sel_hi:[1,0]
	v_pk_fma_f32 v[160:161], v[160:161], s[22:23], v[176:177] op_sel:[0,0,1] op_sel_hi:[1,0,0]
	v_pk_add_f32 v[176:177], v[178:179], v[194:195]
	v_pk_add_f32 v[178:179], v[178:179], v[194:195] neg_lo:[0,1] neg_hi:[0,1]
	v_pk_mul_f32 v[64:65], v[4:5], v[60:61] op_sel:[0,1] op_sel_hi:[1,0]
	v_pk_mul_f32 v[194:195], v[178:179], s[40:41]
	v_pk_mul_f32 v[80:81], v[4:5], v[76:77] op_sel:[0,1] op_sel_hi:[1,0]
	v_pk_fma_f32 v[178:179], v[178:179], s[38:39], v[194:195] op_sel:[0,0,1] op_sel_hi:[1,0,0]
	v_pk_add_f32 v[194:195], v[180:181], v[196:197]
	v_pk_add_f32 v[180:181], v[180:181], v[196:197] neg_lo:[0,1] neg_hi:[0,1]
	v_pk_mul_f32 v[96:97], v[4:5], v[92:93] op_sel:[0,1] op_sel_hi:[1,0]
	v_pk_mul_f32 v[196:197], v[180:181], s[44:45]
	v_pk_mul_f32 v[112:113], v[4:5], v[108:109] op_sel:[0,1] op_sel_hi:[1,0]
	v_pk_fma_f32 v[180:181], v[180:181], s[50:51], v[196:197] op_sel:[0,0,1] op_sel_hi:[1,0,0]
	v_pk_add_f32 v[196:197], v[182:183], v[198:199]
	v_pk_add_f32 v[198:199], v[182:183], v[198:199] neg_lo:[0,1] neg_hi:[0,1]
	v_xor_b32_e32 v22, 0x80000000, v11
	v_pk_add_f32 v[182:183], v[184:185], v[204:205]
	v_pk_add_f32 v[184:185], v[184:185], v[204:205] neg_lo:[0,1] neg_hi:[0,1]
	v_mov_b32_e32 v23, v11
	v_pk_mul_f32 v[204:205], v[184:185], s[44:45]
	v_pk_fma_f32 v[18:19], v[6:7], v[12:13], v[18:19] op_sel_hi:[0,1,1]
	v_pk_fma_f32 v[184:185], v[184:185], s[50:51], v[204:205] op_sel:[0,0,1] op_sel_hi:[1,0,0] neg_lo:[1,0,0] neg_hi:[1,0,0]
	v_pk_add_f32 v[204:205], v[186:187], v[206:207]
	v_pk_add_f32 v[186:187], v[186:187], v[206:207] neg_lo:[0,1] neg_hi:[0,1]
	v_pk_mul_f32 v[20:21], v[14:15], v[12:13] op_sel:[0,1] op_sel_hi:[1,0]
	v_pk_mul_f32 v[206:207], v[186:187], s[40:41]
	v_pk_fma_f32 v[32:33], v[6:7], v[28:29], v[32:33] op_sel_hi:[0,1,1]
	v_pk_fma_f32 v[186:187], v[186:187], s[38:39], v[206:207] op_sel:[0,0,1] op_sel_hi:[1,0,0] neg_lo:[1,0,0] neg_hi:[1,0,0]
	v_pk_add_f32 v[206:207], v[188:189], v[208:209]
	v_pk_add_f32 v[188:189], v[188:189], v[208:209] neg_lo:[0,1] neg_hi:[0,1]
	v_pk_mul_f32 v[36:37], v[14:15], v[28:29] op_sel:[0,1] op_sel_hi:[1,0]
	v_pk_mul_f32 v[208:209], v[188:189], s[24:25]
	v_pk_fma_f32 v[48:49], v[6:7], v[44:45], v[48:49] op_sel_hi:[0,1,1]
	v_pk_fma_f32 v[188:189], v[188:189], s[22:23], v[208:209] op_sel:[0,0,1] op_sel_hi:[1,0,0] neg_lo:[1,0,0] neg_hi:[1,0,0]
	v_pk_add_f32 v[208:209], v[128:129], v[192:193] op_sel:[0,1] op_sel_hi:[1,0] neg_hi:[0,1]
	v_pk_add_f32 v[128:129], v[128:129], v[192:193] op_sel:[0,1] op_sel_hi:[1,0] neg_lo:[0,1]
	v_pk_add_f32 v[192:193], v[130:131], v[162:163]
	v_pk_add_f32 v[130:131], v[130:131], v[162:163] neg_lo:[0,1] neg_hi:[0,1]
	v_pk_mul_f32 v[52:53], v[14:15], v[44:45] op_sel:[0,1] op_sel_hi:[1,0]
	v_pk_mul_f32 v[162:163], v[130:131], s[24:25]
	v_pk_fma_f32 v[64:65], v[6:7], v[60:61], v[64:65] op_sel_hi:[0,1,1]
	v_pk_fma_f32 v[130:131], v[130:131], s[22:23], v[162:163] op_sel:[0,0,1] op_sel_hi:[1,0,0]
	v_pk_add_f32 v[162:163], v[148:149], v[164:165]
	v_pk_add_f32 v[148:149], v[148:149], v[164:165] neg_lo:[0,1] neg_hi:[0,1]
	v_pk_mul_f32 v[68:69], v[14:15], v[60:61] op_sel:[0,1] op_sel_hi:[1,0]
	v_pk_mul_f32 v[164:165], v[148:149], s[40:41]
	v_pk_fma_f32 v[80:81], v[6:7], v[76:77], v[80:81] op_sel_hi:[0,1,1]
	v_pk_fma_f32 v[148:149], v[148:149], s[38:39], v[164:165] op_sel:[0,0,1] op_sel_hi:[1,0,0]
	v_pk_add_f32 v[164:165], v[150:151], v[166:167]
	v_pk_add_f32 v[150:151], v[150:151], v[166:167] neg_lo:[0,1] neg_hi:[0,1]
	v_pk_mul_f32 v[84:85], v[14:15], v[76:77] op_sel:[0,1] op_sel_hi:[1,0]
	v_pk_mul_f32 v[166:167], v[150:151], s[44:45]
	v_pk_fma_f32 v[96:97], v[6:7], v[92:93], v[96:97] op_sel_hi:[0,1,1]
	v_pk_fma_f32 v[150:151], v[150:151], s[50:51], v[166:167] op_sel:[0,0,1] op_sel_hi:[1,0,0]
	v_pk_add_f32 v[166:167], v[152:153], v[168:169]
	v_pk_add_f32 v[168:169], v[152:153], v[168:169] neg_lo:[0,1] neg_hi:[0,1]
	v_pk_mul_f32 v[100:101], v[14:15], v[92:93] op_sel:[0,1] op_sel_hi:[1,0]
	v_pk_add_f32 v[152:153], v[154:155], v[170:171]
	v_pk_add_f32 v[154:155], v[154:155], v[170:171] neg_lo:[0,1] neg_hi:[0,1]
	v_pk_fma_f32 v[112:113], v[6:7], v[108:109], v[112:113] op_sel_hi:[0,1,1]
	v_pk_mul_f32 v[170:171], v[154:155], s[44:45]
	v_pk_mul_f32 v[116:117], v[14:15], v[108:109] op_sel:[0,1] op_sel_hi:[1,0]
	v_pk_fma_f32 v[154:155], v[154:155], s[50:51], v[170:171] op_sel:[0,0,1] op_sel_hi:[1,0,0] neg_lo:[1,0,0] neg_hi:[1,0,0]
	v_pk_add_f32 v[170:171], v[156:157], v[172:173]
	v_pk_add_f32 v[156:157], v[156:157], v[172:173] neg_lo:[0,1] neg_hi:[0,1]
	v_pk_fma_f32 v[20:21], v[8:9], v[12:13], v[20:21] op_sel_hi:[0,1,1]
	v_pk_mul_f32 v[172:173], v[156:157], s[40:41]
	v_pk_mul_f32 v[24:25], v[12:13], v[22:23] op_sel:[1,0] op_sel_hi:[0,1]
	v_pk_fma_f32 v[156:157], v[156:157], s[38:39], v[172:173] op_sel:[0,0,1] op_sel_hi:[1,0,0] neg_lo:[1,0,0] neg_hi:[1,0,0]
	v_pk_add_f32 v[172:173], v[158:159], v[174:175]
	v_pk_add_f32 v[158:159], v[158:159], v[174:175] neg_lo:[0,1] neg_hi:[0,1]
	v_pk_fma_f32 v[36:37], v[8:9], v[28:29], v[36:37] op_sel_hi:[0,1,1]
	v_pk_mul_f32 v[174:175], v[158:159], s[24:25]
	v_pk_mul_f32 v[40:41], v[22:23], v[28:29] op_sel:[0,1] op_sel_hi:[1,0]
	v_pk_fma_f32 v[158:159], v[158:159], s[22:23], v[174:175] op_sel:[0,0,1] op_sel_hi:[1,0,0] neg_lo:[1,0,0] neg_hi:[1,0,0]
	v_pk_add_f32 v[174:175], v[210:211], v[196:197]
	v_pk_add_f32 v[196:197], v[210:211], v[196:197] neg_lo:[0,1] neg_hi:[0,1]
	v_pk_add_f32 v[210:211], v[190:191], v[182:183]
	v_pk_add_f32 v[182:183], v[190:191], v[182:183] neg_lo:[0,1] neg_hi:[0,1]
	v_pk_fma_f32 v[52:53], v[8:9], v[44:45], v[52:53] op_sel_hi:[0,1,1]
	v_pk_mul_f32 v[190:191], v[182:183], s[40:41]
	v_pk_mul_f32 v[56:57], v[22:23], v[44:45] op_sel:[0,1] op_sel_hi:[1,0]
	v_pk_fma_f32 v[182:183], v[182:183], s[38:39], v[190:191] op_sel:[0,0,1] op_sel_hi:[1,0,0]
	v_pk_add_f32 v[190:191], v[176:177], v[204:205]
	v_pk_add_f32 v[204:205], v[176:177], v[204:205] neg_lo:[0,1] neg_hi:[0,1]
	v_pk_fma_f32 v[68:69], v[8:9], v[60:61], v[68:69] op_sel_hi:[0,1,1]
	v_pk_add_f32 v[176:177], v[194:195], v[206:207]
	v_pk_add_f32 v[194:195], v[194:195], v[206:207] neg_lo:[0,1] neg_hi:[0,1]
	v_pk_mul_f32 v[72:73], v[22:23], v[60:61] op_sel:[0,1] op_sel_hi:[1,0]
	v_pk_mul_f32 v[206:207], v[194:195], s[40:41]
	v_pk_fma_f32 v[84:85], v[8:9], v[76:77], v[84:85] op_sel_hi:[0,1,1]
	v_pk_fma_f32 v[194:195], v[194:195], s[38:39], v[206:207] op_sel:[0,0,1] op_sel_hi:[1,0,0] neg_lo:[1,0,0] neg_hi:[1,0,0]
	v_pk_add_f32 v[206:207], v[144:145], v[198:199] op_sel:[0,1] op_sel_hi:[1,0] neg_hi:[0,1]
	v_pk_add_f32 v[144:145], v[144:145], v[198:199] op_sel:[0,1] op_sel_hi:[1,0] neg_lo:[0,1]
	v_pk_add_f32 v[198:199], v[160:161], v[184:185]
	v_pk_add_f32 v[160:161], v[160:161], v[184:185] neg_lo:[0,1] neg_hi:[0,1]
	v_pk_mul_f32 v[88:89], v[22:23], v[76:77] op_sel:[0,1] op_sel_hi:[1,0]
	v_pk_mul_f32 v[184:185], v[160:161], s[40:41]
	v_pk_fma_f32 v[100:101], v[8:9], v[92:93], v[100:101] op_sel_hi:[0,1,1]
	v_pk_fma_f32 v[160:161], v[160:161], s[38:39], v[184:185] op_sel:[0,0,1] op_sel_hi:[1,0,0]
	v_pk_add_f32 v[184:185], v[178:179], v[186:187]
	v_pk_add_f32 v[186:187], v[178:179], v[186:187] neg_lo:[0,1] neg_hi:[0,1]
	v_pk_mul_f32 v[104:105], v[22:23], v[92:93] op_sel:[0,1] op_sel_hi:[1,0]
	v_pk_add_f32 v[178:179], v[180:181], v[188:189]
	v_pk_add_f32 v[180:181], v[180:181], v[188:189] neg_lo:[0,1] neg_hi:[0,1]
	v_pk_fma_f32 v[116:117], v[8:9], v[108:109], v[116:117] op_sel_hi:[0,1,1]
	v_pk_mul_f32 v[188:189], v[180:181], s[40:41]
	v_pk_mul_f32 v[120:121], v[22:23], v[108:109] op_sel:[0,1] op_sel_hi:[1,0]
	v_pk_fma_f32 v[180:181], v[180:181], s[38:39], v[188:189] op_sel:[0,0,1] op_sel_hi:[1,0,0] neg_lo:[1,0,0] neg_hi:[1,0,0]
	v_pk_add_f32 v[188:189], v[208:209], v[166:167]
	v_pk_add_f32 v[166:167], v[208:209], v[166:167] neg_lo:[0,1] neg_hi:[0,1]
	v_pk_add_f32 v[208:209], v[192:193], v[152:153]
	v_pk_add_f32 v[152:153], v[192:193], v[152:153] neg_lo:[0,1] neg_hi:[0,1]
	v_xor_b32_e32 v26, 0x80000000, v19
	v_pk_mul_f32 v[192:193], v[152:153], s[40:41]
	v_xor_b32_e32 v30, 0x80000000, v21
	v_pk_fma_f32 v[152:153], v[152:153], s[38:39], v[192:193] op_sel:[0,0,1] op_sel_hi:[1,0,0]
	v_pk_add_f32 v[192:193], v[162:163], v[170:171]
	v_pk_add_f32 v[170:171], v[162:163], v[170:171] neg_lo:[0,1] neg_hi:[0,1]
	v_pk_fma_f32 v[24:25], v[12:13], v[10:11], v[24:25] op_sel_hi:[1,0,1]
	v_pk_add_f32 v[162:163], v[164:165], v[172:173]
	v_pk_add_f32 v[164:165], v[164:165], v[172:173] neg_lo:[0,1] neg_hi:[0,1]
	v_pk_fma_f32 v[40:41], v[10:11], v[28:29], v[40:41] op_sel_hi:[0,1,1]
	v_pk_mul_f32 v[172:173], v[164:165], s[40:41]
	v_pk_fma_f32 v[56:57], v[10:11], v[44:45], v[56:57] op_sel_hi:[0,1,1]
	v_pk_fma_f32 v[164:165], v[164:165], s[38:39], v[172:173] op_sel:[0,0,1] op_sel_hi:[1,0,0] neg_lo:[1,0,0] neg_hi:[1,0,0]
	v_pk_add_f32 v[172:173], v[128:129], v[168:169] op_sel:[0,1] op_sel_hi:[1,0] neg_hi:[0,1]
	v_pk_add_f32 v[128:129], v[128:129], v[168:169] op_sel:[0,1] op_sel_hi:[1,0] neg_lo:[0,1]
	v_pk_add_f32 v[168:169], v[130:131], v[154:155]
	v_pk_add_f32 v[130:131], v[130:131], v[154:155] neg_lo:[0,1] neg_hi:[0,1]
	v_pk_fma_f32 v[72:73], v[10:11], v[60:61], v[72:73] op_sel_hi:[0,1,1]
	v_pk_mul_f32 v[154:155], v[130:131], s[40:41]
	v_pk_fma_f32 v[88:89], v[10:11], v[76:77], v[88:89] op_sel_hi:[0,1,1]
	v_pk_fma_f32 v[130:131], v[130:131], s[38:39], v[154:155] op_sel:[0,0,1] op_sel_hi:[1,0,0]
	v_pk_add_f32 v[154:155], v[148:149], v[156:157]
	v_pk_add_f32 v[156:157], v[148:149], v[156:157] neg_lo:[0,1] neg_hi:[0,1]
	v_pk_fma_f32 v[104:105], v[10:11], v[92:93], v[104:105] op_sel_hi:[0,1,1]
	v_pk_add_f32 v[148:149], v[150:151], v[158:159]
	v_pk_add_f32 v[150:151], v[150:151], v[158:159] neg_lo:[0,1] neg_hi:[0,1]
	v_pk_fma_f32 v[120:121], v[10:11], v[108:109], v[120:121] op_sel_hi:[0,1,1]
	v_pk_mul_f32 v[158:159], v[150:151], s[40:41]
	v_mov_b32_e32 v27, v19
	v_pk_fma_f32 v[150:151], v[150:151], s[38:39], v[158:159] op_sel:[0,0,1] op_sel_hi:[1,0,0] neg_lo:[1,0,0] neg_hi:[1,0,0]
	v_pk_add_f32 v[158:159], v[174:175], v[190:191]
	v_pk_add_f32 v[174:175], v[174:175], v[190:191] neg_lo:[0,1] neg_hi:[0,1]
	v_pk_add_f32 v[190:191], v[210:211], v[176:177]
	v_pk_add_f32 v[210:211], v[210:211], v[176:177] neg_lo:[0,1] neg_hi:[0,1]
	v_mov_b32_e32 v31, v21
	v_pk_add_f32 v[176:177], v[196:197], v[204:205] op_sel:[0,1] op_sel_hi:[1,0] neg_hi:[0,1]
	v_pk_add_f32 v[196:197], v[196:197], v[204:205] op_sel:[0,1] op_sel_hi:[1,0] neg_lo:[0,1]
	v_pk_add_f32 v[204:205], v[182:183], v[194:195]
	v_pk_add_f32 v[194:195], v[182:183], v[194:195] neg_lo:[0,1] neg_hi:[0,1]
	v_xor_b32_e32 v34, 0x80000000, v25
	v_pk_add_f32 v[182:183], v[206:207], v[184:185]
	v_pk_add_f32 v[184:185], v[206:207], v[184:185] neg_lo:[0,1] neg_hi:[0,1]
	v_pk_add_f32 v[206:207], v[198:199], v[178:179]
	v_pk_add_f32 v[198:199], v[198:199], v[178:179] neg_lo:[0,1] neg_hi:[0,1]
	v_xor_b32_e32 v38, 0x80000000, v29
	v_pk_add_f32 v[178:179], v[144:145], v[186:187] op_sel:[0,1] op_sel_hi:[1,0] neg_hi:[0,1]
	v_pk_add_f32 v[144:145], v[144:145], v[186:187] op_sel:[0,1] op_sel_hi:[1,0] neg_lo:[0,1]
	v_pk_add_f32 v[186:187], v[160:161], v[180:181]
	v_pk_add_f32 v[180:181], v[160:161], v[180:181] neg_lo:[0,1] neg_hi:[0,1]
	v_xor_b32_e32 v42, 0x80000000, v33
	v_pk_add_f32 v[160:161], v[188:189], v[192:193]
	v_pk_add_f32 v[188:189], v[188:189], v[192:193] neg_lo:[0,1] neg_hi:[0,1]
	v_pk_add_f32 v[192:193], v[208:209], v[162:163]
	v_pk_add_f32 v[208:209], v[208:209], v[162:163] neg_lo:[0,1] neg_hi:[0,1]
	v_xor_b32_e32 v46, 0x80000000, v37
	v_pk_add_f32 v[162:163], v[166:167], v[170:171] op_sel:[0,1] op_sel_hi:[1,0] neg_hi:[0,1]
	v_pk_add_f32 v[166:167], v[166:167], v[170:171] op_sel:[0,1] op_sel_hi:[1,0] neg_lo:[0,1]
	v_pk_add_f32 v[170:171], v[152:153], v[164:165]
	v_pk_add_f32 v[164:165], v[152:153], v[164:165] neg_lo:[0,1] neg_hi:[0,1]
	v_mov_b32_e32 v35, v25
	v_pk_add_f32 v[152:153], v[172:173], v[154:155]
	v_pk_add_f32 v[154:155], v[172:173], v[154:155] neg_lo:[0,1] neg_hi:[0,1]
	v_pk_add_f32 v[172:173], v[168:169], v[148:149]
	v_pk_add_f32 v[168:169], v[168:169], v[148:149] neg_lo:[0,1] neg_hi:[0,1]
	v_mov_b32_e32 v39, v29
	v_pk_add_f32 v[148:149], v[128:129], v[156:157] op_sel:[0,1] op_sel_hi:[1,0] neg_hi:[0,1]
	v_pk_add_f32 v[128:129], v[128:129], v[156:157] op_sel:[0,1] op_sel_hi:[1,0] neg_lo:[0,1]
	v_pk_add_f32 v[156:157], v[130:131], v[150:151]
	v_pk_add_f32 v[130:131], v[130:131], v[150:151] neg_lo:[0,1] neg_hi:[0,1]
	v_mov_b32_e32 v43, v33
	v_xor_b32_e32 v151, 0x80000000, v130
	v_mov_b32_e32 v150, v131
	v_pk_add_f32 v[130:131], v[158:159], v[190:191]
	v_pk_add_f32 v[158:159], v[158:159], v[190:191] neg_lo:[0,1] neg_hi:[0,1]
	v_pk_add_f32 v[190:191], v[174:175], v[210:211] op_sel:[0,1] op_sel_hi:[1,0] neg_hi:[0,1]
	v_pk_add_f32 v[174:175], v[174:175], v[210:211] op_sel:[0,1] op_sel_hi:[1,0] neg_lo:[0,1]
	v_pk_add_f32 v[210:211], v[176:177], v[204:205]
	v_pk_add_f32 v[176:177], v[176:177], v[204:205] neg_lo:[0,1] neg_hi:[0,1]
	v_pk_add_f32 v[204:205], v[196:197], v[194:195] op_sel:[0,1] op_sel_hi:[1,0] neg_hi:[0,1]
	v_pk_add_f32 v[194:195], v[196:197], v[194:195] op_sel:[0,1] op_sel_hi:[1,0] neg_lo:[0,1]
	v_pk_add_f32 v[196:197], v[182:183], v[206:207]
	v_pk_add_f32 v[182:183], v[182:183], v[206:207] neg_lo:[0,1] neg_hi:[0,1]
	v_pk_add_f32 v[206:207], v[184:185], v[198:199] op_sel:[0,1] op_sel_hi:[1,0] neg_hi:[0,1]
	v_pk_add_f32 v[184:185], v[184:185], v[198:199] op_sel:[0,1] op_sel_hi:[1,0] neg_lo:[0,1]
	v_pk_add_f32 v[198:199], v[178:179], v[186:187]
	v_pk_add_f32 v[178:179], v[178:179], v[186:187] neg_lo:[0,1] neg_hi:[0,1]
	v_pk_add_f32 v[186:187], v[144:145], v[180:181] op_sel:[0,1] op_sel_hi:[1,0] neg_hi:[0,1]
	v_pk_add_f32 v[144:145], v[144:145], v[180:181] op_sel:[0,1] op_sel_hi:[1,0] neg_lo:[0,1]
	v_pk_add_f32 v[180:181], v[160:161], v[192:193]
	v_pk_add_f32 v[160:161], v[160:161], v[192:193] neg_lo:[0,1] neg_hi:[0,1]
	v_pk_mul_f32 v[4:5], v[4:5], v[180:181] op_sel:[0,1] op_sel_hi:[1,0]
	v_pk_add_f32 v[192:193], v[188:189], v[208:209] op_sel:[0,1] op_sel_hi:[1,0] neg_hi:[0,1]
	v_pk_add_f32 v[188:189], v[188:189], v[208:209] op_sel:[0,1] op_sel_hi:[1,0] neg_lo:[0,1]
	v_pk_add_f32 v[208:209], v[162:163], v[170:171]
	v_pk_add_f32 v[162:163], v[162:163], v[170:171] neg_lo:[0,1] neg_hi:[0,1]
	v_pk_add_f32 v[170:171], v[166:167], v[164:165] op_sel:[0,1] op_sel_hi:[1,0] neg_hi:[0,1]
	v_pk_add_f32 v[164:165], v[166:167], v[164:165] op_sel:[0,1] op_sel_hi:[1,0] neg_lo:[0,1]
	v_pk_add_f32 v[166:167], v[152:153], v[172:173]
	v_pk_fma_f32 v[4:5], v[6:7], v[180:181], v[4:5] op_sel_hi:[0,1,1]
	v_pk_mul_f32 v[6:7], v[14:15], v[196:197] op_sel:[0,1] op_sel_hi:[1,0]
	v_mov_b32_e32 v47, v37
	v_pk_fma_f32 v[6:7], v[8:9], v[196:197], v[6:7] op_sel_hi:[0,1,1]
	v_pk_mul_f32 v[8:9], v[22:23], v[166:167] op_sel:[0,1] op_sel_hi:[1,0]
	v_pk_add_f32 v[152:153], v[152:153], v[172:173] neg_lo:[0,1] neg_hi:[0,1]
	v_pk_fma_f32 v[8:9], v[10:11], v[166:167], v[8:9] op_sel_hi:[0,1,1]
	v_pk_mul_f32 v[10:11], v[16:17], v[210:211] op_sel:[0,1] op_sel_hi:[1,0]
	v_pk_add_f32 v[172:173], v[154:155], v[168:169] op_sel:[0,1] op_sel_hi:[1,0] neg_hi:[0,1]
	v_pk_add_f32 v[154:155], v[154:155], v[168:169] op_sel:[0,1] op_sel_hi:[1,0] neg_lo:[0,1]
	v_pk_add_f32 v[168:169], v[148:149], v[156:157]
	v_pk_fma_f32 v[10:11], v[12:13], v[210:211], v[10:11] op_sel_hi:[0,1,1]
	v_pk_mul_f32 v[12:13], v[26:27], v[208:209] op_sel:[0,1] op_sel_hi:[1,0]
	v_pk_mul_f32 v[14:15], v[30:31], v[198:199] op_sel:[0,1] op_sel_hi:[1,0]
	v_xor_b32_e32 v50, 0x80000000, v41
	v_xor_b32_e32 v54, 0x80000000, v45
	v_xor_b32_e32 v58, 0x80000000, v49
	v_xor_b32_e32 v62, 0x80000000, v53
	v_xor_b32_e32 v66, 0x80000000, v57
	v_xor_b32_e32 v70, 0x80000000, v61
	v_xor_b32_e32 v74, 0x80000000, v65
	v_mov_b32_e32 v51, v41
	v_mov_b32_e32 v55, v45
	v_mov_b32_e32 v59, v49
	v_mov_b32_e32 v63, v53
	v_mov_b32_e32 v67, v57
	v_mov_b32_e32 v71, v61
	v_mov_b32_e32 v75, v65
	v_pk_add_f32 v[148:149], v[148:149], v[156:157] neg_lo:[0,1] neg_hi:[0,1]
	v_pk_add_f32 v[156:157], v[128:129], v[150:151]
	v_pk_fma_f32 v[12:13], v[18:19], v[208:209], v[12:13] op_sel_hi:[0,1,1]
	v_pk_fma_f32 v[14:15], v[20:21], v[198:199], v[14:15] op_sel_hi:[0,1,1]
	v_pk_mul_f32 v[16:17], v[34:35], v[168:169] op_sel:[0,1] op_sel_hi:[1,0]
	v_pk_mul_f32 v[18:19], v[38:39], v[190:191] op_sel:[0,1] op_sel_hi:[1,0]
	v_pk_mul_f32 v[20:21], v[42:43], v[192:193] op_sel:[0,1] op_sel_hi:[1,0]
	v_pk_mul_f32 v[22:23], v[46:47], v[206:207] op_sel:[0,1] op_sel_hi:[1,0]
	v_xor_b32_e32 v78, 0x80000000, v69
	v_xor_b32_e32 v82, 0x80000000, v73
	v_xor_b32_e32 v86, 0x80000000, v77
	v_xor_b32_e32 v90, 0x80000000, v81
	v_xor_b32_e32 v94, 0x80000000, v85
	v_xor_b32_e32 v98, 0x80000000, v89
	v_xor_b32_e32 v102, 0x80000000, v93
	v_xor_b32_e32 v106, 0x80000000, v97
	v_xor_b32_e32 v110, 0x80000000, v101
	v_xor_b32_e32 v114, 0x80000000, v105
	v_xor_b32_e32 v118, 0x80000000, v109
	v_xor_b32_e32 v122, 0x80000000, v113
	v_xor_b32_e32 v124, 0x80000000, v117
	v_xor_b32_e32 v126, 0x80000000, v121
	v_mov_b32_e32 v79, v69
	v_mov_b32_e32 v83, v73
	v_mov_b32_e32 v87, v77
	v_mov_b32_e32 v91, v81
	v_mov_b32_e32 v95, v85
	v_mov_b32_e32 v99, v89
	v_mov_b32_e32 v103, v93
	v_mov_b32_e32 v107, v97
	v_mov_b32_e32 v111, v101
	v_mov_b32_e32 v115, v105
	v_mov_b32_e32 v119, v109
	v_mov_b32_e32 v123, v113
	v_mov_b32_e32 v125, v117
	v_mov_b32_e32 v127, v121
	v_pk_add_f32 v[128:129], v[128:129], v[150:151] neg_lo:[0,1] neg_hi:[0,1]
	v_pk_fma_f32 v[16:17], v[24:25], v[168:169], v[16:17] op_sel_hi:[0,1,1]
	v_pk_fma_f32 v[18:19], v[28:29], v[190:191], v[18:19] op_sel_hi:[0,1,1]
	v_pk_fma_f32 v[20:21], v[32:33], v[192:193], v[20:21] op_sel_hi:[0,1,1]
	v_pk_fma_f32 v[22:23], v[36:37], v[206:207], v[22:23] op_sel_hi:[0,1,1]
	v_pk_mul_f32 v[24:25], v[50:51], v[172:173] op_sel:[0,1] op_sel_hi:[1,0]
	v_pk_mul_f32 v[26:27], v[54:55], v[204:205] op_sel:[0,1] op_sel_hi:[1,0]
	v_pk_mul_f32 v[28:29], v[58:59], v[170:171] op_sel:[0,1] op_sel_hi:[1,0]
	v_pk_mul_f32 v[30:31], v[62:63], v[186:187] op_sel:[0,1] op_sel_hi:[1,0]
	v_pk_mul_f32 v[32:33], v[66:67], v[156:157] op_sel:[0,1] op_sel_hi:[1,0]
	v_pk_mul_f32 v[34:35], v[70:71], v[158:159] op_sel:[0,1] op_sel_hi:[1,0]
	v_pk_mul_f32 v[36:37], v[74:75], v[160:161] op_sel:[0,1] op_sel_hi:[1,0]
	v_pk_fma_f32 v[24:25], v[40:41], v[172:173], v[24:25] op_sel_hi:[0,1,1]
	v_pk_fma_f32 v[26:27], v[44:45], v[204:205], v[26:27] op_sel_hi:[0,1,1]
	v_pk_fma_f32 v[28:29], v[48:49], v[170:171], v[28:29] op_sel_hi:[0,1,1]
	v_pk_fma_f32 v[30:31], v[52:53], v[186:187], v[30:31] op_sel_hi:[0,1,1]
	v_pk_fma_f32 v[32:33], v[56:57], v[156:157], v[32:33] op_sel_hi:[0,1,1]
	v_pk_fma_f32 v[34:35], v[60:61], v[158:159], v[34:35] op_sel_hi:[0,1,1]
	v_pk_fma_f32 v[36:37], v[64:65], v[160:161], v[36:37] op_sel_hi:[0,1,1]
	v_pk_mul_f32 v[38:39], v[78:79], v[182:183] op_sel:[0,1] op_sel_hi:[1,0]
	v_pk_mul_f32 v[40:41], v[82:83], v[152:153] op_sel:[0,1] op_sel_hi:[1,0]
	v_pk_mul_f32 v[42:43], v[86:87], v[176:177] op_sel:[0,1] op_sel_hi:[1,0]
	v_pk_mul_f32 v[44:45], v[90:91], v[162:163] op_sel:[0,1] op_sel_hi:[1,0]
	v_pk_mul_f32 v[46:47], v[94:95], v[178:179] op_sel:[0,1] op_sel_hi:[1,0]
	v_pk_mul_f32 v[48:49], v[98:99], v[148:149] op_sel:[0,1] op_sel_hi:[1,0]
	v_pk_mul_f32 v[50:51], v[102:103], v[174:175] op_sel:[0,1] op_sel_hi:[1,0]
	v_pk_mul_f32 v[52:53], v[106:107], v[188:189] op_sel:[0,1] op_sel_hi:[1,0]
	v_pk_mul_f32 v[54:55], v[110:111], v[184:185] op_sel:[0,1] op_sel_hi:[1,0]
	v_pk_mul_f32 v[56:57], v[114:115], v[154:155] op_sel:[0,1] op_sel_hi:[1,0]
	v_pk_mul_f32 v[58:59], v[118:119], v[194:195] op_sel:[0,1] op_sel_hi:[1,0]
	v_pk_mul_f32 v[60:61], v[122:123], v[164:165] op_sel:[0,1] op_sel_hi:[1,0]
	v_pk_mul_f32 v[62:63], v[124:125], v[144:145] op_sel:[0,1] op_sel_hi:[1,0]
	v_pk_mul_f32 v[64:65], v[126:127], v[128:129] op_sel:[0,1] op_sel_hi:[1,0]
	v_pk_fma_f32 v[38:39], v[68:69], v[182:183], v[38:39] op_sel_hi:[0,1,1]
	v_pk_fma_f32 v[40:41], v[72:73], v[152:153], v[40:41] op_sel_hi:[0,1,1]
	v_pk_fma_f32 v[42:43], v[76:77], v[176:177], v[42:43] op_sel_hi:[0,1,1]
	v_pk_fma_f32 v[44:45], v[80:81], v[162:163], v[44:45] op_sel_hi:[0,1,1]
	v_pk_fma_f32 v[46:47], v[84:85], v[178:179], v[46:47] op_sel_hi:[0,1,1]
	v_pk_fma_f32 v[48:49], v[88:89], v[148:149], v[48:49] op_sel_hi:[0,1,1]
	v_pk_fma_f32 v[50:51], v[92:93], v[174:175], v[50:51] op_sel_hi:[0,1,1]
	v_pk_fma_f32 v[52:53], v[96:97], v[188:189], v[52:53] op_sel_hi:[0,1,1]
	v_pk_fma_f32 v[54:55], v[100:101], v[184:185], v[54:55] op_sel_hi:[0,1,1]
	v_pk_fma_f32 v[56:57], v[104:105], v[154:155], v[56:57] op_sel_hi:[0,1,1]
	v_pk_fma_f32 v[58:59], v[108:109], v[194:195], v[58:59] op_sel_hi:[0,1,1]
	v_pk_fma_f32 v[60:61], v[112:113], v[164:165], v[60:61] op_sel_hi:[0,1,1]
	v_pk_fma_f32 v[62:63], v[116:117], v[144:145], v[62:63] op_sel_hi:[0,1,1]
	v_pk_fma_f32 v[64:65], v[120:121], v[128:129], v[64:65] op_sel_hi:[0,1,1]
	ds_write2_b64 v2, v[130:131], v[34:35] offset1:16
	ds_write2_b64 v2, v[18:19], v[50:51] offset0:33 offset1:49
	ds_write2_b64 v2, v[10:11], v[42:43] offset0:66 offset1:82
	ds_write2_b64 v2, v[26:27], v[58:59] offset0:99 offset1:115
	ds_write2_b64 v2, v[6:7], v[38:39] offset0:132 offset1:148
	ds_write2_b64 v2, v[22:23], v[54:55] offset0:165 offset1:181
	ds_write2_b64 v2, v[14:15], v[46:47] offset0:198 offset1:214
	ds_write2_b64 v2, v[30:31], v[62:63] offset0:231 offset1:247
	ds_write2_b64 v143, v[4:5], v[36:37] offset0:8 offset1:24
	ds_write2_b64 v143, v[20:21], v[52:53] offset0:41 offset1:57
	ds_write2_b64 v143, v[12:13], v[44:45] offset0:74 offset1:90
	ds_write2_b64 v143, v[28:29], v[60:61] offset0:107 offset1:123
	ds_write2_b64 v143, v[8:9], v[40:41] offset0:140 offset1:156
	ds_write2_b64 v143, v[24:25], v[56:57] offset0:173 offset1:189
	ds_write2_b64 v143, v[16:17], v[48:49] offset0:206 offset1:222
	ds_write2_b64 v143, v[32:33], v[64:65] offset0:239 offset1:255
	s_waitcnt lgkmcnt(0)
	s_barrier
	s_nop 0
	v_ashrrev_i32_e32 v2, 31, v142
	v_lshrrev_b32_e32 v2, 23, v2
	v_add_u32_e32 v2, v142, v2
	v_ashrrev_i32_e32 v2, 9, v2
	v_mul_i32_i24_e32 v4, 0x200, v2
	v_sub_u32_e32 v144, v142, v4
	v_lshlrev_b32_e32 v143, 14, v2
	v_lshlrev_b32_e32 v2, 1, v144
	v_bfrev_b32_e32 v2, v2
	v_lshrrev_b32_e32 v2, 22, v2
	v_sub_u32_e32 v2, 0x400, v2
	v_bfrev_b32_e32 v2, v2
	v_lshrrev_b32_e32 v2, 18, v2
	v_and_b32_e32 v2, 0x3ff0, v2
	v_cmp_eq_u32_e32 vcc, 0, v144
	v_lshl_add_u32 v4, v144, 5, v143
	v_lshlrev_b32_e32 v5, 3, v4
	v_cndmask_b32_e64 v2, v2, 16, vcc
	v_ashrrev_i32_e32 v4, 2, v4
	v_or_b32_e32 v2, v2, v143
	v_add3_u32 v56, 0, v5, v4
	v_ashrrev_i32_e32 v4, 5, v2
	v_lshlrev_b32_e32 v2, 3, v2
	v_lshlrev_b32_e32 v4, 3, v4
	v_add3_u32 v2, 0, v2, v4
	ds_read2_b64 v[4:7], v56 offset1:1
	ds_read2_b64 v[8:11], v56 offset0:2 offset1:3
	ds_read2_b64 v[12:15], v2 offset1:1
	ds_read2_b64 v[16:19], v2 offset0:2 offset1:3
	ds_read2_b64 v[20:23], v56 offset0:4 offset1:5
	ds_read2_b64 v[24:27], v56 offset0:6 offset1:7
	ds_read2_b64 v[28:31], v2 offset0:4 offset1:5
	ds_read2_b64 v[32:35], v2 offset0:6 offset1:7
	ds_read2_b64 v[36:39], v56 offset0:8 offset1:9
	ds_read2_b64 v[40:43], v56 offset0:10 offset1:11
	ds_read2_b64 v[48:51], v2 offset0:8 offset1:9
	ds_read2_b64 v[52:55], v2 offset0:10 offset1:11
	ds_read2_b64 v[44:47], v56 offset0:12 offset1:13
	ds_read2_b64 v[56:59], v56 offset0:14 offset1:15
	ds_read2_b64 v[70:73], v2 offset0:12 offset1:13
	ds_read2_b64 v[98:101], v2 offset0:14 offset1:15
	s_waitcnt lgkmcnt(7)
	v_pk_add_f32 v[60:61], v[4:5], v[36:37]
	v_pk_add_f32 v[4:5], v[4:5], v[36:37] neg_lo:[0,1] neg_hi:[0,1]
	v_pk_add_f32 v[36:37], v[6:7], v[38:39]
	v_pk_add_f32 v[6:7], v[6:7], v[38:39] neg_lo:[0,1] neg_hi:[0,1]
	s_waitcnt lgkmcnt(3)
	v_pk_add_f32 v[62:63], v[22:23], v[46:47]
	v_pk_mul_f32 v[38:39], v[6:7], s[24:25]
	v_pk_add_f32 v[22:23], v[22:23], v[46:47] neg_lo:[0,1] neg_hi:[0,1]
	v_pk_fma_f32 v[6:7], v[6:7], s[22:23], v[38:39] op_sel:[0,0,1] op_sel_hi:[1,0,0]
	v_pk_add_f32 v[38:39], v[8:9], v[40:41]
	v_pk_add_f32 v[8:9], v[8:9], v[40:41] neg_lo:[0,1] neg_hi:[0,1]
	v_pk_mul_f32 v[46:47], v[22:23], s[44:45]
	v_pk_mul_f32 v[40:41], v[8:9], s[40:41]
	v_pk_fma_f32 v[22:23], v[22:23], s[50:51], v[46:47] op_sel:[0,0,1] op_sel_hi:[1,0,0] neg_lo:[1,0,0] neg_hi:[1,0,0]
	v_pk_fma_f32 v[8:9], v[8:9], s[38:39], v[40:41] op_sel:[0,0,1] op_sel_hi:[1,0,0]
	v_pk_add_f32 v[40:41], v[10:11], v[42:43]
	v_pk_add_f32 v[10:11], v[10:11], v[42:43] neg_lo:[0,1] neg_hi:[0,1]
	s_waitcnt lgkmcnt(2)
	v_pk_add_f32 v[46:47], v[24:25], v[56:57]
	v_pk_add_f32 v[24:25], v[24:25], v[56:57] neg_lo:[0,1] neg_hi:[0,1]
	v_pk_mul_f32 v[42:43], v[10:11], s[44:45]
	v_pk_mul_f32 v[56:57], v[24:25], s[40:41]
	v_pk_fma_f32 v[10:11], v[10:11], s[50:51], v[42:43] op_sel:[0,0,1] op_sel_hi:[1,0,0]
	v_pk_add_f32 v[42:43], v[20:21], v[44:45]
	v_pk_add_f32 v[44:45], v[20:21], v[44:45] neg_lo:[0,1] neg_hi:[0,1]
	v_pk_fma_f32 v[24:25], v[24:25], s[38:39], v[56:57] op_sel:[0,0,1] op_sel_hi:[1,0,0] neg_lo:[1,0,0] neg_hi:[1,0,0]
	v_pk_add_f32 v[56:57], v[26:27], v[58:59]
	v_pk_add_f32 v[26:27], v[26:27], v[58:59] neg_lo:[0,1] neg_hi:[0,1]
	v_pk_mul_f32 v[58:59], v[26:27], s[24:25]
	v_pk_add_f32 v[64:65], v[40:41], v[56:57]
	v_pk_add_f32 v[40:41], v[40:41], v[56:57] neg_lo:[0,1] neg_hi:[0,1]
	v_pk_fma_f32 v[26:27], v[26:27], s[22:23], v[58:59] op_sel:[0,0,1] op_sel_hi:[1,0,0] neg_lo:[1,0,0] neg_hi:[1,0,0]
	v_pk_mul_f32 v[56:57], v[40:41], s[40:41]
	v_pk_add_f32 v[20:21], v[4:5], v[44:45] op_sel:[0,1] op_sel_hi:[1,0] neg_hi:[0,1]
	v_pk_add_f32 v[4:5], v[4:5], v[44:45] op_sel:[0,1] op_sel_hi:[1,0] neg_lo:[0,1]
	v_pk_add_f32 v[44:45], v[6:7], v[22:23]
	v_pk_add_f32 v[6:7], v[6:7], v[22:23] neg_lo:[0,1] neg_hi:[0,1]
	v_pk_fma_f32 v[40:41], v[40:41], s[38:39], v[56:57] op_sel:[0,0,1] op_sel_hi:[1,0,0] neg_lo:[1,0,0] neg_hi:[1,0,0]
	v_pk_mul_f32 v[22:23], v[6:7], s[40:41]
	v_pk_add_f32 v[56:57], v[10:11], v[26:27]
	v_pk_add_f32 v[10:11], v[10:11], v[26:27] neg_lo:[0,1] neg_hi:[0,1]
	v_pk_add_f32 v[58:59], v[60:61], v[42:43]
	v_pk_add_f32 v[42:43], v[60:61], v[42:43] neg_lo:[0,1] neg_hi:[0,1]
	v_pk_add_f32 v[60:61], v[36:37], v[62:63]
	v_pk_add_f32 v[36:37], v[36:37], v[62:63] neg_lo:[0,1] neg_hi:[0,1]
	v_pk_fma_f32 v[6:7], v[6:7], s[38:39], v[22:23] op_sel:[0,0,1] op_sel_hi:[1,0,0]
	v_pk_add_f32 v[22:23], v[8:9], v[24:25]
	v_pk_add_f32 v[24:25], v[8:9], v[24:25] neg_lo:[0,1] neg_hi:[0,1]
	v_pk_mul_f32 v[26:27], v[10:11], s[40:41]
	v_pk_mul_f32 v[62:63], v[36:37], s[40:41]
	v_pk_fma_f32 v[10:11], v[10:11], s[38:39], v[26:27] op_sel:[0,0,1] op_sel_hi:[1,0,0] neg_lo:[1,0,0] neg_hi:[1,0,0]
	v_pk_fma_f32 v[36:37], v[36:37], s[38:39], v[62:63] op_sel:[0,0,1] op_sel_hi:[1,0,0]
	v_pk_add_f32 v[62:63], v[38:39], v[46:47]
	v_pk_add_f32 v[66:67], v[20:21], v[22:23]
	v_pk_add_f32 v[20:21], v[20:21], v[22:23] neg_lo:[0,1] neg_hi:[0,1]
	v_pk_add_f32 v[22:23], v[44:45], v[56:57]
	v_pk_add_f32 v[44:45], v[44:45], v[56:57] neg_lo:[0,1] neg_hi:[0,1]
	v_pk_add_f32 v[8:9], v[4:5], v[24:25] op_sel:[0,1] op_sel_hi:[1,0] neg_hi:[0,1]
	v_pk_add_f32 v[4:5], v[4:5], v[24:25] op_sel:[0,1] op_sel_hi:[1,0] neg_lo:[0,1]
	v_pk_add_f32 v[24:25], v[6:7], v[10:11]
	v_pk_add_f32 v[10:11], v[6:7], v[10:11] neg_lo:[0,1] neg_hi:[0,1]
	v_pk_add_f32 v[26:27], v[58:59], v[62:63]
	v_pk_add_f32 v[58:59], v[58:59], v[62:63] neg_lo:[0,1] neg_hi:[0,1]
	v_pk_add_f32 v[62:63], v[60:61], v[64:65]
	v_pk_add_f32 v[60:61], v[60:61], v[64:65] neg_lo:[0,1] neg_hi:[0,1]
	v_xor_b32_e32 v57, 0x80000000, v44
	v_mov_b32_e32 v56, v45
	v_xor_b32_e32 v65, 0x80000000, v60
	v_pk_add_f32 v[130:131], v[26:27], v[62:63]
	v_pk_add_f32 v[92:93], v[26:27], v[62:63] neg_lo:[0,1] neg_hi:[0,1]
	v_mov_b32_e32 v64, v61
	v_pk_add_f32 v[62:63], v[20:21], v[56:57]
	v_pk_add_f32 v[78:79], v[20:21], v[56:57] neg_lo:[0,1] neg_hi:[0,1]
	v_pk_add_f32 v[56:57], v[4:5], v[10:11] op_sel:[0,1] op_sel_hi:[1,0] neg_hi:[0,1]
	v_pk_add_f32 v[90:91], v[4:5], v[10:11] op_sel:[0,1] op_sel_hi:[1,0] neg_lo:[0,1]
	v_pk_add_f32 v[10:11], v[14:15], v[50:51] neg_lo:[0,1] neg_hi:[0,1]
	v_pk_add_f32 v[46:47], v[38:39], v[46:47] neg_lo:[0,1] neg_hi:[0,1]
	v_pk_add_f32 v[84:85], v[58:59], v[64:65]
	v_pk_add_f32 v[86:87], v[58:59], v[64:65] neg_lo:[0,1] neg_hi:[0,1]
	v_pk_add_f32 v[80:81], v[8:9], v[24:25]
	v_pk_add_f32 v[64:65], v[8:9], v[24:25] neg_lo:[0,1] neg_hi:[0,1]
	v_pk_add_f32 v[4:5], v[12:13], v[48:49]
	v_pk_add_f32 v[6:7], v[12:13], v[48:49] neg_lo:[0,1] neg_hi:[0,1]
	v_pk_add_f32 v[8:9], v[14:15], v[50:51]
	v_pk_mul_f32 v[12:13], v[10:11], s[24:25]
	v_pk_add_f32 v[14:15], v[16:17], v[52:53] neg_lo:[0,1] neg_hi:[0,1]
	v_pk_fma_f32 v[10:11], v[10:11], s[22:23], v[12:13] op_sel:[0,0,1] op_sel_hi:[1,0,0]
	v_pk_add_f32 v[12:13], v[16:17], v[52:53]
	v_pk_mul_f32 v[16:17], v[14:15], s[40:41]
	v_pk_add_f32 v[38:39], v[42:43], v[46:47] op_sel:[0,1] op_sel_hi:[1,0] neg_hi:[0,1]
	v_pk_add_f32 v[42:43], v[42:43], v[46:47] op_sel:[0,1] op_sel_hi:[1,0] neg_lo:[0,1]
	v_pk_add_f32 v[46:47], v[36:37], v[40:41]
	v_pk_fma_f32 v[14:15], v[14:15], s[38:39], v[16:17] op_sel:[0,0,1] op_sel_hi:[1,0,0]
	v_pk_add_f32 v[16:17], v[18:19], v[54:55]
	v_pk_add_f32 v[18:19], v[18:19], v[54:55] neg_lo:[0,1] neg_hi:[0,1]
	v_pk_add_f32 v[88:89], v[38:39], v[46:47]
	v_pk_add_f32 v[68:69], v[38:39], v[46:47] neg_lo:[0,1] neg_hi:[0,1]
	v_pk_add_f32 v[96:97], v[66:67], v[22:23]
	v_pk_add_f32 v[46:47], v[66:67], v[22:23] neg_lo:[0,1] neg_hi:[0,1]
	v_pk_mul_f32 v[20:21], v[18:19], s[44:45]
	s_waitcnt lgkmcnt(1)
	v_pk_add_f32 v[24:25], v[28:29], v[70:71] neg_lo:[0,1] neg_hi:[0,1]
	v_pk_add_f32 v[26:27], v[30:31], v[72:73] neg_lo:[0,1] neg_hi:[0,1]
	v_pk_fma_f32 v[18:19], v[18:19], s[50:51], v[20:21] op_sel:[0,0,1] op_sel_hi:[1,0,0]
	v_pk_add_f32 v[20:21], v[28:29], v[70:71]
	v_pk_add_f32 v[22:23], v[30:31], v[72:73]
	v_pk_mul_f32 v[28:29], v[26:27], s[44:45]
	s_waitcnt lgkmcnt(0)
	v_pk_add_f32 v[30:31], v[32:33], v[98:99] neg_lo:[0,1] neg_hi:[0,1]
	v_pk_fma_f32 v[26:27], v[26:27], s[50:51], v[28:29] op_sel:[0,0,1] op_sel_hi:[1,0,0] neg_lo:[1,0,0] neg_hi:[1,0,0]
	v_pk_add_f32 v[28:29], v[32:33], v[98:99]
	v_pk_mul_f32 v[32:33], v[30:31], s[40:41]
	v_pk_add_f32 v[36:37], v[36:37], v[40:41] neg_lo:[0,1] neg_hi:[0,1]
	v_pk_fma_f32 v[30:31], v[30:31], s[38:39], v[32:33] op_sel:[0,0,1] op_sel_hi:[1,0,0] neg_lo:[1,0,0] neg_hi:[1,0,0]
	v_pk_add_f32 v[32:33], v[34:35], v[100:101]
	v_pk_add_f32 v[34:35], v[34:35], v[100:101] neg_lo:[0,1] neg_hi:[0,1]
	v_xor_b32_e32 v41, 0x80000000, v36
	v_mov_b32_e32 v40, v37
	v_pk_mul_f32 v[36:37], v[34:35], s[24:25]
	v_mov_b32_e32 v2, v130
	v_pk_fma_f32 v[34:35], v[34:35], s[22:23], v[36:37] op_sel:[0,0,1] op_sel_hi:[1,0,0] neg_lo:[1,0,0] neg_hi:[1,0,0]
	v_pk_add_f32 v[36:37], v[4:5], v[20:21]
	v_pk_add_f32 v[4:5], v[4:5], v[20:21] neg_lo:[0,1] neg_hi:[0,1]
	v_pk_add_f32 v[20:21], v[8:9], v[22:23]
	v_pk_add_f32 v[8:9], v[8:9], v[22:23] neg_lo:[0,1] neg_hi:[0,1]
	v_cmp_ne_u32_e64 s[0:1], 0, v144
	v_pk_mul_f32 v[22:23], v[8:9], s[40:41]
	v_pk_add_f32 v[74:75], v[42:43], v[40:41]
	v_pk_fma_f32 v[8:9], v[8:9], s[38:39], v[22:23] op_sel:[0,0,1] op_sel_hi:[1,0,0]
	v_pk_add_f32 v[22:23], v[12:13], v[28:29]
	v_pk_add_f32 v[28:29], v[12:13], v[28:29] neg_lo:[0,1] neg_hi:[0,1]
	v_pk_add_f32 v[94:95], v[42:43], v[40:41] neg_lo:[0,1] neg_hi:[0,1]
	v_pk_add_f32 v[12:13], v[16:17], v[32:33]
	v_pk_add_f32 v[16:17], v[16:17], v[32:33] neg_lo:[0,1] neg_hi:[0,1]
	s_nop 0
	v_pk_mul_f32 v[32:33], v[16:17], s[40:41]
	s_nop 0
	v_pk_fma_f32 v[16:17], v[16:17], s[38:39], v[32:33] op_sel:[0,0,1] op_sel_hi:[1,0,0] neg_lo:[1,0,0] neg_hi:[1,0,0]
	v_pk_add_f32 v[32:33], v[6:7], v[24:25] op_sel:[0,1] op_sel_hi:[1,0] neg_hi:[0,1]
	v_pk_add_f32 v[6:7], v[6:7], v[24:25] op_sel:[0,1] op_sel_hi:[1,0] neg_lo:[0,1]
	v_pk_add_f32 v[24:25], v[10:11], v[26:27]
	v_pk_add_f32 v[10:11], v[10:11], v[26:27] neg_lo:[0,1] neg_hi:[0,1]
	s_nop 0
	v_pk_mul_f32 v[26:27], v[10:11], s[40:41]
	s_nop 0
	v_pk_fma_f32 v[10:11], v[10:11], s[38:39], v[26:27] op_sel:[0,0,1] op_sel_hi:[1,0,0]
	v_pk_add_f32 v[26:27], v[14:15], v[30:31]
	v_pk_add_f32 v[30:31], v[14:15], v[30:31] neg_lo:[0,1] neg_hi:[0,1]
	s_nop 0
	v_pk_add_f32 v[14:15], v[18:19], v[34:35]
	v_pk_add_f32 v[18:19], v[18:19], v[34:35] neg_lo:[0,1] neg_hi:[0,1]
	s_nop 0
	v_pk_mul_f32 v[34:35], v[18:19], s[40:41]
	s_nop 0
	v_pk_fma_f32 v[18:19], v[18:19], s[38:39], v[34:35] op_sel:[0,0,1] op_sel_hi:[1,0,0] neg_lo:[1,0,0] neg_hi:[1,0,0]
	v_pk_add_f32 v[34:35], v[36:37], v[22:23]
	v_pk_add_f32 v[22:23], v[36:37], v[22:23] neg_lo:[0,1] neg_hi:[0,1]
	v_pk_add_f32 v[36:37], v[20:21], v[12:13]
	v_pk_add_f32 v[12:13], v[20:21], v[12:13] neg_lo:[0,1] neg_hi:[0,1]
	v_pk_add_f32 v[98:99], v[34:35], v[36:37]
	v_xor_b32_e32 v21, 0x80000000, v12
	v_mov_b32_e32 v20, v13
	v_pk_add_f32 v[12:13], v[4:5], v[28:29] op_sel:[0,1] op_sel_hi:[1,0] neg_hi:[0,1]
	v_pk_add_f32 v[4:5], v[4:5], v[28:29] op_sel:[0,1] op_sel_hi:[1,0] neg_lo:[0,1]
	v_pk_add_f32 v[28:29], v[8:9], v[16:17]
	v_pk_add_f32 v[8:9], v[8:9], v[16:17] neg_lo:[0,1] neg_hi:[0,1]
	v_pk_add_f32 v[100:101], v[34:35], v[36:37] neg_lo:[0,1] neg_hi:[0,1]
	v_xor_b32_e32 v17, 0x80000000, v8
	v_mov_b32_e32 v16, v9
	v_pk_add_f32 v[8:9], v[32:33], v[26:27]
	v_pk_add_f32 v[26:27], v[32:33], v[26:27] neg_lo:[0,1] neg_hi:[0,1]
	v_pk_add_f32 v[32:33], v[24:25], v[14:15]
	v_pk_add_f32 v[14:15], v[24:25], v[14:15] neg_lo:[0,1] neg_hi:[0,1]
	v_pk_add_f32 v[102:103], v[22:23], v[20:21]
	v_xor_b32_e32 v25, 0x80000000, v14
	v_mov_b32_e32 v24, v15
	v_pk_add_f32 v[14:15], v[6:7], v[30:31] op_sel:[0,1] op_sel_hi:[1,0] neg_hi:[0,1]
	v_pk_add_f32 v[6:7], v[6:7], v[30:31] op_sel:[0,1] op_sel_hi:[1,0] neg_lo:[0,1]
	v_pk_add_f32 v[30:31], v[10:11], v[18:19]
	v_pk_add_f32 v[10:11], v[10:11], v[18:19] neg_lo:[0,1] neg_hi:[0,1]
	v_pk_add_f32 v[104:105], v[22:23], v[20:21] neg_lo:[0,1] neg_hi:[0,1]
	v_xor_b32_e32 v19, 0x80000000, v10
	v_mov_b32_e32 v18, v11
	v_pk_add_f32 v[106:107], v[12:13], v[28:29]
	v_pk_add_f32 v[108:109], v[12:13], v[28:29] neg_lo:[0,1] neg_hi:[0,1]
	v_pk_add_f32 v[110:111], v[4:5], v[16:17]
	v_pk_add_f32 v[112:113], v[4:5], v[16:17] neg_lo:[0,1] neg_hi:[0,1]
	v_pk_add_f32 v[114:115], v[8:9], v[32:33]
	v_pk_add_f32 v[116:117], v[8:9], v[32:33] neg_lo:[0,1] neg_hi:[0,1]
	v_pk_add_f32 v[118:119], v[26:27], v[24:25]
	v_pk_add_f32 v[120:121], v[26:27], v[24:25] neg_lo:[0,1] neg_hi:[0,1]
	v_pk_add_f32 v[122:123], v[14:15], v[30:31]
	v_pk_add_f32 v[124:125], v[14:15], v[30:31] neg_lo:[0,1] neg_hi:[0,1]
	v_pk_add_f32 v[126:127], v[6:7], v[18:19]
	v_pk_add_f32 v[128:129], v[6:7], v[18:19] neg_lo:[0,1] neg_hi:[0,1]
	v_mov_b32_e32 v4, v131
	v_mov_b32_e32 v5, v3
	v_mov_b64_e32 v[6:7], v[2:3]
	s_and_saveexec_b64 s[50:51], s[0:1]
	s_xor_b64 s[0:1], exec, s[50:51]
	s_cbranch_execz .LBB0_562
	v_pk_add_f32 v[4:5], v[96:97], v[112:113]
	v_pk_add_f32 v[24:25], v[96:97], v[112:113] neg_lo:[0,1] neg_hi:[0,1]
	v_pk_add_f32 v[148:149], v[130:131], v[128:129]
	v_pk_add_f32 v[8:9], v[130:131], v[128:129] neg_lo:[0,1] neg_hi:[0,1]
	v_pk_add_f32 v[128:129], v[126:127], v[92:93]
	v_pk_add_f32 v[10:11], v[126:127], v[92:93] neg_lo:[0,1] neg_hi:[0,1]
	v_pk_add_f32 v[92:93], v[84:85], v[124:125]
	v_pk_add_f32 v[12:13], v[84:85], v[124:125] neg_lo:[0,1] neg_hi:[0,1]
	v_pk_add_f32 v[84:85], v[122:123], v[86:87]
	v_pk_add_f32 v[14:15], v[122:123], v[86:87] neg_lo:[0,1] neg_hi:[0,1]
	v_pk_add_f32 v[86:87], v[88:89], v[120:121]
	v_pk_add_f32 v[16:17], v[88:89], v[120:121] neg_lo:[0,1] neg_hi:[0,1]
	v_pk_add_f32 v[88:89], v[118:119], v[68:69]
	v_pk_add_f32 v[18:19], v[118:119], v[68:69] neg_lo:[0,1] neg_hi:[0,1]
	v_pk_add_f32 v[68:69], v[74:75], v[116:117]
	v_pk_add_f32 v[20:21], v[74:75], v[116:117] neg_lo:[0,1] neg_hi:[0,1]
	v_pk_add_f32 v[74:75], v[114:115], v[94:95]
	v_pk_add_f32 v[22:23], v[114:115], v[94:95] neg_lo:[0,1] neg_hi:[0,1]
	v_mov_b32_e32 v6, v4
	v_mov_b32_e32 v7, v25
	v_pk_mov_b32 v[4:5], v[4:5], v[24:25] op_sel:[1,0]
	v_pk_add_f32 v[94:95], v[110:111], v[46:47]
	v_pk_add_f32 v[24:25], v[110:111], v[46:47] neg_lo:[0,1] neg_hi:[0,1]
	v_pk_add_f32 v[46:47], v[62:63], v[108:109]
	v_pk_add_f32 v[26:27], v[62:63], v[108:109] neg_lo:[0,1] neg_hi:[0,1]
	v_pk_add_f32 v[62:63], v[106:107], v[78:79]
	v_pk_add_f32 v[28:29], v[106:107], v[78:79] neg_lo:[0,1] neg_hi:[0,1]
	v_pk_add_f32 v[78:79], v[80:81], v[104:105]
	v_pk_add_f32 v[30:31], v[80:81], v[104:105] neg_lo:[0,1] neg_hi:[0,1]
	v_pk_add_f32 v[80:81], v[102:103], v[64:65]
	v_pk_add_f32 v[32:33], v[102:103], v[64:65] neg_lo:[0,1] neg_hi:[0,1]
	v_pk_add_f32 v[64:65], v[56:57], v[100:101]
	v_pk_add_f32 v[34:35], v[56:57], v[100:101] neg_lo:[0,1] neg_hi:[0,1]
	v_pk_add_f32 v[56:57], v[98:99], v[90:91]
	v_pk_add_f32 v[36:37], v[98:99], v[90:91] neg_lo:[0,1] neg_hi:[0,1]
	v_pk_mul_f32 v[6:7], v[6:7], 0.5 op_sel_hi:[1,0]
	v_pk_mul_f32 v[4:5], v[4:5], s[46:47]
	v_mov_b32_e32 v39, v8
	v_mov_b32_e32 v38, v149
	v_mov_b32_e32 v41, v10
	v_mov_b32_e32 v40, v129
	v_mov_b32_e32 v43, v12
	v_mov_b32_e32 v42, v93
	v_mov_b32_e32 v45, v14
	v_mov_b32_e32 v44, v85
	v_mov_b32_e32 v49, v16
	v_mov_b32_e32 v48, v87
	v_mov_b32_e32 v51, v18
	v_mov_b32_e32 v50, v89
	v_mov_b32_e32 v53, v20
	v_mov_b32_e32 v52, v69
	v_mov_b32_e32 v55, v22
	v_mov_b32_e32 v54, v75
	v_mov_b32_e32 v59, v24
	v_mov_b32_e32 v58, v95
	v_mov_b32_e32 v61, v26
	v_mov_b32_e32 v60, v47
	v_mov_b32_e32 v67, v28
	v_mov_b32_e32 v66, v63
	v_mov_b32_e32 v71, v30
	v_mov_b32_e32 v70, v79
	v_mov_b32_e32 v73, v32
	v_mov_b32_e32 v72, v81
	v_mov_b32_e32 v77, v34
	v_mov_b32_e32 v76, v65
	v_mov_b32_e32 v83, v36
	v_mov_b32_e32 v82, v57
	v_mov_b32_e32 v8, v148
	v_mov_b32_e32 v10, v128
	v_mov_b32_e32 v12, v92
	v_mov_b32_e32 v14, v84
	v_mov_b32_e32 v16, v86
	v_mov_b32_e32 v18, v88
	v_mov_b32_e32 v20, v68
	v_mov_b32_e32 v22, v74
	v_mov_b32_e32 v24, v94
	v_mov_b32_e32 v26, v46
	v_mov_b32_e32 v28, v62
	v_mov_b32_e32 v30, v78
	v_mov_b32_e32 v32, v80
	v_mov_b32_e32 v34, v64
	v_mov_b32_e32 v36, v56

.LBB0_574:
	s_or_b64 exec, exec, s[0:1]
	v_mov_b32_e32 v2, v142
	s_waitcnt lgkmcnt(0)
	s_barrier
	s_mov_b32 s19, s16
	v_and_b32_e32 v4, 0xff, v2
	v_lshlrev_b32_e32 v5, 5, v2
	v_and_or_b32 v4, v5, s68, v4
	v_ashrrev_i32_e32 v5, 5, v4
	v_cvt_f32_ubyte0_e32 v2, v2
	v_lshlrev_b32_e32 v7, 3, v4
	v_mul_f32_e32 v2, 0x39000000, v2
	v_lshlrev_b32_e32 v5, 3, v5
	v_sin_f32_e32 v4, v2
	v_cos_f32_e32 v6, v2
	v_add3_u32 v2, 0, v7, v5
	ds_read_b64 v[128:129], v2
	ds_read_b64 v[130:131], v2 offset:2112
	ds_read_b64 v[144:145], v2 offset:4224
	ds_read_b64 v[148:149], v2 offset:6336
	ds_read_b64 v[150:151], v2 offset:8448
	ds_read_b64 v[152:153], v2 offset:10560
	ds_read_b64 v[154:155], v2 offset:12672
	ds_read_b64 v[156:157], v2 offset:14784
	ds_read_b64 v[158:159], v2 offset:16896
	ds_read_b64 v[160:161], v2 offset:19008
	ds_read_b64 v[162:163], v2 offset:21120
	ds_read_b64 v[164:165], v2 offset:23232
	ds_read_b64 v[166:167], v2 offset:25344
	ds_read_b64 v[168:169], v2 offset:27456
	ds_read_b64 v[170:171], v2 offset:29568
	ds_read_b64 v[172:173], v2 offset:31680
	ds_read_b64 v[174:175], v2 offset:33792
	ds_read_b64 v[176:177], v2 offset:35904
	ds_read_b64 v[178:179], v2 offset:38016
	ds_read_b64 v[180:181], v2 offset:40128
	ds_read_b64 v[182:183], v2 offset:42240
	ds_read_b64 v[184:185], v2 offset:44352
	ds_read_b64 v[186:187], v2 offset:46464
	ds_read_b64 v[188:189], v2 offset:48576
	ds_read_b64 v[190:191], v2 offset:50688
	ds_read_b64 v[192:193], v2 offset:52800
	ds_read_b64 v[194:195], v2 offset:54912
	ds_read_b64 v[196:197], v2 offset:57024
	ds_read_b64 v[198:199], v2 offset:59136
	ds_read_b64 v[204:205], v2 offset:61248
	ds_read_b64 v[206:207], v2 offset:63360
	ds_read_b64 v[208:209], v2 offset:65472
	s_waitcnt lgkmcnt(14)
	v_pk_add_f32 v[210:211], v[128:129], v[174:175]
	v_pk_add_f32 v[128:129], v[128:129], v[174:175] neg_lo:[0,1] neg_hi:[0,1]
	v_pk_add_f32 v[174:175], v[130:131], v[176:177]
	v_pk_add_f32 v[130:131], v[130:131], v[176:177] neg_lo:[0,1] neg_hi:[0,1]
	s_mov_b32 s0, s9
	v_pk_mul_f32 v[176:177], v[130:131], s[18:19]
	s_mov_b32 s41, s38
	v_pk_fma_f32 v[130:131], v[130:131], s[0:1], v[176:177] op_sel:[0,0,1] op_sel_hi:[1,0,0]
	s_waitcnt lgkmcnt(13)
	v_pk_add_f32 v[176:177], v[144:145], v[178:179]
	v_pk_add_f32 v[144:145], v[144:145], v[178:179] neg_lo:[0,1] neg_hi:[0,1]
	s_mov_b32 s43, s26
	v_pk_mul_f32 v[178:179], v[144:145], s[24:25]
	s_mov_b32 s62, s37
	v_pk_fma_f32 v[144:145], v[144:145], s[22:23], v[178:179] op_sel:[0,0,1] op_sel_hi:[1,0,0]
	s_waitcnt lgkmcnt(12)
	v_pk_add_f32 v[178:179], v[148:149], v[180:181]
	v_pk_add_f32 v[148:149], v[148:149], v[180:181] neg_lo:[0,1] neg_hi:[0,1]
	s_mov_b32 s45, s22
	v_pk_mul_f32 v[180:181], v[148:149], s[36:37]
	s_mov_b32 s50, s25
	v_pk_fma_f32 v[148:149], v[148:149], s[26:27], v[180:181] op_sel:[0,0,1] op_sel_hi:[1,0,0]
	s_waitcnt lgkmcnt(11)
	v_pk_add_f32 v[180:181], v[150:151], v[182:183]
	v_pk_add_f32 v[150:151], v[150:151], v[182:183] neg_lo:[0,1] neg_hi:[0,1]
	v_xor_b32_e32 v7, 0x80000000, v4
	v_pk_mul_f32 v[182:183], v[150:151], s[40:41]
	v_mov_b32_e32 v5, v7
	v_pk_fma_f32 v[150:151], v[150:151], s[38:39], v[182:183] op_sel:[0,0,1] op_sel_hi:[1,0,0]
	s_waitcnt lgkmcnt(10)
	v_pk_add_f32 v[182:183], v[152:153], v[184:185]
	v_pk_add_f32 v[152:153], v[152:153], v[184:185] neg_lo:[0,1] neg_hi:[0,1]
	v_pk_mul_f32 v[8:9], v[6:7], v[4:5] op_sel:[1,0] op_sel_hi:[0,1]
	v_pk_mul_f32 v[184:185], v[152:153], s[42:43]
	v_pk_fma_f32 v[8:9], v[6:7], v[6:7], v[8:9] op_sel_hi:[1,0,1]
	v_pk_fma_f32 v[152:153], v[152:153], s[62:63], v[184:185] op_sel:[0,0,1] op_sel_hi:[1,0,0]
	s_waitcnt lgkmcnt(9)
	v_pk_add_f32 v[184:185], v[154:155], v[186:187]
	v_pk_add_f32 v[154:155], v[154:155], v[186:187] neg_lo:[0,1] neg_hi:[0,1]
	v_xor_b32_e32 v14, 0x80000000, v9
	v_pk_mul_f32 v[186:187], v[154:155], s[44:45]
	v_mov_b32_e32 v15, v9
	v_pk_fma_f32 v[154:155], v[154:155], s[50:51], v[186:187] op_sel:[0,0,1] op_sel_hi:[1,0,0]
	s_waitcnt lgkmcnt(8)
	v_pk_add_f32 v[186:187], v[156:157], v[188:189]
	v_pk_add_f32 v[156:157], v[156:157], v[188:189] neg_lo:[0,1] neg_hi:[0,1]
	v_pk_mul_f32 v[12:13], v[8:9], v[14:15] op_sel:[1,0] op_sel_hi:[0,1]
	v_pk_mul_f32 v[188:189], v[156:157], s[8:9]
	v_pk_fma_f32 v[12:13], v[8:9], v[8:9], v[12:13] op_sel_hi:[1,0,1]
	v_pk_fma_f32 v[156:157], v[156:157], s[16:17], v[188:189] op_sel:[0,0,1] op_sel_hi:[1,0,0]
	s_waitcnt lgkmcnt(7)
	v_pk_add_f32 v[188:189], v[158:159], v[190:191]
	v_pk_add_f32 v[190:191], v[158:159], v[190:191] neg_lo:[0,1] neg_hi:[0,1]
	v_xor_b32_e32 v16, 0x80000000, v13
	s_waitcnt lgkmcnt(6)
	v_pk_add_f32 v[158:159], v[160:161], v[192:193]
	v_pk_add_f32 v[160:161], v[160:161], v[192:193] neg_lo:[0,1] neg_hi:[0,1]
	v_mov_b32_e32 v17, v13
	v_pk_mul_f32 v[192:193], v[160:161], s[8:9]
	v_pk_mul_f32 v[28:29], v[12:13], v[16:17] op_sel:[1,0] op_sel_hi:[0,1]
	v_pk_fma_f32 v[160:161], v[160:161], s[16:17], v[192:193] op_sel:[0,0,1] op_sel_hi:[1,0,0] neg_lo:[1,0,0] neg_hi:[1,0,0]
	s_waitcnt lgkmcnt(5)
	v_pk_add_f32 v[192:193], v[162:163], v[194:195]
	v_pk_add_f32 v[162:163], v[162:163], v[194:195] neg_lo:[0,1] neg_hi:[0,1]
	v_pk_fma_f32 v[28:29], v[12:13], v[12:13], v[28:29] op_sel_hi:[1,0,1]
	v_pk_mul_f32 v[194:195], v[162:163], s[44:45]
	v_pk_mul_f32 v[44:45], v[16:17], v[28:29] op_sel:[0,1] op_sel_hi:[1,0]
	v_pk_fma_f32 v[162:163], v[162:163], s[50:51], v[194:195] op_sel:[0,0,1] op_sel_hi:[1,0,0] neg_lo:[1,0,0] neg_hi:[1,0,0]
	s_waitcnt lgkmcnt(4)
	v_pk_add_f32 v[194:195], v[164:165], v[196:197]
	v_pk_add_f32 v[164:165], v[164:165], v[196:197] neg_lo:[0,1] neg_hi:[0,1]
	v_pk_fma_f32 v[44:45], v[12:13], v[28:29], v[44:45] op_sel_hi:[0,1,1]
	v_pk_mul_f32 v[196:197], v[164:165], s[42:43]
	v_pk_mul_f32 v[60:61], v[16:17], v[44:45] op_sel:[0,1] op_sel_hi:[1,0]
	v_pk_fma_f32 v[164:165], v[164:165], s[62:63], v[196:197] op_sel:[0,0,1] op_sel_hi:[1,0,0] neg_lo:[1,0,0] neg_hi:[1,0,0]
	s_waitcnt lgkmcnt(3)
	v_pk_add_f32 v[196:197], v[166:167], v[198:199]
	v_pk_add_f32 v[166:167], v[166:167], v[198:199] neg_lo:[0,1] neg_hi:[0,1]
	v_pk_fma_f32 v[60:61], v[12:13], v[44:45], v[60:61] op_sel_hi:[0,1,1]
	v_pk_mul_f32 v[198:199], v[166:167], s[40:41]
	v_pk_mul_f32 v[76:77], v[16:17], v[60:61] op_sel:[0,1] op_sel_hi:[1,0]
	v_pk_fma_f32 v[166:167], v[166:167], s[38:39], v[198:199] op_sel:[0,0,1] op_sel_hi:[1,0,0] neg_lo:[1,0,0] neg_hi:[1,0,0]
	s_waitcnt lgkmcnt(2)
	v_pk_add_f32 v[198:199], v[168:169], v[204:205]
	v_pk_add_f32 v[168:169], v[168:169], v[204:205] neg_lo:[0,1] neg_hi:[0,1]
	v_pk_fma_f32 v[76:77], v[12:13], v[60:61], v[76:77] op_sel_hi:[0,1,1]
	v_pk_mul_f32 v[204:205], v[168:169], s[36:37]
	v_pk_mul_f32 v[92:93], v[16:17], v[76:77] op_sel:[0,1] op_sel_hi:[1,0]
	v_pk_fma_f32 v[168:169], v[168:169], s[26:27], v[204:205] op_sel:[0,0,1] op_sel_hi:[1,0,0] neg_lo:[1,0,0] neg_hi:[1,0,0]
	s_waitcnt lgkmcnt(1)
	v_pk_add_f32 v[204:205], v[170:171], v[206:207]
	v_pk_add_f32 v[170:171], v[170:171], v[206:207] neg_lo:[0,1] neg_hi:[0,1]
	v_pk_fma_f32 v[92:93], v[12:13], v[76:77], v[92:93] op_sel_hi:[0,1,1]
	v_pk_mul_f32 v[206:207], v[170:171], s[24:25]
	v_pk_mul_f32 v[108:109], v[16:17], v[92:93] op_sel:[0,1] op_sel_hi:[1,0]
	v_pk_fma_f32 v[170:171], v[170:171], s[22:23], v[206:207] op_sel:[0,0,1] op_sel_hi:[1,0,0] neg_lo:[1,0,0] neg_hi:[1,0,0]
	s_waitcnt lgkmcnt(0)
	v_pk_add_f32 v[206:207], v[172:173], v[208:209]
	v_pk_add_f32 v[172:173], v[172:173], v[208:209] neg_lo:[0,1] neg_hi:[0,1]
	v_pk_mul_f32 v[10:11], v[4:5], v[8:9] op_sel:[0,1] op_sel_hi:[1,0]
	v_pk_mul_f32 v[208:209], v[172:173], s[18:19]
	v_pk_fma_f32 v[108:109], v[12:13], v[92:93], v[108:109] op_sel_hi:[0,1,1]
	v_pk_fma_f32 v[172:173], v[172:173], s[0:1], v[208:209] op_sel:[0,0,1] op_sel_hi:[1,0,0] neg_lo:[1,0,0] neg_hi:[1,0,0]
	v_pk_add_f32 v[208:209], v[210:211], v[188:189]
	v_pk_add_f32 v[188:189], v[210:211], v[188:189] neg_lo:[0,1] neg_hi:[0,1]
	v_pk_add_f32 v[210:211], v[174:175], v[158:159]
	v_pk_add_f32 v[158:159], v[174:175], v[158:159] neg_lo:[0,1] neg_hi:[0,1]
	v_pk_fma_f32 v[10:11], v[6:7], v[8:9], v[10:11] op_sel_hi:[0,1,1]
	v_pk_mul_f32 v[174:175], v[158:159], s[24:25]
	v_pk_mul_f32 v[18:19], v[4:5], v[12:13] op_sel:[0,1] op_sel_hi:[1,0]
	v_pk_fma_f32 v[158:159], v[158:159], s[22:23], v[174:175] op_sel:[0,0,1] op_sel_hi:[1,0,0]
	v_pk_add_f32 v[174:175], v[176:177], v[192:193]
	v_pk_add_f32 v[176:177], v[176:177], v[192:193] neg_lo:[0,1] neg_hi:[0,1]
	v_pk_mul_f32 v[32:33], v[4:5], v[28:29] op_sel:[0,1] op_sel_hi:[1,0]
	v_pk_mul_f32 v[192:193], v[176:177], s[40:41]
	v_pk_mul_f32 v[48:49], v[4:5], v[44:45] op_sel:[0,1] op_sel_hi:[1,0]
	v_pk_fma_f32 v[176:177], v[176:177], s[38:39], v[192:193] op_sel:[0,0,1] op_sel_hi:[1,0,0]
	v_pk_add_f32 v[192:193], v[178:179], v[194:195]
	v_pk_add_f32 v[178:179], v[178:179], v[194:195] neg_lo:[0,1] neg_hi:[0,1]
	v_pk_mul_f32 v[64:65], v[4:5], v[60:61] op_sel:[0,1] op_sel_hi:[1,0]
	v_pk_mul_f32 v[194:195], v[178:179], s[44:45]
	v_pk_mul_f32 v[80:81], v[4:5], v[76:77] op_sel:[0,1] op_sel_hi:[1,0]
	v_pk_fma_f32 v[178:179], v[178:179], s[50:51], v[194:195] op_sel:[0,0,1] op_sel_hi:[1,0,0]
	v_pk_add_f32 v[194:195], v[180:181], v[196:197]
	v_pk_add_f32 v[196:197], v[180:181], v[196:197] neg_lo:[0,1] neg_hi:[0,1]
	v_pk_mul_f32 v[96:97], v[4:5], v[92:93] op_sel:[0,1] op_sel_hi:[1,0]
	v_pk_add_f32 v[180:181], v[182:183], v[198:199]
	v_pk_add_f32 v[182:183], v[182:183], v[198:199] neg_lo:[0,1] neg_hi:[0,1]
	v_pk_mul_f32 v[112:113], v[4:5], v[108:109] op_sel:[0,1] op_sel_hi:[1,0]
	v_pk_mul_f32 v[198:199], v[182:183], s[44:45]
	v_xor_b32_e32 v22, 0x80000000, v11
	v_pk_fma_f32 v[182:183], v[182:183], s[50:51], v[198:199] op_sel:[0,0,1] op_sel_hi:[1,0,0] neg_lo:[1,0,0] neg_hi:[1,0,0]
	v_pk_add_f32 v[198:199], v[184:185], v[204:205]
	v_pk_add_f32 v[184:185], v[184:185], v[204:205] neg_lo:[0,1] neg_hi:[0,1]
	v_mov_b32_e32 v23, v11
	v_pk_mul_f32 v[204:205], v[184:185], s[40:41]
	v_pk_fma_f32 v[18:19], v[6:7], v[12:13], v[18:19] op_sel_hi:[0,1,1]
	v_pk_fma_f32 v[184:185], v[184:185], s[38:39], v[204:205] op_sel:[0,0,1] op_sel_hi:[1,0,0] neg_lo:[1,0,0] neg_hi:[1,0,0]
	v_pk_add_f32 v[204:205], v[186:187], v[206:207]
	v_pk_add_f32 v[186:187], v[186:187], v[206:207] neg_lo:[0,1] neg_hi:[0,1]
	v_pk_mul_f32 v[20:21], v[14:15], v[12:13] op_sel:[0,1] op_sel_hi:[1,0]
	v_pk_mul_f32 v[206:207], v[186:187], s[24:25]
	v_pk_fma_f32 v[32:33], v[6:7], v[28:29], v[32:33] op_sel_hi:[0,1,1]
	v_pk_fma_f32 v[186:187], v[186:187], s[22:23], v[206:207] op_sel:[0,0,1] op_sel_hi:[1,0,0] neg_lo:[1,0,0] neg_hi:[1,0,0]
	v_pk_add_f32 v[206:207], v[128:129], v[190:191] op_sel:[0,1] op_sel_hi:[1,0] neg_hi:[0,1]
	v_pk_add_f32 v[128:129], v[128:129], v[190:191] op_sel:[0,1] op_sel_hi:[1,0] neg_lo:[0,1]
	v_pk_add_f32 v[190:191], v[130:131], v[160:161]
	v_pk_add_f32 v[130:131], v[130:131], v[160:161] neg_lo:[0,1] neg_hi:[0,1]
	v_pk_mul_f32 v[36:37], v[14:15], v[28:29] op_sel:[0,1] op_sel_hi:[1,0]
	v_pk_mul_f32 v[160:161], v[130:131], s[24:25]
	v_pk_fma_f32 v[48:49], v[6:7], v[44:45], v[48:49] op_sel_hi:[0,1,1]
	v_pk_fma_f32 v[130:131], v[130:131], s[22:23], v[160:161] op_sel:[0,0,1] op_sel_hi:[1,0,0]
	v_pk_add_f32 v[160:161], v[144:145], v[162:163]
	v_pk_add_f32 v[144:145], v[144:145], v[162:163] neg_lo:[0,1] neg_hi:[0,1]
	v_pk_mul_f32 v[52:53], v[14:15], v[44:45] op_sel:[0,1] op_sel_hi:[1,0]
	v_pk_mul_f32 v[162:163], v[144:145], s[40:41]
	v_pk_fma_f32 v[64:65], v[6:7], v[60:61], v[64:65] op_sel_hi:[0,1,1]
	v_pk_fma_f32 v[144:145], v[144:145], s[38:39], v[162:163] op_sel:[0,0,1] op_sel_hi:[1,0,0]
	v_pk_add_f32 v[162:163], v[148:149], v[164:165]
	v_pk_add_f32 v[148:149], v[148:149], v[164:165] neg_lo:[0,1] neg_hi:[0,1]
	v_pk_mul_f32 v[68:69], v[14:15], v[60:61] op_sel:[0,1] op_sel_hi:[1,0]
	v_pk_mul_f32 v[164:165], v[148:149], s[44:45]
	v_pk_fma_f32 v[80:81], v[6:7], v[76:77], v[80:81] op_sel_hi:[0,1,1]
	v_pk_fma_f32 v[148:149], v[148:149], s[50:51], v[164:165] op_sel:[0,0,1] op_sel_hi:[1,0,0]
	v_pk_add_f32 v[164:165], v[150:151], v[166:167]
	v_pk_add_f32 v[166:167], v[150:151], v[166:167] neg_lo:[0,1] neg_hi:[0,1]
	v_pk_mul_f32 v[84:85], v[14:15], v[76:77] op_sel:[0,1] op_sel_hi:[1,0]
	v_pk_add_f32 v[150:151], v[152:153], v[168:169]
	v_pk_add_f32 v[152:153], v[152:153], v[168:169] neg_lo:[0,1] neg_hi:[0,1]
	v_pk_fma_f32 v[96:97], v[6:7], v[92:93], v[96:97] op_sel_hi:[0,1,1]
	v_pk_mul_f32 v[168:169], v[152:153], s[44:45]
	v_pk_mul_f32 v[100:101], v[14:15], v[92:93] op_sel:[0,1] op_sel_hi:[1,0]
	v_pk_fma_f32 v[152:153], v[152:153], s[50:51], v[168:169] op_sel:[0,0,1] op_sel_hi:[1,0,0] neg_lo:[1,0,0] neg_hi:[1,0,0]
	v_pk_add_f32 v[168:169], v[154:155], v[170:171]
	v_pk_add_f32 v[154:155], v[154:155], v[170:171] neg_lo:[0,1] neg_hi:[0,1]
	v_pk_fma_f32 v[112:113], v[6:7], v[108:109], v[112:113] op_sel_hi:[0,1,1]
	v_pk_mul_f32 v[170:171], v[154:155], s[40:41]
	v_pk_mul_f32 v[116:117], v[14:15], v[108:109] op_sel:[0,1] op_sel_hi:[1,0]
	v_pk_fma_f32 v[154:155], v[154:155], s[38:39], v[170:171] op_sel:[0,0,1] op_sel_hi:[1,0,0] neg_lo:[1,0,0] neg_hi:[1,0,0]
	v_pk_add_f32 v[170:171], v[156:157], v[172:173]
	v_pk_add_f32 v[156:157], v[156:157], v[172:173] neg_lo:[0,1] neg_hi:[0,1]
	v_pk_fma_f32 v[20:21], v[8:9], v[12:13], v[20:21] op_sel_hi:[0,1,1]
	v_pk_mul_f32 v[172:173], v[156:157], s[24:25]
	v_pk_mul_f32 v[24:25], v[12:13], v[22:23] op_sel:[1,0] op_sel_hi:[0,1]
	v_pk_fma_f32 v[156:157], v[156:157], s[22:23], v[172:173] op_sel:[0,0,1] op_sel_hi:[1,0,0] neg_lo:[1,0,0] neg_hi:[1,0,0]
	v_pk_add_f32 v[172:173], v[208:209], v[194:195]
	v_pk_add_f32 v[194:195], v[208:209], v[194:195] neg_lo:[0,1] neg_hi:[0,1]
	v_pk_add_f32 v[208:209], v[210:211], v[180:181]
	v_pk_add_f32 v[180:181], v[210:211], v[180:181] neg_lo:[0,1] neg_hi:[0,1]
	v_pk_fma_f32 v[36:37], v[8:9], v[28:29], v[36:37] op_sel_hi:[0,1,1]
	v_pk_mul_f32 v[210:211], v[180:181], s[40:41]
	v_pk_mul_f32 v[40:41], v[22:23], v[28:29] op_sel:[0,1] op_sel_hi:[1,0]
	v_pk_fma_f32 v[180:181], v[180:181], s[38:39], v[210:211] op_sel:[0,0,1] op_sel_hi:[1,0,0]
	v_pk_add_f32 v[210:211], v[174:175], v[198:199]
	v_pk_add_f32 v[198:199], v[174:175], v[198:199] neg_lo:[0,1] neg_hi:[0,1]
	v_pk_fma_f32 v[52:53], v[8:9], v[44:45], v[52:53] op_sel_hi:[0,1,1]
	v_pk_add_f32 v[174:175], v[192:193], v[204:205]
	v_pk_add_f32 v[192:193], v[192:193], v[204:205] neg_lo:[0,1] neg_hi:[0,1]
	v_pk_mul_f32 v[56:57], v[22:23], v[44:45] op_sel:[0,1] op_sel_hi:[1,0]
	v_pk_mul_f32 v[204:205], v[192:193], s[40:41]
	v_pk_fma_f32 v[68:69], v[8:9], v[60:61], v[68:69] op_sel_hi:[0,1,1]
	v_pk_fma_f32 v[192:193], v[192:193], s[38:39], v[204:205] op_sel:[0,0,1] op_sel_hi:[1,0,0] neg_lo:[1,0,0] neg_hi:[1,0,0]
	v_pk_add_f32 v[204:205], v[188:189], v[196:197] op_sel:[0,1] op_sel_hi:[1,0] neg_hi:[0,1]
	v_pk_add_f32 v[188:189], v[188:189], v[196:197] op_sel:[0,1] op_sel_hi:[1,0] neg_lo:[0,1]
	v_pk_add_f32 v[196:197], v[158:159], v[182:183]
	v_pk_add_f32 v[158:159], v[158:159], v[182:183] neg_lo:[0,1] neg_hi:[0,1]
	v_pk_mul_f32 v[72:73], v[22:23], v[60:61] op_sel:[0,1] op_sel_hi:[1,0]
	v_pk_mul_f32 v[182:183], v[158:159], s[40:41]
	v_pk_fma_f32 v[84:85], v[8:9], v[76:77], v[84:85] op_sel_hi:[0,1,1]
	v_pk_fma_f32 v[158:159], v[158:159], s[38:39], v[182:183] op_sel:[0,0,1] op_sel_hi:[1,0,0]
	v_pk_add_f32 v[182:183], v[176:177], v[184:185]
	v_pk_add_f32 v[184:185], v[176:177], v[184:185] neg_lo:[0,1] neg_hi:[0,1]
	v_pk_mul_f32 v[88:89], v[22:23], v[76:77] op_sel:[0,1] op_sel_hi:[1,0]
	v_pk_add_f32 v[176:177], v[178:179], v[186:187]
	v_pk_add_f32 v[178:179], v[178:179], v[186:187] neg_lo:[0,1] neg_hi:[0,1]
	v_pk_fma_f32 v[100:101], v[8:9], v[92:93], v[100:101] op_sel_hi:[0,1,1]
	v_pk_mul_f32 v[186:187], v[178:179], s[40:41]
	v_pk_mul_f32 v[104:105], v[22:23], v[92:93] op_sel:[0,1] op_sel_hi:[1,0]
	v_pk_fma_f32 v[178:179], v[178:179], s[38:39], v[186:187] op_sel:[0,0,1] op_sel_hi:[1,0,0] neg_lo:[1,0,0] neg_hi:[1,0,0]
	v_pk_add_f32 v[186:187], v[206:207], v[164:165]
	v_pk_add_f32 v[164:165], v[206:207], v[164:165] neg_lo:[0,1] neg_hi:[0,1]
	v_pk_add_f32 v[206:207], v[190:191], v[150:151]
	v_pk_add_f32 v[150:151], v[190:191], v[150:151] neg_lo:[0,1] neg_hi:[0,1]
	v_pk_fma_f32 v[116:117], v[8:9], v[108:109], v[116:117] op_sel_hi:[0,1,1]
	v_pk_mul_f32 v[190:191], v[150:151], s[40:41]
	v_pk_mul_f32 v[120:121], v[22:23], v[108:109] op_sel:[0,1] op_sel_hi:[1,0]
	v_pk_fma_f32 v[150:151], v[150:151], s[38:39], v[190:191] op_sel:[0,0,1] op_sel_hi:[1,0,0]
	v_pk_add_f32 v[190:191], v[160:161], v[168:169]
	v_pk_add_f32 v[168:169], v[160:161], v[168:169] neg_lo:[0,1] neg_hi:[0,1]
	v_xor_b32_e32 v26, 0x80000000, v19
	v_pk_add_f32 v[160:161], v[162:163], v[170:171]
	v_pk_add_f32 v[162:163], v[162:163], v[170:171] neg_lo:[0,1] neg_hi:[0,1]
	v_xor_b32_e32 v30, 0x80000000, v21
	v_pk_mul_f32 v[170:171], v[162:163], s[40:41]
	v_pk_fma_f32 v[24:25], v[12:13], v[10:11], v[24:25] op_sel_hi:[1,0,1]
	v_pk_fma_f32 v[162:163], v[162:163], s[38:39], v[170:171] op_sel:[0,0,1] op_sel_hi:[1,0,0] neg_lo:[1,0,0] neg_hi:[1,0,0]
	v_pk_add_f32 v[170:171], v[128:129], v[166:167] op_sel:[0,1] op_sel_hi:[1,0] neg_hi:[0,1]
	v_pk_add_f32 v[128:129], v[128:129], v[166:167] op_sel:[0,1] op_sel_hi:[1,0] neg_lo:[0,1]
	v_pk_add_f32 v[166:167], v[130:131], v[152:153]
	v_pk_add_f32 v[130:131], v[130:131], v[152:153] neg_lo:[0,1] neg_hi:[0,1]
	v_pk_fma_f32 v[40:41], v[10:11], v[28:29], v[40:41] op_sel_hi:[0,1,1]
	v_pk_mul_f32 v[152:153], v[130:131], s[40:41]
	v_pk_fma_f32 v[56:57], v[10:11], v[44:45], v[56:57] op_sel_hi:[0,1,1]
	v_pk_fma_f32 v[130:131], v[130:131], s[38:39], v[152:153] op_sel:[0,0,1] op_sel_hi:[1,0,0]
	v_pk_add_f32 v[152:153], v[144:145], v[154:155]
	v_pk_add_f32 v[154:155], v[144:145], v[154:155] neg_lo:[0,1] neg_hi:[0,1]
	v_pk_fma_f32 v[72:73], v[10:11], v[60:61], v[72:73] op_sel_hi:[0,1,1]
	v_pk_add_f32 v[144:145], v[148:149], v[156:157]
	v_pk_add_f32 v[148:149], v[148:149], v[156:157] neg_lo:[0,1] neg_hi:[0,1]
	v_pk_fma_f32 v[88:89], v[10:11], v[76:77], v[88:89] op_sel_hi:[0,1,1]
	v_pk_mul_f32 v[156:157], v[148:149], s[40:41]
	v_pk_fma_f32 v[104:105], v[10:11], v[92:93], v[104:105] op_sel_hi:[0,1,1]
	v_pk_fma_f32 v[148:149], v[148:149], s[38:39], v[156:157] op_sel:[0,0,1] op_sel_hi:[1,0,0] neg_lo:[1,0,0] neg_hi:[1,0,0]
	v_pk_add_f32 v[156:157], v[172:173], v[210:211]
	v_pk_add_f32 v[172:173], v[172:173], v[210:211] neg_lo:[0,1] neg_hi:[0,1]
	v_pk_add_f32 v[210:211], v[208:209], v[174:175]
	v_pk_add_f32 v[208:209], v[208:209], v[174:175] neg_lo:[0,1] neg_hi:[0,1]
	v_pk_fma_f32 v[120:121], v[10:11], v[108:109], v[120:121] op_sel_hi:[0,1,1]
	v_pk_add_f32 v[174:175], v[194:195], v[198:199] op_sel:[0,1] op_sel_hi:[1,0] neg_hi:[0,1]
	v_pk_add_f32 v[194:195], v[194:195], v[198:199] op_sel:[0,1] op_sel_hi:[1,0] neg_lo:[0,1]
	v_pk_add_f32 v[198:199], v[180:181], v[192:193]
	v_pk_add_f32 v[192:193], v[180:181], v[192:193] neg_lo:[0,1] neg_hi:[0,1]
	v_mov_b32_e32 v27, v19
	v_pk_add_f32 v[180:181], v[204:205], v[182:183]
	v_pk_add_f32 v[182:183], v[204:205], v[182:183] neg_lo:[0,1] neg_hi:[0,1]
	v_pk_add_f32 v[204:205], v[196:197], v[176:177]
	v_pk_add_f32 v[196:197], v[196:197], v[176:177] neg_lo:[0,1] neg_hi:[0,1]
	v_mov_b32_e32 v31, v21
	v_pk_add_f32 v[176:177], v[188:189], v[184:185] op_sel:[0,1] op_sel_hi:[1,0] neg_hi:[0,1]
	v_pk_add_f32 v[184:185], v[188:189], v[184:185] op_sel:[0,1] op_sel_hi:[1,0] neg_lo:[0,1]
	v_pk_add_f32 v[188:189], v[158:159], v[178:179]
	v_pk_add_f32 v[178:179], v[158:159], v[178:179] neg_lo:[0,1] neg_hi:[0,1]
	v_xor_b32_e32 v34, 0x80000000, v25
	v_pk_add_f32 v[158:159], v[186:187], v[190:191]
	v_pk_add_f32 v[186:187], v[186:187], v[190:191] neg_lo:[0,1] neg_hi:[0,1]
	v_pk_add_f32 v[190:191], v[206:207], v[160:161]
	v_pk_add_f32 v[206:207], v[206:207], v[160:161] neg_lo:[0,1] neg_hi:[0,1]
	v_xor_b32_e32 v38, 0x80000000, v29
	v_pk_add_f32 v[160:161], v[164:165], v[168:169] op_sel:[0,1] op_sel_hi:[1,0] neg_hi:[0,1]
	v_pk_add_f32 v[164:165], v[164:165], v[168:169] op_sel:[0,1] op_sel_hi:[1,0] neg_lo:[0,1]
	v_pk_add_f32 v[168:169], v[150:151], v[162:163]
	v_pk_add_f32 v[162:163], v[150:151], v[162:163] neg_lo:[0,1] neg_hi:[0,1]
	v_xor_b32_e32 v42, 0x80000000, v33
	v_pk_add_f32 v[150:151], v[170:171], v[152:153]
	v_pk_add_f32 v[152:153], v[170:171], v[152:153] neg_lo:[0,1] neg_hi:[0,1]
	v_pk_add_f32 v[170:171], v[166:167], v[144:145]
	v_pk_add_f32 v[166:167], v[166:167], v[144:145] neg_lo:[0,1] neg_hi:[0,1]
	v_xor_b32_e32 v46, 0x80000000, v37
	v_pk_add_f32 v[144:145], v[128:129], v[154:155] op_sel:[0,1] op_sel_hi:[1,0] neg_hi:[0,1]
	v_pk_add_f32 v[128:129], v[128:129], v[154:155] op_sel:[0,1] op_sel_hi:[1,0] neg_lo:[0,1]
	v_pk_add_f32 v[154:155], v[130:131], v[148:149]
	v_pk_add_f32 v[130:131], v[130:131], v[148:149] neg_lo:[0,1] neg_hi:[0,1]
	v_mov_b32_e32 v35, v25
	v_xor_b32_e32 v149, 0x80000000, v130
	v_mov_b32_e32 v148, v131
	v_pk_add_f32 v[130:131], v[156:157], v[210:211]
	v_pk_add_f32 v[156:157], v[156:157], v[210:211] neg_lo:[0,1] neg_hi:[0,1]
	v_pk_add_f32 v[210:211], v[172:173], v[208:209] op_sel:[0,1] op_sel_hi:[1,0] neg_hi:[0,1]
	v_pk_add_f32 v[172:173], v[172:173], v[208:209] op_sel:[0,1] op_sel_hi:[1,0] neg_lo:[0,1]
	v_pk_add_f32 v[208:209], v[174:175], v[198:199]
	v_pk_add_f32 v[174:175], v[174:175], v[198:199] neg_lo:[0,1] neg_hi:[0,1]
	v_pk_add_f32 v[198:199], v[194:195], v[192:193] op_sel:[0,1] op_sel_hi:[1,0] neg_hi:[0,1]
	v_pk_add_f32 v[192:193], v[194:195], v[192:193] op_sel:[0,1] op_sel_hi:[1,0] neg_lo:[0,1]
	v_pk_add_f32 v[194:195], v[180:181], v[204:205]
	v_pk_add_f32 v[180:181], v[180:181], v[204:205] neg_lo:[0,1] neg_hi:[0,1]
	v_pk_add_f32 v[204:205], v[182:183], v[196:197] op_sel:[0,1] op_sel_hi:[1,0] neg_hi:[0,1]
	v_pk_add_f32 v[182:183], v[182:183], v[196:197] op_sel:[0,1] op_sel_hi:[1,0] neg_lo:[0,1]
	v_pk_add_f32 v[196:197], v[176:177], v[188:189]
	v_pk_add_f32 v[176:177], v[176:177], v[188:189] neg_lo:[0,1] neg_hi:[0,1]
	v_pk_add_f32 v[188:189], v[184:185], v[178:179] op_sel:[0,1] op_sel_hi:[1,0] neg_hi:[0,1]
	v_pk_add_f32 v[178:179], v[184:185], v[178:179] op_sel:[0,1] op_sel_hi:[1,0] neg_lo:[0,1]
	v_pk_add_f32 v[184:185], v[158:159], v[190:191]
	v_pk_add_f32 v[158:159], v[158:159], v[190:191] neg_lo:[0,1] neg_hi:[0,1]
	v_pk_mul_f32 v[4:5], v[4:5], v[184:185] op_sel:[0,1] op_sel_hi:[1,0]
	v_pk_add_f32 v[190:191], v[186:187], v[206:207] op_sel:[0,1] op_sel_hi:[1,0] neg_hi:[0,1]
	v_pk_add_f32 v[186:187], v[186:187], v[206:207] op_sel:[0,1] op_sel_hi:[1,0] neg_lo:[0,1]
	v_pk_add_f32 v[206:207], v[160:161], v[168:169]
	v_pk_add_f32 v[160:161], v[160:161], v[168:169] neg_lo:[0,1] neg_hi:[0,1]
	v_pk_add_f32 v[168:169], v[164:165], v[162:163] op_sel:[0,1] op_sel_hi:[1,0] neg_hi:[0,1]
	v_pk_add_f32 v[162:163], v[164:165], v[162:163] op_sel:[0,1] op_sel_hi:[1,0] neg_lo:[0,1]
	v_pk_add_f32 v[164:165], v[150:151], v[170:171]
	v_pk_fma_f32 v[4:5], v[6:7], v[184:185], v[4:5] op_sel_hi:[0,1,1]
	v_pk_mul_f32 v[6:7], v[14:15], v[194:195] op_sel:[0,1] op_sel_hi:[1,0]
	v_mov_b32_e32 v39, v29
	v_pk_fma_f32 v[6:7], v[8:9], v[194:195], v[6:7] op_sel_hi:[0,1,1]
	v_pk_mul_f32 v[8:9], v[22:23], v[164:165] op_sel:[0,1] op_sel_hi:[1,0]
	v_mov_b32_e32 v43, v33
	v_pk_fma_f32 v[8:9], v[10:11], v[164:165], v[8:9] op_sel_hi:[0,1,1]
	v_pk_mul_f32 v[10:11], v[16:17], v[208:209] op_sel:[0,1] op_sel_hi:[1,0]
	v_mov_b32_e32 v47, v37
	v_pk_add_f32 v[150:151], v[150:151], v[170:171] neg_lo:[0,1] neg_hi:[0,1]
	v_pk_add_f32 v[170:171], v[152:153], v[166:167] op_sel:[0,1] op_sel_hi:[1,0] neg_hi:[0,1]
	v_pk_add_f32 v[152:153], v[152:153], v[166:167] op_sel:[0,1] op_sel_hi:[1,0] neg_lo:[0,1]
	v_pk_add_f32 v[166:167], v[144:145], v[154:155]
	v_pk_fma_f32 v[10:11], v[12:13], v[208:209], v[10:11] op_sel_hi:[0,1,1]
	v_pk_mul_f32 v[12:13], v[26:27], v[206:207] op_sel:[0,1] op_sel_hi:[1,0]
	v_pk_mul_f32 v[14:15], v[30:31], v[196:197] op_sel:[0,1] op_sel_hi:[1,0]
	v_xor_b32_e32 v50, 0x80000000, v41
	v_xor_b32_e32 v54, 0x80000000, v45
	v_xor_b32_e32 v58, 0x80000000, v49
	v_xor_b32_e32 v62, 0x80000000, v53
	v_xor_b32_e32 v66, 0x80000000, v57
	v_xor_b32_e32 v70, 0x80000000, v61
	v_xor_b32_e32 v74, 0x80000000, v65
	v_mov_b32_e32 v51, v41
	v_mov_b32_e32 v55, v45
	v_mov_b32_e32 v59, v49
	v_mov_b32_e32 v63, v53
	v_mov_b32_e32 v67, v57
	v_mov_b32_e32 v71, v61
	v_mov_b32_e32 v75, v65
	v_pk_add_f32 v[144:145], v[144:145], v[154:155] neg_lo:[0,1] neg_hi:[0,1]
	v_pk_add_f32 v[154:155], v[128:129], v[148:149]
	v_pk_fma_f32 v[12:13], v[18:19], v[206:207], v[12:13] op_sel_hi:[0,1,1]
	v_pk_fma_f32 v[14:15], v[20:21], v[196:197], v[14:15] op_sel_hi:[0,1,1]
	v_pk_mul_f32 v[16:17], v[34:35], v[166:167] op_sel:[0,1] op_sel_hi:[1,0]
	v_pk_mul_f32 v[18:19], v[38:39], v[210:211] op_sel:[0,1] op_sel_hi:[1,0]
	v_pk_mul_f32 v[20:21], v[42:43], v[190:191] op_sel:[0,1] op_sel_hi:[1,0]
	v_pk_mul_f32 v[22:23], v[46:47], v[204:205] op_sel:[0,1] op_sel_hi:[1,0]
	v_xor_b32_e32 v78, 0x80000000, v69
	v_xor_b32_e32 v82, 0x80000000, v73
	v_xor_b32_e32 v86, 0x80000000, v77
	v_xor_b32_e32 v90, 0x80000000, v81
	v_xor_b32_e32 v94, 0x80000000, v85
	v_xor_b32_e32 v98, 0x80000000, v89
	v_xor_b32_e32 v102, 0x80000000, v93
	v_xor_b32_e32 v106, 0x80000000, v97
	v_xor_b32_e32 v110, 0x80000000, v101
	v_xor_b32_e32 v114, 0x80000000, v105
	v_xor_b32_e32 v118, 0x80000000, v109
	v_xor_b32_e32 v122, 0x80000000, v113
	v_xor_b32_e32 v124, 0x80000000, v117
	v_xor_b32_e32 v126, 0x80000000, v121
	v_mov_b32_e32 v79, v69
	v_mov_b32_e32 v83, v73
	v_mov_b32_e32 v87, v77
	v_mov_b32_e32 v91, v81
	v_mov_b32_e32 v95, v85
	v_mov_b32_e32 v99, v89
	v_mov_b32_e32 v103, v93
	v_mov_b32_e32 v107, v97
	v_mov_b32_e32 v111, v101
	v_mov_b32_e32 v115, v105
	v_mov_b32_e32 v119, v109
	v_mov_b32_e32 v123, v113
	v_mov_b32_e32 v125, v117
	v_mov_b32_e32 v127, v121
	v_pk_add_f32 v[128:129], v[128:129], v[148:149] neg_lo:[0,1] neg_hi:[0,1]
	v_pk_fma_f32 v[16:17], v[24:25], v[166:167], v[16:17] op_sel_hi:[0,1,1]
	v_pk_fma_f32 v[18:19], v[28:29], v[210:211], v[18:19] op_sel_hi:[0,1,1]
	v_pk_fma_f32 v[20:21], v[32:33], v[190:191], v[20:21] op_sel_hi:[0,1,1]
	v_pk_fma_f32 v[22:23], v[36:37], v[204:205], v[22:23] op_sel_hi:[0,1,1]
	v_pk_mul_f32 v[24:25], v[50:51], v[170:171] op_sel:[0,1] op_sel_hi:[1,0]
	v_pk_mul_f32 v[26:27], v[54:55], v[198:199] op_sel:[0,1] op_sel_hi:[1,0]
	v_pk_mul_f32 v[28:29], v[58:59], v[168:169] op_sel:[0,1] op_sel_hi:[1,0]
	v_pk_mul_f32 v[30:31], v[62:63], v[188:189] op_sel:[0,1] op_sel_hi:[1,0]
	v_pk_mul_f32 v[32:33], v[66:67], v[154:155] op_sel:[0,1] op_sel_hi:[1,0]
	v_pk_mul_f32 v[34:35], v[70:71], v[156:157] op_sel:[0,1] op_sel_hi:[1,0]
	v_pk_mul_f32 v[36:37], v[74:75], v[158:159] op_sel:[0,1] op_sel_hi:[1,0]
	v_pk_fma_f32 v[24:25], v[40:41], v[170:171], v[24:25] op_sel_hi:[0,1,1]
	v_pk_fma_f32 v[26:27], v[44:45], v[198:199], v[26:27] op_sel_hi:[0,1,1]
	v_pk_fma_f32 v[28:29], v[48:49], v[168:169], v[28:29] op_sel_hi:[0,1,1]
	v_pk_fma_f32 v[30:31], v[52:53], v[188:189], v[30:31] op_sel_hi:[0,1,1]
	v_pk_fma_f32 v[32:33], v[56:57], v[154:155], v[32:33] op_sel_hi:[0,1,1]
	v_pk_fma_f32 v[34:35], v[60:61], v[156:157], v[34:35] op_sel_hi:[0,1,1]
	v_pk_fma_f32 v[36:37], v[64:65], v[158:159], v[36:37] op_sel_hi:[0,1,1]
	v_pk_mul_f32 v[38:39], v[78:79], v[180:181] op_sel:[0,1] op_sel_hi:[1,0]
	v_pk_mul_f32 v[40:41], v[82:83], v[150:151] op_sel:[0,1] op_sel_hi:[1,0]
	v_pk_mul_f32 v[42:43], v[86:87], v[174:175] op_sel:[0,1] op_sel_hi:[1,0]
	v_pk_mul_f32 v[44:45], v[90:91], v[160:161] op_sel:[0,1] op_sel_hi:[1,0]
	v_pk_mul_f32 v[46:47], v[94:95], v[176:177] op_sel:[0,1] op_sel_hi:[1,0]
	v_pk_mul_f32 v[48:49], v[98:99], v[144:145] op_sel:[0,1] op_sel_hi:[1,0]
	v_pk_mul_f32 v[50:51], v[102:103], v[172:173] op_sel:[0,1] op_sel_hi:[1,0]
	v_pk_mul_f32 v[52:53], v[106:107], v[186:187] op_sel:[0,1] op_sel_hi:[1,0]
	v_pk_mul_f32 v[54:55], v[110:111], v[182:183] op_sel:[0,1] op_sel_hi:[1,0]
	v_pk_mul_f32 v[56:57], v[114:115], v[152:153] op_sel:[0,1] op_sel_hi:[1,0]
	v_pk_mul_f32 v[58:59], v[118:119], v[192:193] op_sel:[0,1] op_sel_hi:[1,0]
	v_pk_mul_f32 v[60:61], v[122:123], v[162:163] op_sel:[0,1] op_sel_hi:[1,0]
	v_pk_mul_f32 v[62:63], v[124:125], v[178:179] op_sel:[0,1] op_sel_hi:[1,0]
	v_pk_mul_f32 v[64:65], v[126:127], v[128:129] op_sel:[0,1] op_sel_hi:[1,0]
	v_pk_fma_f32 v[38:39], v[68:69], v[180:181], v[38:39] op_sel_hi:[0,1,1]
	v_pk_fma_f32 v[40:41], v[72:73], v[150:151], v[40:41] op_sel_hi:[0,1,1]
	v_pk_fma_f32 v[42:43], v[76:77], v[174:175], v[42:43] op_sel_hi:[0,1,1]
	v_pk_fma_f32 v[44:45], v[80:81], v[160:161], v[44:45] op_sel_hi:[0,1,1]
	v_pk_fma_f32 v[46:47], v[84:85], v[176:177], v[46:47] op_sel_hi:[0,1,1]
	v_pk_fma_f32 v[48:49], v[88:89], v[144:145], v[48:49] op_sel_hi:[0,1,1]
	v_pk_fma_f32 v[50:51], v[92:93], v[172:173], v[50:51] op_sel_hi:[0,1,1]
	v_pk_fma_f32 v[52:53], v[96:97], v[186:187], v[52:53] op_sel_hi:[0,1,1]
	v_pk_fma_f32 v[54:55], v[100:101], v[182:183], v[54:55] op_sel_hi:[0,1,1]
	v_pk_fma_f32 v[56:57], v[104:105], v[152:153], v[56:57] op_sel_hi:[0,1,1]
	v_pk_fma_f32 v[58:59], v[108:109], v[192:193], v[58:59] op_sel_hi:[0,1,1]
	v_pk_fma_f32 v[60:61], v[112:113], v[162:163], v[60:61] op_sel_hi:[0,1,1]
	v_pk_fma_f32 v[62:63], v[116:117], v[178:179], v[62:63] op_sel_hi:[0,1,1]
	v_pk_fma_f32 v[64:65], v[120:121], v[128:129], v[64:65] op_sel_hi:[0,1,1]
	ds_write_b64 v2, v[130:131]
	ds_write_b64 v2, v[34:35] offset:2112
	ds_write_b64 v2, v[18:19] offset:4224
	ds_write_b64 v2, v[50:51] offset:6336
	ds_write_b64 v2, v[10:11] offset:8448
	ds_write_b64 v2, v[42:43] offset:10560
	ds_write_b64 v2, v[26:27] offset:12672
	ds_write_b64 v2, v[58:59] offset:14784
	ds_write_b64 v2, v[6:7] offset:16896
	ds_write_b64 v2, v[38:39] offset:19008
	ds_write_b64 v2, v[22:23] offset:21120
	ds_write_b64 v2, v[54:55] offset:23232
	ds_write_b64 v2, v[14:15] offset:25344
	ds_write_b64 v2, v[46:47] offset:27456
	ds_write_b64 v2, v[30:31] offset:29568
	ds_write_b64 v2, v[62:63] offset:31680
	ds_write_b64 v2, v[4:5] offset:33792
	ds_write_b64 v2, v[36:37] offset:35904
	ds_write_b64 v2, v[20:21] offset:38016
	ds_write_b64 v2, v[52:53] offset:40128
	ds_write_b64 v2, v[12:13] offset:42240
	ds_write_b64 v2, v[44:45] offset:44352
	ds_write_b64 v2, v[28:29] offset:46464
	ds_write_b64 v2, v[60:61] offset:48576
	ds_write_b64 v2, v[8:9] offset:50688
	ds_write_b64 v2, v[40:41] offset:52800
	ds_write_b64 v2, v[24:25] offset:54912
	ds_write_b64 v2, v[56:57] offset:57024
	ds_write_b64 v2, v[16:17] offset:59136
	ds_write_b64 v2, v[48:49] offset:61248
	ds_write_b64 v2, v[32:33] offset:63360
	ds_write_b64 v2, v[64:65] offset:65472
	v_mov_b32_e32 v2, v142
	s_waitcnt lgkmcnt(0)
	s_barrier
	s_nop 0
	v_and_b32_e32 v5, 15, v2
	v_cvt_f32_ubyte0_e32 v4, v5
	v_mul_f32_e32 v6, 0x3b800000, v4
	v_sin_f32_e32 v4, v6
	v_cos_f32_e32 v6, v6
	v_lshlrev_b32_e32 v64, 3, v5
	v_lshlrev_b32_e32 v2, 4, v2
	v_xor_b32_e32 v7, 0x80000000, v4
	v_mov_b32_e32 v5, v7
	v_pk_mul_f32 v[8:9], v[6:7], v[4:5] op_sel:[1,0] op_sel_hi:[0,1]
	v_pk_fma_f32 v[8:9], v[6:7], v[6:7], v[8:9] op_sel_hi:[1,0,1]
	v_and_b32_e32 v2, 0xffffff00, v2
	v_xor_b32_e32 v14, 0x80000000, v9
	v_mov_b32_e32 v15, v9
	v_pk_mul_f32 v[12:13], v[8:9], v[14:15] op_sel:[1,0] op_sel_hi:[0,1]
	v_pk_fma_f32 v[12:13], v[8:9], v[8:9], v[12:13] op_sel_hi:[1,0,1]
	v_pk_mul_f32 v[10:11], v[4:5], v[8:9] op_sel:[0,1] op_sel_hi:[1,0]
	v_xor_b32_e32 v16, 0x80000000, v13
	v_mov_b32_e32 v17, v13
	v_pk_mul_f32 v[32:33], v[12:13], v[16:17] op_sel:[1,0] op_sel_hi:[0,1]
	v_pk_fma_f32 v[32:33], v[12:13], v[12:13], v[32:33] op_sel_hi:[1,0,1]
	v_pk_mul_f32 v[18:19], v[4:5], v[12:13] op_sel:[0,1] op_sel_hi:[1,0]
	v_pk_mul_f32 v[48:49], v[16:17], v[32:33] op_sel:[0,1] op_sel_hi:[1,0]
	v_pk_mul_f32 v[36:37], v[4:5], v[32:33] op_sel:[0,1] op_sel_hi:[1,0]
	v_pk_fma_f32 v[48:49], v[12:13], v[32:33], v[48:49] op_sel_hi:[0,1,1]
	v_pk_mul_f32 v[52:53], v[4:5], v[48:49] op_sel:[0,1] op_sel_hi:[1,0]
	v_pk_fma_f32 v[10:11], v[6:7], v[8:9], v[10:11] op_sel_hi:[0,1,1]
	v_pk_fma_f32 v[18:19], v[6:7], v[12:13], v[18:19] op_sel_hi:[0,1,1]
	v_pk_fma_f32 v[36:37], v[6:7], v[32:33], v[36:37] op_sel_hi:[0,1,1]
	v_pk_fma_f32 v[52:53], v[6:7], v[48:49], v[52:53] op_sel_hi:[0,1,1]
	v_lshlrev_b32_e32 v7, 3, v2
	v_add3_u32 v7, 0, v64, v7
	v_ashrrev_i32_e32 v64, 2, v2
	v_add_u32_e32 v106, v7, v64
	ds_read2_b64 v[64:67], v106 offset1:16
	ds_read2_b64 v[68:71], v106 offset0:33 offset1:49
	ds_read2_b64 v[72:75], v106 offset0:66 offset1:82
	ds_read2_b64 v[76:79], v106 offset0:132 offset1:148
	ds_read2_b64 v[80:83], v106 offset0:99 offset1:115
	ds_read2_b64 v[84:87], v106 offset0:165 offset1:181
	ds_read2_b64 v[88:91], v106 offset0:198 offset1:214
	ds_read2_b64 v[92:95], v106 offset0:231 offset1:247
	s_waitcnt lgkmcnt(4)
	v_pk_add_f32 v[96:97], v[64:65], v[76:77]
	v_pk_add_f32 v[64:65], v[64:65], v[76:77] neg_lo:[0,1] neg_hi:[0,1]
	v_pk_add_f32 v[76:77], v[66:67], v[78:79]
	v_pk_add_f32 v[66:67], v[66:67], v[78:79] neg_lo:[0,1] neg_hi:[0,1]
	s_waitcnt lgkmcnt(1)
	v_pk_add_f32 v[98:99], v[74:75], v[90:91]
	v_pk_mul_f32 v[78:79], v[66:67], s[24:25]
	v_pk_add_f32 v[74:75], v[74:75], v[90:91] neg_lo:[0,1] neg_hi:[0,1]
	v_pk_fma_f32 v[66:67], v[66:67], s[22:23], v[78:79] op_sel:[0,0,1] op_sel_hi:[1,0,0]
	v_pk_add_f32 v[78:79], v[68:69], v[84:85]
	v_pk_add_f32 v[68:69], v[68:69], v[84:85] neg_lo:[0,1] neg_hi:[0,1]
	v_pk_mul_f32 v[90:91], v[74:75], s[44:45]
	v_pk_mul_f32 v[84:85], v[68:69], s[40:41]
	v_pk_fma_f32 v[74:75], v[74:75], s[50:51], v[90:91] op_sel:[0,0,1] op_sel_hi:[1,0,0] neg_lo:[1,0,0] neg_hi:[1,0,0]
	v_pk_fma_f32 v[68:69], v[68:69], s[38:39], v[84:85] op_sel:[0,0,1] op_sel_hi:[1,0,0]
	v_pk_add_f32 v[84:85], v[70:71], v[86:87]
	v_pk_add_f32 v[70:71], v[70:71], v[86:87] neg_lo:[0,1] neg_hi:[0,1]
	s_waitcnt lgkmcnt(0)
	v_pk_add_f32 v[90:91], v[80:81], v[92:93]
	v_pk_add_f32 v[80:81], v[80:81], v[92:93] neg_lo:[0,1] neg_hi:[0,1]
	v_pk_mul_f32 v[86:87], v[70:71], s[44:45]
	v_pk_mul_f32 v[92:93], v[80:81], s[40:41]
	v_pk_fma_f32 v[70:71], v[70:71], s[50:51], v[86:87] op_sel:[0,0,1] op_sel_hi:[1,0,0]
	v_pk_add_f32 v[86:87], v[72:73], v[88:89]
	v_pk_add_f32 v[88:89], v[72:73], v[88:89] neg_lo:[0,1] neg_hi:[0,1]
	v_pk_fma_f32 v[80:81], v[80:81], s[38:39], v[92:93] op_sel:[0,0,1] op_sel_hi:[1,0,0] neg_lo:[1,0,0] neg_hi:[1,0,0]
	v_pk_add_f32 v[92:93], v[82:83], v[94:95]
	v_pk_add_f32 v[82:83], v[82:83], v[94:95] neg_lo:[0,1] neg_hi:[0,1]
	v_pk_mul_f32 v[94:95], v[82:83], s[24:25]
	v_pk_fma_f32 v[82:83], v[82:83], s[22:23], v[94:95] op_sel:[0,0,1] op_sel_hi:[1,0,0] neg_lo:[1,0,0] neg_hi:[1,0,0]
	v_pk_add_f32 v[94:95], v[96:97], v[86:87]
	v_pk_add_f32 v[86:87], v[96:97], v[86:87] neg_lo:[0,1] neg_hi:[0,1]
	v_pk_add_f32 v[96:97], v[76:77], v[98:99]
	v_pk_add_f32 v[76:77], v[76:77], v[98:99] neg_lo:[0,1] neg_hi:[0,1]
	v_pk_add_f32 v[100:101], v[84:85], v[92:93]
	v_pk_add_f32 v[84:85], v[84:85], v[92:93] neg_lo:[0,1] neg_hi:[0,1]
	v_pk_add_f32 v[72:73], v[64:65], v[88:89] op_sel:[0,1] op_sel_hi:[1,0] neg_hi:[0,1]
	v_pk_add_f32 v[64:65], v[64:65], v[88:89] op_sel:[0,1] op_sel_hi:[1,0] neg_lo:[0,1]
	v_pk_add_f32 v[88:89], v[66:67], v[74:75]
	v_pk_add_f32 v[66:67], v[66:67], v[74:75] neg_lo:[0,1] neg_hi:[0,1]
	v_pk_mul_f32 v[98:99], v[76:77], s[40:41]
	v_pk_mul_f32 v[92:93], v[84:85], s[40:41]
	v_pk_mul_f32 v[74:75], v[66:67], s[40:41]
	v_pk_fma_f32 v[76:77], v[76:77], s[38:39], v[98:99] op_sel:[0,0,1] op_sel_hi:[1,0,0]
	v_pk_add_f32 v[98:99], v[78:79], v[90:91]
	v_pk_add_f32 v[90:91], v[78:79], v[90:91] neg_lo:[0,1] neg_hi:[0,1]
	v_pk_fma_f32 v[84:85], v[84:85], s[38:39], v[92:93] op_sel:[0,0,1] op_sel_hi:[1,0,0] neg_lo:[1,0,0] neg_hi:[1,0,0]
	v_pk_fma_f32 v[66:67], v[66:67], s[38:39], v[74:75] op_sel:[0,0,1] op_sel_hi:[1,0,0]
	v_pk_add_f32 v[74:75], v[68:69], v[80:81]
	v_pk_add_f32 v[92:93], v[70:71], v[82:83]
	v_pk_add_f32 v[70:71], v[70:71], v[82:83] neg_lo:[0,1] neg_hi:[0,1]
	v_pk_add_f32 v[68:69], v[68:69], v[80:81] neg_lo:[0,1] neg_hi:[0,1]
	v_pk_mul_f32 v[82:83], v[70:71], s[40:41]
	v_pk_add_f32 v[102:103], v[72:73], v[74:75]
	v_pk_add_f32 v[72:73], v[72:73], v[74:75] neg_lo:[0,1] neg_hi:[0,1]
	v_pk_add_f32 v[74:75], v[88:89], v[92:93]
	v_pk_add_f32 v[92:93], v[88:89], v[92:93] neg_lo:[0,1] neg_hi:[0,1]
	v_xor_b32_e32 v20, 0x80000000, v11
	v_mov_b32_e32 v21, v11
	v_pk_mul_f32 v[24:25], v[14:15], v[12:13] op_sel:[0,1] op_sel_hi:[1,0]
	v_xor_b32_e32 v81, 0x80000000, v68
	v_pk_fma_f32 v[70:71], v[70:71], s[38:39], v[82:83] op_sel:[0,0,1] op_sel_hi:[1,0,0] neg_lo:[1,0,0] neg_hi:[1,0,0]
	v_pk_add_f32 v[78:79], v[86:87], v[90:91] op_sel:[0,1] op_sel_hi:[1,0] neg_hi:[0,1]
	v_pk_add_f32 v[86:87], v[86:87], v[90:91] op_sel:[0,1] op_sel_hi:[1,0] neg_lo:[0,1]
	v_pk_add_f32 v[90:91], v[76:77], v[84:85]
	v_pk_add_f32 v[84:85], v[76:77], v[84:85] neg_lo:[0,1] neg_hi:[0,1]
	v_mov_b32_e32 v80, v69
	v_xor_b32_e32 v22, 0x80000000, v19
	v_mov_b32_e32 v23, v19
	v_pk_fma_f32 v[24:25], v[8:9], v[12:13], v[24:25] op_sel_hi:[0,1,1]
	v_pk_mul_f32 v[28:29], v[12:13], v[20:21] op_sel:[1,0] op_sel_hi:[0,1]
	v_pk_add_f32 v[68:69], v[64:65], v[80:81]
	v_pk_add_f32 v[64:65], v[64:65], v[80:81] neg_lo:[0,1] neg_hi:[0,1]
	v_pk_add_f32 v[80:81], v[66:67], v[70:71]
	v_pk_add_f32 v[70:71], v[66:67], v[70:71] neg_lo:[0,1] neg_hi:[0,1]
	v_pk_add_f32 v[88:89], v[72:73], v[92:93] op_sel:[0,1] op_sel_hi:[1,0] neg_hi:[0,1]
	v_xor_b32_e32 v26, 0x80000000, v25
	v_mov_b32_e32 v27, v25
	v_pk_fma_f32 v[28:29], v[12:13], v[10:11], v[28:29] op_sel_hi:[1,0,1]
	v_pk_add_f32 v[76:77], v[86:87], v[84:85] op_sel:[0,1] op_sel_hi:[1,0] neg_hi:[0,1]
	v_pk_add_f32 v[72:73], v[72:73], v[92:93] op_sel:[0,1] op_sel_hi:[1,0] neg_lo:[0,1]
	v_pk_mul_f32 v[92:93], v[22:23], v[88:89] op_sel:[0,1] op_sel_hi:[1,0]
	v_xor_b32_e32 v30, 0x80000000, v29
	v_mov_b32_e32 v31, v29
	v_pk_add_f32 v[82:83], v[94:95], v[98:99]
	v_pk_add_f32 v[94:95], v[94:95], v[98:99] neg_lo:[0,1] neg_hi:[0,1]
	v_pk_add_f32 v[98:99], v[96:97], v[100:101]
	v_pk_add_f32 v[66:67], v[64:65], v[70:71] op_sel:[0,1] op_sel_hi:[1,0] neg_hi:[0,1]
	v_pk_fma_f32 v[88:89], v[18:19], v[88:89], v[92:93] op_sel_hi:[0,1,1]
	v_pk_mul_f32 v[92:93], v[26:27], v[76:77] op_sel:[0,1] op_sel_hi:[1,0]
	v_xor_b32_e32 v34, 0x80000000, v33
	v_mov_b32_e32 v35, v33
	v_pk_mul_f32 v[40:41], v[14:15], v[32:33] op_sel:[0,1] op_sel_hi:[1,0]
	v_pk_add_f32 v[104:105], v[82:83], v[98:99]
	v_pk_add_f32 v[82:83], v[82:83], v[98:99] neg_lo:[0,1] neg_hi:[0,1]
	v_pk_fma_f32 v[76:77], v[24:25], v[76:77], v[92:93] op_sel_hi:[0,1,1]
	v_pk_mul_f32 v[92:93], v[30:31], v[66:67] op_sel:[0,1] op_sel_hi:[1,0]
	v_xor_b32_e32 v38, 0x80000000, v37
	v_mov_b32_e32 v39, v37
	v_pk_fma_f32 v[40:41], v[8:9], v[32:33], v[40:41] op_sel_hi:[0,1,1]
	v_pk_mul_f32 v[44:45], v[20:21], v[32:33] op_sel:[0,1] op_sel_hi:[1,0]
	v_pk_add_f32 v[84:85], v[86:87], v[84:85] op_sel:[0,1] op_sel_hi:[1,0] neg_lo:[0,1]
	v_pk_add_f32 v[86:87], v[102:103], v[74:75]
	v_pk_add_f32 v[74:75], v[102:103], v[74:75] neg_lo:[0,1] neg_hi:[0,1]
	v_pk_fma_f32 v[66:67], v[28:29], v[66:67], v[92:93] op_sel_hi:[0,1,1]
	v_pk_mul_f32 v[92:93], v[34:35], v[82:83] op_sel:[0,1] op_sel_hi:[1,0]
	v_xor_b32_e32 v42, 0x80000000, v41
	v_mov_b32_e32 v43, v41
	v_pk_fma_f32 v[44:45], v[10:11], v[32:33], v[44:45] op_sel_hi:[0,1,1]
	v_pk_add_f32 v[100:101], v[96:97], v[100:101] neg_lo:[0,1] neg_hi:[0,1]
	v_pk_add_f32 v[98:99], v[78:79], v[90:91]
	v_pk_add_f32 v[78:79], v[78:79], v[90:91] neg_lo:[0,1] neg_hi:[0,1]
	v_pk_fma_f32 v[82:83], v[32:33], v[82:83], v[92:93] op_sel_hi:[0,1,1]
	v_pk_mul_f32 v[92:93], v[38:39], v[74:75] op_sel:[0,1] op_sel_hi:[1,0]
	v_xor_b32_e32 v46, 0x80000000, v45
	v_mov_b32_e32 v47, v45
	v_pk_add_f32 v[90:91], v[68:69], v[80:81]
	v_pk_add_f32 v[68:69], v[68:69], v[80:81] neg_lo:[0,1] neg_hi:[0,1]
	v_pk_fma_f32 v[74:75], v[36:37], v[74:75], v[92:93] op_sel_hi:[0,1,1]
	v_pk_mul_f32 v[92:93], v[42:43], v[78:79] op_sel:[0,1] op_sel_hi:[1,0]
	v_xor_b32_e32 v50, 0x80000000, v49
	v_mov_b32_e32 v51, v49
	v_pk_mul_f32 v[56:57], v[14:15], v[48:49] op_sel:[0,1] op_sel_hi:[1,0]
	v_pk_add_f32 v[96:97], v[94:95], v[100:101] op_sel:[0,1] op_sel_hi:[1,0] neg_hi:[0,1]
	v_pk_add_f32 v[94:95], v[94:95], v[100:101] op_sel:[0,1] op_sel_hi:[1,0] neg_lo:[0,1]
	v_pk_fma_f32 v[78:79], v[40:41], v[78:79], v[92:93] op_sel_hi:[0,1,1]
	v_pk_mul_f32 v[92:93], v[46:47], v[68:69] op_sel:[0,1] op_sel_hi:[1,0]
	v_xor_b32_e32 v54, 0x80000000, v53
	v_mov_b32_e32 v55, v53
	v_pk_fma_f32 v[56:57], v[8:9], v[48:49], v[56:57] op_sel_hi:[0,1,1]
	v_pk_mul_f32 v[60:61], v[20:21], v[48:49] op_sel:[0,1] op_sel_hi:[1,0]
	v_pk_fma_f32 v[68:69], v[44:45], v[68:69], v[92:93] op_sel_hi:[0,1,1]
	v_pk_mul_f32 v[92:93], v[50:51], v[94:95] op_sel:[0,1] op_sel_hi:[1,0]
	v_xor_b32_e32 v58, 0x80000000, v57
	v_mov_b32_e32 v59, v57
	v_pk_fma_f32 v[60:61], v[10:11], v[48:49], v[60:61] op_sel_hi:[0,1,1]
	v_pk_add_f32 v[64:65], v[64:65], v[70:71] op_sel:[0,1] op_sel_hi:[1,0] neg_lo:[0,1]
	v_pk_mul_f32 v[70:71], v[4:5], v[86:87] op_sel:[0,1] op_sel_hi:[1,0]
	v_pk_fma_f32 v[92:93], v[48:49], v[94:95], v[92:93] op_sel_hi:[0,1,1]
	v_pk_mul_f32 v[94:95], v[54:55], v[72:73] op_sel:[0,1] op_sel_hi:[1,0]
	v_xor_b32_e32 v62, 0x80000000, v61
	v_mov_b32_e32 v63, v61
	v_pk_fma_f32 v[70:71], v[6:7], v[86:87], v[70:71] op_sel_hi:[0,1,1]
	v_pk_mul_f32 v[86:87], v[20:21], v[90:91] op_sel:[0,1] op_sel_hi:[1,0]
	v_pk_fma_f32 v[72:73], v[52:53], v[72:73], v[94:95] op_sel_hi:[0,1,1]
	v_pk_mul_f32 v[94:95], v[58:59], v[84:85] op_sel:[0,1] op_sel_hi:[1,0]
	v_add_u32_e32 v2, 0x2000, v2
	v_pk_mul_f32 v[80:81], v[14:15], v[98:99] op_sel:[0,1] op_sel_hi:[1,0]
	v_pk_fma_f32 v[86:87], v[10:11], v[90:91], v[86:87] op_sel_hi:[0,1,1]
	v_pk_mul_f32 v[90:91], v[16:17], v[96:97] op_sel:[0,1] op_sel_hi:[1,0]
	v_pk_fma_f32 v[84:85], v[56:57], v[84:85], v[94:95] op_sel_hi:[0,1,1]
	v_pk_mul_f32 v[94:95], v[62:63], v[64:65] op_sel:[0,1] op_sel_hi:[1,0]
	v_ashrrev_i32_e32 v2, 2, v2
	v_pk_fma_f32 v[80:81], v[8:9], v[98:99], v[80:81] op_sel_hi:[0,1,1]
	v_pk_fma_f32 v[90:91], v[12:13], v[96:97], v[90:91] op_sel_hi:[0,1,1]
	v_pk_fma_f32 v[64:65], v[60:61], v[64:65], v[94:95] op_sel_hi:[0,1,1]
	ds_write2_b64 v106, v[104:105], v[82:83] offset1:16
	ds_write2_b64 v106, v[90:91], v[92:93] offset0:33 offset1:49
	ds_write2_b64 v106, v[80:81], v[78:79] offset0:66 offset1:82
	ds_write2_b64 v106, v[76:77], v[84:85] offset0:99 offset1:115
	ds_write2_b64 v106, v[70:71], v[74:75] offset0:132 offset1:148
	ds_write2_b64 v106, v[88:89], v[72:73] offset0:165 offset1:181
	ds_write2_b64 v106, v[86:87], v[68:69] offset0:198 offset1:214
	ds_write2_b64 v106, v[66:67], v[64:65] offset0:231 offset1:247
	v_add3_u32 v2, v7, v2, s60
	ds_read2_b64 v[64:67], v2 offset1:16
	ds_read2_b64 v[68:71], v2 offset0:33 offset1:49
	ds_read2_b64 v[72:75], v2 offset0:66 offset1:82
	ds_read2_b64 v[76:79], v2 offset0:132 offset1:148
	ds_read2_b64 v[80:83], v2 offset0:99 offset1:115
	ds_read2_b64 v[84:87], v2 offset0:165 offset1:181
	ds_read2_b64 v[88:91], v2 offset0:198 offset1:214
	ds_read2_b64 v[92:95], v2 offset0:231 offset1:247
	s_waitcnt lgkmcnt(4)
	v_pk_add_f32 v[96:97], v[64:65], v[76:77]
	v_pk_add_f32 v[64:65], v[64:65], v[76:77] neg_lo:[0,1] neg_hi:[0,1]
	v_pk_add_f32 v[76:77], v[66:67], v[78:79]
	v_pk_add_f32 v[66:67], v[66:67], v[78:79] neg_lo:[0,1] neg_hi:[0,1]
	s_waitcnt lgkmcnt(1)
	v_pk_add_f32 v[98:99], v[74:75], v[90:91]
	v_pk_mul_f32 v[78:79], v[66:67], s[24:25]
	v_pk_add_f32 v[74:75], v[74:75], v[90:91] neg_lo:[0,1] neg_hi:[0,1]
	v_pk_fma_f32 v[66:67], v[66:67], s[22:23], v[78:79] op_sel:[0,0,1] op_sel_hi:[1,0,0]
	v_pk_add_f32 v[78:79], v[68:69], v[84:85]
	v_pk_add_f32 v[68:69], v[68:69], v[84:85] neg_lo:[0,1] neg_hi:[0,1]
	v_pk_mul_f32 v[90:91], v[74:75], s[44:45]
	v_pk_mul_f32 v[84:85], v[68:69], s[40:41]
	v_pk_fma_f32 v[74:75], v[74:75], s[50:51], v[90:91] op_sel:[0,0,1] op_sel_hi:[1,0,0] neg_lo:[1,0,0] neg_hi:[1,0,0]
	s_waitcnt lgkmcnt(0)
	v_pk_add_f32 v[90:91], v[80:81], v[92:93]
	v_pk_add_f32 v[80:81], v[80:81], v[92:93] neg_lo:[0,1] neg_hi:[0,1]
	v_pk_fma_f32 v[68:69], v[68:69], s[38:39], v[84:85] op_sel:[0,0,1] op_sel_hi:[1,0,0]
	v_pk_add_f32 v[84:85], v[70:71], v[86:87]
	v_pk_add_f32 v[70:71], v[70:71], v[86:87] neg_lo:[0,1] neg_hi:[0,1]
	v_pk_mul_f32 v[92:93], v[80:81], s[40:41]
	v_pk_mul_f32 v[86:87], v[70:71], s[44:45]
	v_pk_fma_f32 v[80:81], v[80:81], s[38:39], v[92:93] op_sel:[0,0,1] op_sel_hi:[1,0,0] neg_lo:[1,0,0] neg_hi:[1,0,0]
	v_pk_add_f32 v[92:93], v[82:83], v[94:95]
	v_pk_add_f32 v[82:83], v[82:83], v[94:95] neg_lo:[0,1] neg_hi:[0,1]
	v_pk_fma_f32 v[70:71], v[70:71], s[50:51], v[86:87] op_sel:[0,0,1] op_sel_hi:[1,0,0]
	v_pk_add_f32 v[86:87], v[72:73], v[88:89]
	v_pk_mul_f32 v[94:95], v[82:83], s[24:25]
	v_pk_add_f32 v[88:89], v[72:73], v[88:89] neg_lo:[0,1] neg_hi:[0,1]
	v_pk_fma_f32 v[82:83], v[82:83], s[22:23], v[94:95] op_sel:[0,0,1] op_sel_hi:[1,0,0] neg_lo:[1,0,0] neg_hi:[1,0,0]
	v_pk_add_f32 v[94:95], v[96:97], v[86:87]
	v_pk_add_f32 v[86:87], v[96:97], v[86:87] neg_lo:[0,1] neg_hi:[0,1]
	v_pk_add_f32 v[96:97], v[76:77], v[98:99]
	v_pk_add_f32 v[76:77], v[76:77], v[98:99] neg_lo:[0,1] neg_hi:[0,1]
	v_pk_mul_f32 v[98:99], v[76:77], s[40:41]
	v_pk_add_f32 v[100:101], v[84:85], v[92:93]
	v_pk_add_f32 v[84:85], v[84:85], v[92:93] neg_lo:[0,1] neg_hi:[0,1]
	v_pk_fma_f32 v[76:77], v[76:77], s[38:39], v[98:99] op_sel:[0,0,1] op_sel_hi:[1,0,0]
	v_pk_add_f32 v[98:99], v[78:79], v[90:91]
	v_pk_add_f32 v[90:91], v[78:79], v[90:91] neg_lo:[0,1] neg_hi:[0,1]
	v_pk_mul_f32 v[92:93], v[84:85], s[40:41]
	v_pk_add_f32 v[72:73], v[64:65], v[88:89] op_sel:[0,1] op_sel_hi:[1,0] neg_hi:[0,1]
	v_pk_add_f32 v[64:65], v[64:65], v[88:89] op_sel:[0,1] op_sel_hi:[1,0] neg_lo:[0,1]
	v_pk_add_f32 v[88:89], v[66:67], v[74:75]
	v_pk_add_f32 v[66:67], v[66:67], v[74:75] neg_lo:[0,1] neg_hi:[0,1]
	v_pk_fma_f32 v[84:85], v[84:85], s[38:39], v[92:93] op_sel:[0,0,1] op_sel_hi:[1,0,0] neg_lo:[1,0,0] neg_hi:[1,0,0]
	v_pk_mul_f32 v[74:75], v[66:67], s[40:41]
	v_pk_fma_f32 v[66:67], v[66:67], s[38:39], v[74:75] op_sel:[0,0,1] op_sel_hi:[1,0,0]
	v_pk_add_f32 v[74:75], v[68:69], v[80:81]
	v_pk_add_f32 v[92:93], v[70:71], v[82:83]
	v_pk_add_f32 v[70:71], v[70:71], v[82:83] neg_lo:[0,1] neg_hi:[0,1]
	v_pk_add_f32 v[78:79], v[86:87], v[90:91] op_sel:[0,1] op_sel_hi:[1,0] neg_hi:[0,1]
	v_pk_add_f32 v[86:87], v[86:87], v[90:91] op_sel:[0,1] op_sel_hi:[1,0] neg_lo:[0,1]
	v_pk_add_f32 v[90:91], v[76:77], v[84:85]
	v_pk_add_f32 v[84:85], v[76:77], v[84:85] neg_lo:[0,1] neg_hi:[0,1]
	v_pk_add_f32 v[80:81], v[68:69], v[80:81] neg_lo:[0,1] neg_hi:[0,1]
	v_pk_mul_f32 v[82:83], v[70:71], s[40:41]
	v_pk_add_f32 v[102:103], v[72:73], v[74:75]
	v_pk_add_f32 v[72:73], v[72:73], v[74:75] neg_lo:[0,1] neg_hi:[0,1]
	v_pk_add_f32 v[74:75], v[88:89], v[92:93]
	v_pk_fma_f32 v[70:71], v[70:71], s[38:39], v[82:83] op_sel:[0,0,1] op_sel_hi:[1,0,0] neg_lo:[1,0,0] neg_hi:[1,0,0]
	v_pk_add_f32 v[82:83], v[94:95], v[98:99]
	v_pk_add_f32 v[94:95], v[94:95], v[98:99] neg_lo:[0,1] neg_hi:[0,1]
	v_pk_add_f32 v[98:99], v[96:97], v[100:101]
	v_pk_add_f32 v[76:77], v[86:87], v[84:85] op_sel:[0,1] op_sel_hi:[1,0] neg_hi:[0,1]
	v_pk_add_f32 v[84:85], v[86:87], v[84:85] op_sel:[0,1] op_sel_hi:[1,0] neg_lo:[0,1]
	v_pk_add_f32 v[86:87], v[102:103], v[74:75]
	v_pk_add_f32 v[100:101], v[96:97], v[100:101] neg_lo:[0,1] neg_hi:[0,1]
	v_pk_add_f32 v[68:69], v[64:65], v[80:81] op_sel:[0,1] op_sel_hi:[1,0] neg_hi:[0,1]
	v_pk_add_f32 v[64:65], v[64:65], v[80:81] op_sel:[0,1] op_sel_hi:[1,0] neg_lo:[0,1]
	v_pk_add_f32 v[80:81], v[66:67], v[70:71]
	v_pk_add_f32 v[104:105], v[82:83], v[98:99]
	v_pk_add_f32 v[82:83], v[82:83], v[98:99] neg_lo:[0,1] neg_hi:[0,1]
	v_pk_add_f32 v[98:99], v[78:79], v[90:91]
	v_pk_mul_f32 v[4:5], v[4:5], v[86:87] op_sel:[0,1] op_sel_hi:[1,0]
	v_pk_add_f32 v[92:93], v[88:89], v[92:93] neg_lo:[0,1] neg_hi:[0,1]
	v_pk_add_f32 v[78:79], v[78:79], v[90:91] neg_lo:[0,1] neg_hi:[0,1]
	v_pk_add_f32 v[90:91], v[68:69], v[80:81]
	v_pk_fma_f32 v[4:5], v[6:7], v[86:87], v[4:5] op_sel_hi:[0,1,1]
	v_pk_mul_f32 v[6:7], v[14:15], v[98:99] op_sel:[0,1] op_sel_hi:[1,0]
	v_pk_add_f32 v[70:71], v[66:67], v[70:71] neg_lo:[0,1] neg_hi:[0,1]
	v_pk_add_f32 v[96:97], v[94:95], v[100:101] op_sel:[0,1] op_sel_hi:[1,0] neg_hi:[0,1]
	v_pk_fma_f32 v[6:7], v[8:9], v[98:99], v[6:7] op_sel_hi:[0,1,1]
	v_pk_mul_f32 v[8:9], v[20:21], v[90:91] op_sel:[0,1] op_sel_hi:[1,0]
	v_pk_add_f32 v[88:89], v[72:73], v[92:93] op_sel:[0,1] op_sel_hi:[1,0] neg_hi:[0,1]
	v_pk_fma_f32 v[8:9], v[10:11], v[90:91], v[8:9] op_sel_hi:[0,1,1]
	v_pk_mul_f32 v[10:11], v[16:17], v[96:97] op_sel:[0,1] op_sel_hi:[1,0]
	v_pk_add_f32 v[66:67], v[64:65], v[70:71] op_sel:[0,1] op_sel_hi:[1,0] neg_hi:[0,1]
	v_pk_fma_f32 v[10:11], v[12:13], v[96:97], v[10:11] op_sel_hi:[0,1,1]
	v_pk_mul_f32 v[12:13], v[22:23], v[88:89] op_sel:[0,1] op_sel_hi:[1,0]
	v_pk_add_f32 v[94:95], v[94:95], v[100:101] op_sel:[0,1] op_sel_hi:[1,0] neg_lo:[0,1]
	v_pk_add_f32 v[74:75], v[102:103], v[74:75] neg_lo:[0,1] neg_hi:[0,1]
	v_pk_add_f32 v[72:73], v[72:73], v[92:93] op_sel:[0,1] op_sel_hi:[1,0] neg_lo:[0,1]
	v_pk_add_f32 v[68:69], v[68:69], v[80:81] neg_lo:[0,1] neg_hi:[0,1]
	v_pk_add_f32 v[64:65], v[64:65], v[70:71] op_sel:[0,1] op_sel_hi:[1,0] neg_lo:[0,1]
	v_pk_fma_f32 v[12:13], v[18:19], v[88:89], v[12:13] op_sel_hi:[0,1,1]
	v_pk_mul_f32 v[14:15], v[26:27], v[76:77] op_sel:[0,1] op_sel_hi:[1,0]
	v_pk_mul_f32 v[16:17], v[30:31], v[66:67] op_sel:[0,1] op_sel_hi:[1,0]
	v_pk_mul_f32 v[18:19], v[34:35], v[82:83] op_sel:[0,1] op_sel_hi:[1,0]
	v_pk_fma_f32 v[14:15], v[24:25], v[76:77], v[14:15] op_sel_hi:[0,1,1]
	v_pk_fma_f32 v[16:17], v[28:29], v[66:67], v[16:17] op_sel_hi:[0,1,1]
	v_pk_fma_f32 v[18:19], v[32:33], v[82:83], v[18:19] op_sel_hi:[0,1,1]
	v_pk_mul_f32 v[20:21], v[38:39], v[74:75] op_sel:[0,1] op_sel_hi:[1,0]
	v_pk_mul_f32 v[22:23], v[42:43], v[78:79] op_sel:[0,1] op_sel_hi:[1,0]
	v_pk_mul_f32 v[24:25], v[46:47], v[68:69] op_sel:[0,1] op_sel_hi:[1,0]
	v_pk_mul_f32 v[26:27], v[50:51], v[94:95] op_sel:[0,1] op_sel_hi:[1,0]
	v_pk_mul_f32 v[28:29], v[54:55], v[72:73] op_sel:[0,1] op_sel_hi:[1,0]
	v_pk_mul_f32 v[30:31], v[58:59], v[84:85] op_sel:[0,1] op_sel_hi:[1,0]
	v_pk_mul_f32 v[32:33], v[62:63], v[64:65] op_sel:[0,1] op_sel_hi:[1,0]
	v_pk_fma_f32 v[20:21], v[36:37], v[74:75], v[20:21] op_sel_hi:[0,1,1]
	v_pk_fma_f32 v[22:23], v[40:41], v[78:79], v[22:23] op_sel_hi:[0,1,1]
	v_pk_fma_f32 v[24:25], v[44:45], v[68:69], v[24:25] op_sel_hi:[0,1,1]
	v_pk_fma_f32 v[26:27], v[48:49], v[94:95], v[26:27] op_sel_hi:[0,1,1]
	v_pk_fma_f32 v[28:29], v[52:53], v[72:73], v[28:29] op_sel_hi:[0,1,1]
	v_pk_fma_f32 v[30:31], v[56:57], v[84:85], v[30:31] op_sel_hi:[0,1,1]
	v_pk_fma_f32 v[32:33], v[60:61], v[64:65], v[32:33] op_sel_hi:[0,1,1]
	ds_write2_b64 v2, v[104:105], v[18:19] offset1:16
	ds_write2_b64 v2, v[10:11], v[26:27] offset0:33 offset1:49
	ds_write2_b64 v2, v[6:7], v[22:23] offset0:66 offset1:82
	ds_write2_b64 v2, v[14:15], v[30:31] offset0:99 offset1:115
	ds_write2_b64 v2, v[4:5], v[20:21] offset0:132 offset1:148
	ds_write2_b64 v2, v[12:13], v[28:29] offset0:165 offset1:181
	ds_write2_b64 v2, v[8:9], v[24:25] offset0:198 offset1:214
	ds_write2_b64 v2, v[16:17], v[32:33] offset0:231 offset1:247
	s_waitcnt lgkmcnt(0)
	s_barrier
	s_nop 0
	v_ashrrev_i32_e32 v2, 31, v142
	v_add_u32_sdwa v2, v142, v2 dst_sel:DWORD dst_unused:UNUSED_PAD src0_sel:DWORD src1_sel:BYTE_3
	v_ashrrev_i32_e32 v145, 8, v2
	v_mul_i32_i24_e32 v2, 0x100, v145
	v_sub_u32_e32 v144, v142, v2
	v_lshlrev_b32_e32 v2, 1, v144
	v_bfrev_b32_e32 v2, v2
	v_lshrrev_b32_e32 v2, 23, v2
	v_sub_u32_e32 v2, 0x200, v2
	v_bfrev_b32_e32 v2, v2
	v_lshrrev_b32_e32 v2, 19, v2
	v_lshlrev_b32_e32 v143, 13, v145
	v_and_b32_e32 v2, 0x1ff0, v2
	v_cmp_eq_u32_e32 vcc, 0, v144
	v_lshl_add_u32 v4, v144, 5, v143
	v_lshlrev_b32_e32 v5, 3, v4
	v_cndmask_b32_e64 v2, v2, 16, vcc
	v_ashrrev_i32_e32 v4, 2, v4
	v_or_b32_e32 v2, v2, v143
	v_add3_u32 v56, 0, v5, v4
	v_ashrrev_i32_e32 v4, 5, v2
	v_lshlrev_b32_e32 v2, 3, v2
	v_lshlrev_b32_e32 v4, 3, v4
	v_add3_u32 v2, 0, v2, v4
	ds_read2_b64 v[4:7], v56 offset1:1
	ds_read2_b64 v[8:11], v56 offset0:2 offset1:3
	ds_read2_b64 v[12:15], v2 offset1:1
	ds_read2_b64 v[16:19], v2 offset0:2 offset1:3
	ds_read2_b64 v[20:23], v56 offset0:4 offset1:5
	ds_read2_b64 v[24:27], v56 offset0:6 offset1:7
	ds_read2_b64 v[28:31], v2 offset0:4 offset1:5
	ds_read2_b64 v[32:35], v2 offset0:6 offset1:7
	ds_read2_b64 v[36:39], v56 offset0:8 offset1:9
	ds_read2_b64 v[40:43], v56 offset0:10 offset1:11
	ds_read2_b64 v[44:47], v2 offset0:8 offset1:9
	ds_read2_b64 v[52:55], v2 offset0:10 offset1:11
	ds_read2_b64 v[48:51], v56 offset0:12 offset1:13
	ds_read2_b64 v[56:59], v56 offset0:14 offset1:15
	ds_read2_b64 v[62:65], v2 offset0:12 offset1:13
	ds_read2_b64 v[74:77], v2 offset0:14 offset1:15
	s_waitcnt lgkmcnt(7)
	v_pk_add_f32 v[60:61], v[4:5], v[36:37]
	v_pk_add_f32 v[4:5], v[4:5], v[36:37] neg_lo:[0,1] neg_hi:[0,1]
	v_pk_add_f32 v[36:37], v[6:7], v[38:39]
	v_pk_add_f32 v[6:7], v[6:7], v[38:39] neg_lo:[0,1] neg_hi:[0,1]
	s_waitcnt lgkmcnt(3)
	v_pk_add_f32 v[66:67], v[22:23], v[50:51]
	v_pk_mul_f32 v[38:39], v[6:7], s[24:25]
	v_pk_add_f32 v[22:23], v[22:23], v[50:51] neg_lo:[0,1] neg_hi:[0,1]
	v_pk_fma_f32 v[6:7], v[6:7], s[22:23], v[38:39] op_sel:[0,0,1] op_sel_hi:[1,0,0]
	v_pk_add_f32 v[38:39], v[8:9], v[40:41]
	v_pk_add_f32 v[8:9], v[8:9], v[40:41] neg_lo:[0,1] neg_hi:[0,1]
	v_pk_mul_f32 v[50:51], v[22:23], s[44:45]
	v_pk_mul_f32 v[40:41], v[8:9], s[40:41]
	v_pk_fma_f32 v[22:23], v[22:23], s[50:51], v[50:51] op_sel:[0,0,1] op_sel_hi:[1,0,0] neg_lo:[1,0,0] neg_hi:[1,0,0]
	v_pk_fma_f32 v[8:9], v[8:9], s[38:39], v[40:41] op_sel:[0,0,1] op_sel_hi:[1,0,0]
	v_pk_add_f32 v[40:41], v[10:11], v[42:43]
	v_pk_add_f32 v[10:11], v[10:11], v[42:43] neg_lo:[0,1] neg_hi:[0,1]
	s_waitcnt lgkmcnt(2)
	v_pk_add_f32 v[50:51], v[24:25], v[56:57]
	v_pk_add_f32 v[24:25], v[24:25], v[56:57] neg_lo:[0,1] neg_hi:[0,1]
	v_pk_mul_f32 v[42:43], v[10:11], s[44:45]
	v_pk_mul_f32 v[56:57], v[24:25], s[40:41]
	v_pk_fma_f32 v[10:11], v[10:11], s[50:51], v[42:43] op_sel:[0,0,1] op_sel_hi:[1,0,0]
	v_pk_add_f32 v[42:43], v[20:21], v[48:49]
	v_pk_add_f32 v[48:49], v[20:21], v[48:49] neg_lo:[0,1] neg_hi:[0,1]
	v_pk_fma_f32 v[24:25], v[24:25], s[38:39], v[56:57] op_sel:[0,0,1] op_sel_hi:[1,0,0] neg_lo:[1,0,0] neg_hi:[1,0,0]
	v_pk_add_f32 v[56:57], v[26:27], v[58:59]
	v_pk_add_f32 v[26:27], v[26:27], v[58:59] neg_lo:[0,1] neg_hi:[0,1]
	v_pk_mul_f32 v[58:59], v[26:27], s[24:25]
	v_pk_add_f32 v[68:69], v[40:41], v[56:57]
	v_pk_add_f32 v[40:41], v[40:41], v[56:57] neg_lo:[0,1] neg_hi:[0,1]
	v_pk_fma_f32 v[26:27], v[26:27], s[22:23], v[58:59] op_sel:[0,0,1] op_sel_hi:[1,0,0] neg_lo:[1,0,0] neg_hi:[1,0,0]
	v_pk_mul_f32 v[56:57], v[40:41], s[40:41]
	v_pk_add_f32 v[20:21], v[4:5], v[48:49] op_sel:[0,1] op_sel_hi:[1,0] neg_hi:[0,1]
	v_pk_add_f32 v[4:5], v[4:5], v[48:49] op_sel:[0,1] op_sel_hi:[1,0] neg_lo:[0,1]
	v_pk_add_f32 v[48:49], v[6:7], v[22:23]
	v_pk_add_f32 v[6:7], v[6:7], v[22:23] neg_lo:[0,1] neg_hi:[0,1]
	v_pk_fma_f32 v[40:41], v[40:41], s[38:39], v[56:57] op_sel:[0,0,1] op_sel_hi:[1,0,0] neg_lo:[1,0,0] neg_hi:[1,0,0]
	v_pk_mul_f32 v[22:23], v[6:7], s[40:41]
	v_pk_add_f32 v[56:57], v[10:11], v[26:27]
	v_pk_add_f32 v[10:11], v[10:11], v[26:27] neg_lo:[0,1] neg_hi:[0,1]
	v_pk_add_f32 v[58:59], v[60:61], v[42:43]
	v_pk_add_f32 v[42:43], v[60:61], v[42:43] neg_lo:[0,1] neg_hi:[0,1]
	v_pk_add_f32 v[60:61], v[36:37], v[66:67]
	v_pk_add_f32 v[36:37], v[36:37], v[66:67] neg_lo:[0,1] neg_hi:[0,1]
	v_pk_fma_f32 v[6:7], v[6:7], s[38:39], v[22:23] op_sel:[0,0,1] op_sel_hi:[1,0,0]
	v_pk_add_f32 v[22:23], v[8:9], v[24:25]
	v_pk_add_f32 v[24:25], v[8:9], v[24:25] neg_lo:[0,1] neg_hi:[0,1]
	v_pk_mul_f32 v[26:27], v[10:11], s[40:41]
	v_pk_mul_f32 v[66:67], v[36:37], s[40:41]
	v_pk_fma_f32 v[10:11], v[10:11], s[38:39], v[26:27] op_sel:[0,0,1] op_sel_hi:[1,0,0] neg_lo:[1,0,0] neg_hi:[1,0,0]
	v_pk_fma_f32 v[36:37], v[36:37], s[38:39], v[66:67] op_sel:[0,0,1] op_sel_hi:[1,0,0]
	v_pk_add_f32 v[66:67], v[38:39], v[50:51]
	v_pk_add_f32 v[8:9], v[4:5], v[24:25] op_sel:[0,1] op_sel_hi:[1,0] neg_hi:[0,1]
	v_pk_add_f32 v[4:5], v[4:5], v[24:25] op_sel:[0,1] op_sel_hi:[1,0] neg_lo:[0,1]
	v_pk_add_f32 v[24:25], v[6:7], v[10:11]
	v_pk_add_f32 v[10:11], v[6:7], v[10:11] neg_lo:[0,1] neg_hi:[0,1]
	v_pk_add_f32 v[26:27], v[58:59], v[66:67]
	v_pk_add_f32 v[58:59], v[58:59], v[66:67] neg_lo:[0,1] neg_hi:[0,1]
	v_pk_add_f32 v[66:67], v[60:61], v[68:69]
	v_pk_add_f32 v[68:69], v[60:61], v[68:69] neg_lo:[0,1] neg_hi:[0,1]
	v_pk_add_f32 v[60:61], v[4:5], v[10:11] op_sel:[0,1] op_sel_hi:[1,0] neg_hi:[0,1]
	v_pk_add_f32 v[90:91], v[4:5], v[10:11] op_sel:[0,1] op_sel_hi:[1,0] neg_lo:[0,1]
	v_pk_add_f32 v[10:11], v[14:15], v[46:47] neg_lo:[0,1] neg_hi:[0,1]
	v_pk_add_f32 v[50:51], v[38:39], v[50:51] neg_lo:[0,1] neg_hi:[0,1]
	v_pk_add_f32 v[84:85], v[58:59], v[68:69] op_sel:[0,1] op_sel_hi:[1,0] neg_hi:[0,1]
	v_pk_add_f32 v[86:87], v[58:59], v[68:69] op_sel:[0,1] op_sel_hi:[1,0] neg_lo:[0,1]
	v_pk_add_f32 v[82:83], v[8:9], v[24:25]
	v_pk_add_f32 v[68:69], v[8:9], v[24:25] neg_lo:[0,1] neg_hi:[0,1]
	v_pk_add_f32 v[4:5], v[12:13], v[44:45]
	v_pk_add_f32 v[6:7], v[12:13], v[44:45] neg_lo:[0,1] neg_hi:[0,1]
	v_pk_add_f32 v[8:9], v[14:15], v[46:47]
	v_pk_mul_f32 v[12:13], v[10:11], s[24:25]
	v_pk_add_f32 v[14:15], v[16:17], v[52:53] neg_lo:[0,1] neg_hi:[0,1]
	v_pk_add_f32 v[70:71], v[20:21], v[22:23]
	v_pk_add_f32 v[20:21], v[20:21], v[22:23] neg_lo:[0,1] neg_hi:[0,1]
	v_pk_add_f32 v[22:23], v[48:49], v[56:57]
	v_pk_add_f32 v[48:49], v[48:49], v[56:57] neg_lo:[0,1] neg_hi:[0,1]
	v_pk_fma_f32 v[10:11], v[10:11], s[22:23], v[12:13] op_sel:[0,0,1] op_sel_hi:[1,0,0]
	v_pk_add_f32 v[12:13], v[16:17], v[52:53]
	v_pk_mul_f32 v[16:17], v[14:15], s[40:41]
	v_pk_add_f32 v[38:39], v[42:43], v[50:51] op_sel:[0,1] op_sel_hi:[1,0] neg_hi:[0,1]
	v_pk_add_f32 v[42:43], v[42:43], v[50:51] op_sel:[0,1] op_sel_hi:[1,0] neg_lo:[0,1]
	v_pk_add_f32 v[50:51], v[36:37], v[40:41]
	v_xor_b32_e32 v57, 0x80000000, v48
	v_mov_b32_e32 v56, v49
	v_pk_fma_f32 v[14:15], v[14:15], s[38:39], v[16:17] op_sel:[0,0,1] op_sel_hi:[1,0,0]
	v_pk_add_f32 v[16:17], v[18:19], v[54:55]
	v_pk_add_f32 v[18:19], v[18:19], v[54:55] neg_lo:[0,1] neg_hi:[0,1]
	v_pk_add_f32 v[130:131], v[26:27], v[66:67]
	v_pk_add_f32 v[92:93], v[26:27], v[66:67] neg_lo:[0,1] neg_hi:[0,1]
	v_pk_add_f32 v[88:89], v[38:39], v[50:51]
	v_pk_add_f32 v[72:73], v[38:39], v[50:51] neg_lo:[0,1] neg_hi:[0,1]
	v_pk_add_f32 v[96:97], v[70:71], v[22:23]
	v_pk_add_f32 v[50:51], v[70:71], v[22:23] neg_lo:[0,1] neg_hi:[0,1]
	v_pk_add_f32 v[66:67], v[20:21], v[56:57]
	v_pk_add_f32 v[80:81], v[20:21], v[56:57] neg_lo:[0,1] neg_hi:[0,1]
	v_pk_mul_f32 v[20:21], v[18:19], s[44:45]
	s_waitcnt lgkmcnt(1)
	v_pk_add_f32 v[24:25], v[28:29], v[62:63] neg_lo:[0,1] neg_hi:[0,1]
	v_pk_add_f32 v[26:27], v[30:31], v[64:65] neg_lo:[0,1] neg_hi:[0,1]
	v_pk_fma_f32 v[18:19], v[18:19], s[50:51], v[20:21] op_sel:[0,0,1] op_sel_hi:[1,0,0]
	v_pk_add_f32 v[20:21], v[28:29], v[62:63]
	v_pk_add_f32 v[22:23], v[30:31], v[64:65]
	v_pk_mul_f32 v[28:29], v[26:27], s[44:45]
	s_waitcnt lgkmcnt(0)
	v_pk_add_f32 v[30:31], v[32:33], v[74:75] neg_lo:[0,1] neg_hi:[0,1]
	v_pk_fma_f32 v[26:27], v[26:27], s[50:51], v[28:29] op_sel:[0,0,1] op_sel_hi:[1,0,0] neg_lo:[1,0,0] neg_hi:[1,0,0]
	v_pk_add_f32 v[28:29], v[32:33], v[74:75]
	v_pk_mul_f32 v[32:33], v[30:31], s[40:41]
	v_pk_add_f32 v[36:37], v[36:37], v[40:41] neg_lo:[0,1] neg_hi:[0,1]
	v_pk_fma_f32 v[30:31], v[30:31], s[38:39], v[32:33] op_sel:[0,0,1] op_sel_hi:[1,0,0] neg_lo:[1,0,0] neg_hi:[1,0,0]
	v_pk_add_f32 v[32:33], v[34:35], v[76:77]
	v_pk_add_f32 v[34:35], v[34:35], v[76:77] neg_lo:[0,1] neg_hi:[0,1]
	v_xor_b32_e32 v41, 0x80000000, v36
	v_mov_b32_e32 v40, v37
	v_pk_mul_f32 v[36:37], v[34:35], s[24:25]
	v_mov_b32_e32 v2, v130
	v_pk_fma_f32 v[34:35], v[34:35], s[22:23], v[36:37] op_sel:[0,0,1] op_sel_hi:[1,0,0] neg_lo:[1,0,0] neg_hi:[1,0,0]
	v_pk_add_f32 v[36:37], v[4:5], v[20:21]
	v_pk_add_f32 v[4:5], v[4:5], v[20:21] neg_lo:[0,1] neg_hi:[0,1]
	v_pk_add_f32 v[20:21], v[8:9], v[22:23]
	v_pk_add_f32 v[8:9], v[8:9], v[22:23] neg_lo:[0,1] neg_hi:[0,1]
	v_cmp_ne_u32_e64 s[0:1], 0, v144
	v_pk_mul_f32 v[22:23], v[8:9], s[40:41]
	v_pk_add_f32 v[78:79], v[42:43], v[40:41]
	v_pk_fma_f32 v[8:9], v[8:9], s[38:39], v[22:23] op_sel:[0,0,1] op_sel_hi:[1,0,0]
	v_pk_add_f32 v[22:23], v[12:13], v[28:29]
	v_pk_add_f32 v[28:29], v[12:13], v[28:29] neg_lo:[0,1] neg_hi:[0,1]
	v_pk_add_f32 v[94:95], v[42:43], v[40:41] neg_lo:[0,1] neg_hi:[0,1]
	v_pk_add_f32 v[12:13], v[16:17], v[32:33]
	v_pk_add_f32 v[16:17], v[16:17], v[32:33] neg_lo:[0,1] neg_hi:[0,1]
	s_nop 0
	v_pk_mul_f32 v[32:33], v[16:17], s[40:41]
	s_nop 0
	v_pk_fma_f32 v[16:17], v[16:17], s[38:39], v[32:33] op_sel:[0,0,1] op_sel_hi:[1,0,0] neg_lo:[1,0,0] neg_hi:[1,0,0]
	v_pk_add_f32 v[32:33], v[6:7], v[24:25] op_sel:[0,1] op_sel_hi:[1,0] neg_hi:[0,1]
	v_pk_add_f32 v[6:7], v[6:7], v[24:25] op_sel:[0,1] op_sel_hi:[1,0] neg_lo:[0,1]
	v_pk_add_f32 v[24:25], v[10:11], v[26:27]
	v_pk_add_f32 v[10:11], v[10:11], v[26:27] neg_lo:[0,1] neg_hi:[0,1]
	s_nop 0
	v_pk_mul_f32 v[26:27], v[10:11], s[40:41]
	s_nop 0
	v_pk_fma_f32 v[10:11], v[10:11], s[38:39], v[26:27] op_sel:[0,0,1] op_sel_hi:[1,0,0]
	v_pk_add_f32 v[26:27], v[14:15], v[30:31]
	v_pk_add_f32 v[30:31], v[14:15], v[30:31] neg_lo:[0,1] neg_hi:[0,1]
	s_nop 0
	v_pk_add_f32 v[14:15], v[18:19], v[34:35]
	v_pk_add_f32 v[18:19], v[18:19], v[34:35] neg_lo:[0,1] neg_hi:[0,1]
	s_nop 0
	v_pk_mul_f32 v[34:35], v[18:19], s[40:41]
	s_nop 0
	v_pk_fma_f32 v[18:19], v[18:19], s[38:39], v[34:35] op_sel:[0,0,1] op_sel_hi:[1,0,0] neg_lo:[1,0,0] neg_hi:[1,0,0]
	v_pk_add_f32 v[34:35], v[36:37], v[22:23]
	v_pk_add_f32 v[22:23], v[36:37], v[22:23] neg_lo:[0,1] neg_hi:[0,1]
	v_pk_add_f32 v[36:37], v[20:21], v[12:13]
	v_pk_add_f32 v[12:13], v[20:21], v[12:13] neg_lo:[0,1] neg_hi:[0,1]
	v_pk_add_f32 v[98:99], v[34:35], v[36:37]
	v_xor_b32_e32 v21, 0x80000000, v12
	v_mov_b32_e32 v20, v13
	v_pk_add_f32 v[12:13], v[4:5], v[28:29] op_sel:[0,1] op_sel_hi:[1,0] neg_hi:[0,1]
	v_pk_add_f32 v[4:5], v[4:5], v[28:29] op_sel:[0,1] op_sel_hi:[1,0] neg_lo:[0,1]
	v_pk_add_f32 v[28:29], v[8:9], v[16:17]
	v_pk_add_f32 v[8:9], v[8:9], v[16:17] neg_lo:[0,1] neg_hi:[0,1]
	v_pk_add_f32 v[100:101], v[34:35], v[36:37] neg_lo:[0,1] neg_hi:[0,1]
	v_xor_b32_e32 v17, 0x80000000, v8
	v_mov_b32_e32 v16, v9
	v_pk_add_f32 v[8:9], v[32:33], v[26:27]
	v_pk_add_f32 v[26:27], v[32:33], v[26:27] neg_lo:[0,1] neg_hi:[0,1]
	v_pk_add_f32 v[32:33], v[24:25], v[14:15]
	v_pk_add_f32 v[14:15], v[24:25], v[14:15] neg_lo:[0,1] neg_hi:[0,1]
	v_pk_add_f32 v[102:103], v[22:23], v[20:21]
	v_xor_b32_e32 v25, 0x80000000, v14
	v_mov_b32_e32 v24, v15
	v_pk_add_f32 v[14:15], v[6:7], v[30:31] op_sel:[0,1] op_sel_hi:[1,0] neg_hi:[0,1]
	v_pk_add_f32 v[6:7], v[6:7], v[30:31] op_sel:[0,1] op_sel_hi:[1,0] neg_lo:[0,1]
	v_pk_add_f32 v[30:31], v[10:11], v[18:19]
	v_pk_add_f32 v[10:11], v[10:11], v[18:19] neg_lo:[0,1] neg_hi:[0,1]
	v_pk_add_f32 v[104:105], v[22:23], v[20:21] neg_lo:[0,1] neg_hi:[0,1]
	v_xor_b32_e32 v19, 0x80000000, v10
	v_mov_b32_e32 v18, v11
	v_pk_add_f32 v[106:107], v[12:13], v[28:29]
	v_pk_add_f32 v[108:109], v[12:13], v[28:29] neg_lo:[0,1] neg_hi:[0,1]
	v_pk_add_f32 v[110:111], v[4:5], v[16:17]
	v_pk_add_f32 v[112:113], v[4:5], v[16:17] neg_lo:[0,1] neg_hi:[0,1]
	v_pk_add_f32 v[114:115], v[8:9], v[32:33]
	v_pk_add_f32 v[116:117], v[8:9], v[32:33] neg_lo:[0,1] neg_hi:[0,1]
	v_pk_add_f32 v[118:119], v[26:27], v[24:25]
	v_pk_add_f32 v[120:121], v[26:27], v[24:25] neg_lo:[0,1] neg_hi:[0,1]
	v_pk_add_f32 v[122:123], v[14:15], v[30:31]
	v_pk_add_f32 v[124:125], v[14:15], v[30:31] neg_lo:[0,1] neg_hi:[0,1]
	v_pk_add_f32 v[126:127], v[6:7], v[18:19]
	v_pk_add_f32 v[128:129], v[6:7], v[18:19] neg_lo:[0,1] neg_hi:[0,1]
	v_mov_b32_e32 v4, v131
	v_mov_b32_e32 v5, v3
	v_mov_b64_e32 v[6:7], v[2:3]
	s_and_saveexec_b64 s[50:51], s[0:1]
	s_xor_b64 s[0:1], exec, s[50:51]
	s_cbranch_execz .LBB0_576
	v_pk_add_f32 v[4:5], v[96:97], v[112:113]
	v_pk_add_f32 v[24:25], v[96:97], v[112:113] neg_lo:[0,1] neg_hi:[0,1]
	v_pk_add_f32 v[148:149], v[130:131], v[128:129]
	v_pk_add_f32 v[8:9], v[130:131], v[128:129] neg_lo:[0,1] neg_hi:[0,1]
	v_pk_add_f32 v[128:129], v[126:127], v[92:93]
	v_pk_add_f32 v[10:11], v[126:127], v[92:93] neg_lo:[0,1] neg_hi:[0,1]
	v_pk_add_f32 v[92:93], v[84:85], v[124:125]
	v_pk_add_f32 v[12:13], v[84:85], v[124:125] neg_lo:[0,1] neg_hi:[0,1]
	v_pk_add_f32 v[84:85], v[122:123], v[86:87]
	v_pk_add_f32 v[14:15], v[122:123], v[86:87] neg_lo:[0,1] neg_hi:[0,1]
	v_pk_add_f32 v[86:87], v[88:89], v[120:121]
	v_pk_add_f32 v[16:17], v[88:89], v[120:121] neg_lo:[0,1] neg_hi:[0,1]
	v_pk_add_f32 v[88:89], v[118:119], v[72:73]
	v_pk_add_f32 v[18:19], v[118:119], v[72:73] neg_lo:[0,1] neg_hi:[0,1]
	v_pk_add_f32 v[72:73], v[78:79], v[116:117]
	v_pk_add_f32 v[20:21], v[78:79], v[116:117] neg_lo:[0,1] neg_hi:[0,1]
	v_pk_add_f32 v[78:79], v[114:115], v[94:95]
	v_pk_add_f32 v[22:23], v[114:115], v[94:95] neg_lo:[0,1] neg_hi:[0,1]
	v_mov_b32_e32 v6, v4
	v_mov_b32_e32 v7, v25
	v_pk_mov_b32 v[4:5], v[4:5], v[24:25] op_sel:[1,0]
	v_pk_add_f32 v[94:95], v[110:111], v[50:51]
	v_pk_add_f32 v[24:25], v[110:111], v[50:51] neg_lo:[0,1] neg_hi:[0,1]
	v_pk_add_f32 v[50:51], v[66:67], v[108:109]
	v_pk_add_f32 v[26:27], v[66:67], v[108:109] neg_lo:[0,1] neg_hi:[0,1]
	v_pk_add_f32 v[66:67], v[106:107], v[80:81]
	v_pk_add_f32 v[28:29], v[106:107], v[80:81] neg_lo:[0,1] neg_hi:[0,1]
	v_pk_add_f32 v[80:81], v[82:83], v[104:105]
	v_pk_add_f32 v[30:31], v[82:83], v[104:105] neg_lo:[0,1] neg_hi:[0,1]
	v_pk_add_f32 v[82:83], v[102:103], v[68:69]
	v_pk_add_f32 v[32:33], v[102:103], v[68:69] neg_lo:[0,1] neg_hi:[0,1]
	v_pk_add_f32 v[68:69], v[60:61], v[100:101]
	v_pk_add_f32 v[34:35], v[60:61], v[100:101] neg_lo:[0,1] neg_hi:[0,1]
	v_pk_add_f32 v[60:61], v[98:99], v[90:91]
	v_pk_add_f32 v[36:37], v[98:99], v[90:91] neg_lo:[0,1] neg_hi:[0,1]
	v_pk_mul_f32 v[6:7], v[6:7], 0.5 op_sel_hi:[1,0]
	v_pk_mul_f32 v[4:5], v[4:5], s[46:47]
	v_mov_b32_e32 v39, v8
	v_mov_b32_e32 v38, v149
	v_mov_b32_e32 v41, v10
	v_mov_b32_e32 v40, v129
	v_mov_b32_e32 v43, v12
	v_mov_b32_e32 v42, v93
	v_mov_b32_e32 v45, v14
	v_mov_b32_e32 v44, v85
	v_mov_b32_e32 v47, v16
	v_mov_b32_e32 v46, v87
	v_mov_b32_e32 v49, v18
	v_mov_b32_e32 v48, v89
	v_mov_b32_e32 v53, v20
	v_mov_b32_e32 v52, v73
	v_mov_b32_e32 v55, v22
	v_mov_b32_e32 v54, v79
	v_mov_b32_e32 v57, v24
	v_mov_b32_e32 v56, v95
	v_mov_b32_e32 v59, v26
	v_mov_b32_e32 v58, v51
	v_mov_b32_e32 v63, v28
	v_mov_b32_e32 v62, v67
	v_mov_b32_e32 v65, v30
	v_mov_b32_e32 v64, v81
	v_mov_b32_e32 v71, v32
	v_mov_b32_e32 v70, v83
	v_mov_b32_e32 v75, v34
	v_mov_b32_e32 v74, v69
	v_mov_b32_e32 v77, v36
	v_mov_b32_e32 v76, v61
	v_mov_b32_e32 v8, v148
	v_mov_b32_e32 v10, v128
	v_mov_b32_e32 v12, v92
	v_mov_b32_e32 v14, v84
	v_mov_b32_e32 v16, v86
	v_mov_b32_e32 v18, v88
	v_mov_b32_e32 v20, v72
	v_mov_b32_e32 v22, v78
	v_mov_b32_e32 v24, v94
	v_mov_b32_e32 v26, v50
	v_mov_b32_e32 v28, v66
	v_mov_b32_e32 v30, v80
	v_mov_b32_e32 v32, v82
	v_mov_b32_e32 v34, v68
	v_mov_b32_e32 v36, v60
